# K-loop MFMA order: serpentine over the whole 32-MFMA segment (accumulator pairs back to back, neighbours share an operand), redundant setprio pairs removed
# baseline (speedup 1.0000x reference)
; #define PG8_STAGE(bufoff, gbase, voff) do { _Pragma("unroll") for (int _i = 0; _i < 2; ++_i) \
;         __builtin_amdgcn_global_load_lds((const unsigned*)((const char*)(gbase) + (voff)[_i]), (PG8_LAS unsigned*)(lds + (bufoff) + ldsw + _i * 8192), 16, 0, 0); } while (0)
; #define PG8_LDA(dst, b, h) do { _Pragma("unroll") for (int m = 0; m < 4; ++m) _Pragma("unroll") for (int k = 0; k < 2; ++k) dst[m][k] = *(const PG8_LAS bf16x8*)(lds + PG8_SA(b, h) + aoff + m * 2048 + k * 1024); } while (0)
; #define PG8_LDB(dst, b, h) do { _Pragma("unroll") for (int n = 0; n < 2; ++n) _Pragma("unroll") for (int k = 0; k < 2; ++k) dst[n][k] = *(const PG8_LAS bf16x8*)(lds + PG8_SB(b, h) + boff + n * 2048 + k * 1024); } while (0)
; #define PG8_MMA(ai, bj, At, Bt) do { __builtin_amdgcn_s_setprio(1); _Pragma("unroll") for (int m = 0; m < 4; ++m) _Pragma("unroll") for (int n = 0; n < 2; ++n) _Pragma("unroll") for (int k = 0; k < 2; ++k) \
;         acc[ai][bj][m][n] = __builtin_amdgcn_mfma_f32_16x16x32_bf16(Bt[n][k], At[m][k], acc[ai][bj][m][n], 0, 0, 0); __builtin_amdgcn_s_setprio(0); } while (0)
; #define PG8_WAIT_V(n) asm volatile("s_waitcnt vmcnt(" #n ")" ::: "memory")
; #define PG8_WAIT_L(n) asm volatile("s_waitcnt lgkmcnt(" #n ")" ::: "memory")
; template <class Epi, class Sched, bool ALIGN_EPI = false, bool SP2 = false, bool APERM = false  >
; __device__ __forceinline__ void gemm_phase(PG8_LAS unsigned char* lds, const Gemm g, const Sched& S, const Epi& E, const int wid  ) {
;     ...
;             const bool last = (t == nt - 2);
;             const char* a1 = cA + (size_t)(t + 1) * kstep;
;             const char* a2 = last ? nA : cA + (size_t)(t + 2) * kstep; const char* b2 = last ? nB : cB + (size_t)(t + 2) * kstep;
;             const char* a3 = a2 + kstep; const char* b3 = b2 + kstep;
;             if (last && has_next) S.a_ready(nxt);
;             if constexpr (SP2) {
;             PG8_LDB(B0, 0, 0); PG8_LDB(B1, 0, 1); PG8_SCHED; PG8_LDA(At, 0, 0); PG8_STAGE(PG8_SA(1, 1), a1 + hstep, voffA);
;             PG8_WAIT_V(8); PG8_WAIT_L(0); PG8_BAR; PG8_MMA(0, 0, At, B0); PG8_MMA(0, 1, At, B1); PG8_BAR; PG8_SCHED;
;             PG8_LDA(At, 0, 1); PG8_STAGE(PG8_SB(0, 0), b2, voffB); PG8_STAGE(PG8_SB(0, 1), b2 + hstep, voffB); PG8_STAGE(PG8_SA(0, 0), a2, voffA);
;             PG8_WAIT_V(8); PG8_WAIT_L(0); PG8_BAR; PG8_MMA(1, 0, At, B0); PG8_MMA(1, 1, At, B1); PG8_BAR; PG8_SCHED;
.LBB0_84:
	v_add_u32_e32 v140, s59, v145
	ds_read_b128 v[154:157], v140
	ds_read_b128 v[158:161], v140 offset:1024
	ds_read_b128 v[162:165], v140 offset:2048
	ds_read_b128 v[166:169], v140 offset:3072
	v_add_u32_e32 v140, s60, v145
	s_add_u32 s69, s26, s86
	ds_read_b128 v[170:173], v140
	ds_read_b128 v[174:177], v140 offset:1024
	ds_read_b128 v[178:181], v140 offset:2048
	ds_read_b128 v[182:185], v140 offset:3072
	s_addc_u32 s70, s27, s87
	s_add_u32 s69, s69, 0x100
	s_addc_u32 s70, s70, 0
	s_add_u32 s71, s64, s86
	s_addc_u32 s72, s65, s87
	s_cmpk_eq_i32 s86, 0xf00
	s_cselect_b32 s91, s19, s70
	s_cselect_b32 s90, s66, s69
	s_cselect_b32 s89, s25, s72
	s_cselect_b32 s88, s67, s71
	v_lshl_add_u64 v[150:151], v[136:137], 0, s[86:87]
	s_add_i32 m0, s3, 0xc000
	ds_read_b128 v[186:189], v149
	ds_read_b128 v[190:193], v149 offset:1024
	ds_read_b128 v[194:197], v149 offset:2048
	ds_read_b128 v[198:201], v149 offset:3072
	ds_read_b128 v[202:205], v149 offset:4096
	ds_read_b128 v[206:209], v149 offset:5120
	ds_read_b128 v[210:213], v149 offset:6144
	ds_read_b128 v[214:217], v149 offset:7168
	global_load_lds_dwordx4 v[150:151], off
	v_lshl_add_u64 v[150:151], v[138:139], 0, s[86:87]
	s_add_i32 m0, s3, 0xe000
	s_nop 0
	global_load_lds_dwordx4 v[150:151], off
	s_waitcnt vmcnt(8)
	s_waitcnt lgkmcnt(0)
	s_barrier
	s_setprio 1
	s_waitcnt lgkmcnt(0)
	v_mfma_f32_16x16x32_bf16 v[124:127], v[154:157], v[186:189], v[124:127]
	v_mfma_f32_16x16x32_bf16 v[124:127], v[158:161], v[190:193], v[124:127]
	v_mfma_f32_16x16x32_bf16 v[120:123], v[166:169], v[190:193], v[120:123]
	v_mfma_f32_16x16x32_bf16 v[120:123], v[162:165], v[186:189], v[120:123]
	v_mfma_f32_16x16x32_bf16 v[92:95], v[170:173], v[186:189], v[92:95]
	v_mfma_f32_16x16x32_bf16 v[92:95], v[174:177], v[190:193], v[92:95]
	v_mfma_f32_16x16x32_bf16 v[88:91], v[182:185], v[190:193], v[88:91]
	v_mfma_f32_16x16x32_bf16 v[88:91], v[178:181], v[186:189], v[88:91]
	v_mfma_f32_16x16x32_bf16 v[80:83], v[178:181], v[194:197], v[80:83]
	v_mfma_f32_16x16x32_bf16 v[80:83], v[182:185], v[198:201], v[80:83]
	v_mfma_f32_16x16x32_bf16 v[84:87], v[174:177], v[198:201], v[84:87]
	v_mfma_f32_16x16x32_bf16 v[84:87], v[170:173], v[194:197], v[84:87]
	v_mfma_f32_16x16x32_bf16 v[112:115], v[162:165], v[194:197], v[112:115]
	v_mfma_f32_16x16x32_bf16 v[112:115], v[166:169], v[198:201], v[112:115]
	v_mfma_f32_16x16x32_bf16 v[116:119], v[158:161], v[198:201], v[116:119]
	v_mfma_f32_16x16x32_bf16 v[116:119], v[154:157], v[194:197], v[116:119]
	v_mfma_f32_16x16x32_bf16 v[108:111], v[154:157], v[202:205], v[108:111]
	v_mfma_f32_16x16x32_bf16 v[108:111], v[158:161], v[206:209], v[108:111]
	v_mfma_f32_16x16x32_bf16 v[104:107], v[166:169], v[206:209], v[104:107]
	v_mfma_f32_16x16x32_bf16 v[104:107], v[162:165], v[202:205], v[104:107]
	v_mfma_f32_16x16x32_bf16 v[76:79], v[170:173], v[202:205], v[76:79]
	v_mfma_f32_16x16x32_bf16 v[76:79], v[174:177], v[206:209], v[76:79]
	v_mfma_f32_16x16x32_bf16 v[72:75], v[182:185], v[206:209], v[72:75]
	v_mfma_f32_16x16x32_bf16 v[72:75], v[178:181], v[202:205], v[72:75]
	v_mfma_f32_16x16x32_bf16 v[64:67], v[178:181], v[210:213], v[64:67]
	v_mfma_f32_16x16x32_bf16 v[64:67], v[182:185], v[214:217], v[64:67]
	v_mfma_f32_16x16x32_bf16 v[68:71], v[174:177], v[214:217], v[68:71]
	v_mfma_f32_16x16x32_bf16 v[68:71], v[170:173], v[210:213], v[68:71]
	v_mfma_f32_16x16x32_bf16 v[96:99], v[162:165], v[210:213], v[96:99]
	v_mfma_f32_16x16x32_bf16 v[96:99], v[166:169], v[214:217], v[96:99]
	v_mfma_f32_16x16x32_bf16 v[100:103], v[158:161], v[214:217], v[100:103]
	v_mfma_f32_16x16x32_bf16 v[100:103], v[154:157], v[210:213], v[100:103]
	s_setprio 0
	s_barrier
	s_add_i32 s69, s59, s53
	v_lshl_add_u64 v[150:151], s[88:89], 0, v[130:131]
	s_mov_b32 m0, s69
	ds_read_b128 v[186:189], v149 offset:16384
	ds_read_b128 v[190:193], v149 offset:17408
	ds_read_b128 v[194:197], v149 offset:18432
	ds_read_b128 v[198:201], v149 offset:19456
	ds_read_b128 v[202:205], v149 offset:20480
	ds_read_b128 v[206:209], v149 offset:21504
	ds_read_b128 v[210:213], v149 offset:22528
	ds_read_b128 v[214:217], v149 offset:23552
	global_load_lds_dwordx4 v[150:151], off
	s_add_i32 m0, s69, 0x2000
	s_add_u32 s70, s88, 0x80000
	v_lshl_add_u64 v[218:219], s[88:89], 0, v[128:129]
	s_addc_u32 s71, s89, 0
	s_add_i32 s69, s60, s53
	global_load_lds_dwordx4 v[218:219], off
	v_lshl_add_u64 v[220:221], s[70:71], 0, v[130:131]
	s_mov_b32 m0, s69
	v_lshl_add_u64 v[222:223], s[90:91], 0, v[128:129]
	global_load_lds_dwordx4 v[220:221], off
	v_lshl_add_u64 v[220:221], s[70:71], 0, v[128:129]
	s_add_i32 m0, s69, 0x2000
	s_nop 0
	global_load_lds_dwordx4 v[220:221], off
	v_lshl_add_u64 v[220:221], s[90:91], 0, v[130:131]
	s_mov_b32 m0, s3
	s_nop 0
	global_load_lds_dwordx4 v[220:221], off
	s_mov_b32 m0, s7
	s_nop 0
	global_load_lds_dwordx4 v[222:223], off
	s_waitcnt vmcnt(8)
	s_waitcnt lgkmcnt(0)
	s_barrier
; #define PG8_STAGE(bufoff, gbase, voff) do { _Pragma("unroll") for (int _i = 0; _i < 2; ++_i) \
;         __builtin_amdgcn_global_load_lds((const unsigned*)((const char*)(gbase) + (voff)[_i]), (PG8_LAS unsigned*)(lds + (bufoff) + ldsw + _i * 8192), 16, 0, 0); } while (0)
; #define PG8_LDA(dst, b, h) do { _Pragma("unroll") for (int m = 0; m < 4; ++m) _Pragma("unroll") for (int k = 0; k < 2; ++k) dst[m][k] = *(const PG8_LAS bf16x8*)(lds + PG8_SA(b, h) + aoff + m * 2048 + k * 1024); } while (0)
; #define PG8_LDB(dst, b, h) do { _Pragma("unroll") for (int n = 0; n < 2; ++n) _Pragma("unroll") for (int k = 0; k < 2; ++k) dst[n][k] = *(const PG8_LAS bf16x8*)(lds + PG8_SB(b, h) + boff + n * 2048 + k * 1024); } while (0)
; #define PG8_MMA(ai, bj, At, Bt) do { __builtin_amdgcn_s_setprio(1); _Pragma("unroll") for (int m = 0; m < 4; ++m) _Pragma("unroll") for (int n = 0; n < 2; ++n) _Pragma("unroll") for (int k = 0; k < 2; ++k) \
;         acc[ai][bj][m][n] = __builtin_amdgcn_mfma_f32_16x16x32_bf16(Bt[n][k], At[m][k], acc[ai][bj][m][n], 0, 0, 0); __builtin_amdgcn_s_setprio(0); } while (0)
; #define PG8_WAIT_V(n) asm volatile("s_waitcnt vmcnt(" #n ")" ::: "memory")
; #define PG8_WAIT_L(n) asm volatile("s_waitcnt lgkmcnt(" #n ")" ::: "memory")
; #define PG8_BAR __builtin_amdgcn_s_barrier()
; #define PG8_SCHED __builtin_amdgcn_sched_barrier(0)
; template <class Epi, class Sched, bool ALIGN_EPI = false, bool SP2 = false, bool APERM = false  >
; __device__ __forceinline__ void gemm_phase(PG8_LAS unsigned char* lds, const Gemm g, const Sched& S, const Epi& E, const int wid  ) {
;     ...
;             PG8_WAIT_V(8); PG8_WAIT_L(0); PG8_BAR; PG8_MMA(1, 0, At, B0); PG8_MMA(1, 1, At, B1); PG8_BAR; PG8_SCHED;
;             PG8_LDB(B0, 1, 0); PG8_LDB(B1, 1, 1); PG8_SCHED; PG8_LDA(At, 1, 0); PG8_STAGE(PG8_SA(0, 1), a2 + hstep, voffA);
;             PG8_WAIT_V(8); PG8_WAIT_L(0); PG8_BAR; PG8_MMA(0, 0, At, B0); PG8_MMA(0, 1, At, B1); PG8_BAR; PG8_SCHED;
	s_setprio 1
	s_waitcnt lgkmcnt(0)
	v_mfma_f32_16x16x32_bf16 v[60:63], v[154:157], v[186:189], v[60:63]
	v_mfma_f32_16x16x32_bf16 v[60:63], v[158:161], v[190:193], v[60:63]
	v_mfma_f32_16x16x32_bf16 v[56:59], v[166:169], v[190:193], v[56:59]
	v_mfma_f32_16x16x32_bf16 v[56:59], v[162:165], v[186:189], v[56:59]
	v_mfma_f32_16x16x32_bf16 v[28:31], v[170:173], v[186:189], v[28:31]
	v_mfma_f32_16x16x32_bf16 v[28:31], v[174:177], v[190:193], v[28:31]
	v_mfma_f32_16x16x32_bf16 v[24:27], v[182:185], v[190:193], v[24:27]
	v_mfma_f32_16x16x32_bf16 v[24:27], v[178:181], v[186:189], v[24:27]
	v_mfma_f32_16x16x32_bf16 v[16:19], v[178:181], v[194:197], v[16:19]
	v_mfma_f32_16x16x32_bf16 v[16:19], v[182:185], v[198:201], v[16:19]
	v_mfma_f32_16x16x32_bf16 v[20:23], v[174:177], v[198:201], v[20:23]
	v_mfma_f32_16x16x32_bf16 v[20:23], v[170:173], v[194:197], v[20:23]
	v_mfma_f32_16x16x32_bf16 v[48:51], v[162:165], v[194:197], v[48:51]
	v_mfma_f32_16x16x32_bf16 v[48:51], v[166:169], v[198:201], v[48:51]
	v_mfma_f32_16x16x32_bf16 v[52:55], v[158:161], v[198:201], v[52:55]
	v_mfma_f32_16x16x32_bf16 v[52:55], v[154:157], v[194:197], v[52:55]
	v_mfma_f32_16x16x32_bf16 v[44:47], v[154:157], v[202:205], v[44:47]
	v_mfma_f32_16x16x32_bf16 v[44:47], v[158:161], v[206:209], v[44:47]
	v_mfma_f32_16x16x32_bf16 v[40:43], v[166:169], v[206:209], v[40:43]
	v_mfma_f32_16x16x32_bf16 v[40:43], v[162:165], v[202:205], v[40:43]
	v_mfma_f32_16x16x32_bf16 v[12:15], v[170:173], v[202:205], v[12:15]
	v_mfma_f32_16x16x32_bf16 v[12:15], v[174:177], v[206:209], v[12:15]
	v_mfma_f32_16x16x32_bf16 v[8:11], v[182:185], v[206:209], v[8:11]
	v_mfma_f32_16x16x32_bf16 v[8:11], v[178:181], v[202:205], v[8:11]
	v_mfma_f32_16x16x32_bf16 v[0:3], v[178:181], v[210:213], v[0:3]
	v_mfma_f32_16x16x32_bf16 v[0:3], v[182:185], v[214:217], v[0:3]
	v_mfma_f32_16x16x32_bf16 v[4:7], v[174:177], v[214:217], v[4:7]
	v_mfma_f32_16x16x32_bf16 v[4:7], v[170:173], v[210:213], v[4:7]
	v_mfma_f32_16x16x32_bf16 v[32:35], v[162:165], v[210:213], v[32:35]
	v_mfma_f32_16x16x32_bf16 v[32:35], v[166:169], v[214:217], v[32:35]
	v_mfma_f32_16x16x32_bf16 v[36:39], v[158:161], v[214:217], v[36:39]
	v_mfma_f32_16x16x32_bf16 v[36:39], v[154:157], v[210:213], v[36:39]
	s_setprio 0
	s_barrier
	s_add_i32 s69, 0, 0x18000
	v_add_u32_e32 v140, s69, v145
	s_add_i32 s72, 0, 0x1c000
	ds_read_b128 v[154:157], v140
	ds_read_b128 v[158:161], v140 offset:1024
	ds_read_b128 v[162:165], v140 offset:2048
	ds_read_b128 v[166:169], v140 offset:3072
	v_add_u32_e32 v140, s72, v145
	ds_read_b128 v[170:173], v140
	ds_read_b128 v[174:177], v140 offset:1024
	ds_read_b128 v[178:181], v140 offset:2048
	ds_read_b128 v[182:185], v140 offset:3072
	s_add_u32 s70, s90, 0x80000
	s_addc_u32 s71, s91, 0
	s_mov_b32 m0, s54
	v_lshl_add_u64 v[224:225], s[70:71], 0, v[130:131]
	ds_read_b128 v[186:189], v149 offset:32768
	ds_read_b128 v[190:193], v149 offset:33792
	ds_read_b128 v[194:197], v149 offset:34816
	ds_read_b128 v[198:201], v149 offset:35840
	ds_read_b128 v[202:205], v149 offset:36864
	ds_read_b128 v[206:209], v149 offset:37888
	ds_read_b128 v[210:213], v149 offset:38912
	ds_read_b128 v[214:217], v149 offset:39936
	global_load_lds_dwordx4 v[224:225], off
	v_lshl_add_u64 v[224:225], s[70:71], 0, v[128:129]
	s_mov_b32 m0, s55
	s_nop 0
	global_load_lds_dwordx4 v[224:225], off
	s_waitcnt vmcnt(8)
	s_waitcnt lgkmcnt(0)
	s_barrier
	s_setprio 1
	s_waitcnt lgkmcnt(0)
	v_mfma_f32_16x16x32_bf16 v[124:127], v[154:157], v[186:189], v[124:127]
	v_mfma_f32_16x16x32_bf16 v[124:127], v[158:161], v[190:193], v[124:127]
	v_mfma_f32_16x16x32_bf16 v[120:123], v[166:169], v[190:193], v[120:123]
	v_mfma_f32_16x16x32_bf16 v[120:123], v[162:165], v[186:189], v[120:123]
	v_mfma_f32_16x16x32_bf16 v[92:95], v[170:173], v[186:189], v[92:95]
	v_mfma_f32_16x16x32_bf16 v[92:95], v[174:177], v[190:193], v[92:95]
	v_mfma_f32_16x16x32_bf16 v[88:91], v[182:185], v[190:193], v[88:91]
	v_mfma_f32_16x16x32_bf16 v[88:91], v[178:181], v[186:189], v[88:91]
	v_mfma_f32_16x16x32_bf16 v[80:83], v[178:181], v[194:197], v[80:83]
	v_mfma_f32_16x16x32_bf16 v[80:83], v[182:185], v[198:201], v[80:83]
	v_mfma_f32_16x16x32_bf16 v[84:87], v[174:177], v[198:201], v[84:87]
	v_mfma_f32_16x16x32_bf16 v[84:87], v[170:173], v[194:197], v[84:87]
	v_mfma_f32_16x16x32_bf16 v[112:115], v[162:165], v[194:197], v[112:115]
	v_mfma_f32_16x16x32_bf16 v[112:115], v[166:169], v[198:201], v[112:115]
	v_mfma_f32_16x16x32_bf16 v[116:119], v[158:161], v[198:201], v[116:119]
	v_mfma_f32_16x16x32_bf16 v[116:119], v[154:157], v[194:197], v[116:119]
	v_mfma_f32_16x16x32_bf16 v[108:111], v[154:157], v[202:205], v[108:111]
	v_mfma_f32_16x16x32_bf16 v[108:111], v[158:161], v[206:209], v[108:111]
	v_mfma_f32_16x16x32_bf16 v[104:107], v[166:169], v[206:209], v[104:107]
	v_mfma_f32_16x16x32_bf16 v[104:107], v[162:165], v[202:205], v[104:107]
	v_mfma_f32_16x16x32_bf16 v[76:79], v[170:173], v[202:205], v[76:79]
	v_mfma_f32_16x16x32_bf16 v[76:79], v[174:177], v[206:209], v[76:79]
	v_mfma_f32_16x16x32_bf16 v[72:75], v[182:185], v[206:209], v[72:75]
	v_mfma_f32_16x16x32_bf16 v[72:75], v[178:181], v[202:205], v[72:75]
	v_mfma_f32_16x16x32_bf16 v[64:67], v[178:181], v[210:213], v[64:67]
	v_mfma_f32_16x16x32_bf16 v[64:67], v[182:185], v[214:217], v[64:67]
	v_mfma_f32_16x16x32_bf16 v[68:71], v[174:177], v[214:217], v[68:71]
	v_mfma_f32_16x16x32_bf16 v[68:71], v[170:173], v[210:213], v[68:71]
	v_mfma_f32_16x16x32_bf16 v[96:99], v[162:165], v[210:213], v[96:99]
	v_mfma_f32_16x16x32_bf16 v[96:99], v[166:169], v[214:217], v[96:99]
	v_mfma_f32_16x16x32_bf16 v[100:103], v[158:161], v[214:217], v[100:103]
	v_mfma_f32_16x16x32_bf16 v[100:103], v[154:157], v[210:213], v[100:103]
	s_setprio 0
	s_barrier
; #define PG8_STAGE(bufoff, gbase, voff) do { _Pragma("unroll") for (int _i = 0; _i < 2; ++_i) \
;         __builtin_amdgcn_global_load_lds((const unsigned*)((const char*)(gbase) + (voff)[_i]), (PG8_LAS unsigned*)(lds + (bufoff) + ldsw + _i * 8192), 16, 0, 0); } while (0)
; #define PG8_LDA(dst, b, h) do { _Pragma("unroll") for (int m = 0; m < 4; ++m) _Pragma("unroll") for (int k = 0; k < 2; ++k) dst[m][k] = *(const PG8_LAS bf16x8*)(lds + PG8_SA(b, h) + aoff + m * 2048 + k * 1024); } while (0)
; #define PG8_MMA(ai, bj, At, Bt) do { __builtin_amdgcn_s_setprio(1); _Pragma("unroll") for (int m = 0; m < 4; ++m) _Pragma("unroll") for (int n = 0; n < 2; ++n) _Pragma("unroll") for (int k = 0; k < 2; ++k) \
;         acc[ai][bj][m][n] = __builtin_amdgcn_mfma_f32_16x16x32_bf16(Bt[n][k], At[m][k], acc[ai][bj][m][n], 0, 0, 0); __builtin_amdgcn_s_setprio(0); } while (0)
; #define PG8_WAIT_V(n) asm volatile("s_waitcnt vmcnt(" #n ")" ::: "memory")
; #define PG8_WAIT_L(n) asm volatile("s_waitcnt lgkmcnt(" #n ")" ::: "memory")
; #define PG8_BAR __builtin_amdgcn_s_barrier()
; #define PG8_SCHED __builtin_amdgcn_sched_barrier(0)
; template <class Epi, class Sched, bool ALIGN_EPI = false, bool SP2 = false, bool APERM = false  >
; __device__ __forceinline__ void gemm_phase(PG8_LAS unsigned char* lds, const Gemm g, const Sched& S, const Epi& E, const int wid  ) {
;     ...
;         for (int t = 0; t < nt; t += 2) {
;             const bool last = (t == nt - 2);
;     ...
;             PG8_LDA(At, 1, 1); PG8_STAGE(PG8_SB(1, 0), b3, voffB); PG8_STAGE(PG8_SB(1, 1), b3 + hstep, voffB); PG8_STAGE(PG8_SA(1, 0), a3, voffA);
;             PG8_WAIT_V(8); PG8_WAIT_L(0); PG8_BAR; PG8_MMA(1, 0, At, B0); PG8_MMA(1, 1, At, B1); PG8_BAR; PG8_SCHED;
;     ...
;         if constexpr (ALIGN_EPI) { if (wr == 0) PG8_BAR; }
	s_add_i32 s69, s69, s53
	v_lshl_add_u64 v[150:151], v[150:151], 0, s[14:15]
	s_mov_b32 m0, s69
	ds_read_b128 v[186:189], v149 offset:49152
	ds_read_b128 v[190:193], v149 offset:50176
	ds_read_b128 v[194:197], v149 offset:51200
	ds_read_b128 v[198:201], v149 offset:52224
	ds_read_b128 v[202:205], v149 offset:53248
	ds_read_b128 v[206:209], v149 offset:54272
	ds_read_b128 v[210:213], v149 offset:55296
	ds_read_b128 v[214:217], v149 offset:56320
	global_load_lds_dwordx4 v[150:151], off
	s_add_i32 m0, s69, 0x2000
	s_add_u32 s70, s88, 0x80080
	v_lshl_add_u64 v[150:151], v[218:219], 0, s[14:15]
	s_addc_u32 s71, s89, 0
	s_add_i32 s69, s72, s53
	global_load_lds_dwordx4 v[150:151], off
	v_lshl_add_u64 v[150:151], s[70:71], 0, v[130:131]
	s_mov_b32 m0, s69
	s_nop 0
	global_load_lds_dwordx4 v[150:151], off
	v_lshl_add_u64 v[150:151], s[70:71], 0, v[128:129]
	s_add_i32 m0, s69, 0x2000
	s_nop 0
	global_load_lds_dwordx4 v[150:151], off
	v_lshl_add_u64 v[150:151], v[220:221], 0, s[14:15]
	s_mov_b32 m0, s57
	s_nop 0
	global_load_lds_dwordx4 v[150:151], off
	v_lshl_add_u64 v[150:151], v[222:223], 0, s[14:15]
	s_mov_b32 m0, s58
	s_nop 0
	global_load_lds_dwordx4 v[150:151], off
	s_waitcnt vmcnt(8)
	s_waitcnt lgkmcnt(0)
	s_barrier
	s_setprio 1
	s_waitcnt lgkmcnt(0)
	v_mfma_f32_16x16x32_bf16 v[60:63], v[154:157], v[186:189], v[60:63]
	v_mfma_f32_16x16x32_bf16 v[60:63], v[158:161], v[190:193], v[60:63]
	v_mfma_f32_16x16x32_bf16 v[56:59], v[166:169], v[190:193], v[56:59]
	v_mfma_f32_16x16x32_bf16 v[56:59], v[162:165], v[186:189], v[56:59]
	v_mfma_f32_16x16x32_bf16 v[28:31], v[170:173], v[186:189], v[28:31]
	v_mfma_f32_16x16x32_bf16 v[28:31], v[174:177], v[190:193], v[28:31]
	v_mfma_f32_16x16x32_bf16 v[24:27], v[182:185], v[190:193], v[24:27]
	v_mfma_f32_16x16x32_bf16 v[24:27], v[178:181], v[186:189], v[24:27]
	v_mfma_f32_16x16x32_bf16 v[16:19], v[178:181], v[194:197], v[16:19]
	v_mfma_f32_16x16x32_bf16 v[16:19], v[182:185], v[198:201], v[16:19]
	v_mfma_f32_16x16x32_bf16 v[20:23], v[174:177], v[198:201], v[20:23]
	v_mfma_f32_16x16x32_bf16 v[20:23], v[170:173], v[194:197], v[20:23]
	v_mfma_f32_16x16x32_bf16 v[48:51], v[162:165], v[194:197], v[48:51]
	v_mfma_f32_16x16x32_bf16 v[48:51], v[166:169], v[198:201], v[48:51]
	v_mfma_f32_16x16x32_bf16 v[52:55], v[158:161], v[198:201], v[52:55]
	v_mfma_f32_16x16x32_bf16 v[52:55], v[154:157], v[194:197], v[52:55]
	v_mfma_f32_16x16x32_bf16 v[44:47], v[154:157], v[202:205], v[44:47]
	v_mfma_f32_16x16x32_bf16 v[44:47], v[158:161], v[206:209], v[44:47]
	v_mfma_f32_16x16x32_bf16 v[40:43], v[166:169], v[206:209], v[40:43]
	v_mfma_f32_16x16x32_bf16 v[40:43], v[162:165], v[202:205], v[40:43]
	v_mfma_f32_16x16x32_bf16 v[12:15], v[170:173], v[202:205], v[12:15]
	v_mfma_f32_16x16x32_bf16 v[12:15], v[174:177], v[206:209], v[12:15]
	v_mfma_f32_16x16x32_bf16 v[8:11], v[182:185], v[206:209], v[8:11]
	v_mfma_f32_16x16x32_bf16 v[8:11], v[178:181], v[202:205], v[8:11]
	v_mfma_f32_16x16x32_bf16 v[0:3], v[178:181], v[210:213], v[0:3]
	v_mfma_f32_16x16x32_bf16 v[0:3], v[182:185], v[214:217], v[0:3]
	v_mfma_f32_16x16x32_bf16 v[4:7], v[174:177], v[214:217], v[4:7]
	v_mfma_f32_16x16x32_bf16 v[4:7], v[170:173], v[210:213], v[4:7]
	v_mfma_f32_16x16x32_bf16 v[32:35], v[162:165], v[210:213], v[32:35]
	v_mfma_f32_16x16x32_bf16 v[32:35], v[166:169], v[214:217], v[32:35]
	v_mfma_f32_16x16x32_bf16 v[36:39], v[158:161], v[214:217], v[36:39]
	v_mfma_f32_16x16x32_bf16 v[36:39], v[154:157], v[210:213], v[36:39]
	s_setprio 0
	s_barrier
	s_add_i32 s68, s68, 2
	s_add_u32 s86, s86, 0x100
	s_addc_u32 s87, s87, 0
	s_cmp_gt_u32 s68, 29
	s_cbranch_scc0 .LBB0_84
	s_and_b64 vcc, exec, s[16:17]
	s_cbranch_vccz .LBB0_87
	s_barrier

; #define PG8_STAGE(bufoff, gbase, voff) do { _Pragma("unroll") for (int _i = 0; _i < 2; ++_i) \
;         __builtin_amdgcn_global_load_lds((const unsigned*)((const char*)(gbase) + (voff)[_i]), (PG8_LAS unsigned*)(lds + (bufoff) + ldsw + _i * 8192), 16, 0, 0); } while (0)
; #define PG8_LDA(dst, b, h) do { _Pragma("unroll") for (int m = 0; m < 4; ++m) _Pragma("unroll") for (int k = 0; k < 2; ++k) dst[m][k] = *(const PG8_LAS bf16x8*)(lds + PG8_SA(b, h) + aoff + m * 2048 + k * 1024); } while (0)
; #define PG8_LDB(dst, b, h) do { _Pragma("unroll") for (int n = 0; n < 2; ++n) _Pragma("unroll") for (int k = 0; k < 2; ++k) dst[n][k] = *(const PG8_LAS bf16x8*)(lds + PG8_SB(b, h) + boff + n * 2048 + k * 1024); } while (0)
; #define PG8_MMA(ai, bj, At, Bt) do { __builtin_amdgcn_s_setprio(1); _Pragma("unroll") for (int m = 0; m < 4; ++m) _Pragma("unroll") for (int n = 0; n < 2; ++n) _Pragma("unroll") for (int k = 0; k < 2; ++k) \
;         acc[ai][bj][m][n] = __builtin_amdgcn_mfma_f32_16x16x32_bf16(Bt[n][k], At[m][k], acc[ai][bj][m][n], 0, 0, 0); __builtin_amdgcn_s_setprio(0); } while (0)
; #define PG8_WAIT_V(n) asm volatile("s_waitcnt vmcnt(" #n ")" ::: "memory")
; #define PG8_WAIT_L(n) asm volatile("s_waitcnt lgkmcnt(" #n ")" ::: "memory")
; template <class Epi, class Sched, bool ALIGN_EPI = false, bool SP2 = false, bool APERM = false  >
; __device__ __forceinline__ void gemm_phase(PG8_LAS unsigned char* lds, const Gemm g, const Sched& S, const Epi& E, const int wid  ) {
;     ...
;             const bool last = (t == nt - 2);
;             const char* a1 = cA + (size_t)(t + 1) * kstep;
;             const char* a2 = last ? nA : cA + (size_t)(t + 2) * kstep; const char* b2 = last ? nB : cB + (size_t)(t + 2) * kstep;
;             const char* a3 = a2 + kstep; const char* b3 = b2 + kstep;
;             if (last && has_next) S.a_ready(nxt);
;             if constexpr (SP2) {
;             PG8_LDB(B0, 0, 0); PG8_LDB(B1, 0, 1); PG8_SCHED; PG8_LDA(At, 0, 0); PG8_STAGE(PG8_SA(1, 1), a1 + hstep, voffA);
;             PG8_WAIT_V(8); PG8_WAIT_L(0); PG8_BAR; PG8_MMA(0, 0, At, B0); PG8_MMA(0, 1, At, B1); PG8_BAR; PG8_SCHED;
;             PG8_LDA(At, 0, 1); PG8_STAGE(PG8_SB(0, 0), b2, voffB); PG8_STAGE(PG8_SB(0, 1), b2 + hstep, voffB); PG8_STAGE(PG8_SA(0, 0), a2, voffA);
;             PG8_WAIT_V(8); PG8_WAIT_L(0); PG8_BAR; PG8_MMA(1, 0, At, B0); PG8_MMA(1, 1, At, B1); PG8_BAR; PG8_SCHED;
.LBB0_310:
	s_or_b32 s58, s55, 1
	v_add_u32_e32 v159, s96, v153
	s_lshl_b64 s[64:65], s[58:59], 7
	s_add_i32 s58, s55, 2
	s_waitcnt lgkmcnt(0)
	ds_read_b128 v[144:147], v159
	ds_read_b128 v[148:151], v159 offset:1024
	ds_read_b128 v[160:163], v159 offset:2048
	ds_read_b128 v[164:167], v159 offset:3072
	v_add_u32_e32 v159, s97, v153
	s_lshl_b64 s[68:69], s[58:59], 7
	ds_read_b128 v[168:171], v159
	ds_read_b128 v[172:175], v159 offset:1024
	ds_read_b128 v[176:179], v159 offset:2048
	ds_read_b128 v[180:183], v159 offset:3072
	s_add_u32 s78, s0, s68
	s_addc_u32 s79, s1, s69
	s_and_b64 s[76:77], s[72:73], exec
	s_cselect_b32 vcc_hi, s13, s79
	s_cselect_b32 vcc_lo, s33, s78
	s_add_u32 s76, s14, s68
	s_addc_u32 s77, s15, s69
	s_and_b64 s[68:69], s[72:73], exec
	s_cselect_b32 s73, s9, s77
	s_cselect_b32 s72, s52, s76
	s_add_u32 s64, s53, s64
	s_addc_u32 s65, s54, s65
	v_lshl_add_u64 v[216:217], s[64:65], 0, v[132:133]
	s_add_i32 m0, s29, 0xc000
	ds_read_b128 v[184:187], v158
	ds_read_b128 v[188:191], v158 offset:1024
	ds_read_b128 v[192:195], v158 offset:2048
	ds_read_b128 v[196:199], v158 offset:3072
	ds_read_b128 v[200:203], v158 offset:4096
	ds_read_b128 v[204:207], v158 offset:5120
	ds_read_b128 v[208:211], v158 offset:6144
	ds_read_b128 v[212:215], v158 offset:7168
	global_load_lds_dwordx4 v[216:217], off
	v_lshl_add_u64 v[216:217], s[64:65], 0, v[136:137]
	s_add_i32 m0, s29, 0xe000
	s_nop 0
	global_load_lds_dwordx4 v[216:217], off
	s_waitcnt vmcnt(8)
	s_waitcnt lgkmcnt(0)
	s_barrier
	s_setprio 1
	s_waitcnt lgkmcnt(0)
	v_mfma_f32_16x16x32_bf16 v[124:127], v[144:147], v[184:187], v[124:127]
	v_mfma_f32_16x16x32_bf16 v[124:127], v[148:151], v[188:191], v[124:127]
	v_mfma_f32_16x16x32_bf16 v[120:123], v[164:167], v[188:191], v[120:123]
	v_mfma_f32_16x16x32_bf16 v[120:123], v[160:163], v[184:187], v[120:123]
	v_mfma_f32_16x16x32_bf16 v[92:95], v[168:171], v[184:187], v[92:95]
	v_mfma_f32_16x16x32_bf16 v[92:95], v[172:175], v[188:191], v[92:95]
	v_mfma_f32_16x16x32_bf16 v[88:91], v[180:183], v[188:191], v[88:91]
	v_mfma_f32_16x16x32_bf16 v[88:91], v[176:179], v[184:187], v[88:91]
	v_mfma_f32_16x16x32_bf16 v[80:83], v[176:179], v[192:195], v[80:83]
	v_mfma_f32_16x16x32_bf16 v[80:83], v[180:183], v[196:199], v[80:83]
	v_mfma_f32_16x16x32_bf16 v[84:87], v[172:175], v[196:199], v[84:87]
	v_mfma_f32_16x16x32_bf16 v[84:87], v[168:171], v[192:195], v[84:87]
	v_mfma_f32_16x16x32_bf16 v[112:115], v[160:163], v[192:195], v[112:115]
	v_mfma_f32_16x16x32_bf16 v[112:115], v[164:167], v[196:199], v[112:115]
	v_mfma_f32_16x16x32_bf16 v[116:119], v[148:151], v[196:199], v[116:119]
	v_mfma_f32_16x16x32_bf16 v[116:119], v[144:147], v[192:195], v[116:119]
	v_mfma_f32_16x16x32_bf16 v[108:111], v[144:147], v[200:203], v[108:111]
	v_mfma_f32_16x16x32_bf16 v[108:111], v[148:151], v[204:207], v[108:111]
	v_mfma_f32_16x16x32_bf16 v[104:107], v[164:167], v[204:207], v[104:107]
	v_mfma_f32_16x16x32_bf16 v[104:107], v[160:163], v[200:203], v[104:107]
	v_mfma_f32_16x16x32_bf16 v[76:79], v[168:171], v[200:203], v[76:79]
	v_mfma_f32_16x16x32_bf16 v[76:79], v[172:175], v[204:207], v[76:79]
	v_mfma_f32_16x16x32_bf16 v[72:75], v[180:183], v[204:207], v[72:75]
	v_mfma_f32_16x16x32_bf16 v[72:75], v[176:179], v[200:203], v[72:75]
	v_mfma_f32_16x16x32_bf16 v[64:67], v[176:179], v[208:211], v[64:67]
	v_mfma_f32_16x16x32_bf16 v[64:67], v[180:183], v[212:215], v[64:67]
	v_mfma_f32_16x16x32_bf16 v[68:71], v[172:175], v[212:215], v[68:71]
	v_mfma_f32_16x16x32_bf16 v[68:71], v[168:171], v[208:211], v[68:71]
	v_mfma_f32_16x16x32_bf16 v[96:99], v[160:163], v[208:211], v[96:99]
	v_mfma_f32_16x16x32_bf16 v[96:99], v[164:167], v[212:215], v[96:99]
	v_mfma_f32_16x16x32_bf16 v[100:103], v[148:151], v[212:215], v[100:103]
	v_mfma_f32_16x16x32_bf16 v[100:103], v[144:147], v[208:211], v[100:103]
	s_setprio 0
	s_barrier
	s_add_i32 s64, s96, s91
	v_lshl_add_u64 v[216:217], s[72:73], 0, v[128:129]
	s_mov_b32 m0, s64
	ds_read_b128 v[184:187], v158 offset:16384
	ds_read_b128 v[188:191], v158 offset:17408
	ds_read_b128 v[192:195], v158 offset:18432
	ds_read_b128 v[196:199], v158 offset:19456
	ds_read_b128 v[200:203], v158 offset:20480
	ds_read_b128 v[204:207], v158 offset:21504
	ds_read_b128 v[208:211], v158 offset:22528
	ds_read_b128 v[212:215], v158 offset:23552
	global_load_lds_dwordx4 v[216:217], off
	s_add_i32 m0, s64, 0x2000
	s_add_u32 s64, s72, 0x80000
	v_lshl_add_u64 v[218:219], s[72:73], 0, v[130:131]
	s_addc_u32 s65, s73, 0
	s_add_i32 s68, s97, s91
	global_load_lds_dwordx4 v[218:219], off
	v_lshl_add_u64 v[220:221], s[64:65], 0, v[128:129]
	s_mov_b32 m0, s68
	v_lshl_add_u64 v[222:223], vcc, 0, v[136:137]
	global_load_lds_dwordx4 v[220:221], off
	v_lshl_add_u64 v[220:221], s[64:65], 0, v[130:131]
	s_add_i32 m0, s68, 0x2000
	s_nop 0
	global_load_lds_dwordx4 v[220:221], off
	v_lshl_add_u64 v[220:221], vcc, 0, v[132:133]
	s_mov_b32 m0, s29
	s_nop 0
	global_load_lds_dwordx4 v[220:221], off
	s_mov_b32 m0, s57
	s_nop 0
	global_load_lds_dwordx4 v[222:223], off
	s_waitcnt vmcnt(8)
	s_waitcnt lgkmcnt(0)
	s_barrier
; #define PG8_STAGE(bufoff, gbase, voff) do { _Pragma("unroll") for (int _i = 0; _i < 2; ++_i) \
;         __builtin_amdgcn_global_load_lds((const unsigned*)((const char*)(gbase) + (voff)[_i]), (PG8_LAS unsigned*)(lds + (bufoff) + ldsw + _i * 8192), 16, 0, 0); } while (0)
; #define PG8_LDA(dst, b, h) do { _Pragma("unroll") for (int m = 0; m < 4; ++m) _Pragma("unroll") for (int k = 0; k < 2; ++k) dst[m][k] = *(const PG8_LAS bf16x8*)(lds + PG8_SA(b, h) + aoff + m * 2048 + k * 1024); } while (0)
; #define PG8_LDB(dst, b, h) do { _Pragma("unroll") for (int n = 0; n < 2; ++n) _Pragma("unroll") for (int k = 0; k < 2; ++k) dst[n][k] = *(const PG8_LAS bf16x8*)(lds + PG8_SB(b, h) + boff + n * 2048 + k * 1024); } while (0)
; #define PG8_MMA(ai, bj, At, Bt) do { __builtin_amdgcn_s_setprio(1); _Pragma("unroll") for (int m = 0; m < 4; ++m) _Pragma("unroll") for (int n = 0; n < 2; ++n) _Pragma("unroll") for (int k = 0; k < 2; ++k) \
;         acc[ai][bj][m][n] = __builtin_amdgcn_mfma_f32_16x16x32_bf16(Bt[n][k], At[m][k], acc[ai][bj][m][n], 0, 0, 0); __builtin_amdgcn_s_setprio(0); } while (0)
; #define PG8_WAIT_V(n) asm volatile("s_waitcnt vmcnt(" #n ")" ::: "memory")
; #define PG8_WAIT_L(n) asm volatile("s_waitcnt lgkmcnt(" #n ")" ::: "memory")
; #define PG8_BAR __builtin_amdgcn_s_barrier()
; #define PG8_SCHED __builtin_amdgcn_sched_barrier(0)
; template <class Epi, class Sched, bool ALIGN_EPI = false, bool SP2 = false, bool APERM = false  >
; __device__ __forceinline__ void gemm_phase(PG8_LAS unsigned char* lds, const Gemm g, const Sched& S, const Epi& E, const int wid  ) {
;     ...
;             PG8_WAIT_V(8); PG8_WAIT_L(0); PG8_BAR; PG8_MMA(1, 0, At, B0); PG8_MMA(1, 1, At, B1); PG8_BAR; PG8_SCHED;
;             PG8_LDB(B0, 1, 0); PG8_LDB(B1, 1, 1); PG8_SCHED; PG8_LDA(At, 1, 0); PG8_STAGE(PG8_SA(0, 1), a2 + hstep, voffA);
;             PG8_WAIT_V(8); PG8_WAIT_L(0); PG8_BAR; PG8_MMA(0, 0, At, B0); PG8_MMA(0, 1, At, B1); PG8_BAR; PG8_SCHED;
	s_setprio 1
	s_waitcnt lgkmcnt(0)
	v_mfma_f32_16x16x32_bf16 v[60:63], v[144:147], v[184:187], v[60:63]
	v_mfma_f32_16x16x32_bf16 v[60:63], v[148:151], v[188:191], v[60:63]
	v_mfma_f32_16x16x32_bf16 v[56:59], v[164:167], v[188:191], v[56:59]
	v_mfma_f32_16x16x32_bf16 v[56:59], v[160:163], v[184:187], v[56:59]
	v_mfma_f32_16x16x32_bf16 v[28:31], v[168:171], v[184:187], v[28:31]
	v_mfma_f32_16x16x32_bf16 v[28:31], v[172:175], v[188:191], v[28:31]
	v_mfma_f32_16x16x32_bf16 v[24:27], v[180:183], v[188:191], v[24:27]
	v_mfma_f32_16x16x32_bf16 v[24:27], v[176:179], v[184:187], v[24:27]
	v_mfma_f32_16x16x32_bf16 v[16:19], v[176:179], v[192:195], v[16:19]
	v_mfma_f32_16x16x32_bf16 v[16:19], v[180:183], v[196:199], v[16:19]
	v_mfma_f32_16x16x32_bf16 v[20:23], v[172:175], v[196:199], v[20:23]
	v_mfma_f32_16x16x32_bf16 v[20:23], v[168:171], v[192:195], v[20:23]
	v_mfma_f32_16x16x32_bf16 v[48:51], v[160:163], v[192:195], v[48:51]
	v_mfma_f32_16x16x32_bf16 v[48:51], v[164:167], v[196:199], v[48:51]
	v_mfma_f32_16x16x32_bf16 v[52:55], v[148:151], v[196:199], v[52:55]
	v_mfma_f32_16x16x32_bf16 v[52:55], v[144:147], v[192:195], v[52:55]
	v_mfma_f32_16x16x32_bf16 v[44:47], v[144:147], v[200:203], v[44:47]
	v_mfma_f32_16x16x32_bf16 v[44:47], v[148:151], v[204:207], v[44:47]
	v_mfma_f32_16x16x32_bf16 v[40:43], v[164:167], v[204:207], v[40:43]
	v_mfma_f32_16x16x32_bf16 v[40:43], v[160:163], v[200:203], v[40:43]
	v_mfma_f32_16x16x32_bf16 v[12:15], v[168:171], v[200:203], v[12:15]
	v_mfma_f32_16x16x32_bf16 v[12:15], v[172:175], v[204:207], v[12:15]
	v_mfma_f32_16x16x32_bf16 v[8:11], v[180:183], v[204:207], v[8:11]
	v_mfma_f32_16x16x32_bf16 v[8:11], v[176:179], v[200:203], v[8:11]
	v_mfma_f32_16x16x32_bf16 v[0:3], v[176:179], v[208:211], v[0:3]
	v_mfma_f32_16x16x32_bf16 v[0:3], v[180:183], v[212:215], v[0:3]
	v_mfma_f32_16x16x32_bf16 v[4:7], v[172:175], v[212:215], v[4:7]
	v_mfma_f32_16x16x32_bf16 v[4:7], v[168:171], v[208:211], v[4:7]
	v_mfma_f32_16x16x32_bf16 v[32:35], v[160:163], v[208:211], v[32:35]
	v_mfma_f32_16x16x32_bf16 v[32:35], v[164:167], v[212:215], v[32:35]
	v_mfma_f32_16x16x32_bf16 v[36:39], v[148:151], v[212:215], v[36:39]
	v_mfma_f32_16x16x32_bf16 v[36:39], v[144:147], v[208:211], v[36:39]
	s_setprio 0
	s_barrier
	s_add_i32 s68, 0, 0x18000
	v_add_u32_e32 v159, s68, v153
	s_add_i32 s69, 0, 0x1c000
	ds_read_b128 v[144:147], v159
	ds_read_b128 v[148:151], v159 offset:1024
	ds_read_b128 v[160:163], v159 offset:2048
	ds_read_b128 v[164:167], v159 offset:3072
	v_add_u32_e32 v159, s69, v153
	ds_read_b128 v[168:171], v159
	ds_read_b128 v[172:175], v159 offset:1024
	ds_read_b128 v[176:179], v159 offset:2048
	ds_read_b128 v[180:183], v159 offset:3072
	s_add_u32 s64, vcc_lo, 0x80000
	s_addc_u32 s65, vcc_hi, 0
	s_mov_b32 m0, s92
	v_lshl_add_u64 v[224:225], s[64:65], 0, v[132:133]
	ds_read_b128 v[184:187], v158 offset:32768
	ds_read_b128 v[188:191], v158 offset:33792
	ds_read_b128 v[192:195], v158 offset:34816
	ds_read_b128 v[196:199], v158 offset:35840
	ds_read_b128 v[200:203], v158 offset:36864
	ds_read_b128 v[204:207], v158 offset:37888
	ds_read_b128 v[208:211], v158 offset:38912
	ds_read_b128 v[212:215], v158 offset:39936
	global_load_lds_dwordx4 v[224:225], off
	v_lshl_add_u64 v[224:225], s[64:65], 0, v[136:137]
	s_mov_b32 m0, s93
	s_nop 0
	global_load_lds_dwordx4 v[224:225], off
	s_waitcnt vmcnt(8)
	s_waitcnt lgkmcnt(0)
	s_barrier
	s_setprio 1
	s_waitcnt lgkmcnt(0)
	v_mfma_f32_16x16x32_bf16 v[124:127], v[144:147], v[184:187], v[124:127]
	v_mfma_f32_16x16x32_bf16 v[124:127], v[148:151], v[188:191], v[124:127]
	v_mfma_f32_16x16x32_bf16 v[120:123], v[164:167], v[188:191], v[120:123]
	v_mfma_f32_16x16x32_bf16 v[120:123], v[160:163], v[184:187], v[120:123]
	v_mfma_f32_16x16x32_bf16 v[92:95], v[168:171], v[184:187], v[92:95]
	v_mfma_f32_16x16x32_bf16 v[92:95], v[172:175], v[188:191], v[92:95]
	v_mfma_f32_16x16x32_bf16 v[88:91], v[180:183], v[188:191], v[88:91]
	v_mfma_f32_16x16x32_bf16 v[88:91], v[176:179], v[184:187], v[88:91]
	v_mfma_f32_16x16x32_bf16 v[80:83], v[176:179], v[192:195], v[80:83]
	v_mfma_f32_16x16x32_bf16 v[80:83], v[180:183], v[196:199], v[80:83]
	v_mfma_f32_16x16x32_bf16 v[84:87], v[172:175], v[196:199], v[84:87]
	v_mfma_f32_16x16x32_bf16 v[84:87], v[168:171], v[192:195], v[84:87]
	v_mfma_f32_16x16x32_bf16 v[112:115], v[160:163], v[192:195], v[112:115]
	v_mfma_f32_16x16x32_bf16 v[112:115], v[164:167], v[196:199], v[112:115]
	v_mfma_f32_16x16x32_bf16 v[116:119], v[148:151], v[196:199], v[116:119]
	v_mfma_f32_16x16x32_bf16 v[116:119], v[144:147], v[192:195], v[116:119]
	v_mfma_f32_16x16x32_bf16 v[108:111], v[144:147], v[200:203], v[108:111]
	v_mfma_f32_16x16x32_bf16 v[108:111], v[148:151], v[204:207], v[108:111]
	v_mfma_f32_16x16x32_bf16 v[104:107], v[164:167], v[204:207], v[104:107]
	v_mfma_f32_16x16x32_bf16 v[104:107], v[160:163], v[200:203], v[104:107]
	v_mfma_f32_16x16x32_bf16 v[76:79], v[168:171], v[200:203], v[76:79]
	v_mfma_f32_16x16x32_bf16 v[76:79], v[172:175], v[204:207], v[76:79]
	v_mfma_f32_16x16x32_bf16 v[72:75], v[180:183], v[204:207], v[72:75]
	v_mfma_f32_16x16x32_bf16 v[72:75], v[176:179], v[200:203], v[72:75]
	v_mfma_f32_16x16x32_bf16 v[64:67], v[176:179], v[208:211], v[64:67]
	v_mfma_f32_16x16x32_bf16 v[64:67], v[180:183], v[212:215], v[64:67]
	v_mfma_f32_16x16x32_bf16 v[68:71], v[172:175], v[212:215], v[68:71]
	v_mfma_f32_16x16x32_bf16 v[68:71], v[168:171], v[208:211], v[68:71]
	v_mfma_f32_16x16x32_bf16 v[96:99], v[160:163], v[208:211], v[96:99]
	v_mfma_f32_16x16x32_bf16 v[96:99], v[164:167], v[212:215], v[96:99]
	v_mfma_f32_16x16x32_bf16 v[100:103], v[148:151], v[212:215], v[100:103]
	v_mfma_f32_16x16x32_bf16 v[100:103], v[144:147], v[208:211], v[100:103]
	s_setprio 0
	s_barrier
; #define PG8_STAGE(bufoff, gbase, voff) do { _Pragma("unroll") for (int _i = 0; _i < 2; ++_i) \
;         __builtin_amdgcn_global_load_lds((const unsigned*)((const char*)(gbase) + (voff)[_i]), (PG8_LAS unsigned*)(lds + (bufoff) + ldsw + _i * 8192), 16, 0, 0); } while (0)
; #define PG8_LDA(dst, b, h) do { _Pragma("unroll") for (int m = 0; m < 4; ++m) _Pragma("unroll") for (int k = 0; k < 2; ++k) dst[m][k] = *(const PG8_LAS bf16x8*)(lds + PG8_SA(b, h) + aoff + m * 2048 + k * 1024); } while (0)
; #define PG8_MMA(ai, bj, At, Bt) do { __builtin_amdgcn_s_setprio(1); _Pragma("unroll") for (int m = 0; m < 4; ++m) _Pragma("unroll") for (int n = 0; n < 2; ++n) _Pragma("unroll") for (int k = 0; k < 2; ++k) \
;         acc[ai][bj][m][n] = __builtin_amdgcn_mfma_f32_16x16x32_bf16(Bt[n][k], At[m][k], acc[ai][bj][m][n], 0, 0, 0); __builtin_amdgcn_s_setprio(0); } while (0)
; #define PG8_WAIT_V(n) asm volatile("s_waitcnt vmcnt(" #n ")" ::: "memory")
; #define PG8_WAIT_L(n) asm volatile("s_waitcnt lgkmcnt(" #n ")" ::: "memory")
; #define PG8_BAR __builtin_amdgcn_s_barrier()
; #define PG8_SCHED __builtin_amdgcn_sched_barrier(0)
; template <class Epi, class Sched, bool ALIGN_EPI = false, bool SP2 = false, bool APERM = false  >
; __device__ __forceinline__ void gemm_phase(PG8_LAS unsigned char* lds, const Gemm g, const Sched& S, const Epi& E, const int wid  ) {
;     ...
;         for (int t = 0; t < nt; t += 2) {
;             const bool last = (t == nt - 2);
;     ...
;             PG8_LDA(At, 1, 1); PG8_STAGE(PG8_SB(1, 0), b3, voffB); PG8_STAGE(PG8_SB(1, 1), b3 + hstep, voffB); PG8_STAGE(PG8_SA(1, 0), a3, voffA);
;             PG8_WAIT_V(8); PG8_WAIT_L(0); PG8_BAR; PG8_MMA(1, 0, At, B0); PG8_MMA(1, 1, At, B1); PG8_BAR; PG8_SCHED;
	s_add_i32 s64, s68, s91
	v_lshl_add_u64 v[216:217], v[216:217], 0, s[60:61]
	s_mov_b32 m0, s64
	ds_read_b128 v[184:187], v158 offset:49152
	ds_read_b128 v[188:191], v158 offset:50176
	ds_read_b128 v[192:195], v158 offset:51200
	ds_read_b128 v[196:199], v158 offset:52224
	ds_read_b128 v[200:203], v158 offset:53248
	ds_read_b128 v[204:207], v158 offset:54272
	ds_read_b128 v[208:211], v158 offset:55296
	ds_read_b128 v[212:215], v158 offset:56320
	global_load_lds_dwordx4 v[216:217], off
	s_add_i32 m0, s64, 0x2000
	s_add_u32 s64, s72, 0x80080
	v_lshl_add_u64 v[216:217], v[218:219], 0, s[60:61]
	s_addc_u32 s65, s73, 0
	s_add_i32 s68, s69, s91
	global_load_lds_dwordx4 v[216:217], off
	v_lshl_add_u64 v[216:217], s[64:65], 0, v[128:129]
	s_mov_b32 m0, s68
	s_nop 0
	global_load_lds_dwordx4 v[216:217], off
	v_lshl_add_u64 v[216:217], s[64:65], 0, v[130:131]
	s_add_i32 m0, s68, 0x2000
	s_nop 0
	global_load_lds_dwordx4 v[216:217], off
	v_lshl_add_u64 v[216:217], v[220:221], 0, s[60:61]
	s_mov_b32 m0, s94
	s_nop 0
	global_load_lds_dwordx4 v[216:217], off
	v_lshl_add_u64 v[216:217], v[222:223], 0, s[60:61]
	s_mov_b32 m0, s95
	s_nop 0
	global_load_lds_dwordx4 v[216:217], off
	s_waitcnt vmcnt(8)
	s_waitcnt lgkmcnt(0)
	s_barrier
	s_setprio 1
	s_waitcnt lgkmcnt(0)
	v_mfma_f32_16x16x32_bf16 v[60:63], v[144:147], v[184:187], v[60:63]
	v_mfma_f32_16x16x32_bf16 v[60:63], v[148:151], v[188:191], v[60:63]
	v_mfma_f32_16x16x32_bf16 v[56:59], v[164:167], v[188:191], v[56:59]
	v_mfma_f32_16x16x32_bf16 v[56:59], v[160:163], v[184:187], v[56:59]
	v_mfma_f32_16x16x32_bf16 v[28:31], v[168:171], v[184:187], v[28:31]
	v_mfma_f32_16x16x32_bf16 v[28:31], v[172:175], v[188:191], v[28:31]
	v_mfma_f32_16x16x32_bf16 v[24:27], v[180:183], v[188:191], v[24:27]
	v_mfma_f32_16x16x32_bf16 v[24:27], v[176:179], v[184:187], v[24:27]
	v_mfma_f32_16x16x32_bf16 v[16:19], v[176:179], v[192:195], v[16:19]
	v_mfma_f32_16x16x32_bf16 v[16:19], v[180:183], v[196:199], v[16:19]
	v_mfma_f32_16x16x32_bf16 v[20:23], v[172:175], v[196:199], v[20:23]
	v_mfma_f32_16x16x32_bf16 v[20:23], v[168:171], v[192:195], v[20:23]
	v_mfma_f32_16x16x32_bf16 v[48:51], v[160:163], v[192:195], v[48:51]
	v_mfma_f32_16x16x32_bf16 v[48:51], v[164:167], v[196:199], v[48:51]
	v_mfma_f32_16x16x32_bf16 v[52:55], v[148:151], v[196:199], v[52:55]
	v_mfma_f32_16x16x32_bf16 v[52:55], v[144:147], v[192:195], v[52:55]
	v_mfma_f32_16x16x32_bf16 v[44:47], v[144:147], v[200:203], v[44:47]
	v_mfma_f32_16x16x32_bf16 v[44:47], v[148:151], v[204:207], v[44:47]
	v_mfma_f32_16x16x32_bf16 v[40:43], v[164:167], v[204:207], v[40:43]
	v_mfma_f32_16x16x32_bf16 v[40:43], v[160:163], v[200:203], v[40:43]
	v_mfma_f32_16x16x32_bf16 v[12:15], v[168:171], v[200:203], v[12:15]
	v_mfma_f32_16x16x32_bf16 v[12:15], v[172:175], v[204:207], v[12:15]
	v_mfma_f32_16x16x32_bf16 v[8:11], v[180:183], v[204:207], v[8:11]
	v_mfma_f32_16x16x32_bf16 v[8:11], v[176:179], v[200:203], v[8:11]
	v_mfma_f32_16x16x32_bf16 v[0:3], v[176:179], v[208:211], v[0:3]
	v_mfma_f32_16x16x32_bf16 v[0:3], v[180:183], v[212:215], v[0:3]
	v_mfma_f32_16x16x32_bf16 v[4:7], v[172:175], v[212:215], v[4:7]
	v_mfma_f32_16x16x32_bf16 v[4:7], v[168:171], v[208:211], v[4:7]
	v_mfma_f32_16x16x32_bf16 v[32:35], v[160:163], v[208:211], v[32:35]
	v_mfma_f32_16x16x32_bf16 v[32:35], v[164:167], v[212:215], v[32:35]
	v_mfma_f32_16x16x32_bf16 v[36:39], v[148:151], v[212:215], v[36:39]
	v_mfma_f32_16x16x32_bf16 v[36:39], v[144:147], v[208:211], v[36:39]
	s_setprio 0
	s_barrier
	s_cmp_gt_u32 s55, 29
	s_cbranch_scc1 .LBB0_312
	s_mov_b32 s55, s58
	s_branch .LBB0_293

; #define PG8_STAGE(bufoff, gbase, voff) do { _Pragma("unroll") for (int _i = 0; _i < 2; ++_i) \
;         __builtin_amdgcn_global_load_lds((const unsigned*)((const char*)(gbase) + (voff)[_i]), (PG8_LAS unsigned*)(lds + (bufoff) + ldsw + _i * 8192), 16, 0, 0); } while (0)
; #define PG8_LDA(dst, b, h) do { _Pragma("unroll") for (int m = 0; m < 4; ++m) _Pragma("unroll") for (int k = 0; k < 2; ++k) dst[m][k] = *(const PG8_LAS bf16x8*)(lds + PG8_SA(b, h) + aoff + m * 2048 + k * 1024); } while (0)
; #define PG8_LDB(dst, b, h) do { _Pragma("unroll") for (int n = 0; n < 2; ++n) _Pragma("unroll") for (int k = 0; k < 2; ++k) dst[n][k] = *(const PG8_LAS bf16x8*)(lds + PG8_SB(b, h) + boff + n * 2048 + k * 1024); } while (0)
; #define PG8_MMA(ai, bj, At, Bt) do { __builtin_amdgcn_s_setprio(1); _Pragma("unroll") for (int m = 0; m < 4; ++m) _Pragma("unroll") for (int n = 0; n < 2; ++n) _Pragma("unroll") for (int k = 0; k < 2; ++k) \
;         acc[ai][bj][m][n] = __builtin_amdgcn_mfma_f32_16x16x32_bf16(Bt[n][k], At[m][k], acc[ai][bj][m][n], 0, 0, 0); __builtin_amdgcn_s_setprio(0); } while (0)
; #define PG8_WAIT_V(n) asm volatile("s_waitcnt vmcnt(" #n ")" ::: "memory")
; #define PG8_WAIT_L(n) asm volatile("s_waitcnt lgkmcnt(" #n ")" ::: "memory")
; template <class Epi, class Sched, bool ALIGN_EPI = false, bool SP2 = false, bool APERM = false  >
; __device__ __forceinline__ void gemm_phase(PG8_LAS unsigned char* lds, const Gemm g, const Sched& S, const Epi& E, const int wid  ) {
;     ...
;             const bool last = (t == nt - 2);
;             const char* a1 = cA + (size_t)(t + 1) * kstep;
;             const char* a2 = last ? nA : cA + (size_t)(t + 2) * kstep; const char* b2 = last ? nB : cB + (size_t)(t + 2) * kstep;
;             const char* a3 = a2 + kstep; const char* b3 = b2 + kstep;
;             if (last && has_next) S.a_ready(nxt);
;             if constexpr (SP2) {
;             PG8_LDB(B0, 0, 0); PG8_LDB(B1, 0, 1); PG8_SCHED; PG8_LDA(At, 0, 0); PG8_STAGE(PG8_SA(1, 1), a1 + hstep, voffA);
;             PG8_WAIT_V(8); PG8_WAIT_L(0); PG8_BAR; PG8_MMA(0, 0, At, B0); PG8_MMA(0, 1, At, B1); PG8_BAR; PG8_SCHED;
;             PG8_LDA(At, 0, 1); PG8_STAGE(PG8_SB(0, 0), b2, voffB); PG8_STAGE(PG8_SB(0, 1), b2 + hstep, voffB); PG8_STAGE(PG8_SA(0, 0), a2, voffA);
;             PG8_WAIT_V(8); PG8_WAIT_L(0); PG8_BAR; PG8_MMA(1, 0, At, B0); PG8_MMA(1, 1, At, B1); PG8_BAR; PG8_SCHED;
.LBB0_390:
	s_lshl_b32 s6, s47, 7
	s_add_u32 s7, s60, s6
	s_addc_u32 s16, s61, 0
	s_add_u32 s14, s7, 0x100
	s_addc_u32 s15, s16, 0
	v_add_u32_e32 v140, s90, v230
	v_add_u32_e32 v156, s74, v230
	s_and_b64 s[0:1], s[12:13], exec
	ds_read_b128 v[128:131], v140
	ds_read_b128 v[132:135], v140 offset:1024
	ds_read_b128 v[136:139], v140 offset:2048
	ds_read_b128 v[140:143], v140 offset:3072
	ds_read_b128 v[144:147], v156
	ds_read_b128 v[148:151], v156 offset:1024
	ds_read_b128 v[152:155], v156 offset:2048
	ds_read_b128 v[156:159], v156 offset:3072
	s_cselect_b32 s15, s31, s15
	s_cselect_b32 s14, s33, s14
	s_add_u32 s0, s56, s6
	s_addc_u32 s1, s57, 0
	s_add_u32 s6, s0, 0x100
	s_addc_u32 s17, s1, 0
	s_and_b64 s[0:1], s[12:13], exec
	s_cselect_b32 s0, s46, s6
	s_cselect_b32 s1, s35, s17
	s_add_u32 s6, s7, 0x80080
	s_addc_u32 s7, s16, 0
	v_lshl_add_u64 v[206:207], s[6:7], 0, v[188:189]
	s_add_i32 m0, s5, 0xc000
	ds_read_b128 v[160:163], v243
	ds_read_b128 v[164:167], v243 offset:1024
	ds_read_b128 v[168:171], v243 offset:2048
	ds_read_b128 v[172:175], v243 offset:3072
	ds_read_b128 v[176:179], v243 offset:4096
	ds_read_b128 v[180:183], v243 offset:5120
	ds_read_b128 v[198:201], v243 offset:6144
	ds_read_b128 v[202:205], v243 offset:7168
	global_load_lds_dwordx4 v[206:207], off
	v_lshl_add_u64 v[206:207], s[6:7], 0, v[190:191]
	s_add_i32 m0, s5, 0xe000
	s_nop 0
	global_load_lds_dwordx4 v[206:207], off
	s_waitcnt vmcnt(8)
	s_waitcnt lgkmcnt(0)
	s_barrier
	s_setprio 1
	s_waitcnt lgkmcnt(0)
	v_mfma_f32_16x16x32_bf16 v[124:127], v[128:131], v[160:163], v[124:127]
	v_mfma_f32_16x16x32_bf16 v[124:127], v[132:135], v[164:167], v[124:127]
	v_mfma_f32_16x16x32_bf16 v[120:123], v[140:143], v[164:167], v[120:123]
	v_mfma_f32_16x16x32_bf16 v[120:123], v[136:139], v[160:163], v[120:123]
	v_mfma_f32_16x16x32_bf16 v[92:95], v[144:147], v[160:163], v[92:95]
	v_mfma_f32_16x16x32_bf16 v[92:95], v[148:151], v[164:167], v[92:95]
	v_mfma_f32_16x16x32_bf16 v[88:91], v[156:159], v[164:167], v[88:91]
	v_mfma_f32_16x16x32_bf16 v[88:91], v[152:155], v[160:163], v[88:91]
	v_mfma_f32_16x16x32_bf16 v[80:83], v[152:155], v[168:171], v[80:83]
	v_mfma_f32_16x16x32_bf16 v[80:83], v[156:159], v[172:175], v[80:83]
	v_mfma_f32_16x16x32_bf16 v[84:87], v[148:151], v[172:175], v[84:87]
	v_mfma_f32_16x16x32_bf16 v[84:87], v[144:147], v[168:171], v[84:87]
	v_mfma_f32_16x16x32_bf16 v[112:115], v[136:139], v[168:171], v[112:115]
	v_mfma_f32_16x16x32_bf16 v[112:115], v[140:143], v[172:175], v[112:115]
	v_mfma_f32_16x16x32_bf16 v[116:119], v[132:135], v[172:175], v[116:119]
	v_mfma_f32_16x16x32_bf16 v[116:119], v[128:131], v[168:171], v[116:119]
	v_mfma_f32_16x16x32_bf16 v[108:111], v[128:131], v[176:179], v[108:111]
	v_mfma_f32_16x16x32_bf16 v[108:111], v[132:135], v[180:183], v[108:111]
	v_mfma_f32_16x16x32_bf16 v[104:107], v[140:143], v[180:183], v[104:107]
	v_mfma_f32_16x16x32_bf16 v[104:107], v[136:139], v[176:179], v[104:107]
	v_mfma_f32_16x16x32_bf16 v[76:79], v[144:147], v[176:179], v[76:79]
	v_mfma_f32_16x16x32_bf16 v[76:79], v[148:151], v[180:183], v[76:79]
	v_mfma_f32_16x16x32_bf16 v[72:75], v[156:159], v[180:183], v[72:75]
	v_mfma_f32_16x16x32_bf16 v[72:75], v[152:155], v[176:179], v[72:75]
	v_mfma_f32_16x16x32_bf16 v[64:67], v[152:155], v[198:201], v[64:67]
	v_mfma_f32_16x16x32_bf16 v[64:67], v[156:159], v[202:205], v[64:67]
	v_mfma_f32_16x16x32_bf16 v[68:71], v[148:151], v[202:205], v[68:71]
	v_mfma_f32_16x16x32_bf16 v[68:71], v[144:147], v[198:201], v[68:71]
	v_mfma_f32_16x16x32_bf16 v[96:99], v[136:139], v[198:201], v[96:99]
	v_mfma_f32_16x16x32_bf16 v[96:99], v[140:143], v[202:205], v[96:99]
	v_mfma_f32_16x16x32_bf16 v[100:103], v[132:135], v[202:205], v[100:103]
	v_mfma_f32_16x16x32_bf16 v[100:103], v[128:131], v[198:201], v[100:103]
	s_setprio 0
	s_barrier
	s_add_i32 s6, s90, s63
	v_lshl_add_u64 v[206:207], s[0:1], 0, v[184:185]
	s_mov_b32 m0, s6
	ds_read_b128 v[160:163], v243 offset:16384
	ds_read_b128 v[164:167], v243 offset:17408
	ds_read_b128 v[168:171], v243 offset:18432
	ds_read_b128 v[172:175], v243 offset:19456
	ds_read_b128 v[176:179], v243 offset:20480
	ds_read_b128 v[180:183], v243 offset:21504
	ds_read_b128 v[198:201], v243 offset:22528
	ds_read_b128 v[202:205], v243 offset:23552
	global_load_lds_dwordx4 v[206:207], off
	s_add_i32 m0, s6, 0x2000
	s_add_u32 s6, s0, 0x80000
	v_lshl_add_u64 v[208:209], s[0:1], 0, v[186:187]
	s_addc_u32 s7, s1, 0
	s_add_i32 s12, s74, s63
	global_load_lds_dwordx4 v[208:209], off
	v_lshl_add_u64 v[210:211], s[6:7], 0, v[184:185]
	s_mov_b32 m0, s12
	v_lshl_add_u64 v[212:213], s[14:15], 0, v[190:191]
	global_load_lds_dwordx4 v[210:211], off
	v_lshl_add_u64 v[210:211], s[6:7], 0, v[186:187]
	s_add_i32 m0, s12, 0x2000
	s_nop 0
	global_load_lds_dwordx4 v[210:211], off
	v_lshl_add_u64 v[210:211], s[14:15], 0, v[188:189]
	s_mov_b32 m0, s5
	s_nop 0
	global_load_lds_dwordx4 v[210:211], off
	s_mov_b32 m0, s87
	s_nop 0
	global_load_lds_dwordx4 v[212:213], off
	s_waitcnt vmcnt(8)
	s_waitcnt lgkmcnt(0)
	s_barrier
; #define PG8_STAGE(bufoff, gbase, voff) do { _Pragma("unroll") for (int _i = 0; _i < 2; ++_i) \
;         __builtin_amdgcn_global_load_lds((const unsigned*)((const char*)(gbase) + (voff)[_i]), (PG8_LAS unsigned*)(lds + (bufoff) + ldsw + _i * 8192), 16, 0, 0); } while (0)
; #define PG8_LDA(dst, b, h) do { _Pragma("unroll") for (int m = 0; m < 4; ++m) _Pragma("unroll") for (int k = 0; k < 2; ++k) dst[m][k] = *(const PG8_LAS bf16x8*)(lds + PG8_SA(b, h) + aoff + m * 2048 + k * 1024); } while (0)
; #define PG8_LDB(dst, b, h) do { _Pragma("unroll") for (int n = 0; n < 2; ++n) _Pragma("unroll") for (int k = 0; k < 2; ++k) dst[n][k] = *(const PG8_LAS bf16x8*)(lds + PG8_SB(b, h) + boff + n * 2048 + k * 1024); } while (0)
; #define PG8_MMA(ai, bj, At, Bt) do { __builtin_amdgcn_s_setprio(1); _Pragma("unroll") for (int m = 0; m < 4; ++m) _Pragma("unroll") for (int n = 0; n < 2; ++n) _Pragma("unroll") for (int k = 0; k < 2; ++k) \
;         acc[ai][bj][m][n] = __builtin_amdgcn_mfma_f32_16x16x32_bf16(Bt[n][k], At[m][k], acc[ai][bj][m][n], 0, 0, 0); __builtin_amdgcn_s_setprio(0); } while (0)
; #define PG8_WAIT_V(n) asm volatile("s_waitcnt vmcnt(" #n ")" ::: "memory")
; #define PG8_WAIT_L(n) asm volatile("s_waitcnt lgkmcnt(" #n ")" ::: "memory")
; #define PG8_BAR __builtin_amdgcn_s_barrier()
; #define PG8_SCHED __builtin_amdgcn_sched_barrier(0)
; template <class Epi, class Sched, bool ALIGN_EPI = false, bool SP2 = false, bool APERM = false  >
; __device__ __forceinline__ void gemm_phase(PG8_LAS unsigned char* lds, const Gemm g, const Sched& S, const Epi& E, const int wid  ) {
;     ...
;             PG8_WAIT_V(8); PG8_WAIT_L(0); PG8_BAR; PG8_MMA(1, 0, At, B0); PG8_MMA(1, 1, At, B1); PG8_BAR; PG8_SCHED;
;             PG8_LDB(B0, 1, 0); PG8_LDB(B1, 1, 1); PG8_SCHED; PG8_LDA(At, 1, 0); PG8_STAGE(PG8_SA(0, 1), a2 + hstep, voffA);
;             PG8_WAIT_V(8); PG8_WAIT_L(0); PG8_BAR; PG8_MMA(0, 0, At, B0); PG8_MMA(0, 1, At, B1); PG8_BAR; PG8_SCHED;
	s_setprio 1
	s_waitcnt lgkmcnt(0)
	v_mfma_f32_16x16x32_bf16 v[60:63], v[128:131], v[160:163], v[60:63]
	v_mfma_f32_16x16x32_bf16 v[60:63], v[132:135], v[164:167], v[60:63]
	v_mfma_f32_16x16x32_bf16 v[56:59], v[140:143], v[164:167], v[56:59]
	v_mfma_f32_16x16x32_bf16 v[56:59], v[136:139], v[160:163], v[56:59]
	v_mfma_f32_16x16x32_bf16 v[28:31], v[144:147], v[160:163], v[28:31]
	v_mfma_f32_16x16x32_bf16 v[28:31], v[148:151], v[164:167], v[28:31]
	v_mfma_f32_16x16x32_bf16 v[24:27], v[156:159], v[164:167], v[24:27]
	v_mfma_f32_16x16x32_bf16 v[24:27], v[152:155], v[160:163], v[24:27]
	v_mfma_f32_16x16x32_bf16 v[16:19], v[152:155], v[168:171], v[16:19]
	v_mfma_f32_16x16x32_bf16 v[16:19], v[156:159], v[172:175], v[16:19]
	v_mfma_f32_16x16x32_bf16 v[20:23], v[148:151], v[172:175], v[20:23]
	v_mfma_f32_16x16x32_bf16 v[20:23], v[144:147], v[168:171], v[20:23]
	v_mfma_f32_16x16x32_bf16 v[48:51], v[136:139], v[168:171], v[48:51]
	v_mfma_f32_16x16x32_bf16 v[48:51], v[140:143], v[172:175], v[48:51]
	v_mfma_f32_16x16x32_bf16 v[52:55], v[132:135], v[172:175], v[52:55]
	v_mfma_f32_16x16x32_bf16 v[52:55], v[128:131], v[168:171], v[52:55]
	v_mfma_f32_16x16x32_bf16 v[44:47], v[128:131], v[176:179], v[44:47]
	v_mfma_f32_16x16x32_bf16 v[44:47], v[132:135], v[180:183], v[44:47]
	v_mfma_f32_16x16x32_bf16 v[40:43], v[140:143], v[180:183], v[40:43]
	v_mfma_f32_16x16x32_bf16 v[40:43], v[136:139], v[176:179], v[40:43]
	v_mfma_f32_16x16x32_bf16 v[12:15], v[144:147], v[176:179], v[12:15]
	v_mfma_f32_16x16x32_bf16 v[12:15], v[148:151], v[180:183], v[12:15]
	v_mfma_f32_16x16x32_bf16 v[8:11], v[156:159], v[180:183], v[8:11]
	v_mfma_f32_16x16x32_bf16 v[8:11], v[152:155], v[176:179], v[8:11]
	v_mfma_f32_16x16x32_bf16 v[0:3], v[152:155], v[198:201], v[0:3]
	v_mfma_f32_16x16x32_bf16 v[0:3], v[156:159], v[202:205], v[0:3]
	v_mfma_f32_16x16x32_bf16 v[4:7], v[148:151], v[202:205], v[4:7]
	v_mfma_f32_16x16x32_bf16 v[4:7], v[144:147], v[198:201], v[4:7]
	v_mfma_f32_16x16x32_bf16 v[32:35], v[136:139], v[198:201], v[32:35]
	v_mfma_f32_16x16x32_bf16 v[32:35], v[140:143], v[202:205], v[32:35]
	v_mfma_f32_16x16x32_bf16 v[36:39], v[132:135], v[202:205], v[36:39]
	v_mfma_f32_16x16x32_bf16 v[36:39], v[128:131], v[198:201], v[36:39]
	s_setprio 0
	s_barrier
	s_add_i32 s12, 0, 0x18000
	s_add_i32 s13, 0, 0x1c000
	v_add_u32_e32 v140, s12, v230
	v_add_u32_e32 v156, s13, v230
	ds_read_b128 v[128:131], v140
	ds_read_b128 v[132:135], v140 offset:1024
	ds_read_b128 v[136:139], v140 offset:2048
	ds_read_b128 v[140:143], v140 offset:3072
	ds_read_b128 v[144:147], v156
	ds_read_b128 v[148:151], v156 offset:1024
	ds_read_b128 v[152:155], v156 offset:2048
	ds_read_b128 v[156:159], v156 offset:3072
	s_add_u32 s6, s14, 0x80000
	s_addc_u32 s7, s15, 0
	s_mov_b32 m0, s10
	v_lshl_add_u64 v[214:215], s[6:7], 0, v[188:189]
	ds_read_b128 v[160:163], v243 offset:32768
	ds_read_b128 v[164:167], v243 offset:33792
	ds_read_b128 v[168:171], v243 offset:34816
	ds_read_b128 v[172:175], v243 offset:35840
	ds_read_b128 v[176:179], v243 offset:36864
	ds_read_b128 v[180:183], v243 offset:37888
	ds_read_b128 v[198:201], v243 offset:38912
	ds_read_b128 v[202:205], v243 offset:39936
	global_load_lds_dwordx4 v[214:215], off
	v_lshl_add_u64 v[214:215], s[6:7], 0, v[190:191]
	s_mov_b32 m0, s11
	s_nop 0
	global_load_lds_dwordx4 v[214:215], off
	s_waitcnt vmcnt(8)
	s_waitcnt lgkmcnt(0)
	s_barrier
	s_setprio 1
	s_waitcnt lgkmcnt(0)
	v_mfma_f32_16x16x32_bf16 v[124:127], v[128:131], v[160:163], v[124:127]
	v_mfma_f32_16x16x32_bf16 v[124:127], v[132:135], v[164:167], v[124:127]
	v_mfma_f32_16x16x32_bf16 v[120:123], v[140:143], v[164:167], v[120:123]
	v_mfma_f32_16x16x32_bf16 v[120:123], v[136:139], v[160:163], v[120:123]
	v_mfma_f32_16x16x32_bf16 v[92:95], v[144:147], v[160:163], v[92:95]
	v_mfma_f32_16x16x32_bf16 v[92:95], v[148:151], v[164:167], v[92:95]
	v_mfma_f32_16x16x32_bf16 v[88:91], v[156:159], v[164:167], v[88:91]
	v_mfma_f32_16x16x32_bf16 v[88:91], v[152:155], v[160:163], v[88:91]
	v_mfma_f32_16x16x32_bf16 v[80:83], v[152:155], v[168:171], v[80:83]
	v_mfma_f32_16x16x32_bf16 v[80:83], v[156:159], v[172:175], v[80:83]
	v_mfma_f32_16x16x32_bf16 v[84:87], v[148:151], v[172:175], v[84:87]
	v_mfma_f32_16x16x32_bf16 v[84:87], v[144:147], v[168:171], v[84:87]
	v_mfma_f32_16x16x32_bf16 v[112:115], v[136:139], v[168:171], v[112:115]
	v_mfma_f32_16x16x32_bf16 v[112:115], v[140:143], v[172:175], v[112:115]
	v_mfma_f32_16x16x32_bf16 v[116:119], v[132:135], v[172:175], v[116:119]
	v_mfma_f32_16x16x32_bf16 v[116:119], v[128:131], v[168:171], v[116:119]
	v_mfma_f32_16x16x32_bf16 v[108:111], v[128:131], v[176:179], v[108:111]
	v_mfma_f32_16x16x32_bf16 v[108:111], v[132:135], v[180:183], v[108:111]
	v_mfma_f32_16x16x32_bf16 v[104:107], v[140:143], v[180:183], v[104:107]
	v_mfma_f32_16x16x32_bf16 v[104:107], v[136:139], v[176:179], v[104:107]
	v_mfma_f32_16x16x32_bf16 v[76:79], v[144:147], v[176:179], v[76:79]
	v_mfma_f32_16x16x32_bf16 v[76:79], v[148:151], v[180:183], v[76:79]
	v_mfma_f32_16x16x32_bf16 v[72:75], v[156:159], v[180:183], v[72:75]
	v_mfma_f32_16x16x32_bf16 v[72:75], v[152:155], v[176:179], v[72:75]
	v_mfma_f32_16x16x32_bf16 v[64:67], v[152:155], v[198:201], v[64:67]
	v_mfma_f32_16x16x32_bf16 v[64:67], v[156:159], v[202:205], v[64:67]
	v_mfma_f32_16x16x32_bf16 v[68:71], v[148:151], v[202:205], v[68:71]
	v_mfma_f32_16x16x32_bf16 v[68:71], v[144:147], v[198:201], v[68:71]
	v_mfma_f32_16x16x32_bf16 v[96:99], v[136:139], v[198:201], v[96:99]
	v_mfma_f32_16x16x32_bf16 v[96:99], v[140:143], v[202:205], v[96:99]
	v_mfma_f32_16x16x32_bf16 v[100:103], v[132:135], v[202:205], v[100:103]
	v_mfma_f32_16x16x32_bf16 v[100:103], v[128:131], v[198:201], v[100:103]
	s_setprio 0
	s_barrier
; #define PG8_STAGE(bufoff, gbase, voff) do { _Pragma("unroll") for (int _i = 0; _i < 2; ++_i) \
;         __builtin_amdgcn_global_load_lds((const unsigned*)((const char*)(gbase) + (voff)[_i]), (PG8_LAS unsigned*)(lds + (bufoff) + ldsw + _i * 8192), 16, 0, 0); } while (0)
; #define PG8_LDA(dst, b, h) do { _Pragma("unroll") for (int m = 0; m < 4; ++m) _Pragma("unroll") for (int k = 0; k < 2; ++k) dst[m][k] = *(const PG8_LAS bf16x8*)(lds + PG8_SA(b, h) + aoff + m * 2048 + k * 1024); } while (0)
; #define PG8_MMA(ai, bj, At, Bt) do { __builtin_amdgcn_s_setprio(1); _Pragma("unroll") for (int m = 0; m < 4; ++m) _Pragma("unroll") for (int n = 0; n < 2; ++n) _Pragma("unroll") for (int k = 0; k < 2; ++k) \
;         acc[ai][bj][m][n] = __builtin_amdgcn_mfma_f32_16x16x32_bf16(Bt[n][k], At[m][k], acc[ai][bj][m][n], 0, 0, 0); __builtin_amdgcn_s_setprio(0); } while (0)
; #define PG8_WAIT_V(n) asm volatile("s_waitcnt vmcnt(" #n ")" ::: "memory")
; #define PG8_WAIT_L(n) asm volatile("s_waitcnt lgkmcnt(" #n ")" ::: "memory")
; #define PG8_BAR __builtin_amdgcn_s_barrier()
; #define PG8_SCHED __builtin_amdgcn_sched_barrier(0)
; template <class Epi, class Sched, bool ALIGN_EPI = false, bool SP2 = false, bool APERM = false  >
; __device__ __forceinline__ void gemm_phase(PG8_LAS unsigned char* lds, const Gemm g, const Sched& S, const Epi& E, const int wid  ) {
;     ...
;             PG8_LDA(At, 1, 1); PG8_STAGE(PG8_SB(1, 0), b3, voffB); PG8_STAGE(PG8_SB(1, 1), b3 + hstep, voffB); PG8_STAGE(PG8_SA(1, 0), a3, voffA);
;             PG8_WAIT_V(8); PG8_WAIT_L(0); PG8_BAR; PG8_MMA(1, 0, At, B0); PG8_MMA(1, 1, At, B1); PG8_BAR; PG8_SCHED;
	s_add_i32 s6, s12, s63
	v_lshl_add_u64 v[206:207], v[206:207], 0, s[72:73]
	s_mov_b32 m0, s6
	ds_read_b128 v[160:163], v243 offset:49152
	ds_read_b128 v[164:167], v243 offset:50176
	ds_read_b128 v[168:171], v243 offset:51200
	ds_read_b128 v[172:175], v243 offset:52224
	ds_read_b128 v[176:179], v243 offset:53248
	ds_read_b128 v[180:183], v243 offset:54272
	ds_read_b128 v[198:201], v243 offset:55296
	ds_read_b128 v[202:205], v243 offset:56320
	global_load_lds_dwordx4 v[206:207], off
	s_add_i32 m0, s6, 0x2000
	s_add_u32 s0, s0, 0x80080
	v_lshl_add_u64 v[206:207], v[208:209], 0, s[72:73]
	s_addc_u32 s1, s1, 0
	s_add_i32 s6, s13, s63
	global_load_lds_dwordx4 v[206:207], off
	v_lshl_add_u64 v[206:207], s[0:1], 0, v[184:185]
	s_mov_b32 m0, s6
	s_nop 0
	global_load_lds_dwordx4 v[206:207], off
	v_lshl_add_u64 v[206:207], s[0:1], 0, v[186:187]
	s_add_i32 m0, s6, 0x2000
	s_nop 0
	global_load_lds_dwordx4 v[206:207], off
	v_lshl_add_u64 v[206:207], v[210:211], 0, s[72:73]
	s_mov_b32 m0, s88
	s_nop 0
	global_load_lds_dwordx4 v[206:207], off
	v_lshl_add_u64 v[206:207], v[212:213], 0, s[72:73]
	s_mov_b32 m0, s89
	s_nop 0
	global_load_lds_dwordx4 v[206:207], off
	s_waitcnt vmcnt(8)
	s_waitcnt lgkmcnt(0)
	s_barrier
	s_setprio 1
	s_waitcnt lgkmcnt(0)
	v_mfma_f32_16x16x32_bf16 v[60:63], v[128:131], v[160:163], v[60:63]
	v_mfma_f32_16x16x32_bf16 v[60:63], v[132:135], v[164:167], v[60:63]
	v_mfma_f32_16x16x32_bf16 v[56:59], v[140:143], v[164:167], v[56:59]
	v_mfma_f32_16x16x32_bf16 v[56:59], v[136:139], v[160:163], v[56:59]
	v_mfma_f32_16x16x32_bf16 v[28:31], v[144:147], v[160:163], v[28:31]
	v_mfma_f32_16x16x32_bf16 v[28:31], v[148:151], v[164:167], v[28:31]
	v_mfma_f32_16x16x32_bf16 v[24:27], v[156:159], v[164:167], v[24:27]
	v_mfma_f32_16x16x32_bf16 v[24:27], v[152:155], v[160:163], v[24:27]
	v_mfma_f32_16x16x32_bf16 v[16:19], v[152:155], v[168:171], v[16:19]
	v_mfma_f32_16x16x32_bf16 v[16:19], v[156:159], v[172:175], v[16:19]
	v_mfma_f32_16x16x32_bf16 v[20:23], v[148:151], v[172:175], v[20:23]
	v_mfma_f32_16x16x32_bf16 v[20:23], v[144:147], v[168:171], v[20:23]
	v_mfma_f32_16x16x32_bf16 v[48:51], v[136:139], v[168:171], v[48:51]
	v_mfma_f32_16x16x32_bf16 v[48:51], v[140:143], v[172:175], v[48:51]
	v_mfma_f32_16x16x32_bf16 v[52:55], v[132:135], v[172:175], v[52:55]
	v_mfma_f32_16x16x32_bf16 v[52:55], v[128:131], v[168:171], v[52:55]
	v_mfma_f32_16x16x32_bf16 v[44:47], v[128:131], v[176:179], v[44:47]
	v_mfma_f32_16x16x32_bf16 v[44:47], v[132:135], v[180:183], v[44:47]
	v_mfma_f32_16x16x32_bf16 v[40:43], v[140:143], v[180:183], v[40:43]
	v_mfma_f32_16x16x32_bf16 v[40:43], v[136:139], v[176:179], v[40:43]
	v_mfma_f32_16x16x32_bf16 v[12:15], v[144:147], v[176:179], v[12:15]
	v_mfma_f32_16x16x32_bf16 v[12:15], v[148:151], v[180:183], v[12:15]
	v_mfma_f32_16x16x32_bf16 v[8:11], v[156:159], v[180:183], v[8:11]
	v_mfma_f32_16x16x32_bf16 v[8:11], v[152:155], v[176:179], v[8:11]
	v_mfma_f32_16x16x32_bf16 v[0:3], v[152:155], v[198:201], v[0:3]
	v_mfma_f32_16x16x32_bf16 v[0:3], v[156:159], v[202:205], v[0:3]
	v_mfma_f32_16x16x32_bf16 v[4:7], v[148:151], v[202:205], v[4:7]
	v_mfma_f32_16x16x32_bf16 v[4:7], v[144:147], v[198:201], v[4:7]
	v_mfma_f32_16x16x32_bf16 v[32:35], v[136:139], v[198:201], v[32:35]
	v_mfma_f32_16x16x32_bf16 v[32:35], v[140:143], v[202:205], v[32:35]
	v_mfma_f32_16x16x32_bf16 v[36:39], v[132:135], v[202:205], v[36:39]
	v_mfma_f32_16x16x32_bf16 v[36:39], v[128:131], v[198:201], v[36:39]
	s_setprio 0
	s_barrier
	s_add_i32 s0, s47, 2
	s_cmp_gt_u32 s47, 29
	s_cbranch_scc1 .LBB0_392
	s_mov_b32 s47, s0
	s_branch .LBB0_368

; #define PG8_STAGE(bufoff, gbase, voff) do { _Pragma("unroll") for (int _i = 0; _i < 2; ++_i) \
;         __builtin_amdgcn_global_load_lds((const unsigned*)((const char*)(gbase) + (voff)[_i]), (PG8_LAS unsigned*)(lds + (bufoff) + ldsw + _i * 8192), 16, 0, 0); } while (0)
; #define PG8_LDA(dst, b, h) do { _Pragma("unroll") for (int m = 0; m < 4; ++m) _Pragma("unroll") for (int k = 0; k < 2; ++k) dst[m][k] = *(const PG8_LAS bf16x8*)(lds + PG8_SA(b, h) + aoff + m * 2048 + k * 1024); } while (0)
; #define PG8_LDB(dst, b, h) do { _Pragma("unroll") for (int n = 0; n < 2; ++n) _Pragma("unroll") for (int k = 0; k < 2; ++k) dst[n][k] = *(const PG8_LAS bf16x8*)(lds + PG8_SB(b, h) + boff + n * 2048 + k * 1024); } while (0)
; #define PG8_MMA(ai, bj, At, Bt) do { __builtin_amdgcn_s_setprio(1); _Pragma("unroll") for (int m = 0; m < 4; ++m) _Pragma("unroll") for (int n = 0; n < 2; ++n) _Pragma("unroll") for (int k = 0; k < 2; ++k) \
;         acc[ai][bj][m][n] = __builtin_amdgcn_mfma_f32_16x16x32_bf16(Bt[n][k], At[m][k], acc[ai][bj][m][n], 0, 0, 0); __builtin_amdgcn_s_setprio(0); } while (0)
; #define PG8_WAIT_V(n) asm volatile("s_waitcnt vmcnt(" #n ")" ::: "memory")
; #define PG8_WAIT_L(n) asm volatile("s_waitcnt lgkmcnt(" #n ")" ::: "memory")
; #define PG8_BAR __builtin_amdgcn_s_barrier()
; #define PG8_SCHED __builtin_amdgcn_sched_barrier(0)
; template <class Epi, class Sched, bool ALIGN_EPI = false, bool SP2 = false, bool APERM = false  >
; __device__ __forceinline__ void gemm_phase(PG8_LAS unsigned char* lds, const Gemm g, const Sched& S, const Epi& E, const int wid  ) {
;     ...
;             const bool last = (t == nt - 2);
;             const char* a1 = cA + (size_t)(t + 1) * kstep;
;             const char* a2 = last ? nA : cA + (size_t)(t + 2) * kstep; const char* b2 = last ? nB : cB + (size_t)(t + 2) * kstep;
;             const char* a3 = a2 + kstep; const char* b3 = b2 + kstep;
;             if (last && has_next) S.a_ready(nxt);
;             if constexpr (SP2) {
;             PG8_LDB(B0, 0, 0); PG8_LDB(B1, 0, 1); PG8_SCHED; PG8_LDA(At, 0, 0); PG8_STAGE(PG8_SA(1, 1), a1 + hstep, voffA);
;             PG8_WAIT_V(8); PG8_WAIT_L(0); PG8_BAR; PG8_MMA(0, 0, At, B0); PG8_MMA(0, 1, At, B1); PG8_BAR; PG8_SCHED;
;             PG8_LDA(At, 0, 1); PG8_STAGE(PG8_SB(0, 0), b2, voffB); PG8_STAGE(PG8_SB(0, 1), b2 + hstep, voffB); PG8_STAGE(PG8_SA(0, 0), a2, voffA);
.LBB0_543:
	s_lshl_b32 s11, s10, 7
	s_add_u32 s46, s0, s11
	s_addc_u32 s47, s1, 0
	v_add_u32_e32 v146, s33, v150
	s_add_u32 s96, s46, 0x100
	s_waitcnt lgkmcnt(0)
	ds_read_b128 v[142:145], v146
	ds_read_b128 v[154:157], v146 offset:1024
	ds_read_b128 v[158:161], v146 offset:2048
	ds_read_b128 v[162:165], v146 offset:3072
	v_add_u32_e32 v146, s64, v150
	s_addc_u32 s97, s47, 0
	ds_read_b128 v[166:169], v146
	ds_read_b128 v[170:173], v146 offset:1024
	ds_read_b128 v[174:177], v146 offset:2048
	ds_read_b128 v[178:181], v146 offset:3072
	s_and_b64 s[8:9], s[94:95], exec
	s_cselect_b32 s97, s89, s97
	s_cselect_b32 s96, s88, s96
	s_add_u32 s8, s12, s11
	s_addc_u32 s9, s13, 0
	s_add_u32 s11, s8, 0x100
	s_addc_u32 vcc_lo, s9, 0
	s_and_b64 s[8:9], s[94:95], exec
	s_cselect_b32 s95, s91, vcc_lo
	s_cselect_b32 s94, s90, s11
	s_add_u32 s8, s46, 0x160080
	s_addc_u32 s9, s47, 0
	v_lshl_add_u64 v[146:147], s[8:9], 0, v[132:133]
	s_add_i32 m0, s76, 0xc000
	ds_read_b128 v[182:185], v153
	ds_read_b128 v[186:189], v153 offset:1024
	ds_read_b128 v[190:193], v153 offset:2048
	ds_read_b128 v[194:197], v153 offset:3072
	ds_read_b128 v[198:201], v153 offset:4096
	ds_read_b128 v[202:205], v153 offset:5120
	ds_read_b128 v[206:209], v153 offset:6144
	ds_read_b128 v[210:213], v153 offset:7168
	global_load_lds_dwordx4 v[146:147], off
	v_lshl_add_u64 v[146:147], s[8:9], 0, v[134:135]
	s_add_i32 m0, s76, 0xe000
	s_nop 0
	global_load_lds_dwordx4 v[146:147], off
	s_waitcnt vmcnt(8)
	s_waitcnt lgkmcnt(0)
	s_barrier
	s_setprio 1
	s_waitcnt lgkmcnt(0)
	v_mfma_f32_16x16x32_bf16 v[124:127], v[142:145], v[182:185], v[124:127]
	v_mfma_f32_16x16x32_bf16 v[124:127], v[154:157], v[186:189], v[124:127]
	v_mfma_f32_16x16x32_bf16 v[120:123], v[162:165], v[186:189], v[120:123]
	v_mfma_f32_16x16x32_bf16 v[120:123], v[158:161], v[182:185], v[120:123]
	v_mfma_f32_16x16x32_bf16 v[92:95], v[166:169], v[182:185], v[92:95]
	v_mfma_f32_16x16x32_bf16 v[92:95], v[170:173], v[186:189], v[92:95]
	v_mfma_f32_16x16x32_bf16 v[88:91], v[178:181], v[186:189], v[88:91]
	v_mfma_f32_16x16x32_bf16 v[88:91], v[174:177], v[182:185], v[88:91]
	v_mfma_f32_16x16x32_bf16 v[80:83], v[174:177], v[190:193], v[80:83]
	v_mfma_f32_16x16x32_bf16 v[80:83], v[178:181], v[194:197], v[80:83]
	v_mfma_f32_16x16x32_bf16 v[84:87], v[170:173], v[194:197], v[84:87]
	v_mfma_f32_16x16x32_bf16 v[84:87], v[166:169], v[190:193], v[84:87]
	v_mfma_f32_16x16x32_bf16 v[112:115], v[158:161], v[190:193], v[112:115]
	v_mfma_f32_16x16x32_bf16 v[112:115], v[162:165], v[194:197], v[112:115]
	v_mfma_f32_16x16x32_bf16 v[116:119], v[154:157], v[194:197], v[116:119]
	v_mfma_f32_16x16x32_bf16 v[116:119], v[142:145], v[190:193], v[116:119]
	v_mfma_f32_16x16x32_bf16 v[108:111], v[142:145], v[198:201], v[108:111]
	v_mfma_f32_16x16x32_bf16 v[108:111], v[154:157], v[202:205], v[108:111]
	v_mfma_f32_16x16x32_bf16 v[104:107], v[162:165], v[202:205], v[104:107]
	v_mfma_f32_16x16x32_bf16 v[104:107], v[158:161], v[198:201], v[104:107]
	v_mfma_f32_16x16x32_bf16 v[76:79], v[166:169], v[198:201], v[76:79]
	v_mfma_f32_16x16x32_bf16 v[76:79], v[170:173], v[202:205], v[76:79]
	v_mfma_f32_16x16x32_bf16 v[72:75], v[178:181], v[202:205], v[72:75]
	v_mfma_f32_16x16x32_bf16 v[72:75], v[174:177], v[198:201], v[72:75]
	v_mfma_f32_16x16x32_bf16 v[64:67], v[174:177], v[206:209], v[64:67]
	v_mfma_f32_16x16x32_bf16 v[64:67], v[178:181], v[210:213], v[64:67]
	v_mfma_f32_16x16x32_bf16 v[68:71], v[170:173], v[210:213], v[68:71]
	v_mfma_f32_16x16x32_bf16 v[68:71], v[166:169], v[206:209], v[68:71]
	v_mfma_f32_16x16x32_bf16 v[96:99], v[158:161], v[206:209], v[96:99]
	v_mfma_f32_16x16x32_bf16 v[96:99], v[162:165], v[210:213], v[96:99]
	v_mfma_f32_16x16x32_bf16 v[100:103], v[154:157], v[210:213], v[100:103]
	v_mfma_f32_16x16x32_bf16 v[100:103], v[142:145], v[206:209], v[100:103]
	s_setprio 0
	s_barrier
	s_add_i32 s8, s33, s16
	v_lshl_add_u64 v[146:147], s[94:95], 0, v[128:129]
	s_mov_b32 m0, s8
	ds_read_b128 v[182:185], v153 offset:16384
	ds_read_b128 v[186:189], v153 offset:17408
	ds_read_b128 v[190:193], v153 offset:18432
	ds_read_b128 v[194:197], v153 offset:19456
	ds_read_b128 v[198:201], v153 offset:20480
	ds_read_b128 v[202:205], v153 offset:21504
	ds_read_b128 v[206:209], v153 offset:22528
	ds_read_b128 v[210:213], v153 offset:23552
	global_load_lds_dwordx4 v[146:147], off
	s_add_i32 m0, s8, 0x2000
	s_add_u32 s8, s94, 0x160000
	v_lshl_add_u64 v[214:215], s[94:95], 0, v[130:131]
	s_addc_u32 s9, s95, 0
	s_add_i32 s11, s64, s16
	global_load_lds_dwordx4 v[214:215], off
	v_lshl_add_u64 v[216:217], s[8:9], 0, v[128:129]
	s_mov_b32 m0, s11
	v_lshl_add_u64 v[218:219], s[96:97], 0, v[134:135]
	global_load_lds_dwordx4 v[216:217], off
	v_lshl_add_u64 v[216:217], s[8:9], 0, v[130:131]
	s_add_i32 m0, s11, 0x2000
	s_nop 0
	global_load_lds_dwordx4 v[216:217], off
	v_lshl_add_u64 v[216:217], s[96:97], 0, v[132:133]
	s_mov_b32 m0, s76
	s_nop 0
	global_load_lds_dwordx4 v[216:217], off
	s_mov_b32 m0, s77
	s_nop 0
	global_load_lds_dwordx4 v[218:219], off
	s_waitcnt vmcnt(8)
	s_waitcnt lgkmcnt(0)
	s_barrier
; #define PG8_STAGE(bufoff, gbase, voff) do { _Pragma("unroll") for (int _i = 0; _i < 2; ++_i) \
;         __builtin_amdgcn_global_load_lds((const unsigned*)((const char*)(gbase) + (voff)[_i]), (PG8_LAS unsigned*)(lds + (bufoff) + ldsw + _i * 8192), 16, 0, 0); } while (0)
; #define PG8_LDA(dst, b, h) do { _Pragma("unroll") for (int m = 0; m < 4; ++m) _Pragma("unroll") for (int k = 0; k < 2; ++k) dst[m][k] = *(const PG8_LAS bf16x8*)(lds + PG8_SA(b, h) + aoff + m * 2048 + k * 1024); } while (0)
; #define PG8_LDB(dst, b, h) do { _Pragma("unroll") for (int n = 0; n < 2; ++n) _Pragma("unroll") for (int k = 0; k < 2; ++k) dst[n][k] = *(const PG8_LAS bf16x8*)(lds + PG8_SB(b, h) + boff + n * 2048 + k * 1024); } while (0)
; #define PG8_MMA(ai, bj, At, Bt) do { __builtin_amdgcn_s_setprio(1); _Pragma("unroll") for (int m = 0; m < 4; ++m) _Pragma("unroll") for (int n = 0; n < 2; ++n) _Pragma("unroll") for (int k = 0; k < 2; ++k) \
;         acc[ai][bj][m][n] = __builtin_amdgcn_mfma_f32_16x16x32_bf16(Bt[n][k], At[m][k], acc[ai][bj][m][n], 0, 0, 0); __builtin_amdgcn_s_setprio(0); } while (0)
; #define PG8_WAIT_V(n) asm volatile("s_waitcnt vmcnt(" #n ")" ::: "memory")
; #define PG8_WAIT_L(n) asm volatile("s_waitcnt lgkmcnt(" #n ")" ::: "memory")
; #define PG8_BAR __builtin_amdgcn_s_barrier()
; #define PG8_SCHED __builtin_amdgcn_sched_barrier(0)
; template <class Epi, class Sched, bool ALIGN_EPI = false, bool SP2 = false, bool APERM = false  >
; __device__ __forceinline__ void gemm_phase(PG8_LAS unsigned char* lds, const Gemm g, const Sched& S, const Epi& E, const int wid  ) {
;     ...
;             PG8_WAIT_V(8); PG8_WAIT_L(0); PG8_BAR; PG8_MMA(1, 0, At, B0); PG8_MMA(1, 1, At, B1); PG8_BAR; PG8_SCHED;
;             PG8_LDB(B0, 1, 0); PG8_LDB(B1, 1, 1); PG8_SCHED; PG8_LDA(At, 1, 0); PG8_STAGE(PG8_SA(0, 1), a2 + hstep, voffA);
;             PG8_WAIT_V(8); PG8_WAIT_L(0); PG8_BAR; PG8_MMA(0, 0, At, B0); PG8_MMA(0, 1, At, B1); PG8_BAR; PG8_SCHED;
	s_setprio 1
	s_waitcnt lgkmcnt(0)
	v_mfma_f32_16x16x32_bf16 v[60:63], v[142:145], v[182:185], v[60:63]
	v_mfma_f32_16x16x32_bf16 v[60:63], v[154:157], v[186:189], v[60:63]
	v_mfma_f32_16x16x32_bf16 v[56:59], v[162:165], v[186:189], v[56:59]
	v_mfma_f32_16x16x32_bf16 v[56:59], v[158:161], v[182:185], v[56:59]
	v_mfma_f32_16x16x32_bf16 v[28:31], v[166:169], v[182:185], v[28:31]
	v_mfma_f32_16x16x32_bf16 v[28:31], v[170:173], v[186:189], v[28:31]
	v_mfma_f32_16x16x32_bf16 v[24:27], v[178:181], v[186:189], v[24:27]
	v_mfma_f32_16x16x32_bf16 v[24:27], v[174:177], v[182:185], v[24:27]
	v_mfma_f32_16x16x32_bf16 v[16:19], v[174:177], v[190:193], v[16:19]
	v_mfma_f32_16x16x32_bf16 v[16:19], v[178:181], v[194:197], v[16:19]
	v_mfma_f32_16x16x32_bf16 v[20:23], v[170:173], v[194:197], v[20:23]
	v_mfma_f32_16x16x32_bf16 v[20:23], v[166:169], v[190:193], v[20:23]
	v_mfma_f32_16x16x32_bf16 v[48:51], v[158:161], v[190:193], v[48:51]
	v_mfma_f32_16x16x32_bf16 v[48:51], v[162:165], v[194:197], v[48:51]
	v_mfma_f32_16x16x32_bf16 v[52:55], v[154:157], v[194:197], v[52:55]
	v_mfma_f32_16x16x32_bf16 v[52:55], v[142:145], v[190:193], v[52:55]
	v_mfma_f32_16x16x32_bf16 v[44:47], v[142:145], v[198:201], v[44:47]
	v_mfma_f32_16x16x32_bf16 v[44:47], v[154:157], v[202:205], v[44:47]
	v_mfma_f32_16x16x32_bf16 v[40:43], v[162:165], v[202:205], v[40:43]
	v_mfma_f32_16x16x32_bf16 v[40:43], v[158:161], v[198:201], v[40:43]
	v_mfma_f32_16x16x32_bf16 v[12:15], v[166:169], v[198:201], v[12:15]
	v_mfma_f32_16x16x32_bf16 v[12:15], v[170:173], v[202:205], v[12:15]
	v_mfma_f32_16x16x32_bf16 v[8:11], v[178:181], v[202:205], v[8:11]
	v_mfma_f32_16x16x32_bf16 v[8:11], v[174:177], v[198:201], v[8:11]
	v_mfma_f32_16x16x32_bf16 v[0:3], v[174:177], v[206:209], v[0:3]
	v_mfma_f32_16x16x32_bf16 v[0:3], v[178:181], v[210:213], v[0:3]
	v_mfma_f32_16x16x32_bf16 v[4:7], v[170:173], v[210:213], v[4:7]
	v_mfma_f32_16x16x32_bf16 v[4:7], v[166:169], v[206:209], v[4:7]
	v_mfma_f32_16x16x32_bf16 v[32:35], v[158:161], v[206:209], v[32:35]
	v_mfma_f32_16x16x32_bf16 v[32:35], v[162:165], v[210:213], v[32:35]
	v_mfma_f32_16x16x32_bf16 v[36:39], v[154:157], v[210:213], v[36:39]
	v_mfma_f32_16x16x32_bf16 v[36:39], v[142:145], v[206:209], v[36:39]
	s_setprio 0
	s_barrier
	s_add_i32 s11, 0, 0x18000
	s_add_i32 s46, 0, 0x1c000
	v_add_u32_e32 v162, s11, v150
	v_add_u32_e32 v178, s46, v150
	ds_read_b128 v[142:145], v162
	ds_read_b128 v[154:157], v162 offset:1024
	ds_read_b128 v[158:161], v162 offset:2048
	ds_read_b128 v[162:165], v162 offset:3072
	ds_read_b128 v[166:169], v178
	ds_read_b128 v[170:173], v178 offset:1024
	ds_read_b128 v[174:177], v178 offset:2048
	ds_read_b128 v[178:181], v178 offset:3072
	s_add_u32 s8, s96, 0x160000
	s_addc_u32 s9, s97, 0
	s_mov_b32 m0, s74
	v_lshl_add_u64 v[220:221], s[8:9], 0, v[132:133]
	ds_read_b128 v[182:185], v153 offset:32768
	ds_read_b128 v[186:189], v153 offset:33792
	ds_read_b128 v[190:193], v153 offset:34816
	ds_read_b128 v[194:197], v153 offset:35840
	ds_read_b128 v[198:201], v153 offset:36864
	ds_read_b128 v[202:205], v153 offset:37888
	ds_read_b128 v[206:209], v153 offset:38912
	ds_read_b128 v[210:213], v153 offset:39936
	global_load_lds_dwordx4 v[220:221], off
	v_lshl_add_u64 v[220:221], s[8:9], 0, v[134:135]
	s_mov_b32 m0, s78
	s_nop 0
	global_load_lds_dwordx4 v[220:221], off
	s_waitcnt vmcnt(8)
	s_waitcnt lgkmcnt(0)
	s_barrier
	s_setprio 1
	s_waitcnt lgkmcnt(0)
	v_mfma_f32_16x16x32_bf16 v[124:127], v[142:145], v[182:185], v[124:127]
	v_mfma_f32_16x16x32_bf16 v[124:127], v[154:157], v[186:189], v[124:127]
	v_mfma_f32_16x16x32_bf16 v[120:123], v[162:165], v[186:189], v[120:123]
	v_mfma_f32_16x16x32_bf16 v[120:123], v[158:161], v[182:185], v[120:123]
	v_mfma_f32_16x16x32_bf16 v[92:95], v[166:169], v[182:185], v[92:95]
	v_mfma_f32_16x16x32_bf16 v[92:95], v[170:173], v[186:189], v[92:95]
	v_mfma_f32_16x16x32_bf16 v[88:91], v[178:181], v[186:189], v[88:91]
	v_mfma_f32_16x16x32_bf16 v[88:91], v[174:177], v[182:185], v[88:91]
	v_mfma_f32_16x16x32_bf16 v[80:83], v[174:177], v[190:193], v[80:83]
	v_mfma_f32_16x16x32_bf16 v[80:83], v[178:181], v[194:197], v[80:83]
	v_mfma_f32_16x16x32_bf16 v[84:87], v[170:173], v[194:197], v[84:87]
	v_mfma_f32_16x16x32_bf16 v[84:87], v[166:169], v[190:193], v[84:87]
	v_mfma_f32_16x16x32_bf16 v[112:115], v[158:161], v[190:193], v[112:115]
	v_mfma_f32_16x16x32_bf16 v[112:115], v[162:165], v[194:197], v[112:115]
	v_mfma_f32_16x16x32_bf16 v[116:119], v[154:157], v[194:197], v[116:119]
	v_mfma_f32_16x16x32_bf16 v[116:119], v[142:145], v[190:193], v[116:119]
	v_mfma_f32_16x16x32_bf16 v[108:111], v[142:145], v[198:201], v[108:111]
	v_mfma_f32_16x16x32_bf16 v[108:111], v[154:157], v[202:205], v[108:111]
	v_mfma_f32_16x16x32_bf16 v[104:107], v[162:165], v[202:205], v[104:107]
	v_mfma_f32_16x16x32_bf16 v[104:107], v[158:161], v[198:201], v[104:107]
	v_mfma_f32_16x16x32_bf16 v[76:79], v[166:169], v[198:201], v[76:79]
	v_mfma_f32_16x16x32_bf16 v[76:79], v[170:173], v[202:205], v[76:79]
	v_mfma_f32_16x16x32_bf16 v[72:75], v[178:181], v[202:205], v[72:75]
	v_mfma_f32_16x16x32_bf16 v[72:75], v[174:177], v[198:201], v[72:75]
	v_mfma_f32_16x16x32_bf16 v[64:67], v[174:177], v[206:209], v[64:67]
	v_mfma_f32_16x16x32_bf16 v[64:67], v[178:181], v[210:213], v[64:67]
	v_mfma_f32_16x16x32_bf16 v[68:71], v[170:173], v[210:213], v[68:71]
	v_mfma_f32_16x16x32_bf16 v[68:71], v[166:169], v[206:209], v[68:71]
	v_mfma_f32_16x16x32_bf16 v[96:99], v[158:161], v[206:209], v[96:99]
	v_mfma_f32_16x16x32_bf16 v[96:99], v[162:165], v[210:213], v[96:99]
	v_mfma_f32_16x16x32_bf16 v[100:103], v[154:157], v[210:213], v[100:103]
	v_mfma_f32_16x16x32_bf16 v[100:103], v[142:145], v[206:209], v[100:103]
	s_setprio 0
	s_barrier
; #define PG8_STAGE(bufoff, gbase, voff) do { _Pragma("unroll") for (int _i = 0; _i < 2; ++_i) \
;         __builtin_amdgcn_global_load_lds((const unsigned*)((const char*)(gbase) + (voff)[_i]), (PG8_LAS unsigned*)(lds + (bufoff) + ldsw + _i * 8192), 16, 0, 0); } while (0)
; #define PG8_LDA(dst, b, h) do { _Pragma("unroll") for (int m = 0; m < 4; ++m) _Pragma("unroll") for (int k = 0; k < 2; ++k) dst[m][k] = *(const PG8_LAS bf16x8*)(lds + PG8_SA(b, h) + aoff + m * 2048 + k * 1024); } while (0)
; #define PG8_MMA(ai, bj, At, Bt) do { __builtin_amdgcn_s_setprio(1); _Pragma("unroll") for (int m = 0; m < 4; ++m) _Pragma("unroll") for (int n = 0; n < 2; ++n) _Pragma("unroll") for (int k = 0; k < 2; ++k) \
;         acc[ai][bj][m][n] = __builtin_amdgcn_mfma_f32_16x16x32_bf16(Bt[n][k], At[m][k], acc[ai][bj][m][n], 0, 0, 0); __builtin_amdgcn_s_setprio(0); } while (0)
; #define PG8_WAIT_V(n) asm volatile("s_waitcnt vmcnt(" #n ")" ::: "memory")
; #define PG8_WAIT_L(n) asm volatile("s_waitcnt lgkmcnt(" #n ")" ::: "memory")
; #define PG8_BAR __builtin_amdgcn_s_barrier()
; #define PG8_SCHED __builtin_amdgcn_sched_barrier(0)
; template <class Epi, class Sched, bool ALIGN_EPI = false, bool SP2 = false, bool APERM = false  >
; __device__ __forceinline__ void gemm_phase(PG8_LAS unsigned char* lds, const Gemm g, const Sched& S, const Epi& E, const int wid  ) {
;     ...
;             PG8_LDA(At, 1, 1); PG8_STAGE(PG8_SB(1, 0), b3, voffB); PG8_STAGE(PG8_SB(1, 1), b3 + hstep, voffB); PG8_STAGE(PG8_SA(1, 0), a3, voffA);
;             PG8_WAIT_V(8); PG8_WAIT_L(0); PG8_BAR; PG8_MMA(1, 0, At, B0); PG8_MMA(1, 1, At, B1); PG8_BAR; PG8_SCHED;
	s_add_i32 s8, s11, s16
	v_lshl_add_u64 v[146:147], v[146:147], 0, s[24:25]
	s_mov_b32 m0, s8
	ds_read_b128 v[182:185], v153 offset:49152
	ds_read_b128 v[186:189], v153 offset:50176
	ds_read_b128 v[190:193], v153 offset:51200
	ds_read_b128 v[194:197], v153 offset:52224
	ds_read_b128 v[198:201], v153 offset:53248
	ds_read_b128 v[202:205], v153 offset:54272
	ds_read_b128 v[206:209], v153 offset:55296
	ds_read_b128 v[210:213], v153 offset:56320
	global_load_lds_dwordx4 v[146:147], off
	s_add_i32 m0, s8, 0x2000
	s_add_u32 s8, s94, 0x160080
	v_lshl_add_u64 v[146:147], v[214:215], 0, s[24:25]
	s_addc_u32 s9, s95, 0
	s_add_i32 s11, s46, s16
	global_load_lds_dwordx4 v[146:147], off
	v_lshl_add_u64 v[146:147], s[8:9], 0, v[128:129]
	s_mov_b32 m0, s11
	s_nop 0
	global_load_lds_dwordx4 v[146:147], off
	v_lshl_add_u64 v[146:147], s[8:9], 0, v[130:131]
	s_add_i32 m0, s11, 0x2000
	s_nop 0
	global_load_lds_dwordx4 v[146:147], off
	v_lshl_add_u64 v[146:147], v[216:217], 0, s[24:25]
	s_mov_b32 m0, s79
	s_nop 0
	global_load_lds_dwordx4 v[146:147], off
	v_lshl_add_u64 v[146:147], v[218:219], 0, s[24:25]
	s_mov_b32 m0, s75
	s_nop 0
	global_load_lds_dwordx4 v[146:147], off
	s_waitcnt vmcnt(8)
	s_waitcnt lgkmcnt(0)
	s_barrier
	s_setprio 1
	s_waitcnt lgkmcnt(0)
	v_mfma_f32_16x16x32_bf16 v[60:63], v[142:145], v[182:185], v[60:63]
	v_mfma_f32_16x16x32_bf16 v[60:63], v[154:157], v[186:189], v[60:63]
	v_mfma_f32_16x16x32_bf16 v[56:59], v[162:165], v[186:189], v[56:59]
	v_mfma_f32_16x16x32_bf16 v[56:59], v[158:161], v[182:185], v[56:59]
	v_mfma_f32_16x16x32_bf16 v[28:31], v[166:169], v[182:185], v[28:31]
	v_mfma_f32_16x16x32_bf16 v[28:31], v[170:173], v[186:189], v[28:31]
	v_mfma_f32_16x16x32_bf16 v[24:27], v[178:181], v[186:189], v[24:27]
	v_mfma_f32_16x16x32_bf16 v[24:27], v[174:177], v[182:185], v[24:27]
	v_mfma_f32_16x16x32_bf16 v[16:19], v[174:177], v[190:193], v[16:19]
	v_mfma_f32_16x16x32_bf16 v[16:19], v[178:181], v[194:197], v[16:19]
	v_mfma_f32_16x16x32_bf16 v[20:23], v[170:173], v[194:197], v[20:23]
	v_mfma_f32_16x16x32_bf16 v[20:23], v[166:169], v[190:193], v[20:23]
	v_mfma_f32_16x16x32_bf16 v[48:51], v[158:161], v[190:193], v[48:51]
	v_mfma_f32_16x16x32_bf16 v[48:51], v[162:165], v[194:197], v[48:51]
	v_mfma_f32_16x16x32_bf16 v[52:55], v[154:157], v[194:197], v[52:55]
	v_mfma_f32_16x16x32_bf16 v[52:55], v[142:145], v[190:193], v[52:55]
	v_mfma_f32_16x16x32_bf16 v[44:47], v[142:145], v[198:201], v[44:47]
	v_mfma_f32_16x16x32_bf16 v[44:47], v[154:157], v[202:205], v[44:47]
	v_mfma_f32_16x16x32_bf16 v[40:43], v[162:165], v[202:205], v[40:43]
	v_mfma_f32_16x16x32_bf16 v[40:43], v[158:161], v[198:201], v[40:43]
	v_mfma_f32_16x16x32_bf16 v[12:15], v[166:169], v[198:201], v[12:15]
	v_mfma_f32_16x16x32_bf16 v[12:15], v[170:173], v[202:205], v[12:15]
	v_mfma_f32_16x16x32_bf16 v[8:11], v[178:181], v[202:205], v[8:11]
	v_mfma_f32_16x16x32_bf16 v[8:11], v[174:177], v[198:201], v[8:11]
	v_mfma_f32_16x16x32_bf16 v[0:3], v[174:177], v[206:209], v[0:3]
	v_mfma_f32_16x16x32_bf16 v[0:3], v[178:181], v[210:213], v[0:3]
	v_mfma_f32_16x16x32_bf16 v[4:7], v[170:173], v[210:213], v[4:7]
	v_mfma_f32_16x16x32_bf16 v[4:7], v[166:169], v[206:209], v[4:7]
	v_mfma_f32_16x16x32_bf16 v[32:35], v[158:161], v[206:209], v[32:35]
	v_mfma_f32_16x16x32_bf16 v[32:35], v[162:165], v[210:213], v[32:35]
	v_mfma_f32_16x16x32_bf16 v[36:39], v[154:157], v[210:213], v[36:39]
	v_mfma_f32_16x16x32_bf16 v[36:39], v[142:145], v[206:209], v[36:39]
	s_setprio 0
	s_barrier
	s_add_i32 s8, s10, 2
	s_cmp_gt_u32 s10, 41
	s_cbranch_scc1 .LBB0_545
	s_mov_b32 s10, s8
	s_branch .LBB0_526

; #define PG8_STAGE(bufoff, gbase, voff) do { _Pragma("unroll") for (int _i = 0; _i < 2; ++_i) \
;         __builtin_amdgcn_global_load_lds((const unsigned*)((const char*)(gbase) + (voff)[_i]), (PG8_LAS unsigned*)(lds + (bufoff) + ldsw + _i * 8192), 16, 0, 0); } while (0)
; #define PG8_LDA(dst, b, h) do { _Pragma("unroll") for (int m = 0; m < 4; ++m) _Pragma("unroll") for (int k = 0; k < 2; ++k) dst[m][k] = *(const PG8_LAS bf16x8*)(lds + PG8_SA(b, h) + aoff + m * 2048 + k * 1024); } while (0)
; #define PG8_LDB(dst, b, h) do { _Pragma("unroll") for (int n = 0; n < 2; ++n) _Pragma("unroll") for (int k = 0; k < 2; ++k) dst[n][k] = *(const PG8_LAS bf16x8*)(lds + PG8_SB(b, h) + boff + n * 2048 + k * 1024); } while (0)
; #define PG8_MMA(ai, bj, At, Bt) do { __builtin_amdgcn_s_setprio(1); _Pragma("unroll") for (int m = 0; m < 4; ++m) _Pragma("unroll") for (int n = 0; n < 2; ++n) _Pragma("unroll") for (int k = 0; k < 2; ++k) \
;         acc[ai][bj][m][n] = __builtin_amdgcn_mfma_f32_16x16x32_bf16(Bt[n][k], At[m][k], acc[ai][bj][m][n], 0, 0, 0); __builtin_amdgcn_s_setprio(0); } while (0)
; #define PG8_WAIT_V(n) asm volatile("s_waitcnt vmcnt(" #n ")" ::: "memory")
; #define PG8_WAIT_L(n) asm volatile("s_waitcnt lgkmcnt(" #n ")" ::: "memory")
; #define PG8_BAR __builtin_amdgcn_s_barrier()
; #define PG8_SCHED __builtin_amdgcn_sched_barrier(0)
; template <class Epi, class Sched, bool ALIGN_EPI = false, bool SP2 = false, bool APERM = false  >
; __device__ __forceinline__ void gemm_phase(PG8_LAS unsigned char* lds, const Gemm g, const Sched& S, const Epi& E, const int wid  ) {
;     ...
;             const bool last = (t == nt - 2);
;             const char* a1 = cA + (size_t)(t + 1) * kstep;
;             const char* a2 = last ? nA : cA + (size_t)(t + 2) * kstep; const char* b2 = last ? nB : cB + (size_t)(t + 2) * kstep;
;             const char* a3 = a2 + kstep; const char* b3 = b2 + kstep;
;             if (last && has_next) S.a_ready(nxt);
;             if constexpr (SP2) {
;             PG8_LDB(B0, 0, 0); PG8_LDB(B1, 0, 1); PG8_SCHED; PG8_LDA(At, 0, 0); PG8_STAGE(PG8_SA(1, 1), a1 + hstep, voffA);
;             PG8_WAIT_V(8); PG8_WAIT_L(0); PG8_BAR; PG8_MMA(0, 0, At, B0); PG8_MMA(0, 1, At, B1); PG8_BAR; PG8_SCHED;
;             PG8_LDA(At, 0, 1); PG8_STAGE(PG8_SB(0, 0), b2, voffB); PG8_STAGE(PG8_SB(0, 1), b2 + hstep, voffB); PG8_STAGE(PG8_SA(0, 0), a2, voffA);
.LBB0_605:
	s_or_b32 s56, s65, 1
	v_add_u32_e32 v159, s88, v153
	s_lshl_b64 s[10:11], s[56:57], 7
	s_add_i32 s56, s65, 2
	s_waitcnt lgkmcnt(0)
	ds_read_b128 v[144:147], v159
	ds_read_b128 v[148:151], v159 offset:1024
	ds_read_b128 v[160:163], v159 offset:2048
	ds_read_b128 v[164:167], v159 offset:3072
	v_add_u32_e32 v159, s89, v153
	s_lshl_b64 s[46:47], s[56:57], 7
	ds_read_b128 v[168:171], v159
	ds_read_b128 v[172:175], v159 offset:1024
	ds_read_b128 v[176:179], v159 offset:2048
	ds_read_b128 v[180:183], v159 offset:3072
	s_add_u32 s68, s0, s46
	s_addc_u32 s69, s1, s47
	s_and_b64 s[52:53], s[30:31], exec
	s_cselect_b32 vcc_hi, s25, s69
	s_cselect_b32 vcc_lo, s24, s68
	s_add_u32 s46, s12, s46
	s_addc_u32 s47, s13, s47
	s_and_b64 s[30:31], s[30:31], exec
	s_cselect_b32 s31, s29, s47
	s_cselect_b32 s30, s28, s46
	s_add_u32 s10, s33, s10
	s_addc_u32 s11, s64, s11
	v_lshl_add_u64 v[216:217], s[10:11], 0, v[132:133]
	s_add_i32 m0, s70, 0xc000
	ds_read_b128 v[184:187], v158
	ds_read_b128 v[188:191], v158 offset:1024
	ds_read_b128 v[192:195], v158 offset:2048
	ds_read_b128 v[196:199], v158 offset:3072
	ds_read_b128 v[200:203], v158 offset:4096
	ds_read_b128 v[204:207], v158 offset:5120
	ds_read_b128 v[208:211], v158 offset:6144
	ds_read_b128 v[212:215], v158 offset:7168
	global_load_lds_dwordx4 v[216:217], off
	v_lshl_add_u64 v[216:217], s[10:11], 0, v[136:137]
	s_add_i32 m0, s70, 0xe000
	s_nop 0
	global_load_lds_dwordx4 v[216:217], off
	s_waitcnt vmcnt(8)
	s_waitcnt lgkmcnt(0)
	s_barrier
	s_setprio 1
	s_waitcnt lgkmcnt(0)
	v_mfma_f32_16x16x32_bf16 v[124:127], v[144:147], v[184:187], v[124:127]
	v_mfma_f32_16x16x32_bf16 v[124:127], v[148:151], v[188:191], v[124:127]
	v_mfma_f32_16x16x32_bf16 v[120:123], v[164:167], v[188:191], v[120:123]
	v_mfma_f32_16x16x32_bf16 v[120:123], v[160:163], v[184:187], v[120:123]
	v_mfma_f32_16x16x32_bf16 v[92:95], v[168:171], v[184:187], v[92:95]
	v_mfma_f32_16x16x32_bf16 v[92:95], v[172:175], v[188:191], v[92:95]
	v_mfma_f32_16x16x32_bf16 v[88:91], v[180:183], v[188:191], v[88:91]
	v_mfma_f32_16x16x32_bf16 v[88:91], v[176:179], v[184:187], v[88:91]
	v_mfma_f32_16x16x32_bf16 v[80:83], v[176:179], v[192:195], v[80:83]
	v_mfma_f32_16x16x32_bf16 v[80:83], v[180:183], v[196:199], v[80:83]
	v_mfma_f32_16x16x32_bf16 v[84:87], v[172:175], v[196:199], v[84:87]
	v_mfma_f32_16x16x32_bf16 v[84:87], v[168:171], v[192:195], v[84:87]
	v_mfma_f32_16x16x32_bf16 v[112:115], v[160:163], v[192:195], v[112:115]
	v_mfma_f32_16x16x32_bf16 v[112:115], v[164:167], v[196:199], v[112:115]
	v_mfma_f32_16x16x32_bf16 v[116:119], v[148:151], v[196:199], v[116:119]
	v_mfma_f32_16x16x32_bf16 v[116:119], v[144:147], v[192:195], v[116:119]
	v_mfma_f32_16x16x32_bf16 v[108:111], v[144:147], v[200:203], v[108:111]
	v_mfma_f32_16x16x32_bf16 v[108:111], v[148:151], v[204:207], v[108:111]
	v_mfma_f32_16x16x32_bf16 v[104:107], v[164:167], v[204:207], v[104:107]
	v_mfma_f32_16x16x32_bf16 v[104:107], v[160:163], v[200:203], v[104:107]
	v_mfma_f32_16x16x32_bf16 v[76:79], v[168:171], v[200:203], v[76:79]
	v_mfma_f32_16x16x32_bf16 v[76:79], v[172:175], v[204:207], v[76:79]
	v_mfma_f32_16x16x32_bf16 v[72:75], v[180:183], v[204:207], v[72:75]
	v_mfma_f32_16x16x32_bf16 v[72:75], v[176:179], v[200:203], v[72:75]
	v_mfma_f32_16x16x32_bf16 v[64:67], v[176:179], v[208:211], v[64:67]
	v_mfma_f32_16x16x32_bf16 v[64:67], v[180:183], v[212:215], v[64:67]
	v_mfma_f32_16x16x32_bf16 v[68:71], v[172:175], v[212:215], v[68:71]
	v_mfma_f32_16x16x32_bf16 v[68:71], v[168:171], v[208:211], v[68:71]
	v_mfma_f32_16x16x32_bf16 v[96:99], v[160:163], v[208:211], v[96:99]
	v_mfma_f32_16x16x32_bf16 v[96:99], v[164:167], v[212:215], v[96:99]
	v_mfma_f32_16x16x32_bf16 v[100:103], v[148:151], v[212:215], v[100:103]
	v_mfma_f32_16x16x32_bf16 v[100:103], v[144:147], v[208:211], v[100:103]
	s_setprio 0
	s_barrier
	s_add_i32 s10, s88, s16
	v_lshl_add_u64 v[216:217], s[30:31], 0, v[128:129]
	s_mov_b32 m0, s10
	ds_read_b128 v[184:187], v158 offset:16384
	ds_read_b128 v[188:191], v158 offset:17408
	ds_read_b128 v[192:195], v158 offset:18432
	ds_read_b128 v[196:199], v158 offset:19456
	ds_read_b128 v[200:203], v158 offset:20480
	ds_read_b128 v[204:207], v158 offset:21504
	ds_read_b128 v[208:211], v158 offset:22528
	ds_read_b128 v[212:215], v158 offset:23552
	global_load_lds_dwordx4 v[216:217], off
	s_add_i32 m0, s10, 0x2000
	s_add_u32 s10, s30, 0x160000
	v_lshl_add_u64 v[218:219], s[30:31], 0, v[130:131]
	s_addc_u32 s11, s31, 0
	s_add_i32 s46, s89, s16
	global_load_lds_dwordx4 v[218:219], off
	v_lshl_add_u64 v[220:221], s[10:11], 0, v[128:129]
	s_mov_b32 m0, s46
	v_lshl_add_u64 v[222:223], vcc, 0, v[136:137]
	global_load_lds_dwordx4 v[220:221], off
	v_lshl_add_u64 v[220:221], s[10:11], 0, v[130:131]
	s_add_i32 m0, s46, 0x2000
	s_nop 0
	global_load_lds_dwordx4 v[220:221], off
	v_lshl_add_u64 v[220:221], vcc, 0, v[132:133]
	s_mov_b32 m0, s70
	s_nop 0
	global_load_lds_dwordx4 v[220:221], off
	s_mov_b32 m0, s71
	s_nop 0
	global_load_lds_dwordx4 v[222:223], off
	s_waitcnt vmcnt(8)
	s_waitcnt lgkmcnt(0)
	s_barrier
; #define PG8_STAGE(bufoff, gbase, voff) do { _Pragma("unroll") for (int _i = 0; _i < 2; ++_i) \
;         __builtin_amdgcn_global_load_lds((const unsigned*)((const char*)(gbase) + (voff)[_i]), (PG8_LAS unsigned*)(lds + (bufoff) + ldsw + _i * 8192), 16, 0, 0); } while (0)
; #define PG8_LDA(dst, b, h) do { _Pragma("unroll") for (int m = 0; m < 4; ++m) _Pragma("unroll") for (int k = 0; k < 2; ++k) dst[m][k] = *(const PG8_LAS bf16x8*)(lds + PG8_SA(b, h) + aoff + m * 2048 + k * 1024); } while (0)
; #define PG8_LDB(dst, b, h) do { _Pragma("unroll") for (int n = 0; n < 2; ++n) _Pragma("unroll") for (int k = 0; k < 2; ++k) dst[n][k] = *(const PG8_LAS bf16x8*)(lds + PG8_SB(b, h) + boff + n * 2048 + k * 1024); } while (0)
; #define PG8_MMA(ai, bj, At, Bt) do { __builtin_amdgcn_s_setprio(1); _Pragma("unroll") for (int m = 0; m < 4; ++m) _Pragma("unroll") for (int n = 0; n < 2; ++n) _Pragma("unroll") for (int k = 0; k < 2; ++k) \
;         acc[ai][bj][m][n] = __builtin_amdgcn_mfma_f32_16x16x32_bf16(Bt[n][k], At[m][k], acc[ai][bj][m][n], 0, 0, 0); __builtin_amdgcn_s_setprio(0); } while (0)
; #define PG8_WAIT_V(n) asm volatile("s_waitcnt vmcnt(" #n ")" ::: "memory")
; #define PG8_WAIT_L(n) asm volatile("s_waitcnt lgkmcnt(" #n ")" ::: "memory")
; #define PG8_BAR __builtin_amdgcn_s_barrier()
; #define PG8_SCHED __builtin_amdgcn_sched_barrier(0)
; template <class Epi, class Sched, bool ALIGN_EPI = false, bool SP2 = false, bool APERM = false  >
; __device__ __forceinline__ void gemm_phase(PG8_LAS unsigned char* lds, const Gemm g, const Sched& S, const Epi& E, const int wid  ) {
;     ...
;             PG8_WAIT_V(8); PG8_WAIT_L(0); PG8_BAR; PG8_MMA(1, 0, At, B0); PG8_MMA(1, 1, At, B1); PG8_BAR; PG8_SCHED;
;             PG8_LDB(B0, 1, 0); PG8_LDB(B1, 1, 1); PG8_SCHED; PG8_LDA(At, 1, 0); PG8_STAGE(PG8_SA(0, 1), a2 + hstep, voffA);
;             PG8_WAIT_V(8); PG8_WAIT_L(0); PG8_BAR; PG8_MMA(0, 0, At, B0); PG8_MMA(0, 1, At, B1); PG8_BAR; PG8_SCHED;
	s_setprio 1
	s_waitcnt lgkmcnt(0)
	v_mfma_f32_16x16x32_bf16 v[60:63], v[144:147], v[184:187], v[60:63]
	v_mfma_f32_16x16x32_bf16 v[60:63], v[148:151], v[188:191], v[60:63]
	v_mfma_f32_16x16x32_bf16 v[56:59], v[164:167], v[188:191], v[56:59]
	v_mfma_f32_16x16x32_bf16 v[56:59], v[160:163], v[184:187], v[56:59]
	v_mfma_f32_16x16x32_bf16 v[28:31], v[168:171], v[184:187], v[28:31]
	v_mfma_f32_16x16x32_bf16 v[28:31], v[172:175], v[188:191], v[28:31]
	v_mfma_f32_16x16x32_bf16 v[24:27], v[180:183], v[188:191], v[24:27]
	v_mfma_f32_16x16x32_bf16 v[24:27], v[176:179], v[184:187], v[24:27]
	v_mfma_f32_16x16x32_bf16 v[16:19], v[176:179], v[192:195], v[16:19]
	v_mfma_f32_16x16x32_bf16 v[16:19], v[180:183], v[196:199], v[16:19]
	v_mfma_f32_16x16x32_bf16 v[20:23], v[172:175], v[196:199], v[20:23]
	v_mfma_f32_16x16x32_bf16 v[20:23], v[168:171], v[192:195], v[20:23]
	v_mfma_f32_16x16x32_bf16 v[48:51], v[160:163], v[192:195], v[48:51]
	v_mfma_f32_16x16x32_bf16 v[48:51], v[164:167], v[196:199], v[48:51]
	v_mfma_f32_16x16x32_bf16 v[52:55], v[148:151], v[196:199], v[52:55]
	v_mfma_f32_16x16x32_bf16 v[52:55], v[144:147], v[192:195], v[52:55]
	v_mfma_f32_16x16x32_bf16 v[44:47], v[144:147], v[200:203], v[44:47]
	v_mfma_f32_16x16x32_bf16 v[44:47], v[148:151], v[204:207], v[44:47]
	v_mfma_f32_16x16x32_bf16 v[40:43], v[164:167], v[204:207], v[40:43]
	v_mfma_f32_16x16x32_bf16 v[40:43], v[160:163], v[200:203], v[40:43]
	v_mfma_f32_16x16x32_bf16 v[12:15], v[168:171], v[200:203], v[12:15]
	v_mfma_f32_16x16x32_bf16 v[12:15], v[172:175], v[204:207], v[12:15]
	v_mfma_f32_16x16x32_bf16 v[8:11], v[180:183], v[204:207], v[8:11]
	v_mfma_f32_16x16x32_bf16 v[8:11], v[176:179], v[200:203], v[8:11]
	v_mfma_f32_16x16x32_bf16 v[0:3], v[176:179], v[208:211], v[0:3]
	v_mfma_f32_16x16x32_bf16 v[0:3], v[180:183], v[212:215], v[0:3]
	v_mfma_f32_16x16x32_bf16 v[4:7], v[172:175], v[212:215], v[4:7]
	v_mfma_f32_16x16x32_bf16 v[4:7], v[168:171], v[208:211], v[4:7]
	v_mfma_f32_16x16x32_bf16 v[32:35], v[160:163], v[208:211], v[32:35]
	v_mfma_f32_16x16x32_bf16 v[32:35], v[164:167], v[212:215], v[32:35]
	v_mfma_f32_16x16x32_bf16 v[36:39], v[148:151], v[212:215], v[36:39]
	v_mfma_f32_16x16x32_bf16 v[36:39], v[144:147], v[208:211], v[36:39]
	s_setprio 0
	s_barrier
	s_add_i32 s46, 0, 0x18000
	v_add_u32_e32 v159, s46, v153
	s_add_i32 s47, 0, 0x1c000
	ds_read_b128 v[144:147], v159
	ds_read_b128 v[148:151], v159 offset:1024
	ds_read_b128 v[160:163], v159 offset:2048
	ds_read_b128 v[164:167], v159 offset:3072
	v_add_u32_e32 v159, s47, v153
	ds_read_b128 v[168:171], v159
	ds_read_b128 v[172:175], v159 offset:1024
	ds_read_b128 v[176:179], v159 offset:2048
	ds_read_b128 v[180:183], v159 offset:3072
	s_add_u32 s10, vcc_lo, 0x160000
	s_addc_u32 s11, vcc_hi, 0
	s_mov_b32 m0, s72
	v_lshl_add_u64 v[224:225], s[10:11], 0, v[132:133]
	ds_read_b128 v[184:187], v158 offset:32768
	ds_read_b128 v[188:191], v158 offset:33792
	ds_read_b128 v[192:195], v158 offset:34816
	ds_read_b128 v[196:199], v158 offset:35840
	ds_read_b128 v[200:203], v158 offset:36864
	ds_read_b128 v[204:207], v158 offset:37888
	ds_read_b128 v[208:211], v158 offset:38912
	ds_read_b128 v[212:215], v158 offset:39936
	global_load_lds_dwordx4 v[224:225], off
	v_lshl_add_u64 v[224:225], s[10:11], 0, v[136:137]
	s_mov_b32 m0, s73
	s_nop 0
	global_load_lds_dwordx4 v[224:225], off
	s_waitcnt vmcnt(8)
	s_waitcnt lgkmcnt(0)
	s_barrier
	s_setprio 1
	s_waitcnt lgkmcnt(0)
	v_mfma_f32_16x16x32_bf16 v[124:127], v[144:147], v[184:187], v[124:127]
	v_mfma_f32_16x16x32_bf16 v[124:127], v[148:151], v[188:191], v[124:127]
	v_mfma_f32_16x16x32_bf16 v[120:123], v[164:167], v[188:191], v[120:123]
	v_mfma_f32_16x16x32_bf16 v[120:123], v[160:163], v[184:187], v[120:123]
	v_mfma_f32_16x16x32_bf16 v[92:95], v[168:171], v[184:187], v[92:95]
	v_mfma_f32_16x16x32_bf16 v[92:95], v[172:175], v[188:191], v[92:95]
	v_mfma_f32_16x16x32_bf16 v[88:91], v[180:183], v[188:191], v[88:91]
	v_mfma_f32_16x16x32_bf16 v[88:91], v[176:179], v[184:187], v[88:91]
	v_mfma_f32_16x16x32_bf16 v[80:83], v[176:179], v[192:195], v[80:83]
	v_mfma_f32_16x16x32_bf16 v[80:83], v[180:183], v[196:199], v[80:83]
	v_mfma_f32_16x16x32_bf16 v[84:87], v[172:175], v[196:199], v[84:87]
	v_mfma_f32_16x16x32_bf16 v[84:87], v[168:171], v[192:195], v[84:87]
	v_mfma_f32_16x16x32_bf16 v[112:115], v[160:163], v[192:195], v[112:115]
	v_mfma_f32_16x16x32_bf16 v[112:115], v[164:167], v[196:199], v[112:115]
	v_mfma_f32_16x16x32_bf16 v[116:119], v[148:151], v[196:199], v[116:119]
	v_mfma_f32_16x16x32_bf16 v[116:119], v[144:147], v[192:195], v[116:119]
	v_mfma_f32_16x16x32_bf16 v[108:111], v[144:147], v[200:203], v[108:111]
	v_mfma_f32_16x16x32_bf16 v[108:111], v[148:151], v[204:207], v[108:111]
	v_mfma_f32_16x16x32_bf16 v[104:107], v[164:167], v[204:207], v[104:107]
	v_mfma_f32_16x16x32_bf16 v[104:107], v[160:163], v[200:203], v[104:107]
	v_mfma_f32_16x16x32_bf16 v[76:79], v[168:171], v[200:203], v[76:79]
	v_mfma_f32_16x16x32_bf16 v[76:79], v[172:175], v[204:207], v[76:79]
	v_mfma_f32_16x16x32_bf16 v[72:75], v[180:183], v[204:207], v[72:75]
	v_mfma_f32_16x16x32_bf16 v[72:75], v[176:179], v[200:203], v[72:75]
	v_mfma_f32_16x16x32_bf16 v[64:67], v[176:179], v[208:211], v[64:67]
	v_mfma_f32_16x16x32_bf16 v[64:67], v[180:183], v[212:215], v[64:67]
	v_mfma_f32_16x16x32_bf16 v[68:71], v[172:175], v[212:215], v[68:71]
	v_mfma_f32_16x16x32_bf16 v[68:71], v[168:171], v[208:211], v[68:71]
	v_mfma_f32_16x16x32_bf16 v[96:99], v[160:163], v[208:211], v[96:99]
	v_mfma_f32_16x16x32_bf16 v[96:99], v[164:167], v[212:215], v[96:99]
	v_mfma_f32_16x16x32_bf16 v[100:103], v[148:151], v[212:215], v[100:103]
	v_mfma_f32_16x16x32_bf16 v[100:103], v[144:147], v[208:211], v[100:103]
	s_setprio 0
	s_barrier
; #define PG8_STAGE(bufoff, gbase, voff) do { _Pragma("unroll") for (int _i = 0; _i < 2; ++_i) \
;         __builtin_amdgcn_global_load_lds((const unsigned*)((const char*)(gbase) + (voff)[_i]), (PG8_LAS unsigned*)(lds + (bufoff) + ldsw + _i * 8192), 16, 0, 0); } while (0)
; #define PG8_LDA(dst, b, h) do { _Pragma("unroll") for (int m = 0; m < 4; ++m) _Pragma("unroll") for (int k = 0; k < 2; ++k) dst[m][k] = *(const PG8_LAS bf16x8*)(lds + PG8_SA(b, h) + aoff + m * 2048 + k * 1024); } while (0)
; #define PG8_MMA(ai, bj, At, Bt) do { __builtin_amdgcn_s_setprio(1); _Pragma("unroll") for (int m = 0; m < 4; ++m) _Pragma("unroll") for (int n = 0; n < 2; ++n) _Pragma("unroll") for (int k = 0; k < 2; ++k) \
;         acc[ai][bj][m][n] = __builtin_amdgcn_mfma_f32_16x16x32_bf16(Bt[n][k], At[m][k], acc[ai][bj][m][n], 0, 0, 0); __builtin_amdgcn_s_setprio(0); } while (0)
; #define PG8_WAIT_V(n) asm volatile("s_waitcnt vmcnt(" #n ")" ::: "memory")
; #define PG8_WAIT_L(n) asm volatile("s_waitcnt lgkmcnt(" #n ")" ::: "memory")
; #define PG8_BAR __builtin_amdgcn_s_barrier()
; #define PG8_SCHED __builtin_amdgcn_sched_barrier(0)
; template <class Epi, class Sched, bool ALIGN_EPI = false, bool SP2 = false, bool APERM = false  >
; __device__ __forceinline__ void gemm_phase(PG8_LAS unsigned char* lds, const Gemm g, const Sched& S, const Epi& E, const int wid  ) {
;     ...
;             PG8_LDA(At, 1, 1); PG8_STAGE(PG8_SB(1, 0), b3, voffB); PG8_STAGE(PG8_SB(1, 1), b3 + hstep, voffB); PG8_STAGE(PG8_SA(1, 0), a3, voffA);
;             PG8_WAIT_V(8); PG8_WAIT_L(0); PG8_BAR; PG8_MMA(1, 0, At, B0); PG8_MMA(1, 1, At, B1); PG8_BAR; PG8_SCHED;
	s_add_i32 s10, s46, s16
	v_lshl_add_u64 v[216:217], v[216:217], 0, s[58:59]
	s_mov_b32 m0, s10
	ds_read_b128 v[184:187], v158 offset:49152
	ds_read_b128 v[188:191], v158 offset:50176
	ds_read_b128 v[192:195], v158 offset:51200
	ds_read_b128 v[196:199], v158 offset:52224
	ds_read_b128 v[200:203], v158 offset:53248
	ds_read_b128 v[204:207], v158 offset:54272
	ds_read_b128 v[208:211], v158 offset:55296
	ds_read_b128 v[212:215], v158 offset:56320
	global_load_lds_dwordx4 v[216:217], off
	s_add_i32 m0, s10, 0x2000
	s_add_u32 s10, s30, 0x160080
	v_lshl_add_u64 v[216:217], v[218:219], 0, s[58:59]
	s_addc_u32 s11, s31, 0
	s_add_i32 s30, s47, s16
	global_load_lds_dwordx4 v[216:217], off
	v_lshl_add_u64 v[216:217], s[10:11], 0, v[128:129]
	s_mov_b32 m0, s30
	s_nop 0
	global_load_lds_dwordx4 v[216:217], off
	v_lshl_add_u64 v[216:217], s[10:11], 0, v[130:131]
	s_add_i32 m0, s30, 0x2000
	s_nop 0
	global_load_lds_dwordx4 v[216:217], off
	v_lshl_add_u64 v[216:217], v[220:221], 0, s[58:59]
	s_mov_b32 m0, s86
	s_nop 0
	global_load_lds_dwordx4 v[216:217], off
	v_lshl_add_u64 v[216:217], v[222:223], 0, s[58:59]
	s_mov_b32 m0, s87
	s_nop 0
	global_load_lds_dwordx4 v[216:217], off
	s_waitcnt vmcnt(8)
	s_waitcnt lgkmcnt(0)
	s_barrier
	s_setprio 1
	s_waitcnt lgkmcnt(0)
	v_mfma_f32_16x16x32_bf16 v[60:63], v[144:147], v[184:187], v[60:63]
	v_mfma_f32_16x16x32_bf16 v[60:63], v[148:151], v[188:191], v[60:63]
	v_mfma_f32_16x16x32_bf16 v[56:59], v[164:167], v[188:191], v[56:59]
	v_mfma_f32_16x16x32_bf16 v[56:59], v[160:163], v[184:187], v[56:59]
	v_mfma_f32_16x16x32_bf16 v[28:31], v[168:171], v[184:187], v[28:31]
	v_mfma_f32_16x16x32_bf16 v[28:31], v[172:175], v[188:191], v[28:31]
	v_mfma_f32_16x16x32_bf16 v[24:27], v[180:183], v[188:191], v[24:27]
	v_mfma_f32_16x16x32_bf16 v[24:27], v[176:179], v[184:187], v[24:27]
	v_mfma_f32_16x16x32_bf16 v[16:19], v[176:179], v[192:195], v[16:19]
	v_mfma_f32_16x16x32_bf16 v[16:19], v[180:183], v[196:199], v[16:19]
	v_mfma_f32_16x16x32_bf16 v[20:23], v[172:175], v[196:199], v[20:23]
	v_mfma_f32_16x16x32_bf16 v[20:23], v[168:171], v[192:195], v[20:23]
	v_mfma_f32_16x16x32_bf16 v[48:51], v[160:163], v[192:195], v[48:51]
	v_mfma_f32_16x16x32_bf16 v[48:51], v[164:167], v[196:199], v[48:51]
	v_mfma_f32_16x16x32_bf16 v[52:55], v[148:151], v[196:199], v[52:55]
	v_mfma_f32_16x16x32_bf16 v[52:55], v[144:147], v[192:195], v[52:55]
	v_mfma_f32_16x16x32_bf16 v[44:47], v[144:147], v[200:203], v[44:47]
	v_mfma_f32_16x16x32_bf16 v[44:47], v[148:151], v[204:207], v[44:47]
	v_mfma_f32_16x16x32_bf16 v[40:43], v[164:167], v[204:207], v[40:43]
	v_mfma_f32_16x16x32_bf16 v[40:43], v[160:163], v[200:203], v[40:43]
	v_mfma_f32_16x16x32_bf16 v[12:15], v[168:171], v[200:203], v[12:15]
	v_mfma_f32_16x16x32_bf16 v[12:15], v[172:175], v[204:207], v[12:15]
	v_mfma_f32_16x16x32_bf16 v[8:11], v[180:183], v[204:207], v[8:11]
	v_mfma_f32_16x16x32_bf16 v[8:11], v[176:179], v[200:203], v[8:11]
	v_mfma_f32_16x16x32_bf16 v[0:3], v[176:179], v[208:211], v[0:3]
	v_mfma_f32_16x16x32_bf16 v[0:3], v[180:183], v[212:215], v[0:3]
	v_mfma_f32_16x16x32_bf16 v[4:7], v[172:175], v[212:215], v[4:7]
	v_mfma_f32_16x16x32_bf16 v[4:7], v[168:171], v[208:211], v[4:7]
	v_mfma_f32_16x16x32_bf16 v[32:35], v[160:163], v[208:211], v[32:35]
	v_mfma_f32_16x16x32_bf16 v[32:35], v[164:167], v[212:215], v[32:35]
	v_mfma_f32_16x16x32_bf16 v[36:39], v[148:151], v[212:215], v[36:39]
	v_mfma_f32_16x16x32_bf16 v[36:39], v[144:147], v[208:211], v[36:39]
	s_setprio 0
	s_barrier
	s_cmp_gt_u32 s65, 41
	s_cbranch_scc1 .LBB0_607
	s_mov_b32 s65, s56
	s_branch .LBB0_588

; #define PG8_STAGE(bufoff, gbase, voff) do { _Pragma("unroll") for (int _i = 0; _i < 2; ++_i) \
;         __builtin_amdgcn_global_load_lds((const unsigned*)((const char*)(gbase) + (voff)[_i]), (PG8_LAS unsigned*)(lds + (bufoff) + ldsw + _i * 8192), 16, 0, 0); } while (0)
; #define PG8_LDA(dst, b, h) do { _Pragma("unroll") for (int m = 0; m < 4; ++m) _Pragma("unroll") for (int k = 0; k < 2; ++k) dst[m][k] = *(const PG8_LAS bf16x8*)(lds + PG8_SA(b, h) + aoff + m * 2048 + k * 1024); } while (0)
; #define PG8_LDB(dst, b, h) do { _Pragma("unroll") for (int n = 0; n < 2; ++n) _Pragma("unroll") for (int k = 0; k < 2; ++k) dst[n][k] = *(const PG8_LAS bf16x8*)(lds + PG8_SB(b, h) + boff + n * 2048 + k * 1024); } while (0)
; #define PG8_MMA(ai, bj, At, Bt) do { __builtin_amdgcn_s_setprio(1); _Pragma("unroll") for (int m = 0; m < 4; ++m) _Pragma("unroll") for (int n = 0; n < 2; ++n) _Pragma("unroll") for (int k = 0; k < 2; ++k) \
;         acc[ai][bj][m][n] = __builtin_amdgcn_mfma_f32_16x16x32_bf16(Bt[n][k], At[m][k], acc[ai][bj][m][n], 0, 0, 0); __builtin_amdgcn_s_setprio(0); } while (0)
; #define PG8_WAIT_V(n) asm volatile("s_waitcnt vmcnt(" #n ")" ::: "memory")
; #define PG8_WAIT_L(n) asm volatile("s_waitcnt lgkmcnt(" #n ")" ::: "memory")
; #define PG8_BAR __builtin_amdgcn_s_barrier()
; #define PG8_SCHED __builtin_amdgcn_sched_barrier(0)
; template <class Epi, class Sched, bool ALIGN_EPI = false, bool SP2 = false, bool APERM = false  >
; __device__ __forceinline__ void gemm_phase(PG8_LAS unsigned char* lds, const Gemm g, const Sched& S, const Epi& E, const int wid  ) {
;     ...
;             const bool last = (t == nt - 2);
;             const char* a1 = cA + (size_t)(t + 1) * kstep;
;             const char* a2 = last ? nA : cA + (size_t)(t + 2) * kstep; const char* b2 = last ? nB : cB + (size_t)(t + 2) * kstep;
;             const char* a3 = a2 + kstep; const char* b3 = b2 + kstep;
;             if (last && has_next) S.a_ready(nxt);
;             if constexpr (SP2) {
;             PG8_LDB(B0, 0, 0); PG8_LDB(B1, 0, 1); PG8_SCHED; PG8_LDA(At, 0, 0); PG8_STAGE(PG8_SA(1, 1), a1 + hstep, voffA);
;             PG8_WAIT_V(8); PG8_WAIT_L(0); PG8_BAR; PG8_MMA(0, 0, At, B0); PG8_MMA(0, 1, At, B1); PG8_BAR; PG8_SCHED;
;             PG8_LDA(At, 0, 1); PG8_STAGE(PG8_SB(0, 0), b2, voffB); PG8_STAGE(PG8_SB(0, 1), b2 + hstep, voffB); PG8_STAGE(PG8_SA(0, 0), a2, voffA);
.LBB0_669:
	v_add_u32_e32 v1, s70, v145
	ds_read_b128 v[152:155], v1
	ds_read_b128 v[156:159], v1 offset:1024
	ds_read_b128 v[160:163], v1 offset:2048
	ds_read_b128 v[164:167], v1 offset:3072
	v_add_u32_e32 v1, s71, v145
	ds_read_b128 v[168:171], v1
	ds_read_b128 v[172:175], v1 offset:1024
	ds_read_b128 v[176:179], v1 offset:2048
	ds_read_b128 v[180:183], v1 offset:3072
	s_add_i32 s80, s54, 2
	s_add_u32 s81, s34, 0x80
	s_addc_u32 s55, s35, 0
	s_cmp_eq_u32 s69, s54
	s_cselect_b32 s54, s28, s81
	s_cselect_b32 s55, s29, s55
	s_cselect_b32 s83, s31, s79
	s_cselect_b32 s82, s30, s78
	s_mov_b32 m0, s72
	v_lshl_add_u64 v[2:3], s[34:35], 0, v[140:141]
	ds_read_b128 v[184:187], v147
	ds_read_b128 v[188:191], v147 offset:1024
	ds_read_b128 v[192:195], v147 offset:2048
	ds_read_b128 v[196:199], v147 offset:3072
	ds_read_b128 v[200:203], v147 offset:4096
	ds_read_b128 v[204:207], v147 offset:5120
	ds_read_b128 v[208:211], v147 offset:6144
	ds_read_b128 v[212:215], v147 offset:7168
	global_load_lds_dwordx4 v[2:3], off
	v_lshl_add_u64 v[2:3], s[34:35], 0, v[142:143]
	s_mov_b32 m0, s73
	s_nop 0
	global_load_lds_dwordx4 v[2:3], off
	s_waitcnt vmcnt(8)
	s_waitcnt lgkmcnt(0)
	s_barrier
	s_setprio 1
	s_waitcnt lgkmcnt(0)
	v_mfma_f32_16x16x32_bf16 v[128:131], v[152:155], v[184:187], v[128:131]
	v_mfma_f32_16x16x32_bf16 v[128:131], v[156:159], v[188:191], v[128:131]
	v_mfma_f32_16x16x32_bf16 v[124:127], v[164:167], v[188:191], v[124:127]
	v_mfma_f32_16x16x32_bf16 v[124:127], v[160:163], v[184:187], v[124:127]
	v_mfma_f32_16x16x32_bf16 v[96:99], v[168:171], v[184:187], v[96:99]
	v_mfma_f32_16x16x32_bf16 v[96:99], v[172:175], v[188:191], v[96:99]
	v_mfma_f32_16x16x32_bf16 v[92:95], v[180:183], v[188:191], v[92:95]
	v_mfma_f32_16x16x32_bf16 v[92:95], v[176:179], v[184:187], v[92:95]
	v_mfma_f32_16x16x32_bf16 v[84:87], v[176:179], v[192:195], v[84:87]
	v_mfma_f32_16x16x32_bf16 v[84:87], v[180:183], v[196:199], v[84:87]
	v_mfma_f32_16x16x32_bf16 v[88:91], v[172:175], v[196:199], v[88:91]
	v_mfma_f32_16x16x32_bf16 v[88:91], v[168:171], v[192:195], v[88:91]
	v_mfma_f32_16x16x32_bf16 v[116:119], v[160:163], v[192:195], v[116:119]
	v_mfma_f32_16x16x32_bf16 v[116:119], v[164:167], v[196:199], v[116:119]
	v_mfma_f32_16x16x32_bf16 v[120:123], v[156:159], v[196:199], v[120:123]
	v_mfma_f32_16x16x32_bf16 v[120:123], v[152:155], v[192:195], v[120:123]
	v_mfma_f32_16x16x32_bf16 v[112:115], v[152:155], v[200:203], v[112:115]
	v_mfma_f32_16x16x32_bf16 v[112:115], v[156:159], v[204:207], v[112:115]
	v_mfma_f32_16x16x32_bf16 v[108:111], v[164:167], v[204:207], v[108:111]
	v_mfma_f32_16x16x32_bf16 v[108:111], v[160:163], v[200:203], v[108:111]
	v_mfma_f32_16x16x32_bf16 v[80:83], v[168:171], v[200:203], v[80:83]
	v_mfma_f32_16x16x32_bf16 v[80:83], v[172:175], v[204:207], v[80:83]
	v_mfma_f32_16x16x32_bf16 v[76:79], v[180:183], v[204:207], v[76:79]
	v_mfma_f32_16x16x32_bf16 v[76:79], v[176:179], v[200:203], v[76:79]
	v_mfma_f32_16x16x32_bf16 v[68:71], v[176:179], v[208:211], v[68:71]
	v_mfma_f32_16x16x32_bf16 v[68:71], v[180:183], v[212:215], v[68:71]
	v_mfma_f32_16x16x32_bf16 v[72:75], v[172:175], v[212:215], v[72:75]
	v_mfma_f32_16x16x32_bf16 v[72:75], v[168:171], v[208:211], v[72:75]
	v_mfma_f32_16x16x32_bf16 v[100:103], v[160:163], v[208:211], v[100:103]
	v_mfma_f32_16x16x32_bf16 v[100:103], v[164:167], v[212:215], v[100:103]
	v_mfma_f32_16x16x32_bf16 v[104:107], v[156:159], v[212:215], v[104:107]
	v_mfma_f32_16x16x32_bf16 v[104:107], v[152:155], v[208:211], v[104:107]
	s_setprio 0
	s_barrier
	s_add_i32 s81, s70, s46
	v_lshl_add_u64 v[148:149], s[82:83], 0, v[136:137]
	s_mov_b32 m0, s81
	ds_read_b128 v[184:187], v147 offset:16384
	ds_read_b128 v[188:191], v147 offset:17408
	ds_read_b128 v[192:195], v147 offset:18432
	ds_read_b128 v[196:199], v147 offset:19456
	ds_read_b128 v[200:203], v147 offset:20480
	ds_read_b128 v[204:207], v147 offset:21504
	ds_read_b128 v[208:211], v147 offset:22528
	ds_read_b128 v[212:215], v147 offset:23552
	global_load_lds_dwordx4 v[148:149], off
	s_add_i32 m0, s81, 0x2000
	v_lshl_add_u64 v[216:217], s[82:83], 0, v[132:133]
	s_add_u32 s82, s82, s4
	s_addc_u32 s83, s83, s5
	s_add_i32 s81, s71, s46
	global_load_lds_dwordx4 v[216:217], off
	v_lshl_add_u64 v[218:219], s[82:83], 0, v[136:137]
	s_mov_b32 m0, s81
	v_lshl_add_u64 v[220:221], s[82:83], 0, v[132:133]
	global_load_lds_dwordx4 v[218:219], off
	s_add_i32 m0, s81, 0x2000
	v_lshl_add_u64 v[222:223], s[54:55], 0, v[138:139]
	global_load_lds_dwordx4 v[220:221], off
	s_mov_b32 m0, s59
	v_lshl_add_u64 v[224:225], s[54:55], 0, v[134:135]
	global_load_lds_dwordx4 v[222:223], off
	s_mov_b32 m0, s63
	s_nop 0
	global_load_lds_dwordx4 v[224:225], off
	s_waitcnt vmcnt(8)
	s_waitcnt lgkmcnt(0)
	s_barrier
; #define PG8_STAGE(bufoff, gbase, voff) do { _Pragma("unroll") for (int _i = 0; _i < 2; ++_i) \
;         __builtin_amdgcn_global_load_lds((const unsigned*)((const char*)(gbase) + (voff)[_i]), (PG8_LAS unsigned*)(lds + (bufoff) + ldsw + _i * 8192), 16, 0, 0); } while (0)
; #define PG8_LDA(dst, b, h) do { _Pragma("unroll") for (int m = 0; m < 4; ++m) _Pragma("unroll") for (int k = 0; k < 2; ++k) dst[m][k] = *(const PG8_LAS bf16x8*)(lds + PG8_SA(b, h) + aoff + m * 2048 + k * 1024); } while (0)
; #define PG8_LDB(dst, b, h) do { _Pragma("unroll") for (int n = 0; n < 2; ++n) _Pragma("unroll") for (int k = 0; k < 2; ++k) dst[n][k] = *(const PG8_LAS bf16x8*)(lds + PG8_SB(b, h) + boff + n * 2048 + k * 1024); } while (0)
; #define PG8_MMA(ai, bj, At, Bt) do { __builtin_amdgcn_s_setprio(1); _Pragma("unroll") for (int m = 0; m < 4; ++m) _Pragma("unroll") for (int n = 0; n < 2; ++n) _Pragma("unroll") for (int k = 0; k < 2; ++k) \
;         acc[ai][bj][m][n] = __builtin_amdgcn_mfma_f32_16x16x32_bf16(Bt[n][k], At[m][k], acc[ai][bj][m][n], 0, 0, 0); __builtin_amdgcn_s_setprio(0); } while (0)
; #define PG8_WAIT_V(n) asm volatile("s_waitcnt vmcnt(" #n ")" ::: "memory")
; #define PG8_WAIT_L(n) asm volatile("s_waitcnt lgkmcnt(" #n ")" ::: "memory")
; #define PG8_BAR __builtin_amdgcn_s_barrier()
; #define PG8_SCHED __builtin_amdgcn_sched_barrier(0)
; template <class Epi, class Sched, bool ALIGN_EPI = false, bool SP2 = false, bool APERM = false  >
; __device__ __forceinline__ void gemm_phase(PG8_LAS unsigned char* lds, const Gemm g, const Sched& S, const Epi& E, const int wid  ) {
;     ...
;             PG8_WAIT_V(8); PG8_WAIT_L(0); PG8_BAR; PG8_MMA(1, 0, At, B0); PG8_MMA(1, 1, At, B1); PG8_BAR; PG8_SCHED;
;             PG8_LDB(B0, 1, 0); PG8_LDB(B1, 1, 1); PG8_SCHED; PG8_LDA(At, 1, 0); PG8_STAGE(PG8_SA(0, 1), a2 + hstep, voffA);
;             PG8_WAIT_V(8); PG8_WAIT_L(0); PG8_BAR; PG8_MMA(0, 0, At, B0); PG8_MMA(0, 1, At, B1); PG8_BAR; PG8_SCHED;
	s_setprio 1
	s_waitcnt lgkmcnt(0)
	v_mfma_f32_16x16x32_bf16 v[64:67], v[152:155], v[184:187], v[64:67]
	v_mfma_f32_16x16x32_bf16 v[64:67], v[156:159], v[188:191], v[64:67]
	v_mfma_f32_16x16x32_bf16 v[60:63], v[164:167], v[188:191], v[60:63]
	v_mfma_f32_16x16x32_bf16 v[60:63], v[160:163], v[184:187], v[60:63]
	v_mfma_f32_16x16x32_bf16 v[32:35], v[168:171], v[184:187], v[32:35]
	v_mfma_f32_16x16x32_bf16 v[32:35], v[172:175], v[188:191], v[32:35]
	v_mfma_f32_16x16x32_bf16 v[28:31], v[180:183], v[188:191], v[28:31]
	v_mfma_f32_16x16x32_bf16 v[28:31], v[176:179], v[184:187], v[28:31]
	v_mfma_f32_16x16x32_bf16 v[20:23], v[176:179], v[192:195], v[20:23]
	v_mfma_f32_16x16x32_bf16 v[20:23], v[180:183], v[196:199], v[20:23]
	v_mfma_f32_16x16x32_bf16 v[24:27], v[172:175], v[196:199], v[24:27]
	v_mfma_f32_16x16x32_bf16 v[24:27], v[168:171], v[192:195], v[24:27]
	v_mfma_f32_16x16x32_bf16 v[52:55], v[160:163], v[192:195], v[52:55]
	v_mfma_f32_16x16x32_bf16 v[52:55], v[164:167], v[196:199], v[52:55]
	v_mfma_f32_16x16x32_bf16 v[56:59], v[156:159], v[196:199], v[56:59]
	v_mfma_f32_16x16x32_bf16 v[56:59], v[152:155], v[192:195], v[56:59]
	v_mfma_f32_16x16x32_bf16 v[48:51], v[152:155], v[200:203], v[48:51]
	v_mfma_f32_16x16x32_bf16 v[48:51], v[156:159], v[204:207], v[48:51]
	v_mfma_f32_16x16x32_bf16 v[44:47], v[164:167], v[204:207], v[44:47]
	v_mfma_f32_16x16x32_bf16 v[44:47], v[160:163], v[200:203], v[44:47]
	v_mfma_f32_16x16x32_bf16 v[16:19], v[168:171], v[200:203], v[16:19]
	v_mfma_f32_16x16x32_bf16 v[16:19], v[172:175], v[204:207], v[16:19]
	v_mfma_f32_16x16x32_bf16 v[12:15], v[180:183], v[204:207], v[12:15]
	v_mfma_f32_16x16x32_bf16 v[12:15], v[176:179], v[200:203], v[12:15]
	v_mfma_f32_16x16x32_bf16 v[2:5], v[176:179], v[208:211], v[4:7]
	v_mfma_f32_16x16x32_bf16 v[2:5], v[180:183], v[212:215], v[2:5]
	v_mfma_f32_16x16x32_bf16 v[8:11], v[172:175], v[212:215], v[8:11]
	v_mfma_f32_16x16x32_bf16 v[8:11], v[168:171], v[208:211], v[8:11]
	v_mfma_f32_16x16x32_bf16 v[36:39], v[160:163], v[208:211], v[36:39]
	v_mfma_f32_16x16x32_bf16 v[36:39], v[164:167], v[212:215], v[36:39]
	v_mfma_f32_16x16x32_bf16 v[40:43], v[156:159], v[212:215], v[40:43]
	v_mfma_f32_16x16x32_bf16 v[40:43], v[152:155], v[208:211], v[40:43]
	s_setprio 0
	s_barrier
	s_add_i32 s81, 0, 0x18000
	v_add_u32_e32 v1, s81, v145
	s_add_i32 s82, 0, 0x1c000
	ds_read_b128 v[152:155], v1
	ds_read_b128 v[156:159], v1 offset:1024
	ds_read_b128 v[160:163], v1 offset:2048
	ds_read_b128 v[164:167], v1 offset:3072
	v_add_u32_e32 v1, s82, v145
	ds_read_b128 v[168:171], v1
	ds_read_b128 v[172:175], v1 offset:1024
	ds_read_b128 v[176:179], v1 offset:2048
	ds_read_b128 v[180:183], v1 offset:3072
	s_add_u32 s54, s54, s4
	s_addc_u32 s55, s55, s5
	s_mov_b32 m0, s64
	v_lshl_add_u64 v[6:7], s[54:55], 0, v[138:139]
	ds_read_b128 v[184:187], v147 offset:32768
	ds_read_b128 v[188:191], v147 offset:33792
	ds_read_b128 v[192:195], v147 offset:34816
	ds_read_b128 v[196:199], v147 offset:35840
	ds_read_b128 v[200:203], v147 offset:36864
	ds_read_b128 v[204:207], v147 offset:37888
	ds_read_b128 v[208:211], v147 offset:38912
	ds_read_b128 v[212:215], v147 offset:39936
	global_load_lds_dwordx4 v[6:7], off
	v_lshl_add_u64 v[6:7], s[54:55], 0, v[134:135]
	s_mov_b32 m0, s65
	s_nop 0
	global_load_lds_dwordx4 v[6:7], off
	s_waitcnt vmcnt(8)
	s_waitcnt lgkmcnt(0)
	s_barrier
	s_setprio 1
	s_waitcnt lgkmcnt(0)
	v_mfma_f32_16x16x32_bf16 v[128:131], v[152:155], v[184:187], v[128:131]
	v_mfma_f32_16x16x32_bf16 v[128:131], v[156:159], v[188:191], v[128:131]
	v_mfma_f32_16x16x32_bf16 v[124:127], v[164:167], v[188:191], v[124:127]
	v_mfma_f32_16x16x32_bf16 v[124:127], v[160:163], v[184:187], v[124:127]
	v_mfma_f32_16x16x32_bf16 v[96:99], v[168:171], v[184:187], v[96:99]
	v_mfma_f32_16x16x32_bf16 v[96:99], v[172:175], v[188:191], v[96:99]
	v_mfma_f32_16x16x32_bf16 v[92:95], v[180:183], v[188:191], v[92:95]
	v_mfma_f32_16x16x32_bf16 v[92:95], v[176:179], v[184:187], v[92:95]
	v_mfma_f32_16x16x32_bf16 v[84:87], v[176:179], v[192:195], v[84:87]
	v_mfma_f32_16x16x32_bf16 v[84:87], v[180:183], v[196:199], v[84:87]
	v_mfma_f32_16x16x32_bf16 v[88:91], v[172:175], v[196:199], v[88:91]
	v_mfma_f32_16x16x32_bf16 v[88:91], v[168:171], v[192:195], v[88:91]
	v_mfma_f32_16x16x32_bf16 v[116:119], v[160:163], v[192:195], v[116:119]
	v_mfma_f32_16x16x32_bf16 v[116:119], v[164:167], v[196:199], v[116:119]
	v_mfma_f32_16x16x32_bf16 v[120:123], v[156:159], v[196:199], v[120:123]
	v_mfma_f32_16x16x32_bf16 v[120:123], v[152:155], v[192:195], v[120:123]
	v_mfma_f32_16x16x32_bf16 v[112:115], v[152:155], v[200:203], v[112:115]
	v_mfma_f32_16x16x32_bf16 v[112:115], v[156:159], v[204:207], v[112:115]
	v_mfma_f32_16x16x32_bf16 v[108:111], v[164:167], v[204:207], v[108:111]
	v_mfma_f32_16x16x32_bf16 v[108:111], v[160:163], v[200:203], v[108:111]
	v_mfma_f32_16x16x32_bf16 v[80:83], v[168:171], v[200:203], v[80:83]
	v_mfma_f32_16x16x32_bf16 v[80:83], v[172:175], v[204:207], v[80:83]
	v_mfma_f32_16x16x32_bf16 v[76:79], v[180:183], v[204:207], v[76:79]
	v_mfma_f32_16x16x32_bf16 v[76:79], v[176:179], v[200:203], v[76:79]
	v_mfma_f32_16x16x32_bf16 v[68:71], v[176:179], v[208:211], v[68:71]
	v_mfma_f32_16x16x32_bf16 v[68:71], v[180:183], v[212:215], v[68:71]
	v_mfma_f32_16x16x32_bf16 v[72:75], v[172:175], v[212:215], v[72:75]
	v_mfma_f32_16x16x32_bf16 v[72:75], v[168:171], v[208:211], v[72:75]
	v_mfma_f32_16x16x32_bf16 v[100:103], v[160:163], v[208:211], v[100:103]
	v_mfma_f32_16x16x32_bf16 v[100:103], v[164:167], v[212:215], v[100:103]
	v_mfma_f32_16x16x32_bf16 v[104:107], v[156:159], v[212:215], v[104:107]
	v_mfma_f32_16x16x32_bf16 v[104:107], v[152:155], v[208:211], v[104:107]
	s_setprio 0
	s_barrier
; #define PG8_STAGE(bufoff, gbase, voff) do { _Pragma("unroll") for (int _i = 0; _i < 2; ++_i) \
;         __builtin_amdgcn_global_load_lds((const unsigned*)((const char*)(gbase) + (voff)[_i]), (PG8_LAS unsigned*)(lds + (bufoff) + ldsw + _i * 8192), 16, 0, 0); } while (0)
; #define PG8_LDA(dst, b, h) do { _Pragma("unroll") for (int m = 0; m < 4; ++m) _Pragma("unroll") for (int k = 0; k < 2; ++k) dst[m][k] = *(const PG8_LAS bf16x8*)(lds + PG8_SA(b, h) + aoff + m * 2048 + k * 1024); } while (0)
; #define PG8_MMA(ai, bj, At, Bt) do { __builtin_amdgcn_s_setprio(1); _Pragma("unroll") for (int m = 0; m < 4; ++m) _Pragma("unroll") for (int n = 0; n < 2; ++n) _Pragma("unroll") for (int k = 0; k < 2; ++k) \
;         acc[ai][bj][m][n] = __builtin_amdgcn_mfma_f32_16x16x32_bf16(Bt[n][k], At[m][k], acc[ai][bj][m][n], 0, 0, 0); __builtin_amdgcn_s_setprio(0); } while (0)
; #define PG8_WAIT_V(n) asm volatile("s_waitcnt vmcnt(" #n ")" ::: "memory")
; #define PG8_WAIT_L(n) asm volatile("s_waitcnt lgkmcnt(" #n ")" ::: "memory")
; #define PG8_BAR __builtin_amdgcn_s_barrier()
; #define PG8_SCHED __builtin_amdgcn_sched_barrier(0)
; template <class Epi, class Sched, bool ALIGN_EPI = false, bool SP2 = false, bool APERM = false  >
; __device__ __forceinline__ void gemm_phase(PG8_LAS unsigned char* lds, const Gemm g, const Sched& S, const Epi& E, const int wid  ) {
;     ...
;             PG8_LDA(At, 1, 1); PG8_STAGE(PG8_SB(1, 0), b3, voffB); PG8_STAGE(PG8_SB(1, 1), b3 + hstep, voffB); PG8_STAGE(PG8_SA(1, 0), a3, voffA);
;             PG8_WAIT_V(8); PG8_WAIT_L(0); PG8_BAR; PG8_MMA(1, 0, At, B0); PG8_MMA(1, 1, At, B1); PG8_BAR; PG8_SCHED;
	s_add_i32 s54, s81, s46
	v_lshl_add_u64 v[6:7], v[148:149], 0, s[16:17]
	s_mov_b32 m0, s54
	ds_read_b128 v[184:187], v147 offset:49152
	ds_read_b128 v[188:191], v147 offset:50176
	ds_read_b128 v[192:195], v147 offset:51200
	ds_read_b128 v[196:199], v147 offset:52224
	ds_read_b128 v[200:203], v147 offset:53248
	ds_read_b128 v[204:207], v147 offset:54272
	ds_read_b128 v[208:211], v147 offset:55296
	ds_read_b128 v[212:215], v147 offset:56320
	global_load_lds_dwordx4 v[6:7], off
	v_lshl_add_u64 v[6:7], v[216:217], 0, s[16:17]
	s_add_i32 m0, s54, 0x2000
	s_add_i32 s54, s82, s46
	global_load_lds_dwordx4 v[6:7], off
	v_lshl_add_u64 v[6:7], v[218:219], 0, s[16:17]
	s_mov_b32 m0, s54
	s_nop 0
	global_load_lds_dwordx4 v[6:7], off
	v_lshl_add_u64 v[6:7], v[220:221], 0, s[16:17]
	s_add_i32 m0, s54, 0x2000
	s_nop 0
	global_load_lds_dwordx4 v[6:7], off
	v_lshl_add_u64 v[6:7], v[222:223], 0, s[16:17]
	s_mov_b32 m0, s67
	s_nop 0
	global_load_lds_dwordx4 v[6:7], off
	v_lshl_add_u64 v[6:7], v[224:225], 0, s[16:17]
	s_mov_b32 m0, s68
	s_nop 0
	global_load_lds_dwordx4 v[6:7], off
	s_waitcnt vmcnt(8)
	s_waitcnt lgkmcnt(0)
	s_barrier
	s_setprio 1
	s_waitcnt lgkmcnt(0)
	v_mfma_f32_16x16x32_bf16 v[64:67], v[152:155], v[184:187], v[64:67]
	v_mfma_f32_16x16x32_bf16 v[60:63], v[160:163], v[184:187], v[60:63]
	v_mfma_f32_16x16x32_bf16 v[56:59], v[152:155], v[192:195], v[56:59]
	v_mfma_f32_16x16x32_bf16 v[52:55], v[160:163], v[192:195], v[52:55]
	v_mfma_f32_16x16x32_bf16 v[48:51], v[152:155], v[200:203], v[48:51]
	v_mfma_f32_16x16x32_bf16 v[44:47], v[160:163], v[200:203], v[44:47]
	v_mfma_f32_16x16x32_bf16 v[40:43], v[152:155], v[208:211], v[40:43]
	v_mfma_f32_16x16x32_bf16 v[36:39], v[160:163], v[208:211], v[36:39]
	v_mfma_f32_16x16x32_bf16 v[64:67], v[156:159], v[188:191], v[64:67]
	v_mfma_f32_16x16x32_bf16 v[60:63], v[164:167], v[188:191], v[60:63]
	v_mfma_f32_16x16x32_bf16 v[56:59], v[156:159], v[196:199], v[56:59]
	v_mfma_f32_16x16x32_bf16 v[52:55], v[164:167], v[196:199], v[52:55]
	v_mfma_f32_16x16x32_bf16 v[48:51], v[156:159], v[204:207], v[48:51]
	v_mfma_f32_16x16x32_bf16 v[44:47], v[164:167], v[204:207], v[44:47]
	v_mfma_f32_16x16x32_bf16 v[40:43], v[156:159], v[212:215], v[40:43]
	v_mfma_f32_16x16x32_bf16 v[36:39], v[164:167], v[212:215], v[36:39]
	v_mfma_f32_16x16x32_bf16 v[32:35], v[168:171], v[184:187], v[32:35]
	v_mfma_f32_16x16x32_bf16 v[28:31], v[176:179], v[184:187], v[28:31]
	v_mfma_f32_16x16x32_bf16 v[24:27], v[168:171], v[192:195], v[24:27]
	v_mfma_f32_16x16x32_bf16 v[20:23], v[176:179], v[192:195], v[20:23]
	v_mfma_f32_16x16x32_bf16 v[16:19], v[168:171], v[200:203], v[16:19]
	v_mfma_f32_16x16x32_bf16 v[12:15], v[176:179], v[200:203], v[12:15]
	v_mfma_f32_16x16x32_bf16 v[6:9], v[168:171], v[208:211], v[8:11]
	v_mfma_f32_16x16x32_bf16 v[2:5], v[176:179], v[208:211], v[2:5]
	v_mfma_f32_16x16x32_bf16 v[32:35], v[172:175], v[188:191], v[32:35]
	v_mfma_f32_16x16x32_bf16 v[28:31], v[180:183], v[188:191], v[28:31]
	v_mfma_f32_16x16x32_bf16 v[24:27], v[172:175], v[196:199], v[24:27]
	v_mfma_f32_16x16x32_bf16 v[20:23], v[180:183], v[196:199], v[20:23]
	v_mfma_f32_16x16x32_bf16 v[16:19], v[172:175], v[204:207], v[16:19]
	v_mfma_f32_16x16x32_bf16 v[12:15], v[180:183], v[204:207], v[12:15]
	v_mfma_f32_16x16x32_bf16 v[8:11], v[172:175], v[212:215], v[6:9]
	v_mfma_f32_16x16x32_bf16 v[4:7], v[180:183], v[212:215], v[2:5]
	s_setprio 0
	s_barrier
	s_add_u32 s34, s34, 0x100
	s_addc_u32 s35, s35, 0
	s_add_u32 s78, s78, 0x100
	s_addc_u32 s79, s79, 0
	s_cmp_ge_i32 s80, s66
	s_mov_b32 s54, s80
	s_cbranch_scc0 .LBB0_669
	v_readlane_b32 s80, v250, 61
	v_readlane_b32 s82, v249, 5
	v_readlane_b32 s81, v250, 62
	s_and_b64 vcc, exec, s[24:25]
	s_cbranch_vccnz .LBB0_662
	s_branch .LBB0_663

; #define PG8_STAGE(bufoff, gbase, voff) do { _Pragma("unroll") for (int _i = 0; _i < 2; ++_i) \
;         __builtin_amdgcn_global_load_lds((const unsigned*)((const char*)(gbase) + (voff)[_i]), (PG8_LAS unsigned*)(lds + (bufoff) + ldsw + _i * 8192), 16, 0, 0); } while (0)
; #define PG8_LDA(dst, b, h) do { _Pragma("unroll") for (int m = 0; m < 4; ++m) _Pragma("unroll") for (int k = 0; k < 2; ++k) dst[m][k] = *(const PG8_LAS bf16x8*)(lds + PG8_SA(b, h) + aoff + m * 2048 + k * 1024); } while (0)
; #define PG8_LDB(dst, b, h) do { _Pragma("unroll") for (int n = 0; n < 2; ++n) _Pragma("unroll") for (int k = 0; k < 2; ++k) dst[n][k] = *(const PG8_LAS bf16x8*)(lds + PG8_SB(b, h) + boff + n * 2048 + k * 1024); } while (0)
; #define PG8_MMA(ai, bj, At, Bt) do { __builtin_amdgcn_s_setprio(1); _Pragma("unroll") for (int m = 0; m < 4; ++m) _Pragma("unroll") for (int n = 0; n < 2; ++n) _Pragma("unroll") for (int k = 0; k < 2; ++k) \
;         acc[ai][bj][m][n] = __builtin_amdgcn_mfma_f32_16x16x32_bf16(Bt[n][k], At[m][k], acc[ai][bj][m][n], 0, 0, 0); __builtin_amdgcn_s_setprio(0); } while (0)
; #define PG8_WAIT_V(n) asm volatile("s_waitcnt vmcnt(" #n ")" ::: "memory")
; #define PG8_WAIT_L(n) asm volatile("s_waitcnt lgkmcnt(" #n ")" ::: "memory")
; #define PG8_BAR __builtin_amdgcn_s_barrier()
; #define PG8_SCHED __builtin_amdgcn_sched_barrier(0)
; template <class Epi, class Sched, bool ALIGN_EPI = false, bool SP2 = false, bool APERM = false  >
; __device__ __forceinline__ void gemm_phase(PG8_LAS unsigned char* lds, const Gemm g, const Sched& S, const Epi& E, const int wid  ) {
;     ...
;             const bool last = (t == nt - 2);
;             const char* a1 = cA + (size_t)(t + 1) * kstep;
;             const char* a2 = last ? nA : cA + (size_t)(t + 2) * kstep; const char* b2 = last ? nB : cB + (size_t)(t + 2) * kstep;
;             const char* a3 = a2 + kstep; const char* b3 = b2 + kstep;
;             if (last && has_next) S.a_ready(nxt);
;             if constexpr (SP2) {
;             PG8_LDB(B0, 0, 0); PG8_LDB(B1, 0, 1); PG8_SCHED; PG8_LDA(At, 0, 0); PG8_STAGE(PG8_SA(1, 1), a1 + hstep, voffA);
;             PG8_WAIT_V(8); PG8_WAIT_L(0); PG8_BAR; PG8_MMA(0, 0, At, B0); PG8_MMA(0, 1, At, B1); PG8_BAR; PG8_SCHED;
;             PG8_LDA(At, 0, 1); PG8_STAGE(PG8_SB(0, 0), b2, voffB); PG8_STAGE(PG8_SB(0, 1), b2 + hstep, voffB); PG8_STAGE(PG8_SA(0, 0), a2, voffA);
.LBB0_715:
	s_lshl_b32 s24, s71, 7
	s_add_u32 s25, s0, s24
	s_addc_u32 s26, s1, 0
	s_add_u32 s27, s25, 0x100
	v_add_u32_e32 v146, s94, v175
	s_addc_u32 s73, s26, 0
	s_waitcnt lgkmcnt(0)
	ds_read_b128 v[128:131], v146
	ds_read_b128 v[132:135], v146 offset:1024
	ds_read_b128 v[136:139], v146 offset:2048
	ds_read_b128 v[154:157], v146 offset:3072
	v_add_u32_e32 v146, s95, v175
	s_and_b64 s[18:19], s[16:17], exec
	ds_read_b128 v[158:161], v146
	ds_read_b128 v[162:165], v146 offset:1024
	ds_read_b128 v[166:169], v146 offset:2048
	ds_read_b128 v[170:173], v146 offset:3072
	s_cselect_b32 s19, s33, s73
	s_cselect_b32 s18, s52, s27
	s_add_u32 s24, s14, s24
	s_addc_u32 s27, s15, 0
	s_add_u32 s24, s24, 0x100
	s_addc_u32 s27, s27, 0
	s_and_b64 s[16:17], s[16:17], exec
	s_cselect_b32 s16, s65, s24
	s_cselect_b32 s17, s64, s27
	s_add_u32 s24, s25, 0x80080
	s_addc_u32 s25, s26, 0
	v_lshl_add_u64 v[214:215], s[24:25], 0, v[144:145]
	s_add_i32 m0, s11, 0xc000
	ds_read_b128 v[182:185], v180
	ds_read_b128 v[186:189], v180 offset:1024
	ds_read_b128 v[190:193], v180 offset:2048
	ds_read_b128 v[194:197], v180 offset:3072
	ds_read_b128 v[198:201], v180 offset:4096
	ds_read_b128 v[202:205], v180 offset:5120
	ds_read_b128 v[206:209], v180 offset:6144
	ds_read_b128 v[210:213], v180 offset:7168
	global_load_lds_dwordx4 v[214:215], off
	v_lshl_add_u64 v[214:215], s[24:25], 0, v[148:149]
	s_add_i32 m0, s11, 0xe000
	s_nop 0
	global_load_lds_dwordx4 v[214:215], off
	s_waitcnt vmcnt(8)
	s_waitcnt lgkmcnt(0)
	s_barrier
	s_setprio 1
	s_waitcnt lgkmcnt(0)
	v_mfma_f32_16x16x32_bf16 v[124:127], v[128:131], v[182:185], v[124:127]
	v_mfma_f32_16x16x32_bf16 v[124:127], v[132:135], v[186:189], v[124:127]
	v_mfma_f32_16x16x32_bf16 v[120:123], v[154:157], v[186:189], v[120:123]
	v_mfma_f32_16x16x32_bf16 v[120:123], v[136:139], v[182:185], v[120:123]
	v_mfma_f32_16x16x32_bf16 v[92:95], v[158:161], v[182:185], v[92:95]
	v_mfma_f32_16x16x32_bf16 v[92:95], v[162:165], v[186:189], v[92:95]
	v_mfma_f32_16x16x32_bf16 v[88:91], v[170:173], v[186:189], v[88:91]
	v_mfma_f32_16x16x32_bf16 v[88:91], v[166:169], v[182:185], v[88:91]
	v_mfma_f32_16x16x32_bf16 v[80:83], v[166:169], v[190:193], v[80:83]
	v_mfma_f32_16x16x32_bf16 v[80:83], v[170:173], v[194:197], v[80:83]
	v_mfma_f32_16x16x32_bf16 v[84:87], v[162:165], v[194:197], v[84:87]
	v_mfma_f32_16x16x32_bf16 v[84:87], v[158:161], v[190:193], v[84:87]
	v_mfma_f32_16x16x32_bf16 v[112:115], v[136:139], v[190:193], v[112:115]
	v_mfma_f32_16x16x32_bf16 v[112:115], v[154:157], v[194:197], v[112:115]
	v_mfma_f32_16x16x32_bf16 v[116:119], v[132:135], v[194:197], v[116:119]
	v_mfma_f32_16x16x32_bf16 v[116:119], v[128:131], v[190:193], v[116:119]
	v_mfma_f32_16x16x32_bf16 v[108:111], v[128:131], v[198:201], v[108:111]
	v_mfma_f32_16x16x32_bf16 v[108:111], v[132:135], v[202:205], v[108:111]
	v_mfma_f32_16x16x32_bf16 v[104:107], v[154:157], v[202:205], v[104:107]
	v_mfma_f32_16x16x32_bf16 v[104:107], v[136:139], v[198:201], v[104:107]
	v_mfma_f32_16x16x32_bf16 v[76:79], v[158:161], v[198:201], v[76:79]
	v_mfma_f32_16x16x32_bf16 v[76:79], v[162:165], v[202:205], v[76:79]
	v_mfma_f32_16x16x32_bf16 v[72:75], v[170:173], v[202:205], v[72:75]
	v_mfma_f32_16x16x32_bf16 v[72:75], v[166:169], v[198:201], v[72:75]
	v_mfma_f32_16x16x32_bf16 v[64:67], v[166:169], v[206:209], v[64:67]
	v_mfma_f32_16x16x32_bf16 v[64:67], v[170:173], v[210:213], v[64:67]
	v_mfma_f32_16x16x32_bf16 v[68:71], v[162:165], v[210:213], v[68:71]
	v_mfma_f32_16x16x32_bf16 v[68:71], v[158:161], v[206:209], v[68:71]
	v_mfma_f32_16x16x32_bf16 v[96:99], v[136:139], v[206:209], v[96:99]
	v_mfma_f32_16x16x32_bf16 v[96:99], v[154:157], v[210:213], v[96:99]
	v_mfma_f32_16x16x32_bf16 v[100:103], v[132:135], v[210:213], v[100:103]
	v_mfma_f32_16x16x32_bf16 v[100:103], v[128:131], v[206:209], v[100:103]
	s_setprio 0
	s_barrier
	s_add_i32 s24, s94, s46
	v_lshl_add_u64 v[214:215], s[16:17], 0, v[140:141]
	s_mov_b32 m0, s24
	ds_read_b128 v[182:185], v180 offset:16384
	ds_read_b128 v[186:189], v180 offset:17408
	ds_read_b128 v[190:193], v180 offset:18432
	ds_read_b128 v[194:197], v180 offset:19456
	ds_read_b128 v[198:201], v180 offset:20480
	ds_read_b128 v[202:205], v180 offset:21504
	ds_read_b128 v[206:209], v180 offset:22528
	ds_read_b128 v[210:213], v180 offset:23552
	global_load_lds_dwordx4 v[214:215], off
	s_add_i32 m0, s24, 0x2000
	s_add_u32 s24, s16, 0x80000
	v_lshl_add_u64 v[216:217], s[16:17], 0, v[142:143]
	s_addc_u32 s25, s17, 0
	s_add_i32 s26, s95, s46
	global_load_lds_dwordx4 v[216:217], off
	v_lshl_add_u64 v[218:219], s[24:25], 0, v[140:141]
	s_mov_b32 m0, s26
	v_lshl_add_u64 v[220:221], s[18:19], 0, v[148:149]
	global_load_lds_dwordx4 v[218:219], off
	v_lshl_add_u64 v[218:219], s[24:25], 0, v[142:143]
	s_add_i32 m0, s26, 0x2000
	s_nop 0
	global_load_lds_dwordx4 v[218:219], off
	v_lshl_add_u64 v[218:219], s[18:19], 0, v[144:145]
	s_mov_b32 m0, s11
	s_nop 0
	global_load_lds_dwordx4 v[218:219], off
	s_mov_b32 m0, s13
	s_nop 0
	global_load_lds_dwordx4 v[220:221], off
	s_waitcnt vmcnt(8)
	s_waitcnt lgkmcnt(0)
	s_barrier
; #define PG8_STAGE(bufoff, gbase, voff) do { _Pragma("unroll") for (int _i = 0; _i < 2; ++_i) \
;         __builtin_amdgcn_global_load_lds((const unsigned*)((const char*)(gbase) + (voff)[_i]), (PG8_LAS unsigned*)(lds + (bufoff) + ldsw + _i * 8192), 16, 0, 0); } while (0)
; #define PG8_LDA(dst, b, h) do { _Pragma("unroll") for (int m = 0; m < 4; ++m) _Pragma("unroll") for (int k = 0; k < 2; ++k) dst[m][k] = *(const PG8_LAS bf16x8*)(lds + PG8_SA(b, h) + aoff + m * 2048 + k * 1024); } while (0)
; #define PG8_LDB(dst, b, h) do { _Pragma("unroll") for (int n = 0; n < 2; ++n) _Pragma("unroll") for (int k = 0; k < 2; ++k) dst[n][k] = *(const PG8_LAS bf16x8*)(lds + PG8_SB(b, h) + boff + n * 2048 + k * 1024); } while (0)
; #define PG8_MMA(ai, bj, At, Bt) do { __builtin_amdgcn_s_setprio(1); _Pragma("unroll") for (int m = 0; m < 4; ++m) _Pragma("unroll") for (int n = 0; n < 2; ++n) _Pragma("unroll") for (int k = 0; k < 2; ++k) \
;         acc[ai][bj][m][n] = __builtin_amdgcn_mfma_f32_16x16x32_bf16(Bt[n][k], At[m][k], acc[ai][bj][m][n], 0, 0, 0); __builtin_amdgcn_s_setprio(0); } while (0)
; #define PG8_WAIT_V(n) asm volatile("s_waitcnt vmcnt(" #n ")" ::: "memory")
; #define PG8_WAIT_L(n) asm volatile("s_waitcnt lgkmcnt(" #n ")" ::: "memory")
; #define PG8_BAR __builtin_amdgcn_s_barrier()
; #define PG8_SCHED __builtin_amdgcn_sched_barrier(0)
; template <class Epi, class Sched, bool ALIGN_EPI = false, bool SP2 = false, bool APERM = false  >
; __device__ __forceinline__ void gemm_phase(PG8_LAS unsigned char* lds, const Gemm g, const Sched& S, const Epi& E, const int wid  ) {
;     ...
;             PG8_WAIT_V(8); PG8_WAIT_L(0); PG8_BAR; PG8_MMA(1, 0, At, B0); PG8_MMA(1, 1, At, B1); PG8_BAR; PG8_SCHED;
;             PG8_LDB(B0, 1, 0); PG8_LDB(B1, 1, 1); PG8_SCHED; PG8_LDA(At, 1, 0); PG8_STAGE(PG8_SA(0, 1), a2 + hstep, voffA);
;             PG8_WAIT_V(8); PG8_WAIT_L(0); PG8_BAR; PG8_MMA(0, 0, At, B0); PG8_MMA(0, 1, At, B1); PG8_BAR; PG8_SCHED;
	s_setprio 1
	s_waitcnt lgkmcnt(0)
	v_mfma_f32_16x16x32_bf16 v[60:63], v[128:131], v[182:185], v[60:63]
	v_mfma_f32_16x16x32_bf16 v[60:63], v[132:135], v[186:189], v[60:63]
	v_mfma_f32_16x16x32_bf16 v[56:59], v[154:157], v[186:189], v[56:59]
	v_mfma_f32_16x16x32_bf16 v[56:59], v[136:139], v[182:185], v[56:59]
	v_mfma_f32_16x16x32_bf16 v[28:31], v[158:161], v[182:185], v[28:31]
	v_mfma_f32_16x16x32_bf16 v[28:31], v[162:165], v[186:189], v[28:31]
	v_mfma_f32_16x16x32_bf16 v[24:27], v[170:173], v[186:189], v[24:27]
	v_mfma_f32_16x16x32_bf16 v[24:27], v[166:169], v[182:185], v[24:27]
	v_mfma_f32_16x16x32_bf16 v[16:19], v[166:169], v[190:193], v[16:19]
	v_mfma_f32_16x16x32_bf16 v[16:19], v[170:173], v[194:197], v[16:19]
	v_mfma_f32_16x16x32_bf16 v[20:23], v[162:165], v[194:197], v[20:23]
	v_mfma_f32_16x16x32_bf16 v[20:23], v[158:161], v[190:193], v[20:23]
	v_mfma_f32_16x16x32_bf16 v[48:51], v[136:139], v[190:193], v[48:51]
	v_mfma_f32_16x16x32_bf16 v[48:51], v[154:157], v[194:197], v[48:51]
	v_mfma_f32_16x16x32_bf16 v[52:55], v[132:135], v[194:197], v[52:55]
	v_mfma_f32_16x16x32_bf16 v[52:55], v[128:131], v[190:193], v[52:55]
	v_mfma_f32_16x16x32_bf16 v[44:47], v[128:131], v[198:201], v[44:47]
	v_mfma_f32_16x16x32_bf16 v[44:47], v[132:135], v[202:205], v[44:47]
	v_mfma_f32_16x16x32_bf16 v[40:43], v[154:157], v[202:205], v[40:43]
	v_mfma_f32_16x16x32_bf16 v[40:43], v[136:139], v[198:201], v[40:43]
	v_mfma_f32_16x16x32_bf16 v[12:15], v[158:161], v[198:201], v[12:15]
	v_mfma_f32_16x16x32_bf16 v[12:15], v[162:165], v[202:205], v[12:15]
	v_mfma_f32_16x16x32_bf16 v[8:11], v[170:173], v[202:205], v[8:11]
	v_mfma_f32_16x16x32_bf16 v[8:11], v[166:169], v[198:201], v[8:11]
	v_mfma_f32_16x16x32_bf16 v[0:3], v[166:169], v[206:209], v[0:3]
	v_mfma_f32_16x16x32_bf16 v[0:3], v[170:173], v[210:213], v[0:3]
	v_mfma_f32_16x16x32_bf16 v[4:7], v[162:165], v[210:213], v[4:7]
	v_mfma_f32_16x16x32_bf16 v[4:7], v[158:161], v[206:209], v[4:7]
	v_mfma_f32_16x16x32_bf16 v[32:35], v[136:139], v[206:209], v[32:35]
	v_mfma_f32_16x16x32_bf16 v[32:35], v[154:157], v[210:213], v[32:35]
	v_mfma_f32_16x16x32_bf16 v[36:39], v[132:135], v[210:213], v[36:39]
	v_mfma_f32_16x16x32_bf16 v[36:39], v[128:131], v[206:209], v[36:39]
	s_setprio 0
	s_barrier
	s_add_i32 s24, 0, 0x18000
	v_add_u32_e32 v146, s24, v175
	s_add_i32 s25, 0, 0x1c000
	ds_read_b128 v[128:131], v146
	ds_read_b128 v[132:135], v146 offset:1024
	ds_read_b128 v[136:139], v146 offset:2048
	ds_read_b128 v[154:157], v146 offset:3072
	v_add_u32_e32 v146, s25, v175
	ds_read_b128 v[158:161], v146
	ds_read_b128 v[162:165], v146 offset:1024
	ds_read_b128 v[166:169], v146 offset:2048
	ds_read_b128 v[170:173], v146 offset:3072
	s_add_u32 s18, s18, 0x80000
	s_addc_u32 s19, s19, 0
	s_mov_b32 m0, s30
	v_lshl_add_u64 v[222:223], s[18:19], 0, v[144:145]
	ds_read_b128 v[182:185], v180 offset:32768
	ds_read_b128 v[186:189], v180 offset:33792
	ds_read_b128 v[190:193], v180 offset:34816
	ds_read_b128 v[194:197], v180 offset:35840
	ds_read_b128 v[198:201], v180 offset:36864
	ds_read_b128 v[202:205], v180 offset:37888
	ds_read_b128 v[206:209], v180 offset:38912
	ds_read_b128 v[210:213], v180 offset:39936
	global_load_lds_dwordx4 v[222:223], off
	v_lshl_add_u64 v[222:223], s[18:19], 0, v[148:149]
	s_mov_b32 m0, s31
	s_nop 0
	global_load_lds_dwordx4 v[222:223], off
	s_waitcnt vmcnt(8)
	s_waitcnt lgkmcnt(0)
	s_barrier
	s_setprio 1
	s_waitcnt lgkmcnt(0)
	v_mfma_f32_16x16x32_bf16 v[124:127], v[128:131], v[182:185], v[124:127]
	v_mfma_f32_16x16x32_bf16 v[124:127], v[132:135], v[186:189], v[124:127]
	v_mfma_f32_16x16x32_bf16 v[120:123], v[154:157], v[186:189], v[120:123]
	v_mfma_f32_16x16x32_bf16 v[120:123], v[136:139], v[182:185], v[120:123]
	v_mfma_f32_16x16x32_bf16 v[92:95], v[158:161], v[182:185], v[92:95]
	v_mfma_f32_16x16x32_bf16 v[92:95], v[162:165], v[186:189], v[92:95]
	v_mfma_f32_16x16x32_bf16 v[88:91], v[170:173], v[186:189], v[88:91]
	v_mfma_f32_16x16x32_bf16 v[88:91], v[166:169], v[182:185], v[88:91]
	v_mfma_f32_16x16x32_bf16 v[80:83], v[166:169], v[190:193], v[80:83]
	v_mfma_f32_16x16x32_bf16 v[80:83], v[170:173], v[194:197], v[80:83]
	v_mfma_f32_16x16x32_bf16 v[84:87], v[162:165], v[194:197], v[84:87]
	v_mfma_f32_16x16x32_bf16 v[84:87], v[158:161], v[190:193], v[84:87]
	v_mfma_f32_16x16x32_bf16 v[112:115], v[136:139], v[190:193], v[112:115]
	v_mfma_f32_16x16x32_bf16 v[112:115], v[154:157], v[194:197], v[112:115]
	v_mfma_f32_16x16x32_bf16 v[116:119], v[132:135], v[194:197], v[116:119]
	v_mfma_f32_16x16x32_bf16 v[116:119], v[128:131], v[190:193], v[116:119]
	v_mfma_f32_16x16x32_bf16 v[108:111], v[128:131], v[198:201], v[108:111]
	v_mfma_f32_16x16x32_bf16 v[108:111], v[132:135], v[202:205], v[108:111]
	v_mfma_f32_16x16x32_bf16 v[104:107], v[154:157], v[202:205], v[104:107]
	v_mfma_f32_16x16x32_bf16 v[104:107], v[136:139], v[198:201], v[104:107]
	v_mfma_f32_16x16x32_bf16 v[76:79], v[158:161], v[198:201], v[76:79]
	v_mfma_f32_16x16x32_bf16 v[76:79], v[162:165], v[202:205], v[76:79]
	v_mfma_f32_16x16x32_bf16 v[72:75], v[170:173], v[202:205], v[72:75]
	v_mfma_f32_16x16x32_bf16 v[72:75], v[166:169], v[198:201], v[72:75]
	v_mfma_f32_16x16x32_bf16 v[64:67], v[166:169], v[206:209], v[64:67]
	v_mfma_f32_16x16x32_bf16 v[64:67], v[170:173], v[210:213], v[64:67]
	v_mfma_f32_16x16x32_bf16 v[68:71], v[162:165], v[210:213], v[68:71]
	v_mfma_f32_16x16x32_bf16 v[68:71], v[158:161], v[206:209], v[68:71]
	v_mfma_f32_16x16x32_bf16 v[96:99], v[136:139], v[206:209], v[96:99]
	v_mfma_f32_16x16x32_bf16 v[96:99], v[154:157], v[210:213], v[96:99]
	v_mfma_f32_16x16x32_bf16 v[100:103], v[132:135], v[210:213], v[100:103]
	v_mfma_f32_16x16x32_bf16 v[100:103], v[128:131], v[206:209], v[100:103]
	s_setprio 0
	s_barrier
; #define PG8_STAGE(bufoff, gbase, voff) do { _Pragma("unroll") for (int _i = 0; _i < 2; ++_i) \
;         __builtin_amdgcn_global_load_lds((const unsigned*)((const char*)(gbase) + (voff)[_i]), (PG8_LAS unsigned*)(lds + (bufoff) + ldsw + _i * 8192), 16, 0, 0); } while (0)
; #define PG8_LDA(dst, b, h) do { _Pragma("unroll") for (int m = 0; m < 4; ++m) _Pragma("unroll") for (int k = 0; k < 2; ++k) dst[m][k] = *(const PG8_LAS bf16x8*)(lds + PG8_SA(b, h) + aoff + m * 2048 + k * 1024); } while (0)
; #define PG8_MMA(ai, bj, At, Bt) do { __builtin_amdgcn_s_setprio(1); _Pragma("unroll") for (int m = 0; m < 4; ++m) _Pragma("unroll") for (int n = 0; n < 2; ++n) _Pragma("unroll") for (int k = 0; k < 2; ++k) \
;         acc[ai][bj][m][n] = __builtin_amdgcn_mfma_f32_16x16x32_bf16(Bt[n][k], At[m][k], acc[ai][bj][m][n], 0, 0, 0); __builtin_amdgcn_s_setprio(0); } while (0)
; #define PG8_WAIT_V(n) asm volatile("s_waitcnt vmcnt(" #n ")" ::: "memory")
; #define PG8_WAIT_L(n) asm volatile("s_waitcnt lgkmcnt(" #n ")" ::: "memory")
; #define PG8_BAR __builtin_amdgcn_s_barrier()
; #define PG8_SCHED __builtin_amdgcn_sched_barrier(0)
; template <class Epi, class Sched, bool ALIGN_EPI = false, bool SP2 = false, bool APERM = false  >
; __device__ __forceinline__ void gemm_phase(PG8_LAS unsigned char* lds, const Gemm g, const Sched& S, const Epi& E, const int wid  ) {
;     ...
;             PG8_LDA(At, 1, 1); PG8_STAGE(PG8_SB(1, 0), b3, voffB); PG8_STAGE(PG8_SB(1, 1), b3 + hstep, voffB); PG8_STAGE(PG8_SA(1, 0), a3, voffA);
;             PG8_WAIT_V(8); PG8_WAIT_L(0); PG8_BAR; PG8_MMA(1, 0, At, B0); PG8_MMA(1, 1, At, B1); PG8_BAR; PG8_SCHED;
	s_add_i32 s18, s24, s46
	v_lshl_add_u64 v[214:215], v[214:215], 0, s[62:63]
	s_mov_b32 m0, s18
	ds_read_b128 v[182:185], v180 offset:49152
	ds_read_b128 v[186:189], v180 offset:50176
	ds_read_b128 v[190:193], v180 offset:51200
	ds_read_b128 v[194:197], v180 offset:52224
	ds_read_b128 v[198:201], v180 offset:53248
	ds_read_b128 v[202:205], v180 offset:54272
	ds_read_b128 v[206:209], v180 offset:55296
	ds_read_b128 v[210:213], v180 offset:56320
	global_load_lds_dwordx4 v[214:215], off
	s_add_i32 m0, s18, 0x2000
	s_add_u32 s16, s16, 0x80080
	v_lshl_add_u64 v[214:215], v[216:217], 0, s[62:63]
	s_addc_u32 s17, s17, 0
	s_add_i32 s18, s25, s46
	global_load_lds_dwordx4 v[214:215], off
	v_lshl_add_u64 v[214:215], s[16:17], 0, v[140:141]
	s_mov_b32 m0, s18
	s_nop 0
	global_load_lds_dwordx4 v[214:215], off
	v_lshl_add_u64 v[214:215], s[16:17], 0, v[142:143]
	s_add_i32 m0, s18, 0x2000
	s_nop 0
	global_load_lds_dwordx4 v[214:215], off
	v_lshl_add_u64 v[214:215], v[218:219], 0, s[62:63]
	s_mov_b32 m0, s53
	s_nop 0
	global_load_lds_dwordx4 v[214:215], off
	v_lshl_add_u64 v[214:215], v[220:221], 0, s[62:63]
	s_mov_b32 m0, s85
	s_nop 0
	global_load_lds_dwordx4 v[214:215], off
	s_waitcnt vmcnt(8)
	s_waitcnt lgkmcnt(0)
	s_barrier
	s_setprio 1
	s_waitcnt lgkmcnt(0)
	v_mfma_f32_16x16x32_bf16 v[60:63], v[128:131], v[182:185], v[60:63]
	v_mfma_f32_16x16x32_bf16 v[60:63], v[132:135], v[186:189], v[60:63]
	v_mfma_f32_16x16x32_bf16 v[56:59], v[154:157], v[186:189], v[56:59]
	v_mfma_f32_16x16x32_bf16 v[56:59], v[136:139], v[182:185], v[56:59]
	v_mfma_f32_16x16x32_bf16 v[28:31], v[158:161], v[182:185], v[28:31]
	v_mfma_f32_16x16x32_bf16 v[28:31], v[162:165], v[186:189], v[28:31]
	v_mfma_f32_16x16x32_bf16 v[24:27], v[170:173], v[186:189], v[24:27]
	v_mfma_f32_16x16x32_bf16 v[24:27], v[166:169], v[182:185], v[24:27]
	v_mfma_f32_16x16x32_bf16 v[16:19], v[166:169], v[190:193], v[16:19]
	v_mfma_f32_16x16x32_bf16 v[16:19], v[170:173], v[194:197], v[16:19]
	v_mfma_f32_16x16x32_bf16 v[20:23], v[162:165], v[194:197], v[20:23]
	v_mfma_f32_16x16x32_bf16 v[20:23], v[158:161], v[190:193], v[20:23]
	v_mfma_f32_16x16x32_bf16 v[48:51], v[136:139], v[190:193], v[48:51]
	v_mfma_f32_16x16x32_bf16 v[48:51], v[154:157], v[194:197], v[48:51]
	v_mfma_f32_16x16x32_bf16 v[52:55], v[132:135], v[194:197], v[52:55]
	v_mfma_f32_16x16x32_bf16 v[52:55], v[128:131], v[190:193], v[52:55]
	v_mfma_f32_16x16x32_bf16 v[44:47], v[128:131], v[198:201], v[44:47]
	v_mfma_f32_16x16x32_bf16 v[44:47], v[132:135], v[202:205], v[44:47]
	v_mfma_f32_16x16x32_bf16 v[40:43], v[154:157], v[202:205], v[40:43]
	v_mfma_f32_16x16x32_bf16 v[40:43], v[136:139], v[198:201], v[40:43]
	v_mfma_f32_16x16x32_bf16 v[12:15], v[158:161], v[198:201], v[12:15]
	v_mfma_f32_16x16x32_bf16 v[12:15], v[162:165], v[202:205], v[12:15]
	v_mfma_f32_16x16x32_bf16 v[8:11], v[170:173], v[202:205], v[8:11]
	v_mfma_f32_16x16x32_bf16 v[8:11], v[166:169], v[198:201], v[8:11]
	v_mfma_f32_16x16x32_bf16 v[0:3], v[166:169], v[206:209], v[0:3]
	v_mfma_f32_16x16x32_bf16 v[0:3], v[170:173], v[210:213], v[0:3]
	v_mfma_f32_16x16x32_bf16 v[4:7], v[162:165], v[210:213], v[4:7]
	v_mfma_f32_16x16x32_bf16 v[4:7], v[158:161], v[206:209], v[4:7]
	v_mfma_f32_16x16x32_bf16 v[32:35], v[136:139], v[206:209], v[32:35]
	v_mfma_f32_16x16x32_bf16 v[32:35], v[154:157], v[210:213], v[32:35]
	v_mfma_f32_16x16x32_bf16 v[36:39], v[132:135], v[210:213], v[36:39]
	v_mfma_f32_16x16x32_bf16 v[36:39], v[128:131], v[206:209], v[36:39]
	s_setprio 0
	s_barrier
	s_add_i32 s16, s71, 2
	s_cmp_gt_u32 s71, 29
	s_cbranch_scc1 .LBB0_717
	s_mov_b32 s71, s16
	s_branch .LBB0_698

; #define PG8_STAGE(bufoff, gbase, voff) do { _Pragma("unroll") for (int _i = 0; _i < 2; ++_i) \
;         __builtin_amdgcn_global_load_lds((const unsigned*)((const char*)(gbase) + (voff)[_i]), (PG8_LAS unsigned*)(lds + (bufoff) + ldsw + _i * 8192), 16, 0, 0); } while (0)
; #define PG8_LDA(dst, b, h) do { _Pragma("unroll") for (int m = 0; m < 4; ++m) _Pragma("unroll") for (int k = 0; k < 2; ++k) dst[m][k] = *(const PG8_LAS bf16x8*)(lds + PG8_SA(b, h) + aoff + m * 2048 + k * 1024); } while (0)
; #define PG8_LDB(dst, b, h) do { _Pragma("unroll") for (int n = 0; n < 2; ++n) _Pragma("unroll") for (int k = 0; k < 2; ++k) dst[n][k] = *(const PG8_LAS bf16x8*)(lds + PG8_SB(b, h) + boff + n * 2048 + k * 1024); } while (0)
; #define PG8_MMA(ai, bj, At, Bt) do { __builtin_amdgcn_s_setprio(1); _Pragma("unroll") for (int m = 0; m < 4; ++m) _Pragma("unroll") for (int n = 0; n < 2; ++n) _Pragma("unroll") for (int k = 0; k < 2; ++k) \
;         acc[ai][bj][m][n] = __builtin_amdgcn_mfma_f32_16x16x32_bf16(Bt[n][k], At[m][k], acc[ai][bj][m][n], 0, 0, 0); __builtin_amdgcn_s_setprio(0); } while (0)
; #define PG8_WAIT_V(n) asm volatile("s_waitcnt vmcnt(" #n ")" ::: "memory")
; #define PG8_WAIT_L(n) asm volatile("s_waitcnt lgkmcnt(" #n ")" ::: "memory")
; #define PG8_BAR __builtin_amdgcn_s_barrier()
; #define PG8_SCHED __builtin_amdgcn_sched_barrier(0)
; template <class Epi, class Sched, bool ALIGN_EPI = false, bool SP2 = false, bool APERM = false  >
; __device__ __forceinline__ void gemm_phase(PG8_LAS unsigned char* lds, const Gemm g, const Sched& S, const Epi& E, const int wid  ) {
;     ...
;             const bool last = (t == nt - 2);
;             const char* a1 = cA + (size_t)(t + 1) * kstep;
;             const char* a2 = last ? nA : cA + (size_t)(t + 2) * kstep; const char* b2 = last ? nB : cB + (size_t)(t + 2) * kstep;
;             const char* a3 = a2 + kstep; const char* b3 = b2 + kstep;
;             if (last && has_next) S.a_ready(nxt);
;             if constexpr (SP2) {
;             PG8_LDB(B0, 0, 0); PG8_LDB(B1, 0, 1); PG8_SCHED; PG8_LDA(At, 0, 0); PG8_STAGE(PG8_SA(1, 1), a1 + hstep, voffA);
;             PG8_WAIT_V(8); PG8_WAIT_L(0); PG8_BAR; PG8_MMA(0, 0, At, B0); PG8_MMA(0, 1, At, B1); PG8_BAR; PG8_SCHED;
;             PG8_LDA(At, 0, 1); PG8_STAGE(PG8_SB(0, 0), b2, voffB); PG8_STAGE(PG8_SB(0, 1), b2 + hstep, voffB); PG8_STAGE(PG8_SA(0, 0), a2, voffA);
.LBB0_793:
	s_lshl_b32 s19, s74, 7
	s_add_u32 s24, s60, s19
	s_addc_u32 s25, s61, 0
	s_add_u32 s16, s24, 0x100
	v_add_u32_e32 v138, s55, v160
	s_addc_u32 s17, s25, 0
	s_waitcnt lgkmcnt(0)
	ds_read_b128 v[128:131], v138
	ds_read_b128 v[146:149], v138 offset:1024
	ds_read_b128 v[150:153], v138 offset:2048
	ds_read_b128 v[154:157], v138 offset:3072
	v_add_u32_e32 v138, s84, v160
	s_and_b64 s[0:1], s[6:7], exec
	ds_read_b128 v[168:171], v138
	ds_read_b128 v[172:175], v138 offset:1024
	ds_read_b128 v[176:179], v138 offset:2048
	ds_read_b128 v[180:183], v138 offset:3072
	s_cselect_b32 s17, s33, s17
	s_cselect_b32 s16, s52, s16
	s_add_u32 s0, s56, s19
	s_addc_u32 s1, s57, 0
	s_add_u32 s19, s0, 0x100
	s_addc_u32 s75, s1, 0
	s_and_b64 s[0:1], s[6:7], exec
	s_cselect_b32 s0, s65, s19
	s_cselect_b32 s1, s64, s75
	s_add_u32 s6, s24, 0x80080
	s_addc_u32 s7, s25, 0
	v_lshl_add_u64 v[216:217], s[6:7], 0, v[136:137]
	s_add_i32 m0, s15, 0xc000
	ds_read_b128 v[184:187], v165
	ds_read_b128 v[188:191], v165 offset:1024
	ds_read_b128 v[192:195], v165 offset:2048
	ds_read_b128 v[196:199], v165 offset:3072
	ds_read_b128 v[200:203], v165 offset:4096
	ds_read_b128 v[204:207], v165 offset:5120
	ds_read_b128 v[208:211], v165 offset:6144
	ds_read_b128 v[212:215], v165 offset:7168
	global_load_lds_dwordx4 v[216:217], off
	v_lshl_add_u64 v[216:217], s[6:7], 0, v[140:141]
	s_add_i32 m0, s15, 0xe000
	s_nop 0
	global_load_lds_dwordx4 v[216:217], off
	s_waitcnt vmcnt(8)
	s_waitcnt lgkmcnt(0)
	s_barrier
	s_setprio 1
	s_waitcnt lgkmcnt(0)
	v_mfma_f32_16x16x32_bf16 v[124:127], v[128:131], v[184:187], v[124:127]
	v_mfma_f32_16x16x32_bf16 v[124:127], v[146:149], v[188:191], v[124:127]
	v_mfma_f32_16x16x32_bf16 v[120:123], v[154:157], v[188:191], v[120:123]
	v_mfma_f32_16x16x32_bf16 v[120:123], v[150:153], v[184:187], v[120:123]
	v_mfma_f32_16x16x32_bf16 v[92:95], v[168:171], v[184:187], v[92:95]
	v_mfma_f32_16x16x32_bf16 v[92:95], v[172:175], v[188:191], v[92:95]
	v_mfma_f32_16x16x32_bf16 v[88:91], v[180:183], v[188:191], v[88:91]
	v_mfma_f32_16x16x32_bf16 v[88:91], v[176:179], v[184:187], v[88:91]
	v_mfma_f32_16x16x32_bf16 v[80:83], v[176:179], v[192:195], v[80:83]
	v_mfma_f32_16x16x32_bf16 v[80:83], v[180:183], v[196:199], v[80:83]
	v_mfma_f32_16x16x32_bf16 v[84:87], v[172:175], v[196:199], v[84:87]
	v_mfma_f32_16x16x32_bf16 v[84:87], v[168:171], v[192:195], v[84:87]
	v_mfma_f32_16x16x32_bf16 v[112:115], v[150:153], v[192:195], v[112:115]
	v_mfma_f32_16x16x32_bf16 v[112:115], v[154:157], v[196:199], v[112:115]
	v_mfma_f32_16x16x32_bf16 v[116:119], v[146:149], v[196:199], v[116:119]
	v_mfma_f32_16x16x32_bf16 v[116:119], v[128:131], v[192:195], v[116:119]
	v_mfma_f32_16x16x32_bf16 v[108:111], v[128:131], v[200:203], v[108:111]
	v_mfma_f32_16x16x32_bf16 v[108:111], v[146:149], v[204:207], v[108:111]
	v_mfma_f32_16x16x32_bf16 v[104:107], v[154:157], v[204:207], v[104:107]
	v_mfma_f32_16x16x32_bf16 v[104:107], v[150:153], v[200:203], v[104:107]
	v_mfma_f32_16x16x32_bf16 v[76:79], v[168:171], v[200:203], v[76:79]
	v_mfma_f32_16x16x32_bf16 v[76:79], v[172:175], v[204:207], v[76:79]
	v_mfma_f32_16x16x32_bf16 v[72:75], v[180:183], v[204:207], v[72:75]
	v_mfma_f32_16x16x32_bf16 v[72:75], v[176:179], v[200:203], v[72:75]
	v_mfma_f32_16x16x32_bf16 v[64:67], v[176:179], v[208:211], v[64:67]
	v_mfma_f32_16x16x32_bf16 v[64:67], v[180:183], v[212:215], v[64:67]
	v_mfma_f32_16x16x32_bf16 v[68:71], v[172:175], v[212:215], v[68:71]
	v_mfma_f32_16x16x32_bf16 v[68:71], v[168:171], v[208:211], v[68:71]
	v_mfma_f32_16x16x32_bf16 v[96:99], v[150:153], v[208:211], v[96:99]
	v_mfma_f32_16x16x32_bf16 v[96:99], v[154:157], v[212:215], v[96:99]
	v_mfma_f32_16x16x32_bf16 v[100:103], v[146:149], v[212:215], v[100:103]
	v_mfma_f32_16x16x32_bf16 v[100:103], v[128:131], v[208:211], v[100:103]
	s_setprio 0
	s_barrier
	s_add_i32 s6, s55, s29
	v_lshl_add_u64 v[216:217], s[0:1], 0, v[132:133]
	s_mov_b32 m0, s6
	ds_read_b128 v[184:187], v165 offset:16384
	ds_read_b128 v[188:191], v165 offset:17408
	ds_read_b128 v[192:195], v165 offset:18432
	ds_read_b128 v[196:199], v165 offset:19456
	ds_read_b128 v[200:203], v165 offset:20480
	ds_read_b128 v[204:207], v165 offset:21504
	ds_read_b128 v[208:211], v165 offset:22528
	ds_read_b128 v[212:215], v165 offset:23552
	global_load_lds_dwordx4 v[216:217], off
	s_add_i32 m0, s6, 0x2000
	s_add_u32 s6, s0, 0x80000
	v_lshl_add_u64 v[218:219], s[0:1], 0, v[134:135]
	s_addc_u32 s7, s1, 0
	s_add_i32 s19, s84, s29
	global_load_lds_dwordx4 v[218:219], off
	v_lshl_add_u64 v[220:221], s[6:7], 0, v[132:133]
	s_mov_b32 m0, s19
	v_lshl_add_u64 v[222:223], s[16:17], 0, v[140:141]
	global_load_lds_dwordx4 v[220:221], off
	v_lshl_add_u64 v[220:221], s[6:7], 0, v[134:135]
	s_add_i32 m0, s19, 0x2000
	s_nop 0
	global_load_lds_dwordx4 v[220:221], off
	v_lshl_add_u64 v[220:221], s[16:17], 0, v[136:137]
	s_mov_b32 m0, s15
	s_nop 0
	global_load_lds_dwordx4 v[220:221], off
	s_mov_b32 m0, s30
	s_nop 0
	global_load_lds_dwordx4 v[222:223], off
	s_waitcnt vmcnt(8)
	s_waitcnt lgkmcnt(0)
	s_barrier
; #define PG8_STAGE(bufoff, gbase, voff) do { _Pragma("unroll") for (int _i = 0; _i < 2; ++_i) \
;         __builtin_amdgcn_global_load_lds((const unsigned*)((const char*)(gbase) + (voff)[_i]), (PG8_LAS unsigned*)(lds + (bufoff) + ldsw + _i * 8192), 16, 0, 0); } while (0)
; #define PG8_LDA(dst, b, h) do { _Pragma("unroll") for (int m = 0; m < 4; ++m) _Pragma("unroll") for (int k = 0; k < 2; ++k) dst[m][k] = *(const PG8_LAS bf16x8*)(lds + PG8_SA(b, h) + aoff + m * 2048 + k * 1024); } while (0)
; #define PG8_LDB(dst, b, h) do { _Pragma("unroll") for (int n = 0; n < 2; ++n) _Pragma("unroll") for (int k = 0; k < 2; ++k) dst[n][k] = *(const PG8_LAS bf16x8*)(lds + PG8_SB(b, h) + boff + n * 2048 + k * 1024); } while (0)
; #define PG8_MMA(ai, bj, At, Bt) do { __builtin_amdgcn_s_setprio(1); _Pragma("unroll") for (int m = 0; m < 4; ++m) _Pragma("unroll") for (int n = 0; n < 2; ++n) _Pragma("unroll") for (int k = 0; k < 2; ++k) \
;         acc[ai][bj][m][n] = __builtin_amdgcn_mfma_f32_16x16x32_bf16(Bt[n][k], At[m][k], acc[ai][bj][m][n], 0, 0, 0); __builtin_amdgcn_s_setprio(0); } while (0)
; #define PG8_WAIT_V(n) asm volatile("s_waitcnt vmcnt(" #n ")" ::: "memory")
; #define PG8_WAIT_L(n) asm volatile("s_waitcnt lgkmcnt(" #n ")" ::: "memory")
; #define PG8_BAR __builtin_amdgcn_s_barrier()
; #define PG8_SCHED __builtin_amdgcn_sched_barrier(0)
; template <class Epi, class Sched, bool ALIGN_EPI = false, bool SP2 = false, bool APERM = false  >
; __device__ __forceinline__ void gemm_phase(PG8_LAS unsigned char* lds, const Gemm g, const Sched& S, const Epi& E, const int wid  ) {
;     ...
;             PG8_WAIT_V(8); PG8_WAIT_L(0); PG8_BAR; PG8_MMA(1, 0, At, B0); PG8_MMA(1, 1, At, B1); PG8_BAR; PG8_SCHED;
;             PG8_LDB(B0, 1, 0); PG8_LDB(B1, 1, 1); PG8_SCHED; PG8_LDA(At, 1, 0); PG8_STAGE(PG8_SA(0, 1), a2 + hstep, voffA);
;             PG8_WAIT_V(8); PG8_WAIT_L(0); PG8_BAR; PG8_MMA(0, 0, At, B0); PG8_MMA(0, 1, At, B1); PG8_BAR; PG8_SCHED;
	s_setprio 1
	s_waitcnt lgkmcnt(0)
	v_mfma_f32_16x16x32_bf16 v[60:63], v[128:131], v[184:187], v[60:63]
	v_mfma_f32_16x16x32_bf16 v[60:63], v[146:149], v[188:191], v[60:63]
	v_mfma_f32_16x16x32_bf16 v[56:59], v[154:157], v[188:191], v[56:59]
	v_mfma_f32_16x16x32_bf16 v[56:59], v[150:153], v[184:187], v[56:59]
	v_mfma_f32_16x16x32_bf16 v[28:31], v[168:171], v[184:187], v[28:31]
	v_mfma_f32_16x16x32_bf16 v[28:31], v[172:175], v[188:191], v[28:31]
	v_mfma_f32_16x16x32_bf16 v[24:27], v[180:183], v[188:191], v[24:27]
	v_mfma_f32_16x16x32_bf16 v[24:27], v[176:179], v[184:187], v[24:27]
	v_mfma_f32_16x16x32_bf16 v[16:19], v[176:179], v[192:195], v[16:19]
	v_mfma_f32_16x16x32_bf16 v[16:19], v[180:183], v[196:199], v[16:19]
	v_mfma_f32_16x16x32_bf16 v[20:23], v[172:175], v[196:199], v[20:23]
	v_mfma_f32_16x16x32_bf16 v[20:23], v[168:171], v[192:195], v[20:23]
	v_mfma_f32_16x16x32_bf16 v[48:51], v[150:153], v[192:195], v[48:51]
	v_mfma_f32_16x16x32_bf16 v[48:51], v[154:157], v[196:199], v[48:51]
	v_mfma_f32_16x16x32_bf16 v[52:55], v[146:149], v[196:199], v[52:55]
	v_mfma_f32_16x16x32_bf16 v[52:55], v[128:131], v[192:195], v[52:55]
	v_mfma_f32_16x16x32_bf16 v[44:47], v[128:131], v[200:203], v[44:47]
	v_mfma_f32_16x16x32_bf16 v[44:47], v[146:149], v[204:207], v[44:47]
	v_mfma_f32_16x16x32_bf16 v[40:43], v[154:157], v[204:207], v[40:43]
	v_mfma_f32_16x16x32_bf16 v[40:43], v[150:153], v[200:203], v[40:43]
	v_mfma_f32_16x16x32_bf16 v[12:15], v[168:171], v[200:203], v[12:15]
	v_mfma_f32_16x16x32_bf16 v[12:15], v[172:175], v[204:207], v[12:15]
	v_mfma_f32_16x16x32_bf16 v[8:11], v[180:183], v[204:207], v[8:11]
	v_mfma_f32_16x16x32_bf16 v[8:11], v[176:179], v[200:203], v[8:11]
	v_mfma_f32_16x16x32_bf16 v[0:3], v[176:179], v[208:211], v[0:3]
	v_mfma_f32_16x16x32_bf16 v[0:3], v[180:183], v[212:215], v[0:3]
	v_mfma_f32_16x16x32_bf16 v[4:7], v[172:175], v[212:215], v[4:7]
	v_mfma_f32_16x16x32_bf16 v[4:7], v[168:171], v[208:211], v[4:7]
	v_mfma_f32_16x16x32_bf16 v[32:35], v[150:153], v[208:211], v[32:35]
	v_mfma_f32_16x16x32_bf16 v[32:35], v[154:157], v[212:215], v[32:35]
	v_mfma_f32_16x16x32_bf16 v[36:39], v[146:149], v[212:215], v[36:39]
	v_mfma_f32_16x16x32_bf16 v[36:39], v[128:131], v[208:211], v[36:39]
	s_setprio 0
	s_barrier
	s_add_i32 s19, 0, 0x18000
	v_add_u32_e32 v138, s19, v160
	s_add_i32 s24, 0, 0x1c000
	ds_read_b128 v[128:131], v138
	ds_read_b128 v[146:149], v138 offset:1024
	ds_read_b128 v[150:153], v138 offset:2048
	ds_read_b128 v[154:157], v138 offset:3072
	v_add_u32_e32 v138, s24, v160
	ds_read_b128 v[168:171], v138
	ds_read_b128 v[172:175], v138 offset:1024
	ds_read_b128 v[176:179], v138 offset:2048
	ds_read_b128 v[180:183], v138 offset:3072
	s_add_u32 s6, s16, 0x80000
	s_addc_u32 s7, s17, 0
	s_mov_b32 m0, s31
	v_lshl_add_u64 v[224:225], s[6:7], 0, v[136:137]
	ds_read_b128 v[184:187], v165 offset:32768
	ds_read_b128 v[188:191], v165 offset:33792
	ds_read_b128 v[192:195], v165 offset:34816
	ds_read_b128 v[196:199], v165 offset:35840
	ds_read_b128 v[200:203], v165 offset:36864
	ds_read_b128 v[204:207], v165 offset:37888
	ds_read_b128 v[208:211], v165 offset:38912
	ds_read_b128 v[212:215], v165 offset:39936
	global_load_lds_dwordx4 v[224:225], off
	v_lshl_add_u64 v[224:225], s[6:7], 0, v[140:141]
	s_mov_b32 m0, s34
	s_nop 0
	global_load_lds_dwordx4 v[224:225], off
	s_waitcnt vmcnt(8)
	s_waitcnt lgkmcnt(0)
	s_barrier
	s_setprio 1
	s_waitcnt lgkmcnt(0)
	v_mfma_f32_16x16x32_bf16 v[124:127], v[128:131], v[184:187], v[124:127]
	v_mfma_f32_16x16x32_bf16 v[124:127], v[146:149], v[188:191], v[124:127]
	v_mfma_f32_16x16x32_bf16 v[120:123], v[154:157], v[188:191], v[120:123]
	v_mfma_f32_16x16x32_bf16 v[120:123], v[150:153], v[184:187], v[120:123]
	v_mfma_f32_16x16x32_bf16 v[92:95], v[168:171], v[184:187], v[92:95]
	v_mfma_f32_16x16x32_bf16 v[92:95], v[172:175], v[188:191], v[92:95]
	v_mfma_f32_16x16x32_bf16 v[88:91], v[180:183], v[188:191], v[88:91]
	v_mfma_f32_16x16x32_bf16 v[88:91], v[176:179], v[184:187], v[88:91]
	v_mfma_f32_16x16x32_bf16 v[80:83], v[176:179], v[192:195], v[80:83]
	v_mfma_f32_16x16x32_bf16 v[80:83], v[180:183], v[196:199], v[80:83]
	v_mfma_f32_16x16x32_bf16 v[84:87], v[172:175], v[196:199], v[84:87]
	v_mfma_f32_16x16x32_bf16 v[84:87], v[168:171], v[192:195], v[84:87]
	v_mfma_f32_16x16x32_bf16 v[112:115], v[150:153], v[192:195], v[112:115]
	v_mfma_f32_16x16x32_bf16 v[112:115], v[154:157], v[196:199], v[112:115]
	v_mfma_f32_16x16x32_bf16 v[116:119], v[146:149], v[196:199], v[116:119]
	v_mfma_f32_16x16x32_bf16 v[116:119], v[128:131], v[192:195], v[116:119]
	v_mfma_f32_16x16x32_bf16 v[108:111], v[128:131], v[200:203], v[108:111]
	v_mfma_f32_16x16x32_bf16 v[108:111], v[146:149], v[204:207], v[108:111]
	v_mfma_f32_16x16x32_bf16 v[104:107], v[154:157], v[204:207], v[104:107]
	v_mfma_f32_16x16x32_bf16 v[104:107], v[150:153], v[200:203], v[104:107]
	v_mfma_f32_16x16x32_bf16 v[76:79], v[168:171], v[200:203], v[76:79]
	v_mfma_f32_16x16x32_bf16 v[76:79], v[172:175], v[204:207], v[76:79]
	v_mfma_f32_16x16x32_bf16 v[72:75], v[180:183], v[204:207], v[72:75]
	v_mfma_f32_16x16x32_bf16 v[72:75], v[176:179], v[200:203], v[72:75]
	v_mfma_f32_16x16x32_bf16 v[64:67], v[176:179], v[208:211], v[64:67]
	v_mfma_f32_16x16x32_bf16 v[64:67], v[180:183], v[212:215], v[64:67]
	v_mfma_f32_16x16x32_bf16 v[68:71], v[172:175], v[212:215], v[68:71]
	v_mfma_f32_16x16x32_bf16 v[68:71], v[168:171], v[208:211], v[68:71]
	v_mfma_f32_16x16x32_bf16 v[96:99], v[150:153], v[208:211], v[96:99]
	v_mfma_f32_16x16x32_bf16 v[96:99], v[154:157], v[212:215], v[96:99]
	v_mfma_f32_16x16x32_bf16 v[100:103], v[146:149], v[212:215], v[100:103]
	v_mfma_f32_16x16x32_bf16 v[100:103], v[128:131], v[208:211], v[100:103]
	s_setprio 0
	s_barrier
; #define PG8_STAGE(bufoff, gbase, voff) do { _Pragma("unroll") for (int _i = 0; _i < 2; ++_i) \
;         __builtin_amdgcn_global_load_lds((const unsigned*)((const char*)(gbase) + (voff)[_i]), (PG8_LAS unsigned*)(lds + (bufoff) + ldsw + _i * 8192), 16, 0, 0); } while (0)
; #define PG8_LDA(dst, b, h) do { _Pragma("unroll") for (int m = 0; m < 4; ++m) _Pragma("unroll") for (int k = 0; k < 2; ++k) dst[m][k] = *(const PG8_LAS bf16x8*)(lds + PG8_SA(b, h) + aoff + m * 2048 + k * 1024); } while (0)
; #define PG8_MMA(ai, bj, At, Bt) do { __builtin_amdgcn_s_setprio(1); _Pragma("unroll") for (int m = 0; m < 4; ++m) _Pragma("unroll") for (int n = 0; n < 2; ++n) _Pragma("unroll") for (int k = 0; k < 2; ++k) \
;         acc[ai][bj][m][n] = __builtin_amdgcn_mfma_f32_16x16x32_bf16(Bt[n][k], At[m][k], acc[ai][bj][m][n], 0, 0, 0); __builtin_amdgcn_s_setprio(0); } while (0)
; #define PG8_WAIT_V(n) asm volatile("s_waitcnt vmcnt(" #n ")" ::: "memory")
; #define PG8_WAIT_L(n) asm volatile("s_waitcnt lgkmcnt(" #n ")" ::: "memory")
; #define PG8_BAR __builtin_amdgcn_s_barrier()
; #define PG8_SCHED __builtin_amdgcn_sched_barrier(0)
; template <class Epi, class Sched, bool ALIGN_EPI = false, bool SP2 = false, bool APERM = false  >
; __device__ __forceinline__ void gemm_phase(PG8_LAS unsigned char* lds, const Gemm g, const Sched& S, const Epi& E, const int wid  ) {
;     ...
;             PG8_LDA(At, 1, 1); PG8_STAGE(PG8_SB(1, 0), b3, voffB); PG8_STAGE(PG8_SB(1, 1), b3 + hstep, voffB); PG8_STAGE(PG8_SA(1, 0), a3, voffA);
;             PG8_WAIT_V(8); PG8_WAIT_L(0); PG8_BAR; PG8_MMA(1, 0, At, B0); PG8_MMA(1, 1, At, B1); PG8_BAR; PG8_SCHED;
	s_add_i32 s6, s19, s29
	v_lshl_add_u64 v[216:217], v[216:217], 0, s[70:71]
	s_mov_b32 m0, s6
	ds_read_b128 v[184:187], v165 offset:49152
	ds_read_b128 v[188:191], v165 offset:50176
	ds_read_b128 v[192:195], v165 offset:51200
	ds_read_b128 v[196:199], v165 offset:52224
	ds_read_b128 v[200:203], v165 offset:53248
	ds_read_b128 v[204:207], v165 offset:54272
	ds_read_b128 v[208:211], v165 offset:55296
	ds_read_b128 v[212:215], v165 offset:56320
	global_load_lds_dwordx4 v[216:217], off
	s_add_i32 m0, s6, 0x2000
	s_add_u32 s0, s0, 0x80080
	v_lshl_add_u64 v[216:217], v[218:219], 0, s[70:71]
	s_addc_u32 s1, s1, 0
	s_add_i32 s6, s24, s29
	global_load_lds_dwordx4 v[216:217], off
	v_lshl_add_u64 v[216:217], s[0:1], 0, v[132:133]
	s_mov_b32 m0, s6
	s_nop 0
	global_load_lds_dwordx4 v[216:217], off
	v_lshl_add_u64 v[216:217], s[0:1], 0, v[134:135]
	s_add_i32 m0, s6, 0x2000
	s_nop 0
	global_load_lds_dwordx4 v[216:217], off
	v_lshl_add_u64 v[216:217], v[220:221], 0, s[70:71]
	s_mov_b32 m0, s35
	s_nop 0
	global_load_lds_dwordx4 v[216:217], off
	v_lshl_add_u64 v[216:217], v[222:223], 0, s[70:71]
	s_mov_b32 m0, s47
	s_nop 0
	global_load_lds_dwordx4 v[216:217], off
	s_waitcnt vmcnt(8)
	s_waitcnt lgkmcnt(0)
	s_barrier
	s_setprio 1
	s_waitcnt lgkmcnt(0)
	v_mfma_f32_16x16x32_bf16 v[60:63], v[128:131], v[184:187], v[60:63]
	v_mfma_f32_16x16x32_bf16 v[60:63], v[146:149], v[188:191], v[60:63]
	v_mfma_f32_16x16x32_bf16 v[56:59], v[154:157], v[188:191], v[56:59]
	v_mfma_f32_16x16x32_bf16 v[56:59], v[150:153], v[184:187], v[56:59]
	v_mfma_f32_16x16x32_bf16 v[28:31], v[168:171], v[184:187], v[28:31]
	v_mfma_f32_16x16x32_bf16 v[28:31], v[172:175], v[188:191], v[28:31]
	v_mfma_f32_16x16x32_bf16 v[24:27], v[180:183], v[188:191], v[24:27]
	v_mfma_f32_16x16x32_bf16 v[24:27], v[176:179], v[184:187], v[24:27]
	v_mfma_f32_16x16x32_bf16 v[16:19], v[176:179], v[192:195], v[16:19]
	v_mfma_f32_16x16x32_bf16 v[16:19], v[180:183], v[196:199], v[16:19]
	v_mfma_f32_16x16x32_bf16 v[20:23], v[172:175], v[196:199], v[20:23]
	v_mfma_f32_16x16x32_bf16 v[20:23], v[168:171], v[192:195], v[20:23]
	v_mfma_f32_16x16x32_bf16 v[48:51], v[150:153], v[192:195], v[48:51]
	v_mfma_f32_16x16x32_bf16 v[48:51], v[154:157], v[196:199], v[48:51]
	v_mfma_f32_16x16x32_bf16 v[52:55], v[146:149], v[196:199], v[52:55]
	v_mfma_f32_16x16x32_bf16 v[52:55], v[128:131], v[192:195], v[52:55]
	v_mfma_f32_16x16x32_bf16 v[44:47], v[128:131], v[200:203], v[44:47]
	v_mfma_f32_16x16x32_bf16 v[44:47], v[146:149], v[204:207], v[44:47]
	v_mfma_f32_16x16x32_bf16 v[40:43], v[154:157], v[204:207], v[40:43]
	v_mfma_f32_16x16x32_bf16 v[40:43], v[150:153], v[200:203], v[40:43]
	v_mfma_f32_16x16x32_bf16 v[12:15], v[168:171], v[200:203], v[12:15]
	v_mfma_f32_16x16x32_bf16 v[12:15], v[172:175], v[204:207], v[12:15]
	v_mfma_f32_16x16x32_bf16 v[8:11], v[180:183], v[204:207], v[8:11]
	v_mfma_f32_16x16x32_bf16 v[8:11], v[176:179], v[200:203], v[8:11]
	v_mfma_f32_16x16x32_bf16 v[0:3], v[176:179], v[208:211], v[0:3]
	v_mfma_f32_16x16x32_bf16 v[0:3], v[180:183], v[212:215], v[0:3]
	v_mfma_f32_16x16x32_bf16 v[4:7], v[172:175], v[212:215], v[4:7]
	v_mfma_f32_16x16x32_bf16 v[4:7], v[168:171], v[208:211], v[4:7]
	v_mfma_f32_16x16x32_bf16 v[32:35], v[150:153], v[208:211], v[32:35]
	v_mfma_f32_16x16x32_bf16 v[32:35], v[154:157], v[212:215], v[32:35]
	v_mfma_f32_16x16x32_bf16 v[36:39], v[146:149], v[212:215], v[36:39]
	v_mfma_f32_16x16x32_bf16 v[36:39], v[128:131], v[208:211], v[36:39]
	s_setprio 0
	s_barrier
	s_add_i32 s0, s74, 2
	s_cmp_gt_u32 s74, 29
	s_cbranch_scc1 .LBB0_795
	s_mov_b32 s74, s0
	s_branch .LBB0_771

; #define PG8_STAGE(bufoff, gbase, voff) do { _Pragma("unroll") for (int _i = 0; _i < 2; ++_i) \
;         __builtin_amdgcn_global_load_lds((const unsigned*)((const char*)(gbase) + (voff)[_i]), (PG8_LAS unsigned*)(lds + (bufoff) + ldsw + _i * 8192), 16, 0, 0); } while (0)
; #define PG8_LDA(dst, b, h) do { _Pragma("unroll") for (int m = 0; m < 4; ++m) _Pragma("unroll") for (int k = 0; k < 2; ++k) dst[m][k] = *(const PG8_LAS bf16x8*)(lds + PG8_SA(b, h) + aoff + m * 2048 + k * 1024); } while (0)
; #define PG8_LDB(dst, b, h) do { _Pragma("unroll") for (int n = 0; n < 2; ++n) _Pragma("unroll") for (int k = 0; k < 2; ++k) dst[n][k] = *(const PG8_LAS bf16x8*)(lds + PG8_SB(b, h) + boff + n * 2048 + k * 1024); } while (0)
; #define PG8_MMA(ai, bj, At, Bt) do { __builtin_amdgcn_s_setprio(1); _Pragma("unroll") for (int m = 0; m < 4; ++m) _Pragma("unroll") for (int n = 0; n < 2; ++n) _Pragma("unroll") for (int k = 0; k < 2; ++k) \
;         acc[ai][bj][m][n] = __builtin_amdgcn_mfma_f32_16x16x32_bf16(Bt[n][k], At[m][k], acc[ai][bj][m][n], 0, 0, 0); __builtin_amdgcn_s_setprio(0); } while (0)
; #define PG8_WAIT_V(n) asm volatile("s_waitcnt vmcnt(" #n ")" ::: "memory")
; #define PG8_WAIT_L(n) asm volatile("s_waitcnt lgkmcnt(" #n ")" ::: "memory")
; #define PG8_BAR __builtin_amdgcn_s_barrier()
; #define PG8_SCHED __builtin_amdgcn_sched_barrier(0)
; template <class Epi, class Sched, bool ALIGN_EPI = false, bool SP2 = false, bool APERM = false  >
; __device__ __forceinline__ void gemm_phase(PG8_LAS unsigned char* lds, const Gemm g, const Sched& S, const Epi& E, const int wid  ) {
;     ...
;             const bool last = (t == nt - 2);
;             const char* a1 = cA + (size_t)(t + 1) * kstep;
;             const char* a2 = last ? nA : cA + (size_t)(t + 2) * kstep; const char* b2 = last ? nB : cB + (size_t)(t + 2) * kstep;
;             const char* a3 = a2 + kstep; const char* b3 = b2 + kstep;
;             if (last && has_next) S.a_ready(nxt);
;             if constexpr (SP2) {
;             PG8_LDB(B0, 0, 0); PG8_LDB(B1, 0, 1); PG8_SCHED; PG8_LDA(At, 0, 0); PG8_STAGE(PG8_SA(1, 1), a1 + hstep, voffA);
;             PG8_WAIT_V(8); PG8_WAIT_L(0); PG8_BAR; PG8_MMA(0, 0, At, B0); PG8_MMA(0, 1, At, B1); PG8_BAR; PG8_SCHED;
;             PG8_LDA(At, 0, 1); PG8_STAGE(PG8_SB(0, 0), b2, voffB); PG8_STAGE(PG8_SB(0, 1), b2 + hstep, voffB); PG8_STAGE(PG8_SA(0, 0), a2, voffA);
.LBB0_1019:
	v_add_u32_e32 v157, s92, v151
	ds_read_b128 v[146:149], v157
	ds_read_b128 v[158:161], v157 offset:1024
	ds_read_b128 v[162:165], v157 offset:2048
	ds_read_b128 v[166:169], v157 offset:3072
	v_add_u32_e32 v157, s93, v151
	s_add_u32 s65, s34, s78
	ds_read_b128 v[170:173], v157
	ds_read_b128 v[174:177], v157 offset:1024
	ds_read_b128 v[178:181], v157 offset:2048
	ds_read_b128 v[182:185], v157 offset:3072
	s_addc_u32 s73, s35, s79
	s_add_u32 s65, s65, 0x100
	s_addc_u32 s73, s73, 0
	s_add_u32 s80, s96, s78
	s_addc_u32 s81, s97, s79
	s_cmpk_eq_i32 s78, 0xf00
	s_cselect_b32 s83, s29, s73
	s_cselect_b32 s82, s33, s65
	s_cselect_b32 s81, s46, s81
	s_cselect_b32 s80, s47, s80
	v_lshl_add_u64 v[218:219], v[142:143], 0, s[78:79]
	s_add_i32 m0, s7, 0xc000
	ds_read_b128 v[186:189], v156
	ds_read_b128 v[190:193], v156 offset:1024
	ds_read_b128 v[194:197], v156 offset:2048
	ds_read_b128 v[198:201], v156 offset:3072
	ds_read_b128 v[202:205], v156 offset:4096
	ds_read_b128 v[206:209], v156 offset:5120
	ds_read_b128 v[210:213], v156 offset:6144
	ds_read_b128 v[214:217], v156 offset:7168
	global_load_lds_dwordx4 v[218:219], off
	v_lshl_add_u64 v[218:219], v[144:145], 0, s[78:79]
	s_add_i32 m0, s7, 0xe000
	s_nop 0
	global_load_lds_dwordx4 v[218:219], off
	s_waitcnt vmcnt(8)
	s_waitcnt lgkmcnt(0)
	s_barrier
	s_setprio 1
	s_waitcnt lgkmcnt(0)
	v_mfma_f32_16x16x32_bf16 v[124:127], v[146:149], v[186:189], v[124:127]
	v_mfma_f32_16x16x32_bf16 v[124:127], v[158:161], v[190:193], v[124:127]
	v_mfma_f32_16x16x32_bf16 v[120:123], v[166:169], v[190:193], v[120:123]
	v_mfma_f32_16x16x32_bf16 v[120:123], v[162:165], v[186:189], v[120:123]
	v_mfma_f32_16x16x32_bf16 v[92:95], v[170:173], v[186:189], v[92:95]
	v_mfma_f32_16x16x32_bf16 v[92:95], v[174:177], v[190:193], v[92:95]
	v_mfma_f32_16x16x32_bf16 v[88:91], v[182:185], v[190:193], v[88:91]
	v_mfma_f32_16x16x32_bf16 v[88:91], v[178:181], v[186:189], v[88:91]
	v_mfma_f32_16x16x32_bf16 v[80:83], v[178:181], v[194:197], v[80:83]
	v_mfma_f32_16x16x32_bf16 v[80:83], v[182:185], v[198:201], v[80:83]
	v_mfma_f32_16x16x32_bf16 v[84:87], v[174:177], v[198:201], v[84:87]
	v_mfma_f32_16x16x32_bf16 v[84:87], v[170:173], v[194:197], v[84:87]
	v_mfma_f32_16x16x32_bf16 v[112:115], v[162:165], v[194:197], v[112:115]
	v_mfma_f32_16x16x32_bf16 v[112:115], v[166:169], v[198:201], v[112:115]
	v_mfma_f32_16x16x32_bf16 v[116:119], v[158:161], v[198:201], v[116:119]
	v_mfma_f32_16x16x32_bf16 v[116:119], v[146:149], v[194:197], v[116:119]
	v_mfma_f32_16x16x32_bf16 v[108:111], v[146:149], v[202:205], v[108:111]
	v_mfma_f32_16x16x32_bf16 v[108:111], v[158:161], v[206:209], v[108:111]
	v_mfma_f32_16x16x32_bf16 v[104:107], v[166:169], v[206:209], v[104:107]
	v_mfma_f32_16x16x32_bf16 v[104:107], v[162:165], v[202:205], v[104:107]
	v_mfma_f32_16x16x32_bf16 v[76:79], v[170:173], v[202:205], v[76:79]
	v_mfma_f32_16x16x32_bf16 v[76:79], v[174:177], v[206:209], v[76:79]
	v_mfma_f32_16x16x32_bf16 v[72:75], v[182:185], v[206:209], v[72:75]
	v_mfma_f32_16x16x32_bf16 v[72:75], v[178:181], v[202:205], v[72:75]
	v_mfma_f32_16x16x32_bf16 v[64:67], v[178:181], v[210:213], v[64:67]
	v_mfma_f32_16x16x32_bf16 v[64:67], v[182:185], v[214:217], v[64:67]
	v_mfma_f32_16x16x32_bf16 v[68:71], v[174:177], v[214:217], v[68:71]
	v_mfma_f32_16x16x32_bf16 v[68:71], v[170:173], v[210:213], v[68:71]
	v_mfma_f32_16x16x32_bf16 v[96:99], v[162:165], v[210:213], v[96:99]
	v_mfma_f32_16x16x32_bf16 v[96:99], v[166:169], v[214:217], v[96:99]
	v_mfma_f32_16x16x32_bf16 v[100:103], v[158:161], v[214:217], v[100:103]
	v_mfma_f32_16x16x32_bf16 v[100:103], v[146:149], v[210:213], v[100:103]
	s_setprio 0
	s_barrier
	s_add_i32 s65, s92, s85
	v_lshl_add_u64 v[218:219], s[80:81], 0, v[130:131]
	s_mov_b32 m0, s65
	ds_read_b128 v[186:189], v156 offset:16384
	ds_read_b128 v[190:193], v156 offset:17408
	ds_read_b128 v[194:197], v156 offset:18432
	ds_read_b128 v[198:201], v156 offset:19456
	ds_read_b128 v[202:205], v156 offset:20480
	ds_read_b128 v[206:209], v156 offset:21504
	ds_read_b128 v[210:213], v156 offset:22528
	ds_read_b128 v[214:217], v156 offset:23552
	global_load_lds_dwordx4 v[218:219], off
	s_add_i32 m0, s65, 0x2000
	s_add_u32 vcc_lo, s80, 0x80000
	v_lshl_add_u64 v[220:221], s[80:81], 0, v[134:135]
	s_addc_u32 vcc_hi, s81, 0
	s_add_i32 s65, s93, s85
	global_load_lds_dwordx4 v[220:221], off
	v_lshl_add_u64 v[222:223], vcc, 0, v[130:131]
	s_mov_b32 m0, s65
	v_lshl_add_u64 v[224:225], s[82:83], 0, v[132:133]
	global_load_lds_dwordx4 v[222:223], off
	v_lshl_add_u64 v[222:223], vcc, 0, v[134:135]
	s_add_i32 m0, s65, 0x2000
	s_nop 0
	global_load_lds_dwordx4 v[222:223], off
	v_lshl_add_u64 v[222:223], s[82:83], 0, v[128:129]
	s_mov_b32 m0, s7
	s_nop 0
	global_load_lds_dwordx4 v[222:223], off
	s_mov_b32 m0, s9
	s_nop 0
	global_load_lds_dwordx4 v[224:225], off
	s_waitcnt vmcnt(8)
	s_waitcnt lgkmcnt(0)
	s_barrier
; #define PG8_STAGE(bufoff, gbase, voff) do { _Pragma("unroll") for (int _i = 0; _i < 2; ++_i) \
;         __builtin_amdgcn_global_load_lds((const unsigned*)((const char*)(gbase) + (voff)[_i]), (PG8_LAS unsigned*)(lds + (bufoff) + ldsw + _i * 8192), 16, 0, 0); } while (0)
; #define PG8_LDA(dst, b, h) do { _Pragma("unroll") for (int m = 0; m < 4; ++m) _Pragma("unroll") for (int k = 0; k < 2; ++k) dst[m][k] = *(const PG8_LAS bf16x8*)(lds + PG8_SA(b, h) + aoff + m * 2048 + k * 1024); } while (0)
; #define PG8_LDB(dst, b, h) do { _Pragma("unroll") for (int n = 0; n < 2; ++n) _Pragma("unroll") for (int k = 0; k < 2; ++k) dst[n][k] = *(const PG8_LAS bf16x8*)(lds + PG8_SB(b, h) + boff + n * 2048 + k * 1024); } while (0)
; #define PG8_MMA(ai, bj, At, Bt) do { __builtin_amdgcn_s_setprio(1); _Pragma("unroll") for (int m = 0; m < 4; ++m) _Pragma("unroll") for (int n = 0; n < 2; ++n) _Pragma("unroll") for (int k = 0; k < 2; ++k) \
;         acc[ai][bj][m][n] = __builtin_amdgcn_mfma_f32_16x16x32_bf16(Bt[n][k], At[m][k], acc[ai][bj][m][n], 0, 0, 0); __builtin_amdgcn_s_setprio(0); } while (0)
; #define PG8_WAIT_V(n) asm volatile("s_waitcnt vmcnt(" #n ")" ::: "memory")
; #define PG8_WAIT_L(n) asm volatile("s_waitcnt lgkmcnt(" #n ")" ::: "memory")
; #define PG8_BAR __builtin_amdgcn_s_barrier()
; #define PG8_SCHED __builtin_amdgcn_sched_barrier(0)
; template <class Epi, class Sched, bool ALIGN_EPI = false, bool SP2 = false, bool APERM = false  >
; __device__ __forceinline__ void gemm_phase(PG8_LAS unsigned char* lds, const Gemm g, const Sched& S, const Epi& E, const int wid  ) {
;     ...
;             PG8_WAIT_V(8); PG8_WAIT_L(0); PG8_BAR; PG8_MMA(1, 0, At, B0); PG8_MMA(1, 1, At, B1); PG8_BAR; PG8_SCHED;
;             PG8_LDB(B0, 1, 0); PG8_LDB(B1, 1, 1); PG8_SCHED; PG8_LDA(At, 1, 0); PG8_STAGE(PG8_SA(0, 1), a2 + hstep, voffA);
;             PG8_WAIT_V(8); PG8_WAIT_L(0); PG8_BAR; PG8_MMA(0, 0, At, B0); PG8_MMA(0, 1, At, B1); PG8_BAR; PG8_SCHED;
	s_setprio 1
	s_waitcnt lgkmcnt(0)
	v_mfma_f32_16x16x32_bf16 v[60:63], v[146:149], v[186:189], v[60:63]
	v_mfma_f32_16x16x32_bf16 v[60:63], v[158:161], v[190:193], v[60:63]
	v_mfma_f32_16x16x32_bf16 v[56:59], v[166:169], v[190:193], v[56:59]
	v_mfma_f32_16x16x32_bf16 v[56:59], v[162:165], v[186:189], v[56:59]
	v_mfma_f32_16x16x32_bf16 v[28:31], v[170:173], v[186:189], v[28:31]
	v_mfma_f32_16x16x32_bf16 v[28:31], v[174:177], v[190:193], v[28:31]
	v_mfma_f32_16x16x32_bf16 v[24:27], v[182:185], v[190:193], v[24:27]
	v_mfma_f32_16x16x32_bf16 v[24:27], v[178:181], v[186:189], v[24:27]
	v_mfma_f32_16x16x32_bf16 v[16:19], v[178:181], v[194:197], v[16:19]
	v_mfma_f32_16x16x32_bf16 v[16:19], v[182:185], v[198:201], v[16:19]
	v_mfma_f32_16x16x32_bf16 v[20:23], v[174:177], v[198:201], v[20:23]
	v_mfma_f32_16x16x32_bf16 v[20:23], v[170:173], v[194:197], v[20:23]
	v_mfma_f32_16x16x32_bf16 v[48:51], v[162:165], v[194:197], v[48:51]
	v_mfma_f32_16x16x32_bf16 v[48:51], v[166:169], v[198:201], v[48:51]
	v_mfma_f32_16x16x32_bf16 v[52:55], v[158:161], v[198:201], v[52:55]
	v_mfma_f32_16x16x32_bf16 v[52:55], v[146:149], v[194:197], v[52:55]
	v_mfma_f32_16x16x32_bf16 v[44:47], v[146:149], v[202:205], v[44:47]
	v_mfma_f32_16x16x32_bf16 v[44:47], v[158:161], v[206:209], v[44:47]
	v_mfma_f32_16x16x32_bf16 v[40:43], v[166:169], v[206:209], v[40:43]
	v_mfma_f32_16x16x32_bf16 v[40:43], v[162:165], v[202:205], v[40:43]
	v_mfma_f32_16x16x32_bf16 v[12:15], v[170:173], v[202:205], v[12:15]
	v_mfma_f32_16x16x32_bf16 v[12:15], v[174:177], v[206:209], v[12:15]
	v_mfma_f32_16x16x32_bf16 v[8:11], v[182:185], v[206:209], v[8:11]
	v_mfma_f32_16x16x32_bf16 v[8:11], v[178:181], v[202:205], v[8:11]
	v_mfma_f32_16x16x32_bf16 v[0:3], v[178:181], v[210:213], v[0:3]
	v_mfma_f32_16x16x32_bf16 v[0:3], v[182:185], v[214:217], v[0:3]
	v_mfma_f32_16x16x32_bf16 v[4:7], v[174:177], v[214:217], v[4:7]
	v_mfma_f32_16x16x32_bf16 v[4:7], v[170:173], v[210:213], v[4:7]
	v_mfma_f32_16x16x32_bf16 v[32:35], v[162:165], v[210:213], v[32:35]
	v_mfma_f32_16x16x32_bf16 v[32:35], v[166:169], v[214:217], v[32:35]
	v_mfma_f32_16x16x32_bf16 v[36:39], v[158:161], v[214:217], v[36:39]
	v_mfma_f32_16x16x32_bf16 v[36:39], v[146:149], v[210:213], v[36:39]
	s_setprio 0
	s_barrier
	s_add_i32 s65, 0, 0x18000
	v_add_u32_e32 v157, s65, v151
	s_add_i32 s73, 0, 0x1c000
	ds_read_b128 v[146:149], v157
	ds_read_b128 v[158:161], v157 offset:1024
	ds_read_b128 v[162:165], v157 offset:2048
	ds_read_b128 v[166:169], v157 offset:3072
	v_add_u32_e32 v157, s73, v151
	ds_read_b128 v[170:173], v157
	ds_read_b128 v[174:177], v157 offset:1024
	ds_read_b128 v[178:181], v157 offset:2048
	ds_read_b128 v[182:185], v157 offset:3072
	s_add_u32 s82, s82, 0x80000
	s_addc_u32 s83, s83, 0
	s_mov_b32 m0, s86
	v_lshl_add_u64 v[226:227], s[82:83], 0, v[128:129]
	ds_read_b128 v[186:189], v156 offset:32768
	ds_read_b128 v[190:193], v156 offset:33792
	ds_read_b128 v[194:197], v156 offset:34816
	ds_read_b128 v[198:201], v156 offset:35840
	ds_read_b128 v[202:205], v156 offset:36864
	ds_read_b128 v[206:209], v156 offset:37888
	ds_read_b128 v[210:213], v156 offset:38912
	ds_read_b128 v[214:217], v156 offset:39936
	global_load_lds_dwordx4 v[226:227], off
	v_lshl_add_u64 v[226:227], s[82:83], 0, v[132:133]
	s_mov_b32 m0, s87
	s_nop 0
	global_load_lds_dwordx4 v[226:227], off
	s_waitcnt vmcnt(8)
	s_waitcnt lgkmcnt(0)
	s_barrier
	s_setprio 1
	s_waitcnt lgkmcnt(0)
	v_mfma_f32_16x16x32_bf16 v[124:127], v[146:149], v[186:189], v[124:127]
	v_mfma_f32_16x16x32_bf16 v[124:127], v[158:161], v[190:193], v[124:127]
	v_mfma_f32_16x16x32_bf16 v[120:123], v[166:169], v[190:193], v[120:123]
	v_mfma_f32_16x16x32_bf16 v[120:123], v[162:165], v[186:189], v[120:123]
	v_mfma_f32_16x16x32_bf16 v[92:95], v[170:173], v[186:189], v[92:95]
	v_mfma_f32_16x16x32_bf16 v[92:95], v[174:177], v[190:193], v[92:95]
	v_mfma_f32_16x16x32_bf16 v[88:91], v[182:185], v[190:193], v[88:91]
	v_mfma_f32_16x16x32_bf16 v[88:91], v[178:181], v[186:189], v[88:91]
	v_mfma_f32_16x16x32_bf16 v[80:83], v[178:181], v[194:197], v[80:83]
	v_mfma_f32_16x16x32_bf16 v[80:83], v[182:185], v[198:201], v[80:83]
	v_mfma_f32_16x16x32_bf16 v[84:87], v[174:177], v[198:201], v[84:87]
	v_mfma_f32_16x16x32_bf16 v[84:87], v[170:173], v[194:197], v[84:87]
	v_mfma_f32_16x16x32_bf16 v[112:115], v[162:165], v[194:197], v[112:115]
	v_mfma_f32_16x16x32_bf16 v[112:115], v[166:169], v[198:201], v[112:115]
	v_mfma_f32_16x16x32_bf16 v[116:119], v[158:161], v[198:201], v[116:119]
	v_mfma_f32_16x16x32_bf16 v[116:119], v[146:149], v[194:197], v[116:119]
	v_mfma_f32_16x16x32_bf16 v[108:111], v[146:149], v[202:205], v[108:111]
	v_mfma_f32_16x16x32_bf16 v[108:111], v[158:161], v[206:209], v[108:111]
	v_mfma_f32_16x16x32_bf16 v[104:107], v[166:169], v[206:209], v[104:107]
	v_mfma_f32_16x16x32_bf16 v[104:107], v[162:165], v[202:205], v[104:107]
	v_mfma_f32_16x16x32_bf16 v[76:79], v[170:173], v[202:205], v[76:79]
	v_mfma_f32_16x16x32_bf16 v[76:79], v[174:177], v[206:209], v[76:79]
	v_mfma_f32_16x16x32_bf16 v[72:75], v[182:185], v[206:209], v[72:75]
	v_mfma_f32_16x16x32_bf16 v[72:75], v[178:181], v[202:205], v[72:75]
	v_mfma_f32_16x16x32_bf16 v[64:67], v[178:181], v[210:213], v[64:67]
	v_mfma_f32_16x16x32_bf16 v[64:67], v[182:185], v[214:217], v[64:67]
	v_mfma_f32_16x16x32_bf16 v[68:71], v[174:177], v[214:217], v[68:71]
	v_mfma_f32_16x16x32_bf16 v[68:71], v[170:173], v[210:213], v[68:71]
	v_mfma_f32_16x16x32_bf16 v[96:99], v[162:165], v[210:213], v[96:99]
	v_mfma_f32_16x16x32_bf16 v[96:99], v[166:169], v[214:217], v[96:99]
	v_mfma_f32_16x16x32_bf16 v[100:103], v[158:161], v[214:217], v[100:103]
	v_mfma_f32_16x16x32_bf16 v[100:103], v[146:149], v[210:213], v[100:103]
	s_setprio 0
	s_barrier
; #define PG8_STAGE(bufoff, gbase, voff) do { _Pragma("unroll") for (int _i = 0; _i < 2; ++_i) \
;         __builtin_amdgcn_global_load_lds((const unsigned*)((const char*)(gbase) + (voff)[_i]), (PG8_LAS unsigned*)(lds + (bufoff) + ldsw + _i * 8192), 16, 0, 0); } while (0)
; #define PG8_LDA(dst, b, h) do { _Pragma("unroll") for (int m = 0; m < 4; ++m) _Pragma("unroll") for (int k = 0; k < 2; ++k) dst[m][k] = *(const PG8_LAS bf16x8*)(lds + PG8_SA(b, h) + aoff + m * 2048 + k * 1024); } while (0)
; #define PG8_MMA(ai, bj, At, Bt) do { __builtin_amdgcn_s_setprio(1); _Pragma("unroll") for (int m = 0; m < 4; ++m) _Pragma("unroll") for (int n = 0; n < 2; ++n) _Pragma("unroll") for (int k = 0; k < 2; ++k) \
;         acc[ai][bj][m][n] = __builtin_amdgcn_mfma_f32_16x16x32_bf16(Bt[n][k], At[m][k], acc[ai][bj][m][n], 0, 0, 0); __builtin_amdgcn_s_setprio(0); } while (0)
; #define PG8_WAIT_V(n) asm volatile("s_waitcnt vmcnt(" #n ")" ::: "memory")
; #define PG8_WAIT_L(n) asm volatile("s_waitcnt lgkmcnt(" #n ")" ::: "memory")
; #define PG8_BAR __builtin_amdgcn_s_barrier()
; #define PG8_SCHED __builtin_amdgcn_sched_barrier(0)
; template <class Epi, class Sched, bool ALIGN_EPI = false, bool SP2 = false, bool APERM = false  >
; __device__ __forceinline__ void gemm_phase(PG8_LAS unsigned char* lds, const Gemm g, const Sched& S, const Epi& E, const int wid  ) {
;     ...
;             PG8_LDA(At, 1, 1); PG8_STAGE(PG8_SB(1, 0), b3, voffB); PG8_STAGE(PG8_SB(1, 1), b3 + hstep, voffB); PG8_STAGE(PG8_SA(1, 0), a3, voffA);
;             PG8_WAIT_V(8); PG8_WAIT_L(0); PG8_BAR; PG8_MMA(1, 0, At, B0); PG8_MMA(1, 1, At, B1); PG8_BAR; PG8_SCHED;
;     ...
;         if constexpr (ALIGN_EPI) { if (wr == 0) PG8_BAR; }
;         if constexpr (!Epi::AFTER_DRAIN) { S.pre_epi(cur); E(acc, cur, wr, wc, fr, fq); S.done(cur); }
	s_add_i32 s65, s65, s85
	v_lshl_add_u64 v[218:219], v[218:219], 0, s[14:15]
	s_mov_b32 m0, s65
	ds_read_b128 v[186:189], v156 offset:49152
	ds_read_b128 v[190:193], v156 offset:50176
	ds_read_b128 v[194:197], v156 offset:51200
	ds_read_b128 v[198:201], v156 offset:52224
	ds_read_b128 v[202:205], v156 offset:53248
	ds_read_b128 v[206:209], v156 offset:54272
	ds_read_b128 v[210:213], v156 offset:55296
	ds_read_b128 v[214:217], v156 offset:56320
	global_load_lds_dwordx4 v[218:219], off
	s_add_i32 m0, s65, 0x2000
	s_add_u32 s80, s80, 0x80080
	v_lshl_add_u64 v[218:219], v[220:221], 0, s[14:15]
	s_addc_u32 s81, s81, 0
	s_add_i32 s65, s73, s85
	global_load_lds_dwordx4 v[218:219], off
	v_lshl_add_u64 v[218:219], s[80:81], 0, v[130:131]
	s_mov_b32 m0, s65
	s_nop 0
	global_load_lds_dwordx4 v[218:219], off
	v_lshl_add_u64 v[218:219], s[80:81], 0, v[134:135]
	s_add_i32 m0, s65, 0x2000
	s_nop 0
	global_load_lds_dwordx4 v[218:219], off
	v_lshl_add_u64 v[218:219], v[222:223], 0, s[14:15]
	s_mov_b32 m0, s90
	s_nop 0
	global_load_lds_dwordx4 v[218:219], off
	v_lshl_add_u64 v[218:219], v[224:225], 0, s[14:15]
	s_mov_b32 m0, s91
	s_nop 0
	global_load_lds_dwordx4 v[218:219], off
	s_waitcnt vmcnt(8)
	s_waitcnt lgkmcnt(0)
	s_barrier
	s_setprio 1
	s_waitcnt lgkmcnt(0)
	v_mfma_f32_16x16x32_bf16 v[60:63], v[146:149], v[186:189], v[60:63]
	v_mfma_f32_16x16x32_bf16 v[60:63], v[158:161], v[190:193], v[60:63]
	v_mfma_f32_16x16x32_bf16 v[56:59], v[166:169], v[190:193], v[56:59]
	v_mfma_f32_16x16x32_bf16 v[56:59], v[162:165], v[186:189], v[56:59]
	v_mfma_f32_16x16x32_bf16 v[28:31], v[170:173], v[186:189], v[28:31]
	v_mfma_f32_16x16x32_bf16 v[28:31], v[174:177], v[190:193], v[28:31]
	v_mfma_f32_16x16x32_bf16 v[24:27], v[182:185], v[190:193], v[24:27]
	v_mfma_f32_16x16x32_bf16 v[24:27], v[178:181], v[186:189], v[24:27]
	v_mfma_f32_16x16x32_bf16 v[16:19], v[178:181], v[194:197], v[16:19]
	v_mfma_f32_16x16x32_bf16 v[16:19], v[182:185], v[198:201], v[16:19]
	v_mfma_f32_16x16x32_bf16 v[20:23], v[174:177], v[198:201], v[20:23]
	v_mfma_f32_16x16x32_bf16 v[20:23], v[170:173], v[194:197], v[20:23]
	v_mfma_f32_16x16x32_bf16 v[48:51], v[162:165], v[194:197], v[48:51]
	v_mfma_f32_16x16x32_bf16 v[48:51], v[166:169], v[198:201], v[48:51]
	v_mfma_f32_16x16x32_bf16 v[52:55], v[158:161], v[198:201], v[52:55]
	v_mfma_f32_16x16x32_bf16 v[52:55], v[146:149], v[194:197], v[52:55]
	v_mfma_f32_16x16x32_bf16 v[44:47], v[146:149], v[202:205], v[44:47]
	v_mfma_f32_16x16x32_bf16 v[44:47], v[158:161], v[206:209], v[44:47]
	v_mfma_f32_16x16x32_bf16 v[40:43], v[166:169], v[206:209], v[40:43]
	v_mfma_f32_16x16x32_bf16 v[40:43], v[162:165], v[202:205], v[40:43]
	v_mfma_f32_16x16x32_bf16 v[12:15], v[170:173], v[202:205], v[12:15]
	v_mfma_f32_16x16x32_bf16 v[12:15], v[174:177], v[206:209], v[12:15]
	v_mfma_f32_16x16x32_bf16 v[8:11], v[182:185], v[206:209], v[8:11]
	v_mfma_f32_16x16x32_bf16 v[8:11], v[178:181], v[202:205], v[8:11]
	v_mfma_f32_16x16x32_bf16 v[0:3], v[178:181], v[210:213], v[0:3]
	v_mfma_f32_16x16x32_bf16 v[0:3], v[182:185], v[214:217], v[0:3]
	v_mfma_f32_16x16x32_bf16 v[4:7], v[174:177], v[214:217], v[4:7]
	v_mfma_f32_16x16x32_bf16 v[4:7], v[170:173], v[210:213], v[4:7]
	v_mfma_f32_16x16x32_bf16 v[32:35], v[162:165], v[210:213], v[32:35]
	v_mfma_f32_16x16x32_bf16 v[32:35], v[166:169], v[214:217], v[32:35]
	v_mfma_f32_16x16x32_bf16 v[36:39], v[158:161], v[214:217], v[36:39]
	v_mfma_f32_16x16x32_bf16 v[36:39], v[146:149], v[210:213], v[36:39]
	s_setprio 0
	s_barrier
	s_add_i32 s64, s64, 2
	s_add_u32 s78, s78, 0x100
	s_addc_u32 s79, s79, 0
	s_cmp_gt_u32 s64, 29
	s_cbranch_scc0 .LBB0_1019
	s_and_b64 vcc, exec, s[16:17]
	s_cbranch_vccz .LBB0_1022
	s_barrier

; #define PG8_STAGE(bufoff, gbase, voff) do { _Pragma("unroll") for (int _i = 0; _i < 2; ++_i) \
;         __builtin_amdgcn_global_load_lds((const unsigned*)((const char*)(gbase) + (voff)[_i]), (PG8_LAS unsigned*)(lds + (bufoff) + ldsw + _i * 8192), 16, 0, 0); } while (0)
; #define PG8_LDA(dst, b, h) do { _Pragma("unroll") for (int m = 0; m < 4; ++m) _Pragma("unroll") for (int k = 0; k < 2; ++k) dst[m][k] = *(const PG8_LAS bf16x8*)(lds + PG8_SA(b, h) + aoff + m * 2048 + k * 1024); } while (0)
; #define PG8_LDB(dst, b, h) do { _Pragma("unroll") for (int n = 0; n < 2; ++n) _Pragma("unroll") for (int k = 0; k < 2; ++k) dst[n][k] = *(const PG8_LAS bf16x8*)(lds + PG8_SB(b, h) + boff + n * 2048 + k * 1024); } while (0)
; #define PG8_MMA(ai, bj, At, Bt) do { __builtin_amdgcn_s_setprio(1); _Pragma("unroll") for (int m = 0; m < 4; ++m) _Pragma("unroll") for (int n = 0; n < 2; ++n) _Pragma("unroll") for (int k = 0; k < 2; ++k) \
;         acc[ai][bj][m][n] = __builtin_amdgcn_mfma_f32_16x16x32_bf16(Bt[n][k], At[m][k], acc[ai][bj][m][n], 0, 0, 0); __builtin_amdgcn_s_setprio(0); } while (0)
; #define PG8_WAIT_V(n) asm volatile("s_waitcnt vmcnt(" #n ")" ::: "memory")
; #define PG8_WAIT_L(n) asm volatile("s_waitcnt lgkmcnt(" #n ")" ::: "memory")
; #define PG8_BAR __builtin_amdgcn_s_barrier()
; #define PG8_SCHED __builtin_amdgcn_sched_barrier(0)
; template <class Epi, class Sched, bool ALIGN_EPI = false, bool SP2 = false, bool APERM = false  >
; __device__ __forceinline__ void gemm_phase(PG8_LAS unsigned char* lds, const Gemm g, const Sched& S, const Epi& E, const int wid  ) {
;     ...
;             const bool last = (t == nt - 2);
;             const char* a1 = cA + (size_t)(t + 1) * kstep;
;             const char* a2 = last ? nA : cA + (size_t)(t + 2) * kstep; const char* b2 = last ? nB : cB + (size_t)(t + 2) * kstep;
;             const char* a3 = a2 + kstep; const char* b3 = b2 + kstep;
;             if (last && has_next) S.a_ready(nxt);
;             if constexpr (SP2) {
;             PG8_LDB(B0, 0, 0); PG8_LDB(B1, 0, 1); PG8_SCHED; PG8_LDA(At, 0, 0); PG8_STAGE(PG8_SA(1, 1), a1 + hstep, voffA);
;             PG8_WAIT_V(8); PG8_WAIT_L(0); PG8_BAR; PG8_MMA(0, 0, At, B0); PG8_MMA(0, 1, At, B1); PG8_BAR; PG8_SCHED;
;             PG8_LDA(At, 0, 1); PG8_STAGE(PG8_SB(0, 0), b2, voffB); PG8_STAGE(PG8_SB(0, 1), b2 + hstep, voffB); PG8_STAGE(PG8_SA(0, 0), a2, voffA);
.LBB0_1099:
	s_lshl_b32 s30, s69, 7
	s_add_u32 s31, s44, s30
	s_addc_u32 s46, s45, 0
	s_add_u32 s14, s31, 0x100
	s_addc_u32 s15, s46, 0
	v_add_u32_e32 v140, s49, v235
	v_add_u32_e32 v156, s62, v235
	s_and_b64 s[10:11], s[12:13], exec
	ds_read_b128 v[128:131], v140
	ds_read_b128 v[132:135], v140 offset:1024
	ds_read_b128 v[136:139], v140 offset:2048
	ds_read_b128 v[140:143], v140 offset:3072
	ds_read_b128 v[144:147], v156
	ds_read_b128 v[148:151], v156 offset:1024
	ds_read_b128 v[152:155], v156 offset:2048
	ds_read_b128 v[156:159], v156 offset:3072
	s_cselect_b32 s15, s8, s15
	s_cselect_b32 s14, s9, s14
	s_add_u32 s10, s36, s30
	s_addc_u32 s11, s37, 0
	s_add_u32 s30, s10, 0x100
	s_addc_u32 s47, s11, 0
	s_and_b64 s[10:11], s[12:13], exec
	s_cselect_b32 s10, s68, s30
	s_cselect_b32 s11, s33, s47
	s_add_u32 s12, s31, 0x80080
	s_addc_u32 s13, s46, 0
	v_lshl_add_u64 v[206:207], s[12:13], 0, v[188:189]
	s_add_i32 m0, s35, 0xc000
	ds_read_b128 v[160:163], v247
	ds_read_b128 v[164:167], v247 offset:1024
	ds_read_b128 v[168:171], v247 offset:2048
	ds_read_b128 v[172:175], v247 offset:3072
	ds_read_b128 v[176:179], v247 offset:4096
	ds_read_b128 v[180:183], v247 offset:5120
	ds_read_b128 v[198:201], v247 offset:6144
	ds_read_b128 v[202:205], v247 offset:7168
	global_load_lds_dwordx4 v[206:207], off
	v_lshl_add_u64 v[206:207], s[12:13], 0, v[190:191]
	s_add_i32 m0, s35, 0xe000
	s_nop 0
	global_load_lds_dwordx4 v[206:207], off
	s_waitcnt vmcnt(8)
	s_waitcnt lgkmcnt(0)
	s_barrier
	s_setprio 1
	s_waitcnt lgkmcnt(0)
	v_mfma_f32_16x16x32_bf16 v[124:127], v[128:131], v[160:163], v[124:127]
	v_mfma_f32_16x16x32_bf16 v[124:127], v[132:135], v[164:167], v[124:127]
	v_mfma_f32_16x16x32_bf16 v[120:123], v[140:143], v[164:167], v[120:123]
	v_mfma_f32_16x16x32_bf16 v[120:123], v[136:139], v[160:163], v[120:123]
	v_mfma_f32_16x16x32_bf16 v[92:95], v[144:147], v[160:163], v[92:95]
	v_mfma_f32_16x16x32_bf16 v[92:95], v[148:151], v[164:167], v[92:95]
	v_mfma_f32_16x16x32_bf16 v[88:91], v[156:159], v[164:167], v[88:91]
	v_mfma_f32_16x16x32_bf16 v[88:91], v[152:155], v[160:163], v[88:91]
	v_mfma_f32_16x16x32_bf16 v[80:83], v[152:155], v[168:171], v[80:83]
	v_mfma_f32_16x16x32_bf16 v[80:83], v[156:159], v[172:175], v[80:83]
	v_mfma_f32_16x16x32_bf16 v[84:87], v[148:151], v[172:175], v[84:87]
	v_mfma_f32_16x16x32_bf16 v[84:87], v[144:147], v[168:171], v[84:87]
	v_mfma_f32_16x16x32_bf16 v[112:115], v[136:139], v[168:171], v[112:115]
	v_mfma_f32_16x16x32_bf16 v[112:115], v[140:143], v[172:175], v[112:115]
	v_mfma_f32_16x16x32_bf16 v[116:119], v[132:135], v[172:175], v[116:119]
	v_mfma_f32_16x16x32_bf16 v[116:119], v[128:131], v[168:171], v[116:119]
	v_mfma_f32_16x16x32_bf16 v[108:111], v[128:131], v[176:179], v[108:111]
	v_mfma_f32_16x16x32_bf16 v[108:111], v[132:135], v[180:183], v[108:111]
	v_mfma_f32_16x16x32_bf16 v[104:107], v[140:143], v[180:183], v[104:107]
	v_mfma_f32_16x16x32_bf16 v[104:107], v[136:139], v[176:179], v[104:107]
	v_mfma_f32_16x16x32_bf16 v[76:79], v[144:147], v[176:179], v[76:79]
	v_mfma_f32_16x16x32_bf16 v[76:79], v[148:151], v[180:183], v[76:79]
	v_mfma_f32_16x16x32_bf16 v[72:75], v[156:159], v[180:183], v[72:75]
	v_mfma_f32_16x16x32_bf16 v[72:75], v[152:155], v[176:179], v[72:75]
	v_mfma_f32_16x16x32_bf16 v[64:67], v[152:155], v[198:201], v[64:67]
	v_mfma_f32_16x16x32_bf16 v[64:67], v[156:159], v[202:205], v[64:67]
	v_mfma_f32_16x16x32_bf16 v[68:71], v[148:151], v[202:205], v[68:71]
	v_mfma_f32_16x16x32_bf16 v[68:71], v[144:147], v[198:201], v[68:71]
	v_mfma_f32_16x16x32_bf16 v[96:99], v[136:139], v[198:201], v[96:99]
	v_mfma_f32_16x16x32_bf16 v[96:99], v[140:143], v[202:205], v[96:99]
	v_mfma_f32_16x16x32_bf16 v[100:103], v[132:135], v[202:205], v[100:103]
	v_mfma_f32_16x16x32_bf16 v[100:103], v[128:131], v[198:201], v[100:103]
	s_setprio 0
	s_barrier
	s_add_i32 s12, s49, s96
	v_lshl_add_u64 v[206:207], s[10:11], 0, v[184:185]
	s_mov_b32 m0, s12
	ds_read_b128 v[160:163], v247 offset:16384
	ds_read_b128 v[164:167], v247 offset:17408
	ds_read_b128 v[168:171], v247 offset:18432
	ds_read_b128 v[172:175], v247 offset:19456
	ds_read_b128 v[176:179], v247 offset:20480
	ds_read_b128 v[180:183], v247 offset:21504
	ds_read_b128 v[198:201], v247 offset:22528
	ds_read_b128 v[202:205], v247 offset:23552
	global_load_lds_dwordx4 v[206:207], off
	s_add_i32 m0, s12, 0x2000
	s_add_u32 s12, s10, 0x80000
	v_lshl_add_u64 v[208:209], s[10:11], 0, v[186:187]
	s_addc_u32 s13, s11, 0
	s_add_i32 s30, s62, s96
	global_load_lds_dwordx4 v[208:209], off
	v_lshl_add_u64 v[210:211], s[12:13], 0, v[184:185]
	s_mov_b32 m0, s30
	v_lshl_add_u64 v[212:213], s[14:15], 0, v[190:191]
	global_load_lds_dwordx4 v[210:211], off
	v_lshl_add_u64 v[210:211], s[12:13], 0, v[186:187]
	s_add_i32 m0, s30, 0x2000
	s_nop 0
	global_load_lds_dwordx4 v[210:211], off
	v_lshl_add_u64 v[210:211], s[14:15], 0, v[188:189]
	s_mov_b32 m0, s35
	s_nop 0
	global_load_lds_dwordx4 v[210:211], off
	s_mov_b32 m0, s2
	s_nop 0
	global_load_lds_dwordx4 v[212:213], off
	s_waitcnt vmcnt(8)
	s_waitcnt lgkmcnt(0)
	s_barrier
; #define PG8_STAGE(bufoff, gbase, voff) do { _Pragma("unroll") for (int _i = 0; _i < 2; ++_i) \
;         __builtin_amdgcn_global_load_lds((const unsigned*)((const char*)(gbase) + (voff)[_i]), (PG8_LAS unsigned*)(lds + (bufoff) + ldsw + _i * 8192), 16, 0, 0); } while (0)
; #define PG8_LDA(dst, b, h) do { _Pragma("unroll") for (int m = 0; m < 4; ++m) _Pragma("unroll") for (int k = 0; k < 2; ++k) dst[m][k] = *(const PG8_LAS bf16x8*)(lds + PG8_SA(b, h) + aoff + m * 2048 + k * 1024); } while (0)
; #define PG8_LDB(dst, b, h) do { _Pragma("unroll") for (int n = 0; n < 2; ++n) _Pragma("unroll") for (int k = 0; k < 2; ++k) dst[n][k] = *(const PG8_LAS bf16x8*)(lds + PG8_SB(b, h) + boff + n * 2048 + k * 1024); } while (0)
; #define PG8_MMA(ai, bj, At, Bt) do { __builtin_amdgcn_s_setprio(1); _Pragma("unroll") for (int m = 0; m < 4; ++m) _Pragma("unroll") for (int n = 0; n < 2; ++n) _Pragma("unroll") for (int k = 0; k < 2; ++k) \
;         acc[ai][bj][m][n] = __builtin_amdgcn_mfma_f32_16x16x32_bf16(Bt[n][k], At[m][k], acc[ai][bj][m][n], 0, 0, 0); __builtin_amdgcn_s_setprio(0); } while (0)
; #define PG8_WAIT_V(n) asm volatile("s_waitcnt vmcnt(" #n ")" ::: "memory")
; #define PG8_WAIT_L(n) asm volatile("s_waitcnt lgkmcnt(" #n ")" ::: "memory")
; #define PG8_BAR __builtin_amdgcn_s_barrier()
; #define PG8_SCHED __builtin_amdgcn_sched_barrier(0)
; template <class Epi, class Sched, bool ALIGN_EPI = false, bool SP2 = false, bool APERM = false  >
; __device__ __forceinline__ void gemm_phase(PG8_LAS unsigned char* lds, const Gemm g, const Sched& S, const Epi& E, const int wid  ) {
;     ...
;             PG8_WAIT_V(8); PG8_WAIT_L(0); PG8_BAR; PG8_MMA(1, 0, At, B0); PG8_MMA(1, 1, At, B1); PG8_BAR; PG8_SCHED;
;             PG8_LDB(B0, 1, 0); PG8_LDB(B1, 1, 1); PG8_SCHED; PG8_LDA(At, 1, 0); PG8_STAGE(PG8_SA(0, 1), a2 + hstep, voffA);
;             PG8_WAIT_V(8); PG8_WAIT_L(0); PG8_BAR; PG8_MMA(0, 0, At, B0); PG8_MMA(0, 1, At, B1); PG8_BAR; PG8_SCHED;
	s_setprio 1
	s_waitcnt lgkmcnt(0)
	v_mfma_f32_16x16x32_bf16 v[60:63], v[128:131], v[160:163], v[60:63]
	v_mfma_f32_16x16x32_bf16 v[60:63], v[132:135], v[164:167], v[60:63]
	v_mfma_f32_16x16x32_bf16 v[56:59], v[140:143], v[164:167], v[56:59]
	v_mfma_f32_16x16x32_bf16 v[56:59], v[136:139], v[160:163], v[56:59]
	v_mfma_f32_16x16x32_bf16 v[28:31], v[144:147], v[160:163], v[28:31]
	v_mfma_f32_16x16x32_bf16 v[28:31], v[148:151], v[164:167], v[28:31]
	v_mfma_f32_16x16x32_bf16 v[24:27], v[156:159], v[164:167], v[24:27]
	v_mfma_f32_16x16x32_bf16 v[24:27], v[152:155], v[160:163], v[24:27]
	v_mfma_f32_16x16x32_bf16 v[16:19], v[152:155], v[168:171], v[16:19]
	v_mfma_f32_16x16x32_bf16 v[16:19], v[156:159], v[172:175], v[16:19]
	v_mfma_f32_16x16x32_bf16 v[20:23], v[148:151], v[172:175], v[20:23]
	v_mfma_f32_16x16x32_bf16 v[20:23], v[144:147], v[168:171], v[20:23]
	v_mfma_f32_16x16x32_bf16 v[48:51], v[136:139], v[168:171], v[48:51]
	v_mfma_f32_16x16x32_bf16 v[48:51], v[140:143], v[172:175], v[48:51]
	v_mfma_f32_16x16x32_bf16 v[52:55], v[132:135], v[172:175], v[52:55]
	v_mfma_f32_16x16x32_bf16 v[52:55], v[128:131], v[168:171], v[52:55]
	v_mfma_f32_16x16x32_bf16 v[44:47], v[128:131], v[176:179], v[44:47]
	v_mfma_f32_16x16x32_bf16 v[44:47], v[132:135], v[180:183], v[44:47]
	v_mfma_f32_16x16x32_bf16 v[40:43], v[140:143], v[180:183], v[40:43]
	v_mfma_f32_16x16x32_bf16 v[40:43], v[136:139], v[176:179], v[40:43]
	v_mfma_f32_16x16x32_bf16 v[12:15], v[144:147], v[176:179], v[12:15]
	v_mfma_f32_16x16x32_bf16 v[12:15], v[148:151], v[180:183], v[12:15]
	v_mfma_f32_16x16x32_bf16 v[8:11], v[156:159], v[180:183], v[8:11]
	v_mfma_f32_16x16x32_bf16 v[8:11], v[152:155], v[176:179], v[8:11]
	v_mfma_f32_16x16x32_bf16 v[0:3], v[152:155], v[198:201], v[0:3]
	v_mfma_f32_16x16x32_bf16 v[0:3], v[156:159], v[202:205], v[0:3]
	v_mfma_f32_16x16x32_bf16 v[4:7], v[148:151], v[202:205], v[4:7]
	v_mfma_f32_16x16x32_bf16 v[4:7], v[144:147], v[198:201], v[4:7]
	v_mfma_f32_16x16x32_bf16 v[32:35], v[136:139], v[198:201], v[32:35]
	v_mfma_f32_16x16x32_bf16 v[32:35], v[140:143], v[202:205], v[32:35]
	v_mfma_f32_16x16x32_bf16 v[36:39], v[132:135], v[202:205], v[36:39]
	v_mfma_f32_16x16x32_bf16 v[36:39], v[128:131], v[198:201], v[36:39]
	s_setprio 0
	s_barrier
	s_add_i32 s30, 0, 0x18000
	s_add_i32 s31, 0, 0x1c000
	v_add_u32_e32 v140, s30, v235
	v_add_u32_e32 v156, s31, v235
	ds_read_b128 v[128:131], v140
	ds_read_b128 v[132:135], v140 offset:1024
	ds_read_b128 v[136:139], v140 offset:2048
	ds_read_b128 v[140:143], v140 offset:3072
	ds_read_b128 v[144:147], v156
	ds_read_b128 v[148:151], v156 offset:1024
	ds_read_b128 v[152:155], v156 offset:2048
	ds_read_b128 v[156:159], v156 offset:3072
	s_add_u32 s12, s14, 0x80000
	s_addc_u32 s13, s15, 0
	s_mov_b32 m0, s3
	v_lshl_add_u64 v[214:215], s[12:13], 0, v[188:189]
	ds_read_b128 v[160:163], v247 offset:32768
	ds_read_b128 v[164:167], v247 offset:33792
	ds_read_b128 v[168:171], v247 offset:34816
	ds_read_b128 v[172:175], v247 offset:35840
	ds_read_b128 v[176:179], v247 offset:36864
	ds_read_b128 v[180:183], v247 offset:37888
	ds_read_b128 v[198:201], v247 offset:38912
	ds_read_b128 v[202:205], v247 offset:39936
	global_load_lds_dwordx4 v[214:215], off
	v_lshl_add_u64 v[214:215], s[12:13], 0, v[190:191]
	s_mov_b32 m0, s52
	s_nop 0
	global_load_lds_dwordx4 v[214:215], off
	s_waitcnt vmcnt(8)
	s_waitcnt lgkmcnt(0)
	s_barrier
	s_setprio 1
	s_waitcnt lgkmcnt(0)
	v_mfma_f32_16x16x32_bf16 v[124:127], v[128:131], v[160:163], v[124:127]
	v_mfma_f32_16x16x32_bf16 v[124:127], v[132:135], v[164:167], v[124:127]
	v_mfma_f32_16x16x32_bf16 v[120:123], v[140:143], v[164:167], v[120:123]
	v_mfma_f32_16x16x32_bf16 v[120:123], v[136:139], v[160:163], v[120:123]
	v_mfma_f32_16x16x32_bf16 v[92:95], v[144:147], v[160:163], v[92:95]
	v_mfma_f32_16x16x32_bf16 v[92:95], v[148:151], v[164:167], v[92:95]
	v_mfma_f32_16x16x32_bf16 v[88:91], v[156:159], v[164:167], v[88:91]
	v_mfma_f32_16x16x32_bf16 v[88:91], v[152:155], v[160:163], v[88:91]
	v_mfma_f32_16x16x32_bf16 v[80:83], v[152:155], v[168:171], v[80:83]
	v_mfma_f32_16x16x32_bf16 v[80:83], v[156:159], v[172:175], v[80:83]
	v_mfma_f32_16x16x32_bf16 v[84:87], v[148:151], v[172:175], v[84:87]
	v_mfma_f32_16x16x32_bf16 v[84:87], v[144:147], v[168:171], v[84:87]
	v_mfma_f32_16x16x32_bf16 v[112:115], v[136:139], v[168:171], v[112:115]
	v_mfma_f32_16x16x32_bf16 v[112:115], v[140:143], v[172:175], v[112:115]
	v_mfma_f32_16x16x32_bf16 v[116:119], v[132:135], v[172:175], v[116:119]
	v_mfma_f32_16x16x32_bf16 v[116:119], v[128:131], v[168:171], v[116:119]
	v_mfma_f32_16x16x32_bf16 v[108:111], v[128:131], v[176:179], v[108:111]
	v_mfma_f32_16x16x32_bf16 v[108:111], v[132:135], v[180:183], v[108:111]
	v_mfma_f32_16x16x32_bf16 v[104:107], v[140:143], v[180:183], v[104:107]
	v_mfma_f32_16x16x32_bf16 v[104:107], v[136:139], v[176:179], v[104:107]
	v_mfma_f32_16x16x32_bf16 v[76:79], v[144:147], v[176:179], v[76:79]
	v_mfma_f32_16x16x32_bf16 v[76:79], v[148:151], v[180:183], v[76:79]
	v_mfma_f32_16x16x32_bf16 v[72:75], v[156:159], v[180:183], v[72:75]
	v_mfma_f32_16x16x32_bf16 v[72:75], v[152:155], v[176:179], v[72:75]
	v_mfma_f32_16x16x32_bf16 v[64:67], v[152:155], v[198:201], v[64:67]
	v_mfma_f32_16x16x32_bf16 v[64:67], v[156:159], v[202:205], v[64:67]
	v_mfma_f32_16x16x32_bf16 v[68:71], v[148:151], v[202:205], v[68:71]
	v_mfma_f32_16x16x32_bf16 v[68:71], v[144:147], v[198:201], v[68:71]
	v_mfma_f32_16x16x32_bf16 v[96:99], v[136:139], v[198:201], v[96:99]
	v_mfma_f32_16x16x32_bf16 v[96:99], v[140:143], v[202:205], v[96:99]
	v_mfma_f32_16x16x32_bf16 v[100:103], v[132:135], v[202:205], v[100:103]
	v_mfma_f32_16x16x32_bf16 v[100:103], v[128:131], v[198:201], v[100:103]
	s_setprio 0
	s_barrier
; #define PG8_STAGE(bufoff, gbase, voff) do { _Pragma("unroll") for (int _i = 0; _i < 2; ++_i) \
;         __builtin_amdgcn_global_load_lds((const unsigned*)((const char*)(gbase) + (voff)[_i]), (PG8_LAS unsigned*)(lds + (bufoff) + ldsw + _i * 8192), 16, 0, 0); } while (0)
; #define PG8_LDA(dst, b, h) do { _Pragma("unroll") for (int m = 0; m < 4; ++m) _Pragma("unroll") for (int k = 0; k < 2; ++k) dst[m][k] = *(const PG8_LAS bf16x8*)(lds + PG8_SA(b, h) + aoff + m * 2048 + k * 1024); } while (0)
; #define PG8_MMA(ai, bj, At, Bt) do { __builtin_amdgcn_s_setprio(1); _Pragma("unroll") for (int m = 0; m < 4; ++m) _Pragma("unroll") for (int n = 0; n < 2; ++n) _Pragma("unroll") for (int k = 0; k < 2; ++k) \
;         acc[ai][bj][m][n] = __builtin_amdgcn_mfma_f32_16x16x32_bf16(Bt[n][k], At[m][k], acc[ai][bj][m][n], 0, 0, 0); __builtin_amdgcn_s_setprio(0); } while (0)
; #define PG8_WAIT_V(n) asm volatile("s_waitcnt vmcnt(" #n ")" ::: "memory")
; #define PG8_WAIT_L(n) asm volatile("s_waitcnt lgkmcnt(" #n ")" ::: "memory")
; #define PG8_BAR __builtin_amdgcn_s_barrier()
; #define PG8_SCHED __builtin_amdgcn_sched_barrier(0)
; template <class Epi, class Sched, bool ALIGN_EPI = false, bool SP2 = false, bool APERM = false  >
; __device__ __forceinline__ void gemm_phase(PG8_LAS unsigned char* lds, const Gemm g, const Sched& S, const Epi& E, const int wid  ) {
;     ...
;         for (int t = 0; t < nt; t += 2) {
;             const bool last = (t == nt - 2);
;     ...
;             PG8_LDA(At, 1, 1); PG8_STAGE(PG8_SB(1, 0), b3, voffB); PG8_STAGE(PG8_SB(1, 1), b3 + hstep, voffB); PG8_STAGE(PG8_SA(1, 0), a3, voffA);
;             PG8_WAIT_V(8); PG8_WAIT_L(0); PG8_BAR; PG8_MMA(1, 0, At, B0); PG8_MMA(1, 1, At, B1); PG8_BAR; PG8_SCHED;
	s_add_i32 s12, s30, s96
	v_lshl_add_u64 v[206:207], v[206:207], 0, s[64:65]
	s_mov_b32 m0, s12
	ds_read_b128 v[160:163], v247 offset:49152
	ds_read_b128 v[164:167], v247 offset:50176
	ds_read_b128 v[168:171], v247 offset:51200
	ds_read_b128 v[172:175], v247 offset:52224
	ds_read_b128 v[176:179], v247 offset:53248
	ds_read_b128 v[180:183], v247 offset:54272
	ds_read_b128 v[198:201], v247 offset:55296
	ds_read_b128 v[202:205], v247 offset:56320
	global_load_lds_dwordx4 v[206:207], off
	s_add_i32 m0, s12, 0x2000
	s_add_u32 s10, s10, 0x80080
	v_lshl_add_u64 v[206:207], v[208:209], 0, s[64:65]
	s_addc_u32 s11, s11, 0
	s_add_i32 s12, s31, s96
	global_load_lds_dwordx4 v[206:207], off
	v_lshl_add_u64 v[206:207], s[10:11], 0, v[184:185]
	s_mov_b32 m0, s12
	s_nop 0
	global_load_lds_dwordx4 v[206:207], off
	v_lshl_add_u64 v[206:207], s[10:11], 0, v[186:187]
	s_add_i32 m0, s12, 0x2000
	s_nop 0
	global_load_lds_dwordx4 v[206:207], off
	v_lshl_add_u64 v[206:207], v[210:211], 0, s[64:65]
	s_mov_b32 m0, s58
	s_nop 0
	global_load_lds_dwordx4 v[206:207], off
	v_lshl_add_u64 v[206:207], v[212:213], 0, s[64:65]
	s_mov_b32 m0, s59
	s_nop 0
	global_load_lds_dwordx4 v[206:207], off
	s_waitcnt vmcnt(8)
	s_waitcnt lgkmcnt(0)
	s_barrier
	s_setprio 1
	s_waitcnt lgkmcnt(0)
	v_mfma_f32_16x16x32_bf16 v[60:63], v[128:131], v[160:163], v[60:63]
	v_mfma_f32_16x16x32_bf16 v[60:63], v[132:135], v[164:167], v[60:63]
	v_mfma_f32_16x16x32_bf16 v[56:59], v[140:143], v[164:167], v[56:59]
	v_mfma_f32_16x16x32_bf16 v[56:59], v[136:139], v[160:163], v[56:59]
	v_mfma_f32_16x16x32_bf16 v[28:31], v[144:147], v[160:163], v[28:31]
	v_mfma_f32_16x16x32_bf16 v[28:31], v[148:151], v[164:167], v[28:31]
	v_mfma_f32_16x16x32_bf16 v[24:27], v[156:159], v[164:167], v[24:27]
	v_mfma_f32_16x16x32_bf16 v[24:27], v[152:155], v[160:163], v[24:27]
	v_mfma_f32_16x16x32_bf16 v[16:19], v[152:155], v[168:171], v[16:19]
	v_mfma_f32_16x16x32_bf16 v[16:19], v[156:159], v[172:175], v[16:19]
	v_mfma_f32_16x16x32_bf16 v[20:23], v[148:151], v[172:175], v[20:23]
	v_mfma_f32_16x16x32_bf16 v[20:23], v[144:147], v[168:171], v[20:23]
	v_mfma_f32_16x16x32_bf16 v[48:51], v[136:139], v[168:171], v[48:51]
	v_mfma_f32_16x16x32_bf16 v[48:51], v[140:143], v[172:175], v[48:51]
	v_mfma_f32_16x16x32_bf16 v[52:55], v[132:135], v[172:175], v[52:55]
	v_mfma_f32_16x16x32_bf16 v[52:55], v[128:131], v[168:171], v[52:55]
	v_mfma_f32_16x16x32_bf16 v[44:47], v[128:131], v[176:179], v[44:47]
	v_mfma_f32_16x16x32_bf16 v[44:47], v[132:135], v[180:183], v[44:47]
	v_mfma_f32_16x16x32_bf16 v[40:43], v[140:143], v[180:183], v[40:43]
	v_mfma_f32_16x16x32_bf16 v[40:43], v[136:139], v[176:179], v[40:43]
	v_mfma_f32_16x16x32_bf16 v[12:15], v[144:147], v[176:179], v[12:15]
	v_mfma_f32_16x16x32_bf16 v[12:15], v[148:151], v[180:183], v[12:15]
	v_mfma_f32_16x16x32_bf16 v[8:11], v[156:159], v[180:183], v[8:11]
	v_mfma_f32_16x16x32_bf16 v[8:11], v[152:155], v[176:179], v[8:11]
	v_mfma_f32_16x16x32_bf16 v[0:3], v[152:155], v[198:201], v[0:3]
	v_mfma_f32_16x16x32_bf16 v[0:3], v[156:159], v[202:205], v[0:3]
	v_mfma_f32_16x16x32_bf16 v[4:7], v[148:151], v[202:205], v[4:7]
	v_mfma_f32_16x16x32_bf16 v[4:7], v[144:147], v[198:201], v[4:7]
	v_mfma_f32_16x16x32_bf16 v[32:35], v[136:139], v[198:201], v[32:35]
	v_mfma_f32_16x16x32_bf16 v[32:35], v[140:143], v[202:205], v[32:35]
	v_mfma_f32_16x16x32_bf16 v[36:39], v[132:135], v[202:205], v[36:39]
	v_mfma_f32_16x16x32_bf16 v[36:39], v[128:131], v[198:201], v[36:39]
	s_setprio 0
	s_barrier
	s_add_i32 s10, s69, 2
	s_cmp_gt_u32 s69, 29
	s_cbranch_scc1 .LBB0_1101
	s_mov_b32 s69, s10
	s_branch .LBB0_1077

; #define PG8_STAGE(bufoff, gbase, voff) do { _Pragma("unroll") for (int _i = 0; _i < 2; ++_i) \
;         __builtin_amdgcn_global_load_lds((const unsigned*)((const char*)(gbase) + (voff)[_i]), (PG8_LAS unsigned*)(lds + (bufoff) + ldsw + _i * 8192), 16, 0, 0); } while (0)
; #define PG8_LDA(dst, b, h) do { _Pragma("unroll") for (int m = 0; m < 4; ++m) _Pragma("unroll") for (int k = 0; k < 2; ++k) dst[m][k] = *(const PG8_LAS bf16x8*)(lds + PG8_SA(b, h) + aoff + m * 2048 + k * 1024); } while (0)
; #define PG8_WAIT_V(n) asm volatile("s_waitcnt vmcnt(" #n ")" ::: "memory")
; #define PG8_WAIT_L(n) asm volatile("s_waitcnt lgkmcnt(" #n ")" ::: "memory")
; template <class Epi, class Sched, bool ALIGN_EPI = false, bool SP2 = false, bool APERM = false  >
; __device__ __forceinline__ void gemm_phase(PG8_LAS unsigned char* lds, const Gemm g, const Sched& S, const Epi& E, const int wid  ) {
;     ...
;         for (int t = 0; t < nt; t += 2) {
;             const bool last = (t == nt - 2);
;             const char* a1 = cA + (size_t)(t + 1) * kstep;
;             const char* a2 = last ? nA : cA + (size_t)(t + 2) * kstep; const char* b2 = last ? nB : cB + (size_t)(t + 2) * kstep;
;             const char* a3 = a2 + kstep; const char* b3 = b2 + kstep;
;             if (last && has_next) S.a_ready(nxt);
;             if constexpr (SP2) {
;             PG8_LDB(B0, 0, 0); PG8_LDB(B1, 0, 1); PG8_SCHED; PG8_LDA(At, 0, 0); PG8_STAGE(PG8_SA(1, 1), a1 + hstep, voffA);
;             PG8_WAIT_V(8); PG8_WAIT_L(0); PG8_BAR; PG8_MMA(0, 0, At, B0); PG8_MMA(0, 1, At, B1); PG8_BAR; PG8_SCHED;
;             PG8_LDA(At, 0, 1); PG8_STAGE(PG8_SB(0, 0), b2, voffB); PG8_STAGE(PG8_SB(0, 1), b2 + hstep, voffB); PG8_STAGE(PG8_SA(0, 0), a2, voffA);
;             PG8_WAIT_V(8); PG8_WAIT_L(0); PG8_BAR; PG8_MMA(1, 0, At, B0); PG8_MMA(1, 1, At, B1); PG8_BAR; PG8_SCHED;
;             PG8_LDB(B0, 1, 0); PG8_LDB(B1, 1, 1); PG8_SCHED; PG8_LDA(At, 1, 0); PG8_STAGE(PG8_SA(0, 1), a2 + hstep, voffA);
;             PG8_WAIT_V(8); PG8_WAIT_L(0); PG8_BAR; PG8_MMA(0, 0, At, B0); PG8_MMA(0, 1, At, B1); PG8_BAR; PG8_SCHED;
;             PG8_LDA(At, 1, 1); PG8_STAGE(PG8_SB(1, 0), b3, voffB); PG8_STAGE(PG8_SB(1, 1), b3 + hstep, voffB); PG8_STAGE(PG8_SA(1, 0), a3, voffA);
;             PG8_WAIT_V(8); PG8_WAIT_L(0); PG8_BAR; PG8_MMA(1, 0, At, B0); PG8_MMA(1, 1, At, B1); PG8_BAR; PG8_SCHED;
.LBB0_1252:
	s_lshl_b32 s74, s53, 7
	s_add_u32 s75, s14, s74
	s_addc_u32 s78, s15, 0
	v_add_u32_e32 v146, s33, v150
	s_add_u32 s72, s75, 0x100
	ds_read_b128 v[142:145], v146
	ds_read_b128 v[154:157], v146 offset:1024
	ds_read_b128 v[158:161], v146 offset:2048
	ds_read_b128 v[162:165], v146 offset:3072
	v_add_u32_e32 v146, s96, v150
	s_addc_u32 s73, s78, 0
	ds_read_b128 v[166:169], v146
	ds_read_b128 v[170:173], v146 offset:1024
	ds_read_b128 v[174:177], v146 offset:2048
	ds_read_b128 v[178:181], v146 offset:3072
	s_and_b64 s[46:47], s[70:71], exec
	s_cselect_b32 s73, s65, s73
	s_cselect_b32 s72, s64, s72
	s_add_u32 s46, s10, s74
	s_addc_u32 s47, s11, 0
	s_add_u32 s74, s46, 0x100
	s_addc_u32 vcc_lo, s47, 0
	s_and_b64 s[46:47], s[70:71], exec
	s_cselect_b32 s71, s67, vcc_lo
	s_cselect_b32 s70, s66, s74
	s_add_u32 s46, s75, 0x160080
	s_addc_u32 s47, s78, 0
	v_lshl_add_u64 v[146:147], s[46:47], 0, v[132:133]
	s_add_i32 m0, s87, 0xc000
	ds_read_b128 v[182:185], v153
	ds_read_b128 v[186:189], v153 offset:1024
	ds_read_b128 v[190:193], v153 offset:2048
	ds_read_b128 v[194:197], v153 offset:3072
	ds_read_b128 v[198:201], v153 offset:4096
	ds_read_b128 v[202:205], v153 offset:5120
	ds_read_b128 v[206:209], v153 offset:6144
	ds_read_b128 v[210:213], v153 offset:7168
	global_load_lds_dwordx4 v[146:147], off
	v_lshl_add_u64 v[146:147], s[46:47], 0, v[134:135]
	s_add_i32 m0, s87, 0xe000
	s_nop 0
	global_load_lds_dwordx4 v[146:147], off
	s_waitcnt vmcnt(8)
	s_waitcnt lgkmcnt(0)
	s_barrier
	s_setprio 1
	s_waitcnt lgkmcnt(0)
	v_mfma_f32_16x16x32_bf16 v[124:127], v[142:145], v[182:185], v[124:127]
	v_mfma_f32_16x16x32_bf16 v[124:127], v[154:157], v[186:189], v[124:127]
	v_mfma_f32_16x16x32_bf16 v[120:123], v[162:165], v[186:189], v[120:123]
	v_mfma_f32_16x16x32_bf16 v[120:123], v[158:161], v[182:185], v[120:123]
	v_mfma_f32_16x16x32_bf16 v[92:95], v[166:169], v[182:185], v[92:95]
	v_mfma_f32_16x16x32_bf16 v[92:95], v[170:173], v[186:189], v[92:95]
	v_mfma_f32_16x16x32_bf16 v[88:91], v[178:181], v[186:189], v[88:91]
	v_mfma_f32_16x16x32_bf16 v[88:91], v[174:177], v[182:185], v[88:91]
	v_mfma_f32_16x16x32_bf16 v[80:83], v[174:177], v[190:193], v[80:83]
	v_mfma_f32_16x16x32_bf16 v[80:83], v[178:181], v[194:197], v[80:83]
	v_mfma_f32_16x16x32_bf16 v[84:87], v[170:173], v[194:197], v[84:87]
	v_mfma_f32_16x16x32_bf16 v[84:87], v[166:169], v[190:193], v[84:87]
	v_mfma_f32_16x16x32_bf16 v[112:115], v[158:161], v[190:193], v[112:115]
	v_mfma_f32_16x16x32_bf16 v[112:115], v[162:165], v[194:197], v[112:115]
	v_mfma_f32_16x16x32_bf16 v[116:119], v[154:157], v[194:197], v[116:119]
	v_mfma_f32_16x16x32_bf16 v[116:119], v[142:145], v[190:193], v[116:119]
	v_mfma_f32_16x16x32_bf16 v[108:111], v[142:145], v[198:201], v[108:111]
	v_mfma_f32_16x16x32_bf16 v[108:111], v[154:157], v[202:205], v[108:111]
	v_mfma_f32_16x16x32_bf16 v[104:107], v[162:165], v[202:205], v[104:107]
	v_mfma_f32_16x16x32_bf16 v[104:107], v[158:161], v[198:201], v[104:107]
	v_mfma_f32_16x16x32_bf16 v[76:79], v[166:169], v[198:201], v[76:79]
	v_mfma_f32_16x16x32_bf16 v[76:79], v[170:173], v[202:205], v[76:79]
	v_mfma_f32_16x16x32_bf16 v[72:75], v[178:181], v[202:205], v[72:75]
	v_mfma_f32_16x16x32_bf16 v[72:75], v[174:177], v[198:201], v[72:75]
	v_mfma_f32_16x16x32_bf16 v[64:67], v[174:177], v[206:209], v[64:67]
	v_mfma_f32_16x16x32_bf16 v[64:67], v[178:181], v[210:213], v[64:67]
	v_mfma_f32_16x16x32_bf16 v[68:71], v[170:173], v[210:213], v[68:71]
	v_mfma_f32_16x16x32_bf16 v[68:71], v[166:169], v[206:209], v[68:71]
	v_mfma_f32_16x16x32_bf16 v[96:99], v[158:161], v[206:209], v[96:99]
	v_mfma_f32_16x16x32_bf16 v[96:99], v[162:165], v[210:213], v[96:99]
	v_mfma_f32_16x16x32_bf16 v[100:103], v[154:157], v[210:213], v[100:103]
	v_mfma_f32_16x16x32_bf16 v[100:103], v[142:145], v[206:209], v[100:103]
	s_setprio 0
	s_barrier
	s_add_i32 s46, s33, s79
	v_lshl_add_u64 v[146:147], s[70:71], 0, v[128:129]
	s_mov_b32 m0, s46
	ds_read_b128 v[182:185], v153 offset:16384
	ds_read_b128 v[186:189], v153 offset:17408
	ds_read_b128 v[190:193], v153 offset:18432
	ds_read_b128 v[194:197], v153 offset:19456
	ds_read_b128 v[198:201], v153 offset:20480
	ds_read_b128 v[202:205], v153 offset:21504
	ds_read_b128 v[206:209], v153 offset:22528
	ds_read_b128 v[210:213], v153 offset:23552
	global_load_lds_dwordx4 v[146:147], off
	s_add_i32 m0, s46, 0x2000
	s_add_u32 s46, s70, 0x160000
	v_lshl_add_u64 v[214:215], s[70:71], 0, v[130:131]
	s_addc_u32 s47, s71, 0
	s_add_i32 s74, s96, s79
	global_load_lds_dwordx4 v[214:215], off
	v_lshl_add_u64 v[216:217], s[46:47], 0, v[128:129]
	s_mov_b32 m0, s74
	v_lshl_add_u64 v[218:219], s[72:73], 0, v[134:135]
	global_load_lds_dwordx4 v[216:217], off
	v_lshl_add_u64 v[216:217], s[46:47], 0, v[130:131]
	s_add_i32 m0, s74, 0x2000
	s_nop 0
	global_load_lds_dwordx4 v[216:217], off
	v_lshl_add_u64 v[216:217], s[72:73], 0, v[132:133]
	s_mov_b32 m0, s87
	s_nop 0
	global_load_lds_dwordx4 v[216:217], off
	s_mov_b32 m0, s88
	s_nop 0
	global_load_lds_dwordx4 v[218:219], off
	s_waitcnt vmcnt(8)
	s_waitcnt lgkmcnt(0)
	s_barrier
; #define PG8_STAGE(bufoff, gbase, voff) do { _Pragma("unroll") for (int _i = 0; _i < 2; ++_i) \
;         __builtin_amdgcn_global_load_lds((const unsigned*)((const char*)(gbase) + (voff)[_i]), (PG8_LAS unsigned*)(lds + (bufoff) + ldsw + _i * 8192), 16, 0, 0); } while (0)
; #define PG8_LDA(dst, b, h) do { _Pragma("unroll") for (int m = 0; m < 4; ++m) _Pragma("unroll") for (int k = 0; k < 2; ++k) dst[m][k] = *(const PG8_LAS bf16x8*)(lds + PG8_SA(b, h) + aoff + m * 2048 + k * 1024); } while (0)
; #define PG8_LDB(dst, b, h) do { _Pragma("unroll") for (int n = 0; n < 2; ++n) _Pragma("unroll") for (int k = 0; k < 2; ++k) dst[n][k] = *(const PG8_LAS bf16x8*)(lds + PG8_SB(b, h) + boff + n * 2048 + k * 1024); } while (0)
; #define PG8_MMA(ai, bj, At, Bt) do { __builtin_amdgcn_s_setprio(1); _Pragma("unroll") for (int m = 0; m < 4; ++m) _Pragma("unroll") for (int n = 0; n < 2; ++n) _Pragma("unroll") for (int k = 0; k < 2; ++k) \
;         acc[ai][bj][m][n] = __builtin_amdgcn_mfma_f32_16x16x32_bf16(Bt[n][k], At[m][k], acc[ai][bj][m][n], 0, 0, 0); __builtin_amdgcn_s_setprio(0); } while (0)
; #define PG8_WAIT_V(n) asm volatile("s_waitcnt vmcnt(" #n ")" ::: "memory")
; #define PG8_WAIT_L(n) asm volatile("s_waitcnt lgkmcnt(" #n ")" ::: "memory")
; #define PG8_BAR __builtin_amdgcn_s_barrier()
; #define PG8_SCHED __builtin_amdgcn_sched_barrier(0)
; template <class Epi, class Sched, bool ALIGN_EPI = false, bool SP2 = false, bool APERM = false  >
; __device__ __forceinline__ void gemm_phase(PG8_LAS unsigned char* lds, const Gemm g, const Sched& S, const Epi& E, const int wid  ) {
;     ...
;             PG8_WAIT_V(8); PG8_WAIT_L(0); PG8_BAR; PG8_MMA(0, 0, At, B0); PG8_MMA(0, 1, At, B1); PG8_BAR; PG8_SCHED;
;             PG8_LDA(At, 0, 1); PG8_STAGE(PG8_SB(0, 0), b2, voffB); PG8_STAGE(PG8_SB(0, 1), b2 + hstep, voffB); PG8_STAGE(PG8_SA(0, 0), a2, voffA);
;             PG8_WAIT_V(8); PG8_WAIT_L(0); PG8_BAR; PG8_MMA(1, 0, At, B0); PG8_MMA(1, 1, At, B1); PG8_BAR; PG8_SCHED;
;             PG8_LDB(B0, 1, 0); PG8_LDB(B1, 1, 1); PG8_SCHED; PG8_LDA(At, 1, 0); PG8_STAGE(PG8_SA(0, 1), a2 + hstep, voffA);
;             PG8_WAIT_V(8); PG8_WAIT_L(0); PG8_BAR; PG8_MMA(0, 0, At, B0); PG8_MMA(0, 1, At, B1); PG8_BAR; PG8_SCHED;
	s_setprio 1
	s_waitcnt lgkmcnt(0)
	v_mfma_f32_16x16x32_bf16 v[60:63], v[142:145], v[182:185], v[60:63]
	v_mfma_f32_16x16x32_bf16 v[60:63], v[154:157], v[186:189], v[60:63]
	v_mfma_f32_16x16x32_bf16 v[56:59], v[162:165], v[186:189], v[56:59]
	v_mfma_f32_16x16x32_bf16 v[56:59], v[158:161], v[182:185], v[56:59]
	v_mfma_f32_16x16x32_bf16 v[28:31], v[166:169], v[182:185], v[28:31]
	v_mfma_f32_16x16x32_bf16 v[28:31], v[170:173], v[186:189], v[28:31]
	v_mfma_f32_16x16x32_bf16 v[24:27], v[178:181], v[186:189], v[24:27]
	v_mfma_f32_16x16x32_bf16 v[24:27], v[174:177], v[182:185], v[24:27]
	v_mfma_f32_16x16x32_bf16 v[16:19], v[174:177], v[190:193], v[16:19]
	v_mfma_f32_16x16x32_bf16 v[16:19], v[178:181], v[194:197], v[16:19]
	v_mfma_f32_16x16x32_bf16 v[20:23], v[170:173], v[194:197], v[20:23]
	v_mfma_f32_16x16x32_bf16 v[20:23], v[166:169], v[190:193], v[20:23]
	v_mfma_f32_16x16x32_bf16 v[48:51], v[158:161], v[190:193], v[48:51]
	v_mfma_f32_16x16x32_bf16 v[48:51], v[162:165], v[194:197], v[48:51]
	v_mfma_f32_16x16x32_bf16 v[52:55], v[154:157], v[194:197], v[52:55]
	v_mfma_f32_16x16x32_bf16 v[52:55], v[142:145], v[190:193], v[52:55]
	v_mfma_f32_16x16x32_bf16 v[44:47], v[142:145], v[198:201], v[44:47]
	v_mfma_f32_16x16x32_bf16 v[44:47], v[154:157], v[202:205], v[44:47]
	v_mfma_f32_16x16x32_bf16 v[40:43], v[162:165], v[202:205], v[40:43]
	v_mfma_f32_16x16x32_bf16 v[40:43], v[158:161], v[198:201], v[40:43]
	v_mfma_f32_16x16x32_bf16 v[12:15], v[166:169], v[198:201], v[12:15]
	v_mfma_f32_16x16x32_bf16 v[12:15], v[170:173], v[202:205], v[12:15]
	v_mfma_f32_16x16x32_bf16 v[8:11], v[178:181], v[202:205], v[8:11]
	v_mfma_f32_16x16x32_bf16 v[8:11], v[174:177], v[198:201], v[8:11]
	v_mfma_f32_16x16x32_bf16 v[0:3], v[174:177], v[206:209], v[0:3]
	v_mfma_f32_16x16x32_bf16 v[0:3], v[178:181], v[210:213], v[0:3]
	v_mfma_f32_16x16x32_bf16 v[4:7], v[170:173], v[210:213], v[4:7]
	v_mfma_f32_16x16x32_bf16 v[4:7], v[166:169], v[206:209], v[4:7]
	v_mfma_f32_16x16x32_bf16 v[32:35], v[158:161], v[206:209], v[32:35]
	v_mfma_f32_16x16x32_bf16 v[32:35], v[162:165], v[210:213], v[32:35]
	v_mfma_f32_16x16x32_bf16 v[36:39], v[154:157], v[210:213], v[36:39]
	v_mfma_f32_16x16x32_bf16 v[36:39], v[142:145], v[206:209], v[36:39]
	s_setprio 0
	s_barrier
	s_add_i32 s74, 0, 0x18000
	s_add_i32 s75, 0, 0x1c000
	v_add_u32_e32 v162, s74, v150
	v_add_u32_e32 v178, s75, v150
	ds_read_b128 v[142:145], v162
	ds_read_b128 v[154:157], v162 offset:1024
	ds_read_b128 v[158:161], v162 offset:2048
	ds_read_b128 v[162:165], v162 offset:3072
	ds_read_b128 v[166:169], v178
	ds_read_b128 v[170:173], v178 offset:1024
	ds_read_b128 v[174:177], v178 offset:2048
	ds_read_b128 v[178:181], v178 offset:3072
	s_add_u32 s46, s72, 0x160000
	s_addc_u32 s47, s73, 0
	s_mov_b32 m0, s89
	v_lshl_add_u64 v[220:221], s[46:47], 0, v[132:133]
	ds_read_b128 v[182:185], v153 offset:32768
	ds_read_b128 v[186:189], v153 offset:33792
	ds_read_b128 v[190:193], v153 offset:34816
	ds_read_b128 v[194:197], v153 offset:35840
	ds_read_b128 v[198:201], v153 offset:36864
	ds_read_b128 v[202:205], v153 offset:37888
	ds_read_b128 v[206:209], v153 offset:38912
	ds_read_b128 v[210:213], v153 offset:39936
	global_load_lds_dwordx4 v[220:221], off
	v_lshl_add_u64 v[220:221], s[46:47], 0, v[134:135]
	s_mov_b32 m0, s90
	s_nop 0
	global_load_lds_dwordx4 v[220:221], off
	s_waitcnt vmcnt(8)
	s_waitcnt lgkmcnt(0)
	s_barrier
	s_setprio 1
	s_waitcnt lgkmcnt(0)
	v_mfma_f32_16x16x32_bf16 v[124:127], v[142:145], v[182:185], v[124:127]
	v_mfma_f32_16x16x32_bf16 v[124:127], v[154:157], v[186:189], v[124:127]
	v_mfma_f32_16x16x32_bf16 v[120:123], v[162:165], v[186:189], v[120:123]
	v_mfma_f32_16x16x32_bf16 v[120:123], v[158:161], v[182:185], v[120:123]
	v_mfma_f32_16x16x32_bf16 v[92:95], v[166:169], v[182:185], v[92:95]
	v_mfma_f32_16x16x32_bf16 v[92:95], v[170:173], v[186:189], v[92:95]
	v_mfma_f32_16x16x32_bf16 v[88:91], v[178:181], v[186:189], v[88:91]
	v_mfma_f32_16x16x32_bf16 v[88:91], v[174:177], v[182:185], v[88:91]
	v_mfma_f32_16x16x32_bf16 v[80:83], v[174:177], v[190:193], v[80:83]
	v_mfma_f32_16x16x32_bf16 v[80:83], v[178:181], v[194:197], v[80:83]
	v_mfma_f32_16x16x32_bf16 v[84:87], v[170:173], v[194:197], v[84:87]
	v_mfma_f32_16x16x32_bf16 v[84:87], v[166:169], v[190:193], v[84:87]
	v_mfma_f32_16x16x32_bf16 v[112:115], v[158:161], v[190:193], v[112:115]
	v_mfma_f32_16x16x32_bf16 v[112:115], v[162:165], v[194:197], v[112:115]
	v_mfma_f32_16x16x32_bf16 v[116:119], v[154:157], v[194:197], v[116:119]
	v_mfma_f32_16x16x32_bf16 v[116:119], v[142:145], v[190:193], v[116:119]
	v_mfma_f32_16x16x32_bf16 v[108:111], v[142:145], v[198:201], v[108:111]
	v_mfma_f32_16x16x32_bf16 v[108:111], v[154:157], v[202:205], v[108:111]
	v_mfma_f32_16x16x32_bf16 v[104:107], v[162:165], v[202:205], v[104:107]
	v_mfma_f32_16x16x32_bf16 v[104:107], v[158:161], v[198:201], v[104:107]
	v_mfma_f32_16x16x32_bf16 v[76:79], v[166:169], v[198:201], v[76:79]
	v_mfma_f32_16x16x32_bf16 v[76:79], v[170:173], v[202:205], v[76:79]
	v_mfma_f32_16x16x32_bf16 v[72:75], v[178:181], v[202:205], v[72:75]
	v_mfma_f32_16x16x32_bf16 v[72:75], v[174:177], v[198:201], v[72:75]
	v_mfma_f32_16x16x32_bf16 v[64:67], v[174:177], v[206:209], v[64:67]
	v_mfma_f32_16x16x32_bf16 v[64:67], v[178:181], v[210:213], v[64:67]
	v_mfma_f32_16x16x32_bf16 v[68:71], v[170:173], v[210:213], v[68:71]
	v_mfma_f32_16x16x32_bf16 v[68:71], v[166:169], v[206:209], v[68:71]
	v_mfma_f32_16x16x32_bf16 v[96:99], v[158:161], v[206:209], v[96:99]
	v_mfma_f32_16x16x32_bf16 v[96:99], v[162:165], v[210:213], v[96:99]
	v_mfma_f32_16x16x32_bf16 v[100:103], v[154:157], v[210:213], v[100:103]
	v_mfma_f32_16x16x32_bf16 v[100:103], v[142:145], v[206:209], v[100:103]
	s_setprio 0
	s_barrier
; #define PG8_STAGE(bufoff, gbase, voff) do { _Pragma("unroll") for (int _i = 0; _i < 2; ++_i) \
;         __builtin_amdgcn_global_load_lds((const unsigned*)((const char*)(gbase) + (voff)[_i]), (PG8_LAS unsigned*)(lds + (bufoff) + ldsw + _i * 8192), 16, 0, 0); } while (0)
; #define PG8_LDA(dst, b, h) do { _Pragma("unroll") for (int m = 0; m < 4; ++m) _Pragma("unroll") for (int k = 0; k < 2; ++k) dst[m][k] = *(const PG8_LAS bf16x8*)(lds + PG8_SA(b, h) + aoff + m * 2048 + k * 1024); } while (0)
; #define PG8_MMA(ai, bj, At, Bt) do { __builtin_amdgcn_s_setprio(1); _Pragma("unroll") for (int m = 0; m < 4; ++m) _Pragma("unroll") for (int n = 0; n < 2; ++n) _Pragma("unroll") for (int k = 0; k < 2; ++k) \
;         acc[ai][bj][m][n] = __builtin_amdgcn_mfma_f32_16x16x32_bf16(Bt[n][k], At[m][k], acc[ai][bj][m][n], 0, 0, 0); __builtin_amdgcn_s_setprio(0); } while (0)
; #define PG8_WAIT_V(n) asm volatile("s_waitcnt vmcnt(" #n ")" ::: "memory")
; #define PG8_WAIT_L(n) asm volatile("s_waitcnt lgkmcnt(" #n ")" ::: "memory")
; #define PG8_BAR __builtin_amdgcn_s_barrier()
; #define PG8_SCHED __builtin_amdgcn_sched_barrier(0)
; template <class Epi, class Sched, bool ALIGN_EPI = false, bool SP2 = false, bool APERM = false  >
; __device__ __forceinline__ void gemm_phase(PG8_LAS unsigned char* lds, const Gemm g, const Sched& S, const Epi& E, const int wid  ) {
;     ...
;         for (int t = 0; t < nt; t += 2) {
;             const bool last = (t == nt - 2);
;     ...
;             PG8_LDA(At, 1, 1); PG8_STAGE(PG8_SB(1, 0), b3, voffB); PG8_STAGE(PG8_SB(1, 1), b3 + hstep, voffB); PG8_STAGE(PG8_SA(1, 0), a3, voffA);
;             PG8_WAIT_V(8); PG8_WAIT_L(0); PG8_BAR; PG8_MMA(1, 0, At, B0); PG8_MMA(1, 1, At, B1); PG8_BAR; PG8_SCHED;
	s_add_i32 s46, s74, s79
	v_lshl_add_u64 v[146:147], v[146:147], 0, s[24:25]
	s_mov_b32 m0, s46
	ds_read_b128 v[182:185], v153 offset:49152
	ds_read_b128 v[186:189], v153 offset:50176
	ds_read_b128 v[190:193], v153 offset:51200
	ds_read_b128 v[194:197], v153 offset:52224
	ds_read_b128 v[198:201], v153 offset:53248
	ds_read_b128 v[202:205], v153 offset:54272
	ds_read_b128 v[206:209], v153 offset:55296
	ds_read_b128 v[210:213], v153 offset:56320
	global_load_lds_dwordx4 v[146:147], off
	s_add_i32 m0, s46, 0x2000
	s_add_u32 s46, s70, 0x160080
	v_lshl_add_u64 v[146:147], v[214:215], 0, s[24:25]
	s_addc_u32 s47, s71, 0
	s_add_i32 s70, s75, s79
	global_load_lds_dwordx4 v[146:147], off
	v_lshl_add_u64 v[146:147], s[46:47], 0, v[128:129]
	s_mov_b32 m0, s70
	s_nop 0
	global_load_lds_dwordx4 v[146:147], off
	v_lshl_add_u64 v[146:147], s[46:47], 0, v[130:131]
	s_add_i32 m0, s70, 0x2000
	s_nop 0
	global_load_lds_dwordx4 v[146:147], off
	v_lshl_add_u64 v[146:147], v[216:217], 0, s[24:25]
	s_mov_b32 m0, s93
	s_nop 0
	global_load_lds_dwordx4 v[146:147], off
	v_lshl_add_u64 v[146:147], v[218:219], 0, s[24:25]
	s_mov_b32 m0, s95
	s_nop 0
	global_load_lds_dwordx4 v[146:147], off
	s_waitcnt vmcnt(8)
	s_waitcnt lgkmcnt(0)
	s_barrier
	s_setprio 1
	s_waitcnt lgkmcnt(0)
	v_mfma_f32_16x16x32_bf16 v[60:63], v[142:145], v[182:185], v[60:63]
	v_mfma_f32_16x16x32_bf16 v[60:63], v[154:157], v[186:189], v[60:63]
	v_mfma_f32_16x16x32_bf16 v[56:59], v[162:165], v[186:189], v[56:59]
	v_mfma_f32_16x16x32_bf16 v[56:59], v[158:161], v[182:185], v[56:59]
	v_mfma_f32_16x16x32_bf16 v[28:31], v[166:169], v[182:185], v[28:31]
	v_mfma_f32_16x16x32_bf16 v[28:31], v[170:173], v[186:189], v[28:31]
	v_mfma_f32_16x16x32_bf16 v[24:27], v[178:181], v[186:189], v[24:27]
	v_mfma_f32_16x16x32_bf16 v[24:27], v[174:177], v[182:185], v[24:27]
	v_mfma_f32_16x16x32_bf16 v[16:19], v[174:177], v[190:193], v[16:19]
	v_mfma_f32_16x16x32_bf16 v[16:19], v[178:181], v[194:197], v[16:19]
	v_mfma_f32_16x16x32_bf16 v[20:23], v[170:173], v[194:197], v[20:23]
	v_mfma_f32_16x16x32_bf16 v[20:23], v[166:169], v[190:193], v[20:23]
	v_mfma_f32_16x16x32_bf16 v[48:51], v[158:161], v[190:193], v[48:51]
	v_mfma_f32_16x16x32_bf16 v[48:51], v[162:165], v[194:197], v[48:51]
	v_mfma_f32_16x16x32_bf16 v[52:55], v[154:157], v[194:197], v[52:55]
	v_mfma_f32_16x16x32_bf16 v[52:55], v[142:145], v[190:193], v[52:55]
	v_mfma_f32_16x16x32_bf16 v[44:47], v[142:145], v[198:201], v[44:47]
	v_mfma_f32_16x16x32_bf16 v[44:47], v[154:157], v[202:205], v[44:47]
	v_mfma_f32_16x16x32_bf16 v[40:43], v[162:165], v[202:205], v[40:43]
	v_mfma_f32_16x16x32_bf16 v[40:43], v[158:161], v[198:201], v[40:43]
	v_mfma_f32_16x16x32_bf16 v[12:15], v[166:169], v[198:201], v[12:15]
	v_mfma_f32_16x16x32_bf16 v[12:15], v[170:173], v[202:205], v[12:15]
	v_mfma_f32_16x16x32_bf16 v[8:11], v[178:181], v[202:205], v[8:11]
	v_mfma_f32_16x16x32_bf16 v[8:11], v[174:177], v[198:201], v[8:11]
	v_mfma_f32_16x16x32_bf16 v[0:3], v[174:177], v[206:209], v[0:3]
	v_mfma_f32_16x16x32_bf16 v[0:3], v[178:181], v[210:213], v[0:3]
	v_mfma_f32_16x16x32_bf16 v[4:7], v[170:173], v[210:213], v[4:7]
	v_mfma_f32_16x16x32_bf16 v[4:7], v[166:169], v[206:209], v[4:7]
	v_mfma_f32_16x16x32_bf16 v[32:35], v[158:161], v[206:209], v[32:35]
	v_mfma_f32_16x16x32_bf16 v[32:35], v[162:165], v[210:213], v[32:35]
	v_mfma_f32_16x16x32_bf16 v[36:39], v[154:157], v[210:213], v[36:39]
	v_mfma_f32_16x16x32_bf16 v[36:39], v[142:145], v[206:209], v[36:39]
	s_setprio 0
	s_barrier
	s_add_i32 s46, s53, 2
	s_cmp_gt_u32 s53, 41
	s_cbranch_scc1 .LBB0_1254
	s_mov_b32 s53, s46
	s_branch .LBB0_1235

; #define PG8_STAGE(bufoff, gbase, voff) do { _Pragma("unroll") for (int _i = 0; _i < 2; ++_i) \
;         __builtin_amdgcn_global_load_lds((const unsigned*)((const char*)(gbase) + (voff)[_i]), (PG8_LAS unsigned*)(lds + (bufoff) + ldsw + _i * 8192), 16, 0, 0); } while (0)
; #define PG8_LDA(dst, b, h) do { _Pragma("unroll") for (int m = 0; m < 4; ++m) _Pragma("unroll") for (int k = 0; k < 2; ++k) dst[m][k] = *(const PG8_LAS bf16x8*)(lds + PG8_SA(b, h) + aoff + m * 2048 + k * 1024); } while (0)
; #define PG8_WAIT_V(n) asm volatile("s_waitcnt vmcnt(" #n ")" ::: "memory")
; #define PG8_WAIT_L(n) asm volatile("s_waitcnt lgkmcnt(" #n ")" ::: "memory")
; template <class Epi, class Sched, bool ALIGN_EPI = false, bool SP2 = false, bool APERM = false  >
; __device__ __forceinline__ void gemm_phase(PG8_LAS unsigned char* lds, const Gemm g, const Sched& S, const Epi& E, const int wid  ) {
;     ...
;         for (int t = 0; t < nt; t += 2) {
;             const bool last = (t == nt - 2);
;             const char* a1 = cA + (size_t)(t + 1) * kstep;
;             const char* a2 = last ? nA : cA + (size_t)(t + 2) * kstep; const char* b2 = last ? nB : cB + (size_t)(t + 2) * kstep;
;             const char* a3 = a2 + kstep; const char* b3 = b2 + kstep;
;             if (last && has_next) S.a_ready(nxt);
;             if constexpr (SP2) {
;             PG8_LDB(B0, 0, 0); PG8_LDB(B1, 0, 1); PG8_SCHED; PG8_LDA(At, 0, 0); PG8_STAGE(PG8_SA(1, 1), a1 + hstep, voffA);
;             PG8_WAIT_V(8); PG8_WAIT_L(0); PG8_BAR; PG8_MMA(0, 0, At, B0); PG8_MMA(0, 1, At, B1); PG8_BAR; PG8_SCHED;
;             PG8_LDA(At, 0, 1); PG8_STAGE(PG8_SB(0, 0), b2, voffB); PG8_STAGE(PG8_SB(0, 1), b2 + hstep, voffB); PG8_STAGE(PG8_SA(0, 0), a2, voffA);
;             PG8_WAIT_V(8); PG8_WAIT_L(0); PG8_BAR; PG8_MMA(1, 0, At, B0); PG8_MMA(1, 1, At, B1); PG8_BAR; PG8_SCHED;
;             PG8_LDB(B0, 1, 0); PG8_LDB(B1, 1, 1); PG8_SCHED; PG8_LDA(At, 1, 0); PG8_STAGE(PG8_SA(0, 1), a2 + hstep, voffA);
;             PG8_WAIT_V(8); PG8_WAIT_L(0); PG8_BAR; PG8_MMA(0, 0, At, B0); PG8_MMA(0, 1, At, B1); PG8_BAR; PG8_SCHED;
;             PG8_LDA(At, 1, 1); PG8_STAGE(PG8_SB(1, 0), b3, voffB); PG8_STAGE(PG8_SB(1, 1), b3 + hstep, voffB); PG8_STAGE(PG8_SA(1, 0), a3, voffA);
;             PG8_WAIT_V(8); PG8_WAIT_L(0); PG8_BAR; PG8_MMA(1, 0, At, B0); PG8_MMA(1, 1, At, B1); PG8_BAR; PG8_SCHED;
.LBB0_1314:
	s_or_b32 s36, s78, 1
	v_add_u32_e32 v159, s52, v153
	s_lshl_b64 s[74:75], s[36:37], 7
	s_add_i32 s36, s78, 2
	s_waitcnt lgkmcnt(0)
	ds_read_b128 v[144:147], v159
	ds_read_b128 v[148:151], v159 offset:1024
	ds_read_b128 v[160:163], v159 offset:2048
	ds_read_b128 v[164:167], v159 offset:3072
	v_add_u32_e32 v159, s95, v153
	s_lshl_b64 s[76:77], s[36:37], 7
	ds_read_b128 v[168:171], v159
	ds_read_b128 v[172:175], v159 offset:1024
	ds_read_b128 v[176:179], v159 offset:2048
	ds_read_b128 v[180:183], v159 offset:3072
	s_add_u32 vcc_lo, s14, s76
	s_addc_u32 vcc_hi, s15, s77
	s_and_b64 s[72:73], s[70:71], exec
	s_cselect_b32 s73, s25, vcc_hi
	s_cselect_b32 s72, s24, vcc_lo
	s_add_u32 s76, s10, s76
	s_addc_u32 s77, s11, s77
	s_and_b64 s[70:71], s[70:71], exec
	s_cselect_b32 s71, s29, s77
	s_cselect_b32 s70, s28, s76
	s_add_u32 s74, s33, s74
	s_addc_u32 s75, s53, s75
	v_lshl_add_u64 v[216:217], s[74:75], 0, v[132:133]
	s_add_i32 m0, s85, 0xc000
	ds_read_b128 v[184:187], v158
	ds_read_b128 v[188:191], v158 offset:1024
	ds_read_b128 v[192:195], v158 offset:2048
	ds_read_b128 v[196:199], v158 offset:3072
	ds_read_b128 v[200:203], v158 offset:4096
	ds_read_b128 v[204:207], v158 offset:5120
	ds_read_b128 v[208:211], v158 offset:6144
	ds_read_b128 v[212:215], v158 offset:7168
	global_load_lds_dwordx4 v[216:217], off
	v_lshl_add_u64 v[216:217], s[74:75], 0, v[136:137]
	s_add_i32 m0, s85, 0xe000
	s_nop 0
	global_load_lds_dwordx4 v[216:217], off
	s_waitcnt vmcnt(8)
	s_waitcnt lgkmcnt(0)
	s_barrier
	s_setprio 1
	s_waitcnt lgkmcnt(0)
	v_mfma_f32_16x16x32_bf16 v[124:127], v[144:147], v[184:187], v[124:127]
	v_mfma_f32_16x16x32_bf16 v[124:127], v[148:151], v[188:191], v[124:127]
	v_mfma_f32_16x16x32_bf16 v[120:123], v[164:167], v[188:191], v[120:123]
	v_mfma_f32_16x16x32_bf16 v[120:123], v[160:163], v[184:187], v[120:123]
	v_mfma_f32_16x16x32_bf16 v[92:95], v[168:171], v[184:187], v[92:95]
	v_mfma_f32_16x16x32_bf16 v[92:95], v[172:175], v[188:191], v[92:95]
	v_mfma_f32_16x16x32_bf16 v[88:91], v[180:183], v[188:191], v[88:91]
	v_mfma_f32_16x16x32_bf16 v[88:91], v[176:179], v[184:187], v[88:91]
	v_mfma_f32_16x16x32_bf16 v[80:83], v[176:179], v[192:195], v[80:83]
	v_mfma_f32_16x16x32_bf16 v[80:83], v[180:183], v[196:199], v[80:83]
	v_mfma_f32_16x16x32_bf16 v[84:87], v[172:175], v[196:199], v[84:87]
	v_mfma_f32_16x16x32_bf16 v[84:87], v[168:171], v[192:195], v[84:87]
	v_mfma_f32_16x16x32_bf16 v[112:115], v[160:163], v[192:195], v[112:115]
	v_mfma_f32_16x16x32_bf16 v[112:115], v[164:167], v[196:199], v[112:115]
	v_mfma_f32_16x16x32_bf16 v[116:119], v[148:151], v[196:199], v[116:119]
	v_mfma_f32_16x16x32_bf16 v[116:119], v[144:147], v[192:195], v[116:119]
	v_mfma_f32_16x16x32_bf16 v[108:111], v[144:147], v[200:203], v[108:111]
	v_mfma_f32_16x16x32_bf16 v[108:111], v[148:151], v[204:207], v[108:111]
	v_mfma_f32_16x16x32_bf16 v[104:107], v[164:167], v[204:207], v[104:107]
	v_mfma_f32_16x16x32_bf16 v[104:107], v[160:163], v[200:203], v[104:107]
	v_mfma_f32_16x16x32_bf16 v[76:79], v[168:171], v[200:203], v[76:79]
	v_mfma_f32_16x16x32_bf16 v[76:79], v[172:175], v[204:207], v[76:79]
	v_mfma_f32_16x16x32_bf16 v[72:75], v[180:183], v[204:207], v[72:75]
	v_mfma_f32_16x16x32_bf16 v[72:75], v[176:179], v[200:203], v[72:75]
	v_mfma_f32_16x16x32_bf16 v[64:67], v[176:179], v[208:211], v[64:67]
	v_mfma_f32_16x16x32_bf16 v[64:67], v[180:183], v[212:215], v[64:67]
	v_mfma_f32_16x16x32_bf16 v[68:71], v[172:175], v[212:215], v[68:71]
	v_mfma_f32_16x16x32_bf16 v[68:71], v[168:171], v[208:211], v[68:71]
	v_mfma_f32_16x16x32_bf16 v[96:99], v[160:163], v[208:211], v[96:99]
	v_mfma_f32_16x16x32_bf16 v[96:99], v[164:167], v[212:215], v[96:99]
	v_mfma_f32_16x16x32_bf16 v[100:103], v[148:151], v[212:215], v[100:103]
	v_mfma_f32_16x16x32_bf16 v[100:103], v[144:147], v[208:211], v[100:103]
	s_setprio 0
	s_barrier
	s_add_i32 s74, s52, s79
	v_lshl_add_u64 v[216:217], s[70:71], 0, v[128:129]
	s_mov_b32 m0, s74
	ds_read_b128 v[184:187], v158 offset:16384
	ds_read_b128 v[188:191], v158 offset:17408
	ds_read_b128 v[192:195], v158 offset:18432
	ds_read_b128 v[196:199], v158 offset:19456
	ds_read_b128 v[200:203], v158 offset:20480
	ds_read_b128 v[204:207], v158 offset:21504
	ds_read_b128 v[208:211], v158 offset:22528
	ds_read_b128 v[212:215], v158 offset:23552
	global_load_lds_dwordx4 v[216:217], off
	s_add_i32 m0, s74, 0x2000
	s_add_u32 s74, s70, 0x160000
	v_lshl_add_u64 v[218:219], s[70:71], 0, v[130:131]
	s_addc_u32 s75, s71, 0
	s_add_i32 s76, s95, s79
	global_load_lds_dwordx4 v[218:219], off
	v_lshl_add_u64 v[220:221], s[74:75], 0, v[128:129]
	s_mov_b32 m0, s76
	v_lshl_add_u64 v[222:223], s[72:73], 0, v[136:137]
	global_load_lds_dwordx4 v[220:221], off
	v_lshl_add_u64 v[220:221], s[74:75], 0, v[130:131]
	s_add_i32 m0, s76, 0x2000
	s_nop 0
	global_load_lds_dwordx4 v[220:221], off
	v_lshl_add_u64 v[220:221], s[72:73], 0, v[132:133]
	s_mov_b32 m0, s85
	s_nop 0
	global_load_lds_dwordx4 v[220:221], off
	s_mov_b32 m0, s88
	s_nop 0
	global_load_lds_dwordx4 v[222:223], off
	s_waitcnt vmcnt(8)
	s_waitcnt lgkmcnt(0)
	s_barrier
; #define PG8_STAGE(bufoff, gbase, voff) do { _Pragma("unroll") for (int _i = 0; _i < 2; ++_i) \
;         __builtin_amdgcn_global_load_lds((const unsigned*)((const char*)(gbase) + (voff)[_i]), (PG8_LAS unsigned*)(lds + (bufoff) + ldsw + _i * 8192), 16, 0, 0); } while (0)
; #define PG8_LDA(dst, b, h) do { _Pragma("unroll") for (int m = 0; m < 4; ++m) _Pragma("unroll") for (int k = 0; k < 2; ++k) dst[m][k] = *(const PG8_LAS bf16x8*)(lds + PG8_SA(b, h) + aoff + m * 2048 + k * 1024); } while (0)
; #define PG8_LDB(dst, b, h) do { _Pragma("unroll") for (int n = 0; n < 2; ++n) _Pragma("unroll") for (int k = 0; k < 2; ++k) dst[n][k] = *(const PG8_LAS bf16x8*)(lds + PG8_SB(b, h) + boff + n * 2048 + k * 1024); } while (0)
; #define PG8_MMA(ai, bj, At, Bt) do { __builtin_amdgcn_s_setprio(1); _Pragma("unroll") for (int m = 0; m < 4; ++m) _Pragma("unroll") for (int n = 0; n < 2; ++n) _Pragma("unroll") for (int k = 0; k < 2; ++k) \
;         acc[ai][bj][m][n] = __builtin_amdgcn_mfma_f32_16x16x32_bf16(Bt[n][k], At[m][k], acc[ai][bj][m][n], 0, 0, 0); __builtin_amdgcn_s_setprio(0); } while (0)
; #define PG8_WAIT_V(n) asm volatile("s_waitcnt vmcnt(" #n ")" ::: "memory")
; #define PG8_WAIT_L(n) asm volatile("s_waitcnt lgkmcnt(" #n ")" ::: "memory")
; #define PG8_BAR __builtin_amdgcn_s_barrier()
; #define PG8_SCHED __builtin_amdgcn_sched_barrier(0)
; template <class Epi, class Sched, bool ALIGN_EPI = false, bool SP2 = false, bool APERM = false  >
; __device__ __forceinline__ void gemm_phase(PG8_LAS unsigned char* lds, const Gemm g, const Sched& S, const Epi& E, const int wid  ) {
;     ...
;             PG8_WAIT_V(8); PG8_WAIT_L(0); PG8_BAR; PG8_MMA(0, 0, At, B0); PG8_MMA(0, 1, At, B1); PG8_BAR; PG8_SCHED;
;             PG8_LDA(At, 0, 1); PG8_STAGE(PG8_SB(0, 0), b2, voffB); PG8_STAGE(PG8_SB(0, 1), b2 + hstep, voffB); PG8_STAGE(PG8_SA(0, 0), a2, voffA);
;             PG8_WAIT_V(8); PG8_WAIT_L(0); PG8_BAR; PG8_MMA(1, 0, At, B0); PG8_MMA(1, 1, At, B1); PG8_BAR; PG8_SCHED;
;             PG8_LDB(B0, 1, 0); PG8_LDB(B1, 1, 1); PG8_SCHED; PG8_LDA(At, 1, 0); PG8_STAGE(PG8_SA(0, 1), a2 + hstep, voffA);
;             PG8_WAIT_V(8); PG8_WAIT_L(0); PG8_BAR; PG8_MMA(0, 0, At, B0); PG8_MMA(0, 1, At, B1); PG8_BAR; PG8_SCHED;
	s_setprio 1
	s_waitcnt lgkmcnt(0)
	v_mfma_f32_16x16x32_bf16 v[60:63], v[144:147], v[184:187], v[60:63]
	v_mfma_f32_16x16x32_bf16 v[60:63], v[148:151], v[188:191], v[60:63]
	v_mfma_f32_16x16x32_bf16 v[56:59], v[164:167], v[188:191], v[56:59]
	v_mfma_f32_16x16x32_bf16 v[56:59], v[160:163], v[184:187], v[56:59]
	v_mfma_f32_16x16x32_bf16 v[28:31], v[168:171], v[184:187], v[28:31]
	v_mfma_f32_16x16x32_bf16 v[28:31], v[172:175], v[188:191], v[28:31]
	v_mfma_f32_16x16x32_bf16 v[24:27], v[180:183], v[188:191], v[24:27]
	v_mfma_f32_16x16x32_bf16 v[24:27], v[176:179], v[184:187], v[24:27]
	v_mfma_f32_16x16x32_bf16 v[16:19], v[176:179], v[192:195], v[16:19]
	v_mfma_f32_16x16x32_bf16 v[16:19], v[180:183], v[196:199], v[16:19]
	v_mfma_f32_16x16x32_bf16 v[20:23], v[172:175], v[196:199], v[20:23]
	v_mfma_f32_16x16x32_bf16 v[20:23], v[168:171], v[192:195], v[20:23]
	v_mfma_f32_16x16x32_bf16 v[48:51], v[160:163], v[192:195], v[48:51]
	v_mfma_f32_16x16x32_bf16 v[48:51], v[164:167], v[196:199], v[48:51]
	v_mfma_f32_16x16x32_bf16 v[52:55], v[148:151], v[196:199], v[52:55]
	v_mfma_f32_16x16x32_bf16 v[52:55], v[144:147], v[192:195], v[52:55]
	v_mfma_f32_16x16x32_bf16 v[44:47], v[144:147], v[200:203], v[44:47]
	v_mfma_f32_16x16x32_bf16 v[44:47], v[148:151], v[204:207], v[44:47]
	v_mfma_f32_16x16x32_bf16 v[40:43], v[164:167], v[204:207], v[40:43]
	v_mfma_f32_16x16x32_bf16 v[40:43], v[160:163], v[200:203], v[40:43]
	v_mfma_f32_16x16x32_bf16 v[12:15], v[168:171], v[200:203], v[12:15]
	v_mfma_f32_16x16x32_bf16 v[12:15], v[172:175], v[204:207], v[12:15]
	v_mfma_f32_16x16x32_bf16 v[8:11], v[180:183], v[204:207], v[8:11]
	v_mfma_f32_16x16x32_bf16 v[8:11], v[176:179], v[200:203], v[8:11]
	v_mfma_f32_16x16x32_bf16 v[0:3], v[176:179], v[208:211], v[0:3]
	v_mfma_f32_16x16x32_bf16 v[0:3], v[180:183], v[212:215], v[0:3]
	v_mfma_f32_16x16x32_bf16 v[4:7], v[172:175], v[212:215], v[4:7]
	v_mfma_f32_16x16x32_bf16 v[4:7], v[168:171], v[208:211], v[4:7]
	v_mfma_f32_16x16x32_bf16 v[32:35], v[160:163], v[208:211], v[32:35]
	v_mfma_f32_16x16x32_bf16 v[32:35], v[164:167], v[212:215], v[32:35]
	v_mfma_f32_16x16x32_bf16 v[36:39], v[148:151], v[212:215], v[36:39]
	v_mfma_f32_16x16x32_bf16 v[36:39], v[144:147], v[208:211], v[36:39]
	s_setprio 0
	s_barrier
	s_add_i32 s74, 0, 0x18000
	v_add_u32_e32 v159, s74, v153
	s_add_i32 s75, 0, 0x1c000
	ds_read_b128 v[144:147], v159
	ds_read_b128 v[148:151], v159 offset:1024
	ds_read_b128 v[160:163], v159 offset:2048
	ds_read_b128 v[164:167], v159 offset:3072
	v_add_u32_e32 v159, s75, v153
	ds_read_b128 v[168:171], v159
	ds_read_b128 v[172:175], v159 offset:1024
	ds_read_b128 v[176:179], v159 offset:2048
	ds_read_b128 v[180:183], v159 offset:3072
	s_add_u32 s72, s72, 0x160000
	s_addc_u32 s73, s73, 0
	s_mov_b32 m0, s89
	v_lshl_add_u64 v[224:225], s[72:73], 0, v[132:133]
	ds_read_b128 v[184:187], v158 offset:32768
	ds_read_b128 v[188:191], v158 offset:33792
	ds_read_b128 v[192:195], v158 offset:34816
	ds_read_b128 v[196:199], v158 offset:35840
	ds_read_b128 v[200:203], v158 offset:36864
	ds_read_b128 v[204:207], v158 offset:37888
	ds_read_b128 v[208:211], v158 offset:38912
	ds_read_b128 v[212:215], v158 offset:39936
	global_load_lds_dwordx4 v[224:225], off
	v_lshl_add_u64 v[224:225], s[72:73], 0, v[136:137]
	s_mov_b32 m0, s90
	s_nop 0
	global_load_lds_dwordx4 v[224:225], off
	s_waitcnt vmcnt(8)
	s_waitcnt lgkmcnt(0)
	s_barrier
	s_setprio 1
	s_waitcnt lgkmcnt(0)
	v_mfma_f32_16x16x32_bf16 v[124:127], v[144:147], v[184:187], v[124:127]
	v_mfma_f32_16x16x32_bf16 v[124:127], v[148:151], v[188:191], v[124:127]
	v_mfma_f32_16x16x32_bf16 v[120:123], v[164:167], v[188:191], v[120:123]
	v_mfma_f32_16x16x32_bf16 v[120:123], v[160:163], v[184:187], v[120:123]
	v_mfma_f32_16x16x32_bf16 v[92:95], v[168:171], v[184:187], v[92:95]
	v_mfma_f32_16x16x32_bf16 v[92:95], v[172:175], v[188:191], v[92:95]
	v_mfma_f32_16x16x32_bf16 v[88:91], v[180:183], v[188:191], v[88:91]
	v_mfma_f32_16x16x32_bf16 v[88:91], v[176:179], v[184:187], v[88:91]
	v_mfma_f32_16x16x32_bf16 v[80:83], v[176:179], v[192:195], v[80:83]
	v_mfma_f32_16x16x32_bf16 v[80:83], v[180:183], v[196:199], v[80:83]
	v_mfma_f32_16x16x32_bf16 v[84:87], v[172:175], v[196:199], v[84:87]
	v_mfma_f32_16x16x32_bf16 v[84:87], v[168:171], v[192:195], v[84:87]
	v_mfma_f32_16x16x32_bf16 v[112:115], v[160:163], v[192:195], v[112:115]
	v_mfma_f32_16x16x32_bf16 v[112:115], v[164:167], v[196:199], v[112:115]
	v_mfma_f32_16x16x32_bf16 v[116:119], v[148:151], v[196:199], v[116:119]
	v_mfma_f32_16x16x32_bf16 v[116:119], v[144:147], v[192:195], v[116:119]
	v_mfma_f32_16x16x32_bf16 v[108:111], v[144:147], v[200:203], v[108:111]
	v_mfma_f32_16x16x32_bf16 v[108:111], v[148:151], v[204:207], v[108:111]
	v_mfma_f32_16x16x32_bf16 v[104:107], v[164:167], v[204:207], v[104:107]
	v_mfma_f32_16x16x32_bf16 v[104:107], v[160:163], v[200:203], v[104:107]
	v_mfma_f32_16x16x32_bf16 v[76:79], v[168:171], v[200:203], v[76:79]
	v_mfma_f32_16x16x32_bf16 v[76:79], v[172:175], v[204:207], v[76:79]
	v_mfma_f32_16x16x32_bf16 v[72:75], v[180:183], v[204:207], v[72:75]
	v_mfma_f32_16x16x32_bf16 v[72:75], v[176:179], v[200:203], v[72:75]
	v_mfma_f32_16x16x32_bf16 v[64:67], v[176:179], v[208:211], v[64:67]
	v_mfma_f32_16x16x32_bf16 v[64:67], v[180:183], v[212:215], v[64:67]
	v_mfma_f32_16x16x32_bf16 v[68:71], v[172:175], v[212:215], v[68:71]
	v_mfma_f32_16x16x32_bf16 v[68:71], v[168:171], v[208:211], v[68:71]
	v_mfma_f32_16x16x32_bf16 v[96:99], v[160:163], v[208:211], v[96:99]
	v_mfma_f32_16x16x32_bf16 v[96:99], v[164:167], v[212:215], v[96:99]
	v_mfma_f32_16x16x32_bf16 v[100:103], v[148:151], v[212:215], v[100:103]
	v_mfma_f32_16x16x32_bf16 v[100:103], v[144:147], v[208:211], v[100:103]
	s_setprio 0
	s_barrier
; #define PG8_STAGE(bufoff, gbase, voff) do { _Pragma("unroll") for (int _i = 0; _i < 2; ++_i) \
;         __builtin_amdgcn_global_load_lds((const unsigned*)((const char*)(gbase) + (voff)[_i]), (PG8_LAS unsigned*)(lds + (bufoff) + ldsw + _i * 8192), 16, 0, 0); } while (0)
; #define PG8_LDA(dst, b, h) do { _Pragma("unroll") for (int m = 0; m < 4; ++m) _Pragma("unroll") for (int k = 0; k < 2; ++k) dst[m][k] = *(const PG8_LAS bf16x8*)(lds + PG8_SA(b, h) + aoff + m * 2048 + k * 1024); } while (0)
; #define PG8_MMA(ai, bj, At, Bt) do { __builtin_amdgcn_s_setprio(1); _Pragma("unroll") for (int m = 0; m < 4; ++m) _Pragma("unroll") for (int n = 0; n < 2; ++n) _Pragma("unroll") for (int k = 0; k < 2; ++k) \
;         acc[ai][bj][m][n] = __builtin_amdgcn_mfma_f32_16x16x32_bf16(Bt[n][k], At[m][k], acc[ai][bj][m][n], 0, 0, 0); __builtin_amdgcn_s_setprio(0); } while (0)
; #define PG8_WAIT_V(n) asm volatile("s_waitcnt vmcnt(" #n ")" ::: "memory")
; #define PG8_WAIT_L(n) asm volatile("s_waitcnt lgkmcnt(" #n ")" ::: "memory")
; #define PG8_BAR __builtin_amdgcn_s_barrier()
; #define PG8_SCHED __builtin_amdgcn_sched_barrier(0)
; template <class Epi, class Sched, bool ALIGN_EPI = false, bool SP2 = false, bool APERM = false  >
; __device__ __forceinline__ void gemm_phase(PG8_LAS unsigned char* lds, const Gemm g, const Sched& S, const Epi& E, const int wid  ) {
;     ...
;         for (int t = 0; t < nt; t += 2) {
;             const bool last = (t == nt - 2);
;     ...
;             PG8_LDA(At, 1, 1); PG8_STAGE(PG8_SB(1, 0), b3, voffB); PG8_STAGE(PG8_SB(1, 1), b3 + hstep, voffB); PG8_STAGE(PG8_SA(1, 0), a3, voffA);
;             PG8_WAIT_V(8); PG8_WAIT_L(0); PG8_BAR; PG8_MMA(1, 0, At, B0); PG8_MMA(1, 1, At, B1); PG8_BAR; PG8_SCHED;
	s_add_i32 s72, s74, s79
	v_lshl_add_u64 v[216:217], v[216:217], 0, s[38:39]
	s_mov_b32 m0, s72
	ds_read_b128 v[184:187], v158 offset:49152
	ds_read_b128 v[188:191], v158 offset:50176
	ds_read_b128 v[192:195], v158 offset:51200
	ds_read_b128 v[196:199], v158 offset:52224
	ds_read_b128 v[200:203], v158 offset:53248
	ds_read_b128 v[204:207], v158 offset:54272
	ds_read_b128 v[208:211], v158 offset:55296
	ds_read_b128 v[212:215], v158 offset:56320
	global_load_lds_dwordx4 v[216:217], off
	s_add_i32 m0, s72, 0x2000
	s_add_u32 s70, s70, 0x160080
	v_lshl_add_u64 v[216:217], v[218:219], 0, s[38:39]
	s_addc_u32 s71, s71, 0
	s_add_i32 s72, s75, s79
	global_load_lds_dwordx4 v[216:217], off
	v_lshl_add_u64 v[216:217], s[70:71], 0, v[128:129]
	s_mov_b32 m0, s72
	s_nop 0
	global_load_lds_dwordx4 v[216:217], off
	v_lshl_add_u64 v[216:217], s[70:71], 0, v[130:131]
	s_add_i32 m0, s72, 0x2000
	s_nop 0
	global_load_lds_dwordx4 v[216:217], off
	v_lshl_add_u64 v[216:217], v[220:221], 0, s[38:39]
	s_mov_b32 m0, s93
	s_nop 0
	global_load_lds_dwordx4 v[216:217], off
	v_lshl_add_u64 v[216:217], v[222:223], 0, s[38:39]
	s_mov_b32 m0, s94
	s_nop 0
	global_load_lds_dwordx4 v[216:217], off
	s_waitcnt vmcnt(8)
	s_waitcnt lgkmcnt(0)
	s_barrier
	s_setprio 1
	s_waitcnt lgkmcnt(0)
	v_mfma_f32_16x16x32_bf16 v[60:63], v[144:147], v[184:187], v[60:63]
	v_mfma_f32_16x16x32_bf16 v[60:63], v[148:151], v[188:191], v[60:63]
	v_mfma_f32_16x16x32_bf16 v[56:59], v[164:167], v[188:191], v[56:59]
	v_mfma_f32_16x16x32_bf16 v[56:59], v[160:163], v[184:187], v[56:59]
	v_mfma_f32_16x16x32_bf16 v[28:31], v[168:171], v[184:187], v[28:31]
	v_mfma_f32_16x16x32_bf16 v[28:31], v[172:175], v[188:191], v[28:31]
	v_mfma_f32_16x16x32_bf16 v[24:27], v[180:183], v[188:191], v[24:27]
	v_mfma_f32_16x16x32_bf16 v[24:27], v[176:179], v[184:187], v[24:27]
	v_mfma_f32_16x16x32_bf16 v[16:19], v[176:179], v[192:195], v[16:19]
	v_mfma_f32_16x16x32_bf16 v[16:19], v[180:183], v[196:199], v[16:19]
	v_mfma_f32_16x16x32_bf16 v[20:23], v[172:175], v[196:199], v[20:23]
	v_mfma_f32_16x16x32_bf16 v[20:23], v[168:171], v[192:195], v[20:23]
	v_mfma_f32_16x16x32_bf16 v[48:51], v[160:163], v[192:195], v[48:51]
	v_mfma_f32_16x16x32_bf16 v[48:51], v[164:167], v[196:199], v[48:51]
	v_mfma_f32_16x16x32_bf16 v[52:55], v[148:151], v[196:199], v[52:55]
	v_mfma_f32_16x16x32_bf16 v[52:55], v[144:147], v[192:195], v[52:55]
	v_mfma_f32_16x16x32_bf16 v[44:47], v[144:147], v[200:203], v[44:47]
	v_mfma_f32_16x16x32_bf16 v[44:47], v[148:151], v[204:207], v[44:47]
	v_mfma_f32_16x16x32_bf16 v[40:43], v[164:167], v[204:207], v[40:43]
	v_mfma_f32_16x16x32_bf16 v[40:43], v[160:163], v[200:203], v[40:43]
	v_mfma_f32_16x16x32_bf16 v[12:15], v[168:171], v[200:203], v[12:15]
	v_mfma_f32_16x16x32_bf16 v[12:15], v[172:175], v[204:207], v[12:15]
	v_mfma_f32_16x16x32_bf16 v[8:11], v[180:183], v[204:207], v[8:11]
	v_mfma_f32_16x16x32_bf16 v[8:11], v[176:179], v[200:203], v[8:11]
	v_mfma_f32_16x16x32_bf16 v[0:3], v[176:179], v[208:211], v[0:3]
	v_mfma_f32_16x16x32_bf16 v[0:3], v[180:183], v[212:215], v[0:3]
	v_mfma_f32_16x16x32_bf16 v[4:7], v[172:175], v[212:215], v[4:7]
	v_mfma_f32_16x16x32_bf16 v[4:7], v[168:171], v[208:211], v[4:7]
	v_mfma_f32_16x16x32_bf16 v[32:35], v[160:163], v[208:211], v[32:35]
	v_mfma_f32_16x16x32_bf16 v[32:35], v[164:167], v[212:215], v[32:35]
	v_mfma_f32_16x16x32_bf16 v[36:39], v[148:151], v[212:215], v[36:39]
	v_mfma_f32_16x16x32_bf16 v[36:39], v[144:147], v[208:211], v[36:39]
	s_setprio 0
	s_barrier
	s_cmp_gt_u32 s78, 41
	s_cbranch_scc1 .LBB0_1316
	s_mov_b32 s78, s36
	s_branch .LBB0_1297

; #define PG8_STAGE(bufoff, gbase, voff) do { _Pragma("unroll") for (int _i = 0; _i < 2; ++_i) \
;         __builtin_amdgcn_global_load_lds((const unsigned*)((const char*)(gbase) + (voff)[_i]), (PG8_LAS unsigned*)(lds + (bufoff) + ldsw + _i * 8192), 16, 0, 0); } while (0)
; #define PG8_LDA(dst, b, h) do { _Pragma("unroll") for (int m = 0; m < 4; ++m) _Pragma("unroll") for (int k = 0; k < 2; ++k) dst[m][k] = *(const PG8_LAS bf16x8*)(lds + PG8_SA(b, h) + aoff + m * 2048 + k * 1024); } while (0)
; #define PG8_WAIT_V(n) asm volatile("s_waitcnt vmcnt(" #n ")" ::: "memory")
; #define PG8_WAIT_L(n) asm volatile("s_waitcnt lgkmcnt(" #n ")" ::: "memory")
; template <class Epi, class Sched, bool ALIGN_EPI = false, bool SP2 = false, bool APERM = false  >
; __device__ __forceinline__ void gemm_phase(PG8_LAS unsigned char* lds, const Gemm g, const Sched& S, const Epi& E, const int wid  ) {
;     ...
;         for (int t = 0; t < nt; t += 2) {
;             const bool last = (t == nt - 2);
;             const char* a1 = cA + (size_t)(t + 1) * kstep;
;             const char* a2 = last ? nA : cA + (size_t)(t + 2) * kstep; const char* b2 = last ? nB : cB + (size_t)(t + 2) * kstep;
;             const char* a3 = a2 + kstep; const char* b3 = b2 + kstep;
;             if (last && has_next) S.a_ready(nxt);
;             if constexpr (SP2) {
;             PG8_LDB(B0, 0, 0); PG8_LDB(B1, 0, 1); PG8_SCHED; PG8_LDA(At, 0, 0); PG8_STAGE(PG8_SA(1, 1), a1 + hstep, voffA);
;             PG8_WAIT_V(8); PG8_WAIT_L(0); PG8_BAR; PG8_MMA(0, 0, At, B0); PG8_MMA(0, 1, At, B1); PG8_BAR; PG8_SCHED;
;             PG8_LDA(At, 0, 1); PG8_STAGE(PG8_SB(0, 0), b2, voffB); PG8_STAGE(PG8_SB(0, 1), b2 + hstep, voffB); PG8_STAGE(PG8_SA(0, 0), a2, voffA);
;             PG8_WAIT_V(8); PG8_WAIT_L(0); PG8_BAR; PG8_MMA(1, 0, At, B0); PG8_MMA(1, 1, At, B1); PG8_BAR; PG8_SCHED;
;             PG8_LDB(B0, 1, 0); PG8_LDB(B1, 1, 1); PG8_SCHED; PG8_LDA(At, 1, 0); PG8_STAGE(PG8_SA(0, 1), a2 + hstep, voffA);
;             PG8_WAIT_V(8); PG8_WAIT_L(0); PG8_BAR; PG8_MMA(0, 0, At, B0); PG8_MMA(0, 1, At, B1); PG8_BAR; PG8_SCHED;
;             PG8_LDA(At, 1, 1); PG8_STAGE(PG8_SB(1, 0), b3, voffB); PG8_STAGE(PG8_SB(1, 1), b3 + hstep, voffB); PG8_STAGE(PG8_SA(1, 0), a3, voffA);
;             PG8_WAIT_V(8); PG8_WAIT_L(0); PG8_BAR; PG8_MMA(1, 0, At, B0); PG8_MMA(1, 1, At, B1); PG8_BAR; PG8_SCHED;
.LBB0_1373:
	v_add_u32_e32 v1, s78, v146
	ds_read_b128 v[150:153], v1
	ds_read_b128 v[154:157], v1 offset:1024
	ds_read_b128 v[158:161], v1 offset:2048
	ds_read_b128 v[162:165], v1 offset:3072
	v_add_u32_e32 v1, s79, v146
	ds_read_b128 v[166:169], v1
	ds_read_b128 v[170:173], v1 offset:1024
	ds_read_b128 v[174:177], v1 offset:2048
	ds_read_b128 v[178:181], v1 offset:3072
	s_add_i32 s88, s56, 2
	s_add_u32 s89, s54, 0x80
	s_addc_u32 s57, s55, 0
	s_cmp_eq_u32 s75, s56
	s_cselect_b32 s56, s48, s89
	s_cselect_b32 s57, s49, s57
	s_cselect_b32 s91, s53, s87
	s_cselect_b32 s90, s52, s86
	s_mov_b32 m0, s80
	v_lshl_add_u64 v[2:3], s[54:55], 0, v[140:141]
	ds_read_b128 v[182:185], v148
	ds_read_b128 v[186:189], v148 offset:1024
	ds_read_b128 v[190:193], v148 offset:2048
	ds_read_b128 v[194:197], v148 offset:3072
	ds_read_b128 v[198:201], v148 offset:4096
	ds_read_b128 v[202:205], v148 offset:5120
	ds_read_b128 v[206:209], v148 offset:6144
	ds_read_b128 v[210:213], v148 offset:7168
	global_load_lds_dwordx4 v[2:3], off
	v_lshl_add_u64 v[2:3], s[54:55], 0, v[142:143]
	s_mov_b32 m0, s81
	s_nop 0
	global_load_lds_dwordx4 v[2:3], off
	s_waitcnt vmcnt(8)
	s_waitcnt lgkmcnt(0)
	s_barrier
	s_setprio 1
	s_waitcnt lgkmcnt(0)
	v_mfma_f32_16x16x32_bf16 v[128:131], v[150:153], v[182:185], v[128:131]
	v_mfma_f32_16x16x32_bf16 v[128:131], v[154:157], v[186:189], v[128:131]
	v_mfma_f32_16x16x32_bf16 v[124:127], v[162:165], v[186:189], v[124:127]
	v_mfma_f32_16x16x32_bf16 v[124:127], v[158:161], v[182:185], v[124:127]
	v_mfma_f32_16x16x32_bf16 v[96:99], v[166:169], v[182:185], v[96:99]
	v_mfma_f32_16x16x32_bf16 v[96:99], v[170:173], v[186:189], v[96:99]
	v_mfma_f32_16x16x32_bf16 v[92:95], v[178:181], v[186:189], v[92:95]
	v_mfma_f32_16x16x32_bf16 v[92:95], v[174:177], v[182:185], v[92:95]
	v_mfma_f32_16x16x32_bf16 v[84:87], v[174:177], v[190:193], v[84:87]
	v_mfma_f32_16x16x32_bf16 v[84:87], v[178:181], v[194:197], v[84:87]
	v_mfma_f32_16x16x32_bf16 v[88:91], v[170:173], v[194:197], v[88:91]
	v_mfma_f32_16x16x32_bf16 v[88:91], v[166:169], v[190:193], v[88:91]
	v_mfma_f32_16x16x32_bf16 v[116:119], v[158:161], v[190:193], v[116:119]
	v_mfma_f32_16x16x32_bf16 v[116:119], v[162:165], v[194:197], v[116:119]
	v_mfma_f32_16x16x32_bf16 v[120:123], v[154:157], v[194:197], v[120:123]
	v_mfma_f32_16x16x32_bf16 v[120:123], v[150:153], v[190:193], v[120:123]
	v_mfma_f32_16x16x32_bf16 v[112:115], v[150:153], v[198:201], v[112:115]
	v_mfma_f32_16x16x32_bf16 v[112:115], v[154:157], v[202:205], v[112:115]
	v_mfma_f32_16x16x32_bf16 v[108:111], v[162:165], v[202:205], v[108:111]
	v_mfma_f32_16x16x32_bf16 v[108:111], v[158:161], v[198:201], v[108:111]
	v_mfma_f32_16x16x32_bf16 v[80:83], v[166:169], v[198:201], v[80:83]
	v_mfma_f32_16x16x32_bf16 v[80:83], v[170:173], v[202:205], v[80:83]
	v_mfma_f32_16x16x32_bf16 v[76:79], v[178:181], v[202:205], v[76:79]
	v_mfma_f32_16x16x32_bf16 v[76:79], v[174:177], v[198:201], v[76:79]
	v_mfma_f32_16x16x32_bf16 v[68:71], v[174:177], v[206:209], v[68:71]
	v_mfma_f32_16x16x32_bf16 v[68:71], v[178:181], v[210:213], v[68:71]
	v_mfma_f32_16x16x32_bf16 v[72:75], v[170:173], v[210:213], v[72:75]
	v_mfma_f32_16x16x32_bf16 v[72:75], v[166:169], v[206:209], v[72:75]
	v_mfma_f32_16x16x32_bf16 v[100:103], v[158:161], v[206:209], v[100:103]
	v_mfma_f32_16x16x32_bf16 v[100:103], v[162:165], v[210:213], v[100:103]
	v_mfma_f32_16x16x32_bf16 v[104:107], v[154:157], v[210:213], v[104:107]
	v_mfma_f32_16x16x32_bf16 v[104:107], v[150:153], v[206:209], v[104:107]
	s_setprio 0
	s_barrier
	s_add_i32 s89, s78, s76
	v_lshl_add_u64 v[214:215], s[90:91], 0, v[136:137]
	s_mov_b32 m0, s89
	ds_read_b128 v[182:185], v148 offset:16384
	ds_read_b128 v[186:189], v148 offset:17408
	ds_read_b128 v[190:193], v148 offset:18432
	ds_read_b128 v[194:197], v148 offset:19456
	ds_read_b128 v[198:201], v148 offset:20480
	ds_read_b128 v[202:205], v148 offset:21504
	ds_read_b128 v[206:209], v148 offset:22528
	ds_read_b128 v[210:213], v148 offset:23552
	global_load_lds_dwordx4 v[214:215], off
	s_add_i32 m0, s89, 0x2000
	v_lshl_add_u64 v[216:217], s[90:91], 0, v[132:133]
	s_add_u32 s90, s90, s4
	s_addc_u32 s91, s91, s5
	s_add_i32 s89, s79, s76
	global_load_lds_dwordx4 v[216:217], off
	v_lshl_add_u64 v[218:219], s[90:91], 0, v[136:137]
	s_mov_b32 m0, s89
	v_lshl_add_u64 v[220:221], s[90:91], 0, v[132:133]
	global_load_lds_dwordx4 v[218:219], off
	s_add_i32 m0, s89, 0x2000
	v_lshl_add_u64 v[222:223], s[56:57], 0, v[138:139]
	global_load_lds_dwordx4 v[220:221], off
	s_mov_b32 m0, s66
	v_lshl_add_u64 v[224:225], s[56:57], 0, v[134:135]
	global_load_lds_dwordx4 v[222:223], off
	s_mov_b32 m0, s69
	s_nop 0
	global_load_lds_dwordx4 v[224:225], off
	s_waitcnt vmcnt(8)
	s_waitcnt lgkmcnt(0)
	s_barrier
; #define PG8_STAGE(bufoff, gbase, voff) do { _Pragma("unroll") for (int _i = 0; _i < 2; ++_i) \
;         __builtin_amdgcn_global_load_lds((const unsigned*)((const char*)(gbase) + (voff)[_i]), (PG8_LAS unsigned*)(lds + (bufoff) + ldsw + _i * 8192), 16, 0, 0); } while (0)
; #define PG8_LDA(dst, b, h) do { _Pragma("unroll") for (int m = 0; m < 4; ++m) _Pragma("unroll") for (int k = 0; k < 2; ++k) dst[m][k] = *(const PG8_LAS bf16x8*)(lds + PG8_SA(b, h) + aoff + m * 2048 + k * 1024); } while (0)
; #define PG8_LDB(dst, b, h) do { _Pragma("unroll") for (int n = 0; n < 2; ++n) _Pragma("unroll") for (int k = 0; k < 2; ++k) dst[n][k] = *(const PG8_LAS bf16x8*)(lds + PG8_SB(b, h) + boff + n * 2048 + k * 1024); } while (0)
; #define PG8_MMA(ai, bj, At, Bt) do { __builtin_amdgcn_s_setprio(1); _Pragma("unroll") for (int m = 0; m < 4; ++m) _Pragma("unroll") for (int n = 0; n < 2; ++n) _Pragma("unroll") for (int k = 0; k < 2; ++k) \
;         acc[ai][bj][m][n] = __builtin_amdgcn_mfma_f32_16x16x32_bf16(Bt[n][k], At[m][k], acc[ai][bj][m][n], 0, 0, 0); __builtin_amdgcn_s_setprio(0); } while (0)
; #define PG8_WAIT_V(n) asm volatile("s_waitcnt vmcnt(" #n ")" ::: "memory")
; #define PG8_WAIT_L(n) asm volatile("s_waitcnt lgkmcnt(" #n ")" ::: "memory")
; #define PG8_BAR __builtin_amdgcn_s_barrier()
; #define PG8_SCHED __builtin_amdgcn_sched_barrier(0)
; template <class Epi, class Sched, bool ALIGN_EPI = false, bool SP2 = false, bool APERM = false  >
; __device__ __forceinline__ void gemm_phase(PG8_LAS unsigned char* lds, const Gemm g, const Sched& S, const Epi& E, const int wid  ) {
;     ...
;             PG8_WAIT_V(8); PG8_WAIT_L(0); PG8_BAR; PG8_MMA(0, 0, At, B0); PG8_MMA(0, 1, At, B1); PG8_BAR; PG8_SCHED;
;             PG8_LDA(At, 0, 1); PG8_STAGE(PG8_SB(0, 0), b2, voffB); PG8_STAGE(PG8_SB(0, 1), b2 + hstep, voffB); PG8_STAGE(PG8_SA(0, 0), a2, voffA);
;             PG8_WAIT_V(8); PG8_WAIT_L(0); PG8_BAR; PG8_MMA(1, 0, At, B0); PG8_MMA(1, 1, At, B1); PG8_BAR; PG8_SCHED;
;             PG8_LDB(B0, 1, 0); PG8_LDB(B1, 1, 1); PG8_SCHED; PG8_LDA(At, 1, 0); PG8_STAGE(PG8_SA(0, 1), a2 + hstep, voffA);
;             PG8_WAIT_V(8); PG8_WAIT_L(0); PG8_BAR; PG8_MMA(0, 0, At, B0); PG8_MMA(0, 1, At, B1); PG8_BAR; PG8_SCHED;
	s_setprio 1
	s_waitcnt lgkmcnt(0)
	v_mfma_f32_16x16x32_bf16 v[64:67], v[150:153], v[182:185], v[64:67]
	v_mfma_f32_16x16x32_bf16 v[64:67], v[154:157], v[186:189], v[64:67]
	v_mfma_f32_16x16x32_bf16 v[60:63], v[162:165], v[186:189], v[60:63]
	v_mfma_f32_16x16x32_bf16 v[60:63], v[158:161], v[182:185], v[60:63]
	v_mfma_f32_16x16x32_bf16 v[32:35], v[166:169], v[182:185], v[32:35]
	v_mfma_f32_16x16x32_bf16 v[32:35], v[170:173], v[186:189], v[32:35]
	v_mfma_f32_16x16x32_bf16 v[28:31], v[178:181], v[186:189], v[28:31]
	v_mfma_f32_16x16x32_bf16 v[28:31], v[174:177], v[182:185], v[28:31]
	v_mfma_f32_16x16x32_bf16 v[20:23], v[174:177], v[190:193], v[20:23]
	v_mfma_f32_16x16x32_bf16 v[20:23], v[178:181], v[194:197], v[20:23]
	v_mfma_f32_16x16x32_bf16 v[24:27], v[170:173], v[194:197], v[24:27]
	v_mfma_f32_16x16x32_bf16 v[24:27], v[166:169], v[190:193], v[24:27]
	v_mfma_f32_16x16x32_bf16 v[52:55], v[158:161], v[190:193], v[52:55]
	v_mfma_f32_16x16x32_bf16 v[52:55], v[162:165], v[194:197], v[52:55]
	v_mfma_f32_16x16x32_bf16 v[56:59], v[154:157], v[194:197], v[56:59]
	v_mfma_f32_16x16x32_bf16 v[56:59], v[150:153], v[190:193], v[56:59]
	v_mfma_f32_16x16x32_bf16 v[48:51], v[150:153], v[198:201], v[48:51]
	v_mfma_f32_16x16x32_bf16 v[48:51], v[154:157], v[202:205], v[48:51]
	v_mfma_f32_16x16x32_bf16 v[44:47], v[162:165], v[202:205], v[44:47]
	v_mfma_f32_16x16x32_bf16 v[44:47], v[158:161], v[198:201], v[44:47]
	v_mfma_f32_16x16x32_bf16 v[16:19], v[166:169], v[198:201], v[16:19]
	v_mfma_f32_16x16x32_bf16 v[16:19], v[170:173], v[202:205], v[16:19]
	v_mfma_f32_16x16x32_bf16 v[12:15], v[178:181], v[202:205], v[12:15]
	v_mfma_f32_16x16x32_bf16 v[12:15], v[174:177], v[198:201], v[12:15]
	v_mfma_f32_16x16x32_bf16 v[2:5], v[174:177], v[206:209], v[4:7]
	v_mfma_f32_16x16x32_bf16 v[2:5], v[178:181], v[210:213], v[2:5]
	v_mfma_f32_16x16x32_bf16 v[8:11], v[170:173], v[210:213], v[8:11]
	v_mfma_f32_16x16x32_bf16 v[8:11], v[166:169], v[206:209], v[8:11]
	v_mfma_f32_16x16x32_bf16 v[36:39], v[158:161], v[206:209], v[36:39]
	v_mfma_f32_16x16x32_bf16 v[36:39], v[162:165], v[210:213], v[36:39]
	v_mfma_f32_16x16x32_bf16 v[40:43], v[154:157], v[210:213], v[40:43]
	v_mfma_f32_16x16x32_bf16 v[40:43], v[150:153], v[206:209], v[40:43]
	s_setprio 0
	s_barrier
	s_add_i32 s89, 0, 0x18000
	v_add_u32_e32 v1, s89, v146
	s_add_i32 s90, 0, 0x1c000
	ds_read_b128 v[150:153], v1
	ds_read_b128 v[154:157], v1 offset:1024
	ds_read_b128 v[158:161], v1 offset:2048
	ds_read_b128 v[162:165], v1 offset:3072
	v_add_u32_e32 v1, s90, v146
	ds_read_b128 v[166:169], v1
	ds_read_b128 v[170:173], v1 offset:1024
	ds_read_b128 v[174:177], v1 offset:2048
	ds_read_b128 v[178:181], v1 offset:3072
	s_add_u32 s56, s56, s4
	s_addc_u32 s57, s57, s5
	s_mov_b32 m0, s70
	v_lshl_add_u64 v[6:7], s[56:57], 0, v[138:139]
	ds_read_b128 v[182:185], v148 offset:32768
	ds_read_b128 v[186:189], v148 offset:33792
	ds_read_b128 v[190:193], v148 offset:34816
	ds_read_b128 v[194:197], v148 offset:35840
	ds_read_b128 v[198:201], v148 offset:36864
	ds_read_b128 v[202:205], v148 offset:37888
	ds_read_b128 v[206:209], v148 offset:38912
	ds_read_b128 v[210:213], v148 offset:39936
	global_load_lds_dwordx4 v[6:7], off
	v_lshl_add_u64 v[6:7], s[56:57], 0, v[134:135]
	s_mov_b32 m0, s71
	s_nop 0
	global_load_lds_dwordx4 v[6:7], off
	s_waitcnt vmcnt(8)
	s_waitcnt lgkmcnt(0)
	s_barrier
	s_setprio 1
	s_waitcnt lgkmcnt(0)
	v_mfma_f32_16x16x32_bf16 v[128:131], v[150:153], v[182:185], v[128:131]
	v_mfma_f32_16x16x32_bf16 v[128:131], v[154:157], v[186:189], v[128:131]
	v_mfma_f32_16x16x32_bf16 v[124:127], v[162:165], v[186:189], v[124:127]
	v_mfma_f32_16x16x32_bf16 v[124:127], v[158:161], v[182:185], v[124:127]
	v_mfma_f32_16x16x32_bf16 v[96:99], v[166:169], v[182:185], v[96:99]
	v_mfma_f32_16x16x32_bf16 v[96:99], v[170:173], v[186:189], v[96:99]
	v_mfma_f32_16x16x32_bf16 v[92:95], v[178:181], v[186:189], v[92:95]
	v_mfma_f32_16x16x32_bf16 v[92:95], v[174:177], v[182:185], v[92:95]
	v_mfma_f32_16x16x32_bf16 v[84:87], v[174:177], v[190:193], v[84:87]
	v_mfma_f32_16x16x32_bf16 v[84:87], v[178:181], v[194:197], v[84:87]
	v_mfma_f32_16x16x32_bf16 v[88:91], v[170:173], v[194:197], v[88:91]
	v_mfma_f32_16x16x32_bf16 v[88:91], v[166:169], v[190:193], v[88:91]
	v_mfma_f32_16x16x32_bf16 v[116:119], v[158:161], v[190:193], v[116:119]
	v_mfma_f32_16x16x32_bf16 v[116:119], v[162:165], v[194:197], v[116:119]
	v_mfma_f32_16x16x32_bf16 v[120:123], v[154:157], v[194:197], v[120:123]
	v_mfma_f32_16x16x32_bf16 v[120:123], v[150:153], v[190:193], v[120:123]
	v_mfma_f32_16x16x32_bf16 v[112:115], v[150:153], v[198:201], v[112:115]
	v_mfma_f32_16x16x32_bf16 v[112:115], v[154:157], v[202:205], v[112:115]
	v_mfma_f32_16x16x32_bf16 v[108:111], v[162:165], v[202:205], v[108:111]
	v_mfma_f32_16x16x32_bf16 v[108:111], v[158:161], v[198:201], v[108:111]
	v_mfma_f32_16x16x32_bf16 v[80:83], v[166:169], v[198:201], v[80:83]
	v_mfma_f32_16x16x32_bf16 v[80:83], v[170:173], v[202:205], v[80:83]
	v_mfma_f32_16x16x32_bf16 v[76:79], v[178:181], v[202:205], v[76:79]
	v_mfma_f32_16x16x32_bf16 v[76:79], v[174:177], v[198:201], v[76:79]
	v_mfma_f32_16x16x32_bf16 v[68:71], v[174:177], v[206:209], v[68:71]
	v_mfma_f32_16x16x32_bf16 v[68:71], v[178:181], v[210:213], v[68:71]
	v_mfma_f32_16x16x32_bf16 v[72:75], v[170:173], v[210:213], v[72:75]
	v_mfma_f32_16x16x32_bf16 v[72:75], v[166:169], v[206:209], v[72:75]
	v_mfma_f32_16x16x32_bf16 v[100:103], v[158:161], v[206:209], v[100:103]
	v_mfma_f32_16x16x32_bf16 v[100:103], v[162:165], v[210:213], v[100:103]
	v_mfma_f32_16x16x32_bf16 v[104:107], v[154:157], v[210:213], v[104:107]
	v_mfma_f32_16x16x32_bf16 v[104:107], v[150:153], v[206:209], v[104:107]
	s_setprio 0
	s_barrier
; #define PG8_STAGE(bufoff, gbase, voff) do { _Pragma("unroll") for (int _i = 0; _i < 2; ++_i) \
;         __builtin_amdgcn_global_load_lds((const unsigned*)((const char*)(gbase) + (voff)[_i]), (PG8_LAS unsigned*)(lds + (bufoff) + ldsw + _i * 8192), 16, 0, 0); } while (0)
; #define PG8_LDA(dst, b, h) do { _Pragma("unroll") for (int m = 0; m < 4; ++m) _Pragma("unroll") for (int k = 0; k < 2; ++k) dst[m][k] = *(const PG8_LAS bf16x8*)(lds + PG8_SA(b, h) + aoff + m * 2048 + k * 1024); } while (0)
; #define PG8_MMA(ai, bj, At, Bt) do { __builtin_amdgcn_s_setprio(1); _Pragma("unroll") for (int m = 0; m < 4; ++m) _Pragma("unroll") for (int n = 0; n < 2; ++n) _Pragma("unroll") for (int k = 0; k < 2; ++k) \
;         acc[ai][bj][m][n] = __builtin_amdgcn_mfma_f32_16x16x32_bf16(Bt[n][k], At[m][k], acc[ai][bj][m][n], 0, 0, 0); __builtin_amdgcn_s_setprio(0); } while (0)
; #define PG8_WAIT_V(n) asm volatile("s_waitcnt vmcnt(" #n ")" ::: "memory")
; #define PG8_WAIT_L(n) asm volatile("s_waitcnt lgkmcnt(" #n ")" ::: "memory")
; #define PG8_BAR __builtin_amdgcn_s_barrier()
; #define PG8_SCHED __builtin_amdgcn_sched_barrier(0)
; template <class Epi, class Sched, bool ALIGN_EPI = false, bool SP2 = false, bool APERM = false  >
; __device__ __forceinline__ void gemm_phase(PG8_LAS unsigned char* lds, const Gemm g, const Sched& S, const Epi& E, const int wid  ) {
;     ...
;         for (int t = 0; t < nt; t += 2) {
;             const bool last = (t == nt - 2);
;     ...
;             PG8_LDA(At, 1, 1); PG8_STAGE(PG8_SB(1, 0), b3, voffB); PG8_STAGE(PG8_SB(1, 1), b3 + hstep, voffB); PG8_STAGE(PG8_SA(1, 0), a3, voffA);
;             PG8_WAIT_V(8); PG8_WAIT_L(0); PG8_BAR; PG8_MMA(1, 0, At, B0); PG8_MMA(1, 1, At, B1); PG8_BAR; PG8_SCHED;
	s_add_i32 s56, s89, s76
	v_lshl_add_u64 v[6:7], v[214:215], 0, s[16:17]
	s_mov_b32 m0, s56
	ds_read_b128 v[182:185], v148 offset:49152
	ds_read_b128 v[186:189], v148 offset:50176
	ds_read_b128 v[190:193], v148 offset:51200
	ds_read_b128 v[194:197], v148 offset:52224
	ds_read_b128 v[198:201], v148 offset:53248
	ds_read_b128 v[202:205], v148 offset:54272
	ds_read_b128 v[206:209], v148 offset:55296
	ds_read_b128 v[210:213], v148 offset:56320
	global_load_lds_dwordx4 v[6:7], off
	v_lshl_add_u64 v[6:7], v[216:217], 0, s[16:17]
	s_add_i32 m0, s56, 0x2000
	s_add_i32 s56, s90, s76
	global_load_lds_dwordx4 v[6:7], off
	v_lshl_add_u64 v[6:7], v[218:219], 0, s[16:17]
	s_mov_b32 m0, s56
	s_nop 0
	global_load_lds_dwordx4 v[6:7], off
	v_lshl_add_u64 v[6:7], v[220:221], 0, s[16:17]
	s_add_i32 m0, s56, 0x2000
	s_nop 0
	global_load_lds_dwordx4 v[6:7], off
	v_lshl_add_u64 v[6:7], v[222:223], 0, s[16:17]
	s_mov_b32 m0, s73
	s_nop 0
	global_load_lds_dwordx4 v[6:7], off
	v_lshl_add_u64 v[6:7], v[224:225], 0, s[16:17]
	s_mov_b32 m0, s74
	s_nop 0
	global_load_lds_dwordx4 v[6:7], off
	s_waitcnt vmcnt(8)
	s_waitcnt lgkmcnt(0)
	s_barrier
	s_setprio 1
	s_waitcnt lgkmcnt(0)
	v_mfma_f32_16x16x32_bf16 v[64:67], v[150:153], v[182:185], v[64:67]
	v_mfma_f32_16x16x32_bf16 v[60:63], v[158:161], v[182:185], v[60:63]
	v_mfma_f32_16x16x32_bf16 v[56:59], v[150:153], v[190:193], v[56:59]
	v_mfma_f32_16x16x32_bf16 v[52:55], v[158:161], v[190:193], v[52:55]
	v_mfma_f32_16x16x32_bf16 v[48:51], v[150:153], v[198:201], v[48:51]
	v_mfma_f32_16x16x32_bf16 v[44:47], v[158:161], v[198:201], v[44:47]
	v_mfma_f32_16x16x32_bf16 v[40:43], v[150:153], v[206:209], v[40:43]
	v_mfma_f32_16x16x32_bf16 v[36:39], v[158:161], v[206:209], v[36:39]
	v_mfma_f32_16x16x32_bf16 v[64:67], v[154:157], v[186:189], v[64:67]
	v_mfma_f32_16x16x32_bf16 v[60:63], v[162:165], v[186:189], v[60:63]
	v_mfma_f32_16x16x32_bf16 v[56:59], v[154:157], v[194:197], v[56:59]
	v_mfma_f32_16x16x32_bf16 v[52:55], v[162:165], v[194:197], v[52:55]
	v_mfma_f32_16x16x32_bf16 v[48:51], v[154:157], v[202:205], v[48:51]
	v_mfma_f32_16x16x32_bf16 v[44:47], v[162:165], v[202:205], v[44:47]
	v_mfma_f32_16x16x32_bf16 v[40:43], v[154:157], v[210:213], v[40:43]
	v_mfma_f32_16x16x32_bf16 v[36:39], v[162:165], v[210:213], v[36:39]
	v_mfma_f32_16x16x32_bf16 v[32:35], v[166:169], v[182:185], v[32:35]
	v_mfma_f32_16x16x32_bf16 v[28:31], v[174:177], v[182:185], v[28:31]
	v_mfma_f32_16x16x32_bf16 v[24:27], v[166:169], v[190:193], v[24:27]
	v_mfma_f32_16x16x32_bf16 v[20:23], v[174:177], v[190:193], v[20:23]
	v_mfma_f32_16x16x32_bf16 v[16:19], v[166:169], v[198:201], v[16:19]
	v_mfma_f32_16x16x32_bf16 v[12:15], v[174:177], v[198:201], v[12:15]
	v_mfma_f32_16x16x32_bf16 v[6:9], v[166:169], v[206:209], v[8:11]
	v_mfma_f32_16x16x32_bf16 v[2:5], v[174:177], v[206:209], v[2:5]
	v_mfma_f32_16x16x32_bf16 v[32:35], v[170:173], v[186:189], v[32:35]
	v_mfma_f32_16x16x32_bf16 v[28:31], v[178:181], v[186:189], v[28:31]
	v_mfma_f32_16x16x32_bf16 v[24:27], v[170:173], v[194:197], v[24:27]
	v_mfma_f32_16x16x32_bf16 v[20:23], v[178:181], v[194:197], v[20:23]
	v_mfma_f32_16x16x32_bf16 v[16:19], v[170:173], v[202:205], v[16:19]
	v_mfma_f32_16x16x32_bf16 v[12:15], v[178:181], v[202:205], v[12:15]
	v_mfma_f32_16x16x32_bf16 v[8:11], v[170:173], v[210:213], v[6:9]
	v_mfma_f32_16x16x32_bf16 v[4:7], v[178:181], v[210:213], v[2:5]
	s_setprio 0
	s_barrier
	s_add_u32 s54, s54, 0x100
	s_addc_u32 s55, s55, 0
	s_add_u32 s86, s86, 0x100
	s_addc_u32 s87, s87, 0
	s_cmp_ge_i32 s88, s72
	s_mov_b32 s56, s88
	s_cbranch_scc0 .LBB0_1373

; #define PG8_STAGE(bufoff, gbase, voff) do { _Pragma("unroll") for (int _i = 0; _i < 2; ++_i) \
;         __builtin_amdgcn_global_load_lds((const unsigned*)((const char*)(gbase) + (voff)[_i]), (PG8_LAS unsigned*)(lds + (bufoff) + ldsw + _i * 8192), 16, 0, 0); } while (0)
; #define PG8_LDA(dst, b, h) do { _Pragma("unroll") for (int m = 0; m < 4; ++m) _Pragma("unroll") for (int k = 0; k < 2; ++k) dst[m][k] = *(const PG8_LAS bf16x8*)(lds + PG8_SA(b, h) + aoff + m * 2048 + k * 1024); } while (0)
; #define PG8_WAIT_V(n) asm volatile("s_waitcnt vmcnt(" #n ")" ::: "memory")
; #define PG8_WAIT_L(n) asm volatile("s_waitcnt lgkmcnt(" #n ")" ::: "memory")
; template <class Epi, class Sched, bool ALIGN_EPI = false, bool SP2 = false, bool APERM = false  >
; __device__ __forceinline__ void gemm_phase(PG8_LAS unsigned char* lds, const Gemm g, const Sched& S, const Epi& E, const int wid  ) {
;     ...
;         for (int t = 0; t < nt; t += 2) {
;             const bool last = (t == nt - 2);
;             const char* a1 = cA + (size_t)(t + 1) * kstep;
;             const char* a2 = last ? nA : cA + (size_t)(t + 2) * kstep; const char* b2 = last ? nB : cB + (size_t)(t + 2) * kstep;
;             const char* a3 = a2 + kstep; const char* b3 = b2 + kstep;
;             if (last && has_next) S.a_ready(nxt);
;             if constexpr (SP2) {
;             PG8_LDB(B0, 0, 0); PG8_LDB(B1, 0, 1); PG8_SCHED; PG8_LDA(At, 0, 0); PG8_STAGE(PG8_SA(1, 1), a1 + hstep, voffA);
;             PG8_WAIT_V(8); PG8_WAIT_L(0); PG8_BAR; PG8_MMA(0, 0, At, B0); PG8_MMA(0, 1, At, B1); PG8_BAR; PG8_SCHED;
;             PG8_LDA(At, 0, 1); PG8_STAGE(PG8_SB(0, 0), b2, voffB); PG8_STAGE(PG8_SB(0, 1), b2 + hstep, voffB); PG8_STAGE(PG8_SA(0, 0), a2, voffA);
;             PG8_WAIT_V(8); PG8_WAIT_L(0); PG8_BAR; PG8_MMA(1, 0, At, B0); PG8_MMA(1, 1, At, B1); PG8_BAR; PG8_SCHED;
;             PG8_LDB(B0, 1, 0); PG8_LDB(B1, 1, 1); PG8_SCHED; PG8_LDA(At, 1, 0); PG8_STAGE(PG8_SA(0, 1), a2 + hstep, voffA);
;             PG8_WAIT_V(8); PG8_WAIT_L(0); PG8_BAR; PG8_MMA(0, 0, At, B0); PG8_MMA(0, 1, At, B1); PG8_BAR; PG8_SCHED;
;             PG8_LDA(At, 1, 1); PG8_STAGE(PG8_SB(1, 0), b3, voffB); PG8_STAGE(PG8_SB(1, 1), b3 + hstep, voffB); PG8_STAGE(PG8_SA(1, 0), a3, voffA);
;             PG8_WAIT_V(8); PG8_WAIT_L(0); PG8_BAR; PG8_MMA(1, 0, At, B0); PG8_MMA(1, 1, At, B1); PG8_BAR; PG8_SCHED;
.LBB0_1423:
	s_lshl_b32 s24, s89, 7
	s_add_u32 s25, s30, s24
	s_addc_u32 s26, s31, 0
	s_add_u32 s27, s25, 0x100
	s_addc_u32 s90, s26, 0
	v_add_u32_e32 v140, s85, v173
	v_add_u32_e32 v154, s86, v173
	s_and_b64 s[18:19], s[6:7], exec
	s_waitcnt lgkmcnt(0)
	ds_read_b128 v[128:131], v140
	ds_read_b128 v[132:135], v140 offset:1024
	ds_read_b128 v[136:139], v140 offset:2048
	ds_read_b128 v[140:143], v140 offset:3072
	ds_read_b128 v[144:147], v154
	ds_read_b128 v[162:165], v154 offset:1024
	ds_read_b128 v[166:169], v154 offset:2048
	ds_read_b128 v[180:183], v154 offset:3072
	s_cselect_b32 s19, s33, s90
	s_cselect_b32 s18, s65, s27
	s_add_u32 s24, s14, s24
	s_addc_u32 s27, s15, 0
	s_add_u32 s24, s24, 0x100
	s_addc_u32 s27, s27, 0
	s_and_b64 s[6:7], s[6:7], exec
	s_cselect_b32 s6, s88, s24
	s_cselect_b32 s7, s67, s27
	s_add_u32 s24, s25, 0x80080
	s_addc_u32 s25, s26, 0
	v_lshl_add_u64 v[170:171], s[24:25], 0, v[152:153]
	s_add_i32 m0, s11, 0xc000
	ds_read_b128 v[184:187], v178
	ds_read_b128 v[188:191], v178 offset:1024
	ds_read_b128 v[192:195], v178 offset:2048
	ds_read_b128 v[196:199], v178 offset:3072
	ds_read_b128 v[200:203], v178 offset:4096
	ds_read_b128 v[204:207], v178 offset:5120
	ds_read_b128 v[208:211], v178 offset:6144
	ds_read_b128 v[212:215], v178 offset:7168
	global_load_lds_dwordx4 v[170:171], off
	v_lshl_add_u64 v[170:171], s[24:25], 0, v[156:157]
	s_add_i32 m0, s11, 0xe000
	s_nop 0
	global_load_lds_dwordx4 v[170:171], off
	s_waitcnt vmcnt(8)
	s_waitcnt lgkmcnt(0)
	s_barrier
	s_setprio 1
	s_waitcnt lgkmcnt(0)
	v_mfma_f32_16x16x32_bf16 v[124:127], v[128:131], v[184:187], v[124:127]
	v_mfma_f32_16x16x32_bf16 v[124:127], v[132:135], v[188:191], v[124:127]
	v_mfma_f32_16x16x32_bf16 v[120:123], v[140:143], v[188:191], v[120:123]
	v_mfma_f32_16x16x32_bf16 v[120:123], v[136:139], v[184:187], v[120:123]
	v_mfma_f32_16x16x32_bf16 v[92:95], v[144:147], v[184:187], v[92:95]
	v_mfma_f32_16x16x32_bf16 v[92:95], v[162:165], v[188:191], v[92:95]
	v_mfma_f32_16x16x32_bf16 v[88:91], v[180:183], v[188:191], v[88:91]
	v_mfma_f32_16x16x32_bf16 v[88:91], v[166:169], v[184:187], v[88:91]
	v_mfma_f32_16x16x32_bf16 v[80:83], v[166:169], v[192:195], v[80:83]
	v_mfma_f32_16x16x32_bf16 v[80:83], v[180:183], v[196:199], v[80:83]
	v_mfma_f32_16x16x32_bf16 v[84:87], v[162:165], v[196:199], v[84:87]
	v_mfma_f32_16x16x32_bf16 v[84:87], v[144:147], v[192:195], v[84:87]
	v_mfma_f32_16x16x32_bf16 v[112:115], v[136:139], v[192:195], v[112:115]
	v_mfma_f32_16x16x32_bf16 v[112:115], v[140:143], v[196:199], v[112:115]
	v_mfma_f32_16x16x32_bf16 v[116:119], v[132:135], v[196:199], v[116:119]
	v_mfma_f32_16x16x32_bf16 v[116:119], v[128:131], v[192:195], v[116:119]
	v_mfma_f32_16x16x32_bf16 v[108:111], v[128:131], v[200:203], v[108:111]
	v_mfma_f32_16x16x32_bf16 v[108:111], v[132:135], v[204:207], v[108:111]
	v_mfma_f32_16x16x32_bf16 v[104:107], v[140:143], v[204:207], v[104:107]
	v_mfma_f32_16x16x32_bf16 v[104:107], v[136:139], v[200:203], v[104:107]
	v_mfma_f32_16x16x32_bf16 v[76:79], v[144:147], v[200:203], v[76:79]
	v_mfma_f32_16x16x32_bf16 v[76:79], v[162:165], v[204:207], v[76:79]
	v_mfma_f32_16x16x32_bf16 v[72:75], v[180:183], v[204:207], v[72:75]
	v_mfma_f32_16x16x32_bf16 v[72:75], v[166:169], v[200:203], v[72:75]
	v_mfma_f32_16x16x32_bf16 v[64:67], v[166:169], v[208:211], v[64:67]
	v_mfma_f32_16x16x32_bf16 v[64:67], v[180:183], v[212:215], v[64:67]
	v_mfma_f32_16x16x32_bf16 v[68:71], v[162:165], v[212:215], v[68:71]
	v_mfma_f32_16x16x32_bf16 v[68:71], v[144:147], v[208:211], v[68:71]
	v_mfma_f32_16x16x32_bf16 v[96:99], v[136:139], v[208:211], v[96:99]
	v_mfma_f32_16x16x32_bf16 v[96:99], v[140:143], v[212:215], v[96:99]
	v_mfma_f32_16x16x32_bf16 v[100:103], v[132:135], v[212:215], v[100:103]
	v_mfma_f32_16x16x32_bf16 v[100:103], v[128:131], v[208:211], v[100:103]
	s_setprio 0
	s_barrier
	s_add_i32 s24, s85, s76
	v_lshl_add_u64 v[170:171], s[6:7], 0, v[148:149]
	s_mov_b32 m0, s24
	ds_read_b128 v[184:187], v178 offset:16384
	ds_read_b128 v[188:191], v178 offset:17408
	ds_read_b128 v[192:195], v178 offset:18432
	ds_read_b128 v[196:199], v178 offset:19456
	ds_read_b128 v[200:203], v178 offset:20480
	ds_read_b128 v[204:207], v178 offset:21504
	ds_read_b128 v[208:211], v178 offset:22528
	ds_read_b128 v[212:215], v178 offset:23552
	global_load_lds_dwordx4 v[170:171], off
	s_add_i32 m0, s24, 0x2000
	s_add_u32 s24, s6, 0x80000
	v_lshl_add_u64 v[216:217], s[6:7], 0, v[150:151]
	s_addc_u32 s25, s7, 0
	s_add_i32 s26, s86, s76
	global_load_lds_dwordx4 v[216:217], off
	v_lshl_add_u64 v[218:219], s[24:25], 0, v[148:149]
	s_mov_b32 m0, s26
	v_lshl_add_u64 v[220:221], s[18:19], 0, v[156:157]
	global_load_lds_dwordx4 v[218:219], off
	v_lshl_add_u64 v[218:219], s[24:25], 0, v[150:151]
	s_add_i32 m0, s26, 0x2000
	s_nop 0
	global_load_lds_dwordx4 v[218:219], off
	v_lshl_add_u64 v[218:219], s[18:19], 0, v[152:153]
	s_mov_b32 m0, s11
	s_nop 0
	global_load_lds_dwordx4 v[218:219], off
	s_mov_b32 m0, s13
	s_nop 0
	global_load_lds_dwordx4 v[220:221], off
	s_waitcnt vmcnt(8)
	s_waitcnt lgkmcnt(0)
	s_barrier
; #define PG8_STAGE(bufoff, gbase, voff) do { _Pragma("unroll") for (int _i = 0; _i < 2; ++_i) \
;         __builtin_amdgcn_global_load_lds((const unsigned*)((const char*)(gbase) + (voff)[_i]), (PG8_LAS unsigned*)(lds + (bufoff) + ldsw + _i * 8192), 16, 0, 0); } while (0)
; #define PG8_LDA(dst, b, h) do { _Pragma("unroll") for (int m = 0; m < 4; ++m) _Pragma("unroll") for (int k = 0; k < 2; ++k) dst[m][k] = *(const PG8_LAS bf16x8*)(lds + PG8_SA(b, h) + aoff + m * 2048 + k * 1024); } while (0)
; #define PG8_LDB(dst, b, h) do { _Pragma("unroll") for (int n = 0; n < 2; ++n) _Pragma("unroll") for (int k = 0; k < 2; ++k) dst[n][k] = *(const PG8_LAS bf16x8*)(lds + PG8_SB(b, h) + boff + n * 2048 + k * 1024); } while (0)
; #define PG8_MMA(ai, bj, At, Bt) do { __builtin_amdgcn_s_setprio(1); _Pragma("unroll") for (int m = 0; m < 4; ++m) _Pragma("unroll") for (int n = 0; n < 2; ++n) _Pragma("unroll") for (int k = 0; k < 2; ++k) \
;         acc[ai][bj][m][n] = __builtin_amdgcn_mfma_f32_16x16x32_bf16(Bt[n][k], At[m][k], acc[ai][bj][m][n], 0, 0, 0); __builtin_amdgcn_s_setprio(0); } while (0)
; #define PG8_WAIT_V(n) asm volatile("s_waitcnt vmcnt(" #n ")" ::: "memory")
; #define PG8_WAIT_L(n) asm volatile("s_waitcnt lgkmcnt(" #n ")" ::: "memory")
; #define PG8_BAR __builtin_amdgcn_s_barrier()
; #define PG8_SCHED __builtin_amdgcn_sched_barrier(0)
; template <class Epi, class Sched, bool ALIGN_EPI = false, bool SP2 = false, bool APERM = false  >
; __device__ __forceinline__ void gemm_phase(PG8_LAS unsigned char* lds, const Gemm g, const Sched& S, const Epi& E, const int wid  ) {
;     ...
;             PG8_WAIT_V(8); PG8_WAIT_L(0); PG8_BAR; PG8_MMA(0, 0, At, B0); PG8_MMA(0, 1, At, B1); PG8_BAR; PG8_SCHED;
;             PG8_LDA(At, 0, 1); PG8_STAGE(PG8_SB(0, 0), b2, voffB); PG8_STAGE(PG8_SB(0, 1), b2 + hstep, voffB); PG8_STAGE(PG8_SA(0, 0), a2, voffA);
;             PG8_WAIT_V(8); PG8_WAIT_L(0); PG8_BAR; PG8_MMA(1, 0, At, B0); PG8_MMA(1, 1, At, B1); PG8_BAR; PG8_SCHED;
;             PG8_LDB(B0, 1, 0); PG8_LDB(B1, 1, 1); PG8_SCHED; PG8_LDA(At, 1, 0); PG8_STAGE(PG8_SA(0, 1), a2 + hstep, voffA);
;             PG8_WAIT_V(8); PG8_WAIT_L(0); PG8_BAR; PG8_MMA(0, 0, At, B0); PG8_MMA(0, 1, At, B1); PG8_BAR; PG8_SCHED;
	s_setprio 1
	s_waitcnt lgkmcnt(0)
	v_mfma_f32_16x16x32_bf16 v[60:63], v[128:131], v[184:187], v[60:63]
	v_mfma_f32_16x16x32_bf16 v[60:63], v[132:135], v[188:191], v[60:63]
	v_mfma_f32_16x16x32_bf16 v[56:59], v[140:143], v[188:191], v[56:59]
	v_mfma_f32_16x16x32_bf16 v[56:59], v[136:139], v[184:187], v[56:59]
	v_mfma_f32_16x16x32_bf16 v[28:31], v[144:147], v[184:187], v[28:31]
	v_mfma_f32_16x16x32_bf16 v[28:31], v[162:165], v[188:191], v[28:31]
	v_mfma_f32_16x16x32_bf16 v[24:27], v[180:183], v[188:191], v[24:27]
	v_mfma_f32_16x16x32_bf16 v[24:27], v[166:169], v[184:187], v[24:27]
	v_mfma_f32_16x16x32_bf16 v[16:19], v[166:169], v[192:195], v[16:19]
	v_mfma_f32_16x16x32_bf16 v[16:19], v[180:183], v[196:199], v[16:19]
	v_mfma_f32_16x16x32_bf16 v[20:23], v[162:165], v[196:199], v[20:23]
	v_mfma_f32_16x16x32_bf16 v[20:23], v[144:147], v[192:195], v[20:23]
	v_mfma_f32_16x16x32_bf16 v[48:51], v[136:139], v[192:195], v[48:51]
	v_mfma_f32_16x16x32_bf16 v[48:51], v[140:143], v[196:199], v[48:51]
	v_mfma_f32_16x16x32_bf16 v[52:55], v[132:135], v[196:199], v[52:55]
	v_mfma_f32_16x16x32_bf16 v[52:55], v[128:131], v[192:195], v[52:55]
	v_mfma_f32_16x16x32_bf16 v[44:47], v[128:131], v[200:203], v[44:47]
	v_mfma_f32_16x16x32_bf16 v[44:47], v[132:135], v[204:207], v[44:47]
	v_mfma_f32_16x16x32_bf16 v[40:43], v[140:143], v[204:207], v[40:43]
	v_mfma_f32_16x16x32_bf16 v[40:43], v[136:139], v[200:203], v[40:43]
	v_mfma_f32_16x16x32_bf16 v[12:15], v[144:147], v[200:203], v[12:15]
	v_mfma_f32_16x16x32_bf16 v[12:15], v[162:165], v[204:207], v[12:15]
	v_mfma_f32_16x16x32_bf16 v[8:11], v[180:183], v[204:207], v[8:11]
	v_mfma_f32_16x16x32_bf16 v[8:11], v[166:169], v[200:203], v[8:11]
	v_mfma_f32_16x16x32_bf16 v[0:3], v[166:169], v[208:211], v[0:3]
	v_mfma_f32_16x16x32_bf16 v[0:3], v[180:183], v[212:215], v[0:3]
	v_mfma_f32_16x16x32_bf16 v[4:7], v[162:165], v[212:215], v[4:7]
	v_mfma_f32_16x16x32_bf16 v[4:7], v[144:147], v[208:211], v[4:7]
	v_mfma_f32_16x16x32_bf16 v[32:35], v[136:139], v[208:211], v[32:35]
	v_mfma_f32_16x16x32_bf16 v[32:35], v[140:143], v[212:215], v[32:35]
	v_mfma_f32_16x16x32_bf16 v[36:39], v[132:135], v[212:215], v[36:39]
	v_mfma_f32_16x16x32_bf16 v[36:39], v[128:131], v[208:211], v[36:39]
	s_setprio 0
	s_barrier
	s_add_i32 s24, 0, 0x18000
	s_add_i32 s25, 0, 0x1c000
	v_add_u32_e32 v140, s24, v173
	v_add_u32_e32 v154, s25, v173
	ds_read_b128 v[128:131], v140
	ds_read_b128 v[132:135], v140 offset:1024
	ds_read_b128 v[136:139], v140 offset:2048
	ds_read_b128 v[140:143], v140 offset:3072
	ds_read_b128 v[144:147], v154
	ds_read_b128 v[162:165], v154 offset:1024
	ds_read_b128 v[166:169], v154 offset:2048
	ds_read_b128 v[180:183], v154 offset:3072
	s_add_u32 s18, s18, 0x80000
	s_addc_u32 s19, s19, 0
	s_mov_b32 m0, s78
	v_lshl_add_u64 v[222:223], s[18:19], 0, v[152:153]
	ds_read_b128 v[184:187], v178 offset:32768
	ds_read_b128 v[188:191], v178 offset:33792
	ds_read_b128 v[192:195], v178 offset:34816
	ds_read_b128 v[196:199], v178 offset:35840
	ds_read_b128 v[200:203], v178 offset:36864
	ds_read_b128 v[204:207], v178 offset:37888
	ds_read_b128 v[208:211], v178 offset:38912
	ds_read_b128 v[212:215], v178 offset:39936
	global_load_lds_dwordx4 v[222:223], off
	v_lshl_add_u64 v[222:223], s[18:19], 0, v[156:157]
	s_mov_b32 m0, s79
	s_nop 0
	global_load_lds_dwordx4 v[222:223], off
	s_waitcnt vmcnt(8)
	s_waitcnt lgkmcnt(0)
	s_barrier
	s_setprio 1
	s_waitcnt lgkmcnt(0)
	v_mfma_f32_16x16x32_bf16 v[124:127], v[128:131], v[184:187], v[124:127]
	v_mfma_f32_16x16x32_bf16 v[124:127], v[132:135], v[188:191], v[124:127]
	v_mfma_f32_16x16x32_bf16 v[120:123], v[140:143], v[188:191], v[120:123]
	v_mfma_f32_16x16x32_bf16 v[120:123], v[136:139], v[184:187], v[120:123]
	v_mfma_f32_16x16x32_bf16 v[92:95], v[144:147], v[184:187], v[92:95]
	v_mfma_f32_16x16x32_bf16 v[92:95], v[162:165], v[188:191], v[92:95]
	v_mfma_f32_16x16x32_bf16 v[88:91], v[180:183], v[188:191], v[88:91]
	v_mfma_f32_16x16x32_bf16 v[88:91], v[166:169], v[184:187], v[88:91]
	v_mfma_f32_16x16x32_bf16 v[80:83], v[166:169], v[192:195], v[80:83]
	v_mfma_f32_16x16x32_bf16 v[80:83], v[180:183], v[196:199], v[80:83]
	v_mfma_f32_16x16x32_bf16 v[84:87], v[162:165], v[196:199], v[84:87]
	v_mfma_f32_16x16x32_bf16 v[84:87], v[144:147], v[192:195], v[84:87]
	v_mfma_f32_16x16x32_bf16 v[112:115], v[136:139], v[192:195], v[112:115]
	v_mfma_f32_16x16x32_bf16 v[112:115], v[140:143], v[196:199], v[112:115]
	v_mfma_f32_16x16x32_bf16 v[116:119], v[132:135], v[196:199], v[116:119]
	v_mfma_f32_16x16x32_bf16 v[116:119], v[128:131], v[192:195], v[116:119]
	v_mfma_f32_16x16x32_bf16 v[108:111], v[128:131], v[200:203], v[108:111]
	v_mfma_f32_16x16x32_bf16 v[108:111], v[132:135], v[204:207], v[108:111]
	v_mfma_f32_16x16x32_bf16 v[104:107], v[140:143], v[204:207], v[104:107]
	v_mfma_f32_16x16x32_bf16 v[104:107], v[136:139], v[200:203], v[104:107]
	v_mfma_f32_16x16x32_bf16 v[76:79], v[144:147], v[200:203], v[76:79]
	v_mfma_f32_16x16x32_bf16 v[76:79], v[162:165], v[204:207], v[76:79]
	v_mfma_f32_16x16x32_bf16 v[72:75], v[180:183], v[204:207], v[72:75]
	v_mfma_f32_16x16x32_bf16 v[72:75], v[166:169], v[200:203], v[72:75]
	v_mfma_f32_16x16x32_bf16 v[64:67], v[166:169], v[208:211], v[64:67]
	v_mfma_f32_16x16x32_bf16 v[64:67], v[180:183], v[212:215], v[64:67]
	v_mfma_f32_16x16x32_bf16 v[68:71], v[162:165], v[212:215], v[68:71]
	v_mfma_f32_16x16x32_bf16 v[68:71], v[144:147], v[208:211], v[68:71]
	v_mfma_f32_16x16x32_bf16 v[96:99], v[136:139], v[208:211], v[96:99]
	v_mfma_f32_16x16x32_bf16 v[96:99], v[140:143], v[212:215], v[96:99]
	v_mfma_f32_16x16x32_bf16 v[100:103], v[132:135], v[212:215], v[100:103]
	v_mfma_f32_16x16x32_bf16 v[100:103], v[128:131], v[208:211], v[100:103]
	s_setprio 0
	s_barrier
; #define PG8_STAGE(bufoff, gbase, voff) do { _Pragma("unroll") for (int _i = 0; _i < 2; ++_i) \
;         __builtin_amdgcn_global_load_lds((const unsigned*)((const char*)(gbase) + (voff)[_i]), (PG8_LAS unsigned*)(lds + (bufoff) + ldsw + _i * 8192), 16, 0, 0); } while (0)
; #define PG8_LDA(dst, b, h) do { _Pragma("unroll") for (int m = 0; m < 4; ++m) _Pragma("unroll") for (int k = 0; k < 2; ++k) dst[m][k] = *(const PG8_LAS bf16x8*)(lds + PG8_SA(b, h) + aoff + m * 2048 + k * 1024); } while (0)
; #define PG8_MMA(ai, bj, At, Bt) do { __builtin_amdgcn_s_setprio(1); _Pragma("unroll") for (int m = 0; m < 4; ++m) _Pragma("unroll") for (int n = 0; n < 2; ++n) _Pragma("unroll") for (int k = 0; k < 2; ++k) \
;         acc[ai][bj][m][n] = __builtin_amdgcn_mfma_f32_16x16x32_bf16(Bt[n][k], At[m][k], acc[ai][bj][m][n], 0, 0, 0); __builtin_amdgcn_s_setprio(0); } while (0)
; #define PG8_WAIT_V(n) asm volatile("s_waitcnt vmcnt(" #n ")" ::: "memory")
; #define PG8_WAIT_L(n) asm volatile("s_waitcnt lgkmcnt(" #n ")" ::: "memory")
; #define PG8_BAR __builtin_amdgcn_s_barrier()
; #define PG8_SCHED __builtin_amdgcn_sched_barrier(0)
; template <class Epi, class Sched, bool ALIGN_EPI = false, bool SP2 = false, bool APERM = false  >
; __device__ __forceinline__ void gemm_phase(PG8_LAS unsigned char* lds, const Gemm g, const Sched& S, const Epi& E, const int wid  ) {
;     ...
;         for (int t = 0; t < nt; t += 2) {
;             const bool last = (t == nt - 2);
;     ...
;             PG8_LDA(At, 1, 1); PG8_STAGE(PG8_SB(1, 0), b3, voffB); PG8_STAGE(PG8_SB(1, 1), b3 + hstep, voffB); PG8_STAGE(PG8_SA(1, 0), a3, voffA);
;             PG8_WAIT_V(8); PG8_WAIT_L(0); PG8_BAR; PG8_MMA(1, 0, At, B0); PG8_MMA(1, 1, At, B1); PG8_BAR; PG8_SCHED;
	s_add_i32 s18, s24, s76
	v_lshl_add_u64 v[170:171], v[170:171], 0, s[40:41]
	s_mov_b32 m0, s18
	ds_read_b128 v[184:187], v178 offset:49152
	ds_read_b128 v[188:191], v178 offset:50176
	ds_read_b128 v[192:195], v178 offset:51200
	ds_read_b128 v[196:199], v178 offset:52224
	ds_read_b128 v[200:203], v178 offset:53248
	ds_read_b128 v[204:207], v178 offset:54272
	ds_read_b128 v[208:211], v178 offset:55296
	ds_read_b128 v[212:215], v178 offset:56320
	global_load_lds_dwordx4 v[170:171], off
	s_add_i32 m0, s18, 0x2000
	s_add_u32 s6, s6, 0x80080
	v_lshl_add_u64 v[170:171], v[216:217], 0, s[40:41]
	s_addc_u32 s7, s7, 0
	s_add_i32 s18, s25, s76
	global_load_lds_dwordx4 v[170:171], off
	v_lshl_add_u64 v[170:171], s[6:7], 0, v[148:149]
	s_mov_b32 m0, s18
	s_nop 0
	global_load_lds_dwordx4 v[170:171], off
	v_lshl_add_u64 v[170:171], s[6:7], 0, v[150:151]
	s_add_i32 m0, s18, 0x2000
	s_nop 0
	global_load_lds_dwordx4 v[170:171], off
	v_lshl_add_u64 v[170:171], v[218:219], 0, s[40:41]
	s_mov_b32 m0, s82
	s_nop 0
	global_load_lds_dwordx4 v[170:171], off
	v_lshl_add_u64 v[170:171], v[220:221], 0, s[40:41]
	s_mov_b32 m0, s84
	s_nop 0
	global_load_lds_dwordx4 v[170:171], off
	s_waitcnt vmcnt(8)
	s_waitcnt lgkmcnt(0)
	s_barrier
	s_setprio 1
	s_waitcnt lgkmcnt(0)
	v_mfma_f32_16x16x32_bf16 v[60:63], v[128:131], v[184:187], v[60:63]
	v_mfma_f32_16x16x32_bf16 v[60:63], v[132:135], v[188:191], v[60:63]
	v_mfma_f32_16x16x32_bf16 v[56:59], v[140:143], v[188:191], v[56:59]
	v_mfma_f32_16x16x32_bf16 v[56:59], v[136:139], v[184:187], v[56:59]
	v_mfma_f32_16x16x32_bf16 v[28:31], v[144:147], v[184:187], v[28:31]
	v_mfma_f32_16x16x32_bf16 v[28:31], v[162:165], v[188:191], v[28:31]
	v_mfma_f32_16x16x32_bf16 v[24:27], v[180:183], v[188:191], v[24:27]
	v_mfma_f32_16x16x32_bf16 v[24:27], v[166:169], v[184:187], v[24:27]
	v_mfma_f32_16x16x32_bf16 v[16:19], v[166:169], v[192:195], v[16:19]
	v_mfma_f32_16x16x32_bf16 v[16:19], v[180:183], v[196:199], v[16:19]
	v_mfma_f32_16x16x32_bf16 v[20:23], v[162:165], v[196:199], v[20:23]
	v_mfma_f32_16x16x32_bf16 v[20:23], v[144:147], v[192:195], v[20:23]
	v_mfma_f32_16x16x32_bf16 v[48:51], v[136:139], v[192:195], v[48:51]
	v_mfma_f32_16x16x32_bf16 v[48:51], v[140:143], v[196:199], v[48:51]
	v_mfma_f32_16x16x32_bf16 v[52:55], v[132:135], v[196:199], v[52:55]
	v_mfma_f32_16x16x32_bf16 v[52:55], v[128:131], v[192:195], v[52:55]
	v_mfma_f32_16x16x32_bf16 v[44:47], v[128:131], v[200:203], v[44:47]
	v_mfma_f32_16x16x32_bf16 v[44:47], v[132:135], v[204:207], v[44:47]
	v_mfma_f32_16x16x32_bf16 v[40:43], v[140:143], v[204:207], v[40:43]
	v_mfma_f32_16x16x32_bf16 v[40:43], v[136:139], v[200:203], v[40:43]
	v_mfma_f32_16x16x32_bf16 v[12:15], v[144:147], v[200:203], v[12:15]
	v_mfma_f32_16x16x32_bf16 v[12:15], v[162:165], v[204:207], v[12:15]
	v_mfma_f32_16x16x32_bf16 v[8:11], v[180:183], v[204:207], v[8:11]
	v_mfma_f32_16x16x32_bf16 v[8:11], v[166:169], v[200:203], v[8:11]
	v_mfma_f32_16x16x32_bf16 v[0:3], v[166:169], v[208:211], v[0:3]
	v_mfma_f32_16x16x32_bf16 v[0:3], v[180:183], v[212:215], v[0:3]
	v_mfma_f32_16x16x32_bf16 v[4:7], v[162:165], v[212:215], v[4:7]
	v_mfma_f32_16x16x32_bf16 v[4:7], v[144:147], v[208:211], v[4:7]
	v_mfma_f32_16x16x32_bf16 v[32:35], v[136:139], v[208:211], v[32:35]
	v_mfma_f32_16x16x32_bf16 v[32:35], v[140:143], v[212:215], v[32:35]
	v_mfma_f32_16x16x32_bf16 v[36:39], v[132:135], v[212:215], v[36:39]
	v_mfma_f32_16x16x32_bf16 v[36:39], v[128:131], v[208:211], v[36:39]
	s_setprio 0
	s_barrier
	s_add_i32 s6, s89, 2
	s_cmp_gt_u32 s89, 29
	s_cbranch_scc1 .LBB0_1425
	s_mov_b32 s89, s6
	s_branch .LBB0_1406
